# MFMA accumulator chains ordered weight-fragment-major (consecutive chains share SrcA pair)
# speedup vs baseline: 1.0120x; 1.0022x over previous
; #define PG8_STAGE(bufoff, gbase, voff) do { _Pragma("unroll") for (int _i = 0; _i < 2; ++_i) \
;         __builtin_amdgcn_global_load_lds((const unsigned*)((const char*)(gbase) + (voff)[_i]), (PG8_LAS unsigned*)(lds + (bufoff) + ldsw + _i * 8192), 16, 0, 0); } while (0)
; #define PG8_LDA(dst, b, h) do { _Pragma("unroll") for (int m = 0; m < 4; ++m) _Pragma("unroll") for (int k = 0; k < 2; ++k) dst[m][k] = *(const PG8_LAS bf16x8*)(lds + PG8_SA(b, h) + aoff + m * 2048 + k * 1024); } while (0)
; #define PG8_LDB(dst, b, h) do { _Pragma("unroll") for (int n = 0; n < 2; ++n) _Pragma("unroll") for (int k = 0; k < 2; ++k) dst[n][k] = *(const PG8_LAS bf16x8*)(lds + PG8_SB(b, h) + boff + n * 2048 + k * 1024); } while (0)
; #define PG8_WAIT_V(n) asm volatile("s_waitcnt vmcnt(" #n ")" ::: "memory")
; #define PG8_WAIT_L(n) asm volatile("s_waitcnt lgkmcnt(" #n ")" ::: "memory")
; #define PG8_BAR __builtin_amdgcn_s_barrier()
; #define PG8_SCHED __builtin_amdgcn_sched_barrier(0)
; template <class Epi, class Sched, bool ALIGN_EPI = false, bool SP2 = false, bool I8 = false>
; __device__ __forceinline__ void gemm_phase(PG8_LAS unsigned char* lds, const Gemm g, const Sched& S, const Epi& E) {
;     ...
;         const bool has_next = S.next(ui + 1, nxt);
;         const char* nA = has_next ? (const char*)g.A + (size_t)nxt.pm * tstep : cA; const char* nB = has_next ? (const char*)g.Bt + (size_t)nxt.pn * tstep : cB;
;         for (int t = 0; t < nt; t += 2) {
;             const bool last = (t == nt - 2);
;             const char* a1 = cA + (size_t)(t + 1) * kstep;
;             const char* a2 = last ? nA : cA + (size_t)(t + 2) * kstep; const char* b2 = last ? nB : cB + (size_t)(t + 2) * kstep;
;             const char* a3 = a2 + kstep; const char* b3 = b2 + kstep;
;             if (last && has_next) S.a_ready(nxt);
;             if constexpr (SP2) {
;             PG8_LDB(B0, 0, 0); PG8_LDB(B1, 0, 1); PG8_SCHED; PG8_LDA(At, 0, 0); PG8_STAGE(PG8_SA(1, 1), a1 + hstep, voffA);
;             PG8_WAIT_V(8); PG8_WAIT_L(0); PG8_BAR; PG8_MMA(0, 0, At, B0); PG8_MMA(0, 1, At, B1); PG8_BAR; PG8_SCHED;
;             PG8_LDA(At, 0, 1); PG8_STAGE(PG8_SB(0, 0), b2, voffB); PG8_STAGE(PG8_SB(0, 1), b2 + hstep, voffB); PG8_STAGE(PG8_SA(0, 0), a2, voffA);
;             PG8_WAIT_V(8); PG8_WAIT_L(0); PG8_BAR; PG8_MMA(1, 0, At, B0); PG8_MMA(1, 1, At, B1); PG8_BAR; PG8_SCHED;
.LBB0_207:
	s_ashr_i32 s19, s18, 31
	s_lshl_b64 s[22:23], s[18:19], 20
	s_add_u32 s22, s28, s22
	s_addc_u32 s23, s34, s23
	s_and_b64 s[24:25], s[6:7], exec
	s_cselect_b32 s19, s23, s27
	s_cselect_b32 s64, s22, s26
	s_ashr_i32 s17, s16, 31
	s_lshl_b64 s[24:25], s[16:17], 20
	s_add_u32 s24, s35, s24
	s_addc_u32 s25, s42, s25
	s_and_b64 s[40:41], s[6:7], exec
	s_cselect_b32 s17, s25, s37
	s_cselect_b32 s65, s24, s36
	s_add_u32 s26, s26, 0x80080
	s_addc_u32 s27, s27, 0
	s_add_u32 s72, s36, 0x100
	s_addc_u32 s73, s37, 0
	s_mov_b32 s76, -2
	s_add_u32 s36, s26, 0xfff80080
	s_addc_u32 s37, s27, -1
	s_add_i32 s50, 0, 0x10000
	s_cmp_eq_u32 s76, 28
	s_cselect_b32 s41, s19, s37
	s_cselect_b32 s40, s64, s36
	s_cselect_b32 s37, s17, s73
	s_cselect_b32 s36, s65, s72
	s_add_i32 s56, 0, 0x14000
	v_add_u32_e32 v136, s50, v175
	v_add_u32_e32 v172, s56, v175
	ds_read_b128 v[116:119], v136
	ds_read_b128 v[124:127], v136 offset:1024
	ds_read_b128 v[132:135], v136 offset:2048
	ds_read_b128 v[136:139], v136 offset:3072
	ds_read_b128 v[160:163], v172
	ds_read_b128 v[164:167], v172 offset:1024
	ds_read_b128 v[168:171], v172 offset:2048
	ds_read_b128 v[178:181], v172 offset:3072
	v_lshl_add_u64 v[172:173], s[26:27], 0, v[156:157]
	s_add_i32 m0, s44, 0xc000
	ds_read_b128 v[182:185], v177
	ds_read_b128 v[186:189], v177 offset:1024
	ds_read_b128 v[204:207], v177 offset:2048
	ds_read_b128 v[208:211], v177 offset:3072
	ds_read_b128 v[212:215], v177 offset:4096
	ds_read_b128 v[216:219], v177 offset:5120
	ds_read_b128 v[220:223], v177 offset:6144
	ds_read_b128 v[224:227], v177 offset:7168
	global_load_lds_dwordx4 v[172:173], off
	v_lshl_add_u64 v[172:173], s[26:27], 0, v[158:159]
	s_add_i32 m0, s44, 0xe000
	s_nop 0
	global_load_lds_dwordx4 v[172:173], off
	s_waitcnt vmcnt(8)
	s_waitcnt lgkmcnt(0)
	s_barrier
	s_setprio 1
	s_waitcnt lgkmcnt(0)
	v_mfma_i32_16x16x64_i8 v[144:147], v[116:119], v[182:185], 0
	v_mfma_i32_16x16x64_i8 v[144:147], v[124:127], v[186:189], v[144:147]
	v_mfma_i32_16x16x64_i8 v[112:115], v[116:119], v[204:207], 0
	v_mfma_i32_16x16x64_i8 v[112:115], v[124:127], v[208:211], v[112:115]
	v_mfma_i32_16x16x64_i8 v[96:99], v[116:119], v[212:215], 0
	v_mfma_i32_16x16x64_i8 v[96:99], v[124:127], v[216:219], v[96:99]
	v_mfma_i32_16x16x64_i8 v[80:83], v[116:119], v[220:223], 0
	v_mfma_i32_16x16x64_i8 v[80:83], v[124:127], v[224:227], v[80:83]
	v_mfma_i32_16x16x64_i8 v[140:143], v[132:135], v[182:185], 0
	v_mfma_i32_16x16x64_i8 v[140:143], v[136:139], v[186:189], v[140:143]
	v_mfma_i32_16x16x64_i8 v[108:111], v[132:135], v[204:207], 0
	v_mfma_i32_16x16x64_i8 v[108:111], v[136:139], v[208:211], v[108:111]
	v_mfma_i32_16x16x64_i8 v[92:95], v[132:135], v[212:215], 0
	v_mfma_i32_16x16x64_i8 v[92:95], v[136:139], v[216:219], v[92:95]
	v_mfma_i32_16x16x64_i8 v[76:79], v[132:135], v[220:223], 0
	v_mfma_i32_16x16x64_i8 v[76:79], v[136:139], v[224:227], v[76:79]
	s_setprio 0
	s_setprio 1
	v_mfma_i32_16x16x64_i8 v[128:131], v[160:163], v[182:185], 0
	v_mfma_i32_16x16x64_i8 v[128:131], v[164:167], v[186:189], v[128:131]
	v_mfma_i32_16x16x64_i8 v[104:107], v[160:163], v[204:207], 0
	v_mfma_i32_16x16x64_i8 v[104:107], v[164:167], v[208:211], v[104:107]
	v_mfma_i32_16x16x64_i8 v[88:91], v[160:163], v[212:215], 0
	v_mfma_i32_16x16x64_i8 v[88:91], v[164:167], v[216:219], v[88:91]
	v_mfma_i32_16x16x64_i8 v[72:75], v[160:163], v[220:223], 0
	v_mfma_i32_16x16x64_i8 v[72:75], v[164:167], v[224:227], v[72:75]
	v_mfma_i32_16x16x64_i8 v[120:123], v[168:171], v[182:185], 0
	v_mfma_i32_16x16x64_i8 v[120:123], v[178:181], v[186:189], v[120:123]
	v_mfma_i32_16x16x64_i8 v[100:103], v[168:171], v[204:207], 0
	v_mfma_i32_16x16x64_i8 v[100:103], v[178:181], v[208:211], v[100:103]
	v_mfma_i32_16x16x64_i8 v[84:87], v[168:171], v[212:215], 0
	v_mfma_i32_16x16x64_i8 v[84:87], v[178:181], v[216:219], v[84:87]
	v_mfma_i32_16x16x64_i8 v[68:71], v[168:171], v[220:223], 0
	v_mfma_i32_16x16x64_i8 v[68:71], v[178:181], v[224:227], v[68:71]
	s_setprio 0
	s_barrier
	s_add_i32 s50, s50, s43
	v_lshl_add_u64 v[172:173], s[36:37], 0, v[2:3]
	s_mov_b32 m0, s50
	ds_read_b128 v[182:185], v177 offset:16384
	ds_read_b128 v[186:189], v177 offset:17408
	ds_read_b128 v[204:207], v177 offset:18432
	ds_read_b128 v[208:211], v177 offset:19456
	ds_read_b128 v[212:215], v177 offset:20480
	ds_read_b128 v[216:219], v177 offset:21504
	ds_read_b128 v[220:223], v177 offset:22528
	ds_read_b128 v[224:227], v177 offset:23552
	global_load_lds_dwordx4 v[172:173], off
	s_add_i32 m0, s50, 0x2000
	s_add_u32 s50, s36, 0x80000
	v_lshl_add_u64 v[190:191], s[36:37], 0, v[148:149]
	s_addc_u32 s51, s37, 0
	s_add_i32 s56, s56, s43
	global_load_lds_dwordx4 v[190:191], off
	v_lshl_add_u64 v[228:229], s[50:51], 0, v[2:3]
	s_mov_b32 m0, s56
	v_lshl_add_u64 v[240:241], s[40:41], 0, v[150:151]
	global_load_lds_dwordx4 v[228:229], off
	v_lshl_add_u64 v[228:229], s[50:51], 0, v[148:149]
	s_add_i32 m0, s56, 0x2000
	s_nop 0
	global_load_lds_dwordx4 v[228:229], off
	v_lshl_add_u64 v[228:229], s[40:41], 0, v[152:153]
	s_mov_b32 m0, s44
	s_nop 0
	global_load_lds_dwordx4 v[228:229], off
	s_mov_b32 m0, s45
	s_nop 0
	global_load_lds_dwordx4 v[240:241], off
	s_waitcnt vmcnt(8)
	s_waitcnt lgkmcnt(0)
	s_barrier
; #define PG8_STAGE(bufoff, gbase, voff) do { _Pragma("unroll") for (int _i = 0; _i < 2; ++_i) \
;         __builtin_amdgcn_global_load_lds((const unsigned*)((const char*)(gbase) + (voff)[_i]), (PG8_LAS unsigned*)(lds + (bufoff) + ldsw + _i * 8192), 16, 0, 0); } while (0)
; #define PG8_LDA(dst, b, h) do { _Pragma("unroll") for (int m = 0; m < 4; ++m) _Pragma("unroll") for (int k = 0; k < 2; ++k) dst[m][k] = *(const PG8_LAS bf16x8*)(lds + PG8_SA(b, h) + aoff + m * 2048 + k * 1024); } while (0)
; #define PG8_LDB(dst, b, h) do { _Pragma("unroll") for (int n = 0; n < 2; ++n) _Pragma("unroll") for (int k = 0; k < 2; ++k) dst[n][k] = *(const PG8_LAS bf16x8*)(lds + PG8_SB(b, h) + boff + n * 2048 + k * 1024); } while (0)
; #define PG8_WAIT_V(n) asm volatile("s_waitcnt vmcnt(" #n ")" ::: "memory")
; #define PG8_WAIT_L(n) asm volatile("s_waitcnt lgkmcnt(" #n ")" ::: "memory")
; #define PG8_BAR __builtin_amdgcn_s_barrier()
; #define PG8_SCHED __builtin_amdgcn_sched_barrier(0)
; template <class Epi, class Sched, bool ALIGN_EPI = false, bool SP2 = false, bool I8 = false>
; __device__ __forceinline__ void gemm_phase(PG8_LAS unsigned char* lds, const Gemm g, const Sched& S, const Epi& E) {
;     ...
;             PG8_WAIT_V(8); PG8_WAIT_L(0); PG8_BAR; PG8_MMA(1, 0, At, B0); PG8_MMA(1, 1, At, B1); PG8_BAR; PG8_SCHED;
;             PG8_LDB(B0, 1, 0); PG8_LDB(B1, 1, 1); PG8_SCHED; PG8_LDA(At, 1, 0); PG8_STAGE(PG8_SA(0, 1), a2 + hstep, voffA);
;             PG8_WAIT_V(8); PG8_WAIT_L(0); PG8_BAR; PG8_MMA(0, 0, At, B0); PG8_MMA(0, 1, At, B1); PG8_BAR; PG8_SCHED;
;             PG8_LDA(At, 1, 1); PG8_STAGE(PG8_SB(1, 0), b3, voffB); PG8_STAGE(PG8_SB(1, 1), b3 + hstep, voffB); PG8_STAGE(PG8_SA(1, 0), a3, voffA);
	s_setprio 1
	s_waitcnt lgkmcnt(0)
	v_mfma_i32_16x16x64_i8 v[64:67], v[116:119], v[182:185], 0
	v_mfma_i32_16x16x64_i8 v[64:67], v[124:127], v[186:189], v[64:67]
	v_mfma_i32_16x16x64_i8 v[48:51], v[116:119], v[204:207], 0
	v_mfma_i32_16x16x64_i8 v[48:51], v[124:127], v[208:211], v[48:51]
	v_mfma_i32_16x16x64_i8 v[32:35], v[116:119], v[212:215], 0
	v_mfma_i32_16x16x64_i8 v[32:35], v[124:127], v[216:219], v[32:35]
	v_mfma_i32_16x16x64_i8 v[16:19], v[116:119], v[220:223], 0
	v_mfma_i32_16x16x64_i8 v[16:19], v[124:127], v[224:227], v[16:19]
	v_mfma_i32_16x16x64_i8 v[60:63], v[132:135], v[182:185], 0
	v_mfma_i32_16x16x64_i8 v[60:63], v[136:139], v[186:189], v[60:63]
	v_mfma_i32_16x16x64_i8 v[44:47], v[132:135], v[204:207], 0
	v_mfma_i32_16x16x64_i8 v[44:47], v[136:139], v[208:211], v[44:47]
	v_mfma_i32_16x16x64_i8 v[28:31], v[132:135], v[212:215], 0
	v_mfma_i32_16x16x64_i8 v[28:31], v[136:139], v[216:219], v[28:31]
	v_mfma_i32_16x16x64_i8 v[12:15], v[132:135], v[220:223], 0
	v_mfma_i32_16x16x64_i8 v[12:15], v[136:139], v[224:227], v[12:15]
	s_setprio 0
	s_setprio 1
	v_mfma_i32_16x16x64_i8 v[56:59], v[160:163], v[182:185], 0
	v_mfma_i32_16x16x64_i8 v[56:59], v[164:167], v[186:189], v[56:59]
	v_mfma_i32_16x16x64_i8 v[40:43], v[160:163], v[204:207], 0
	v_mfma_i32_16x16x64_i8 v[40:43], v[164:167], v[208:211], v[40:43]
	v_mfma_i32_16x16x64_i8 v[24:27], v[160:163], v[212:215], 0
	v_mfma_i32_16x16x64_i8 v[24:27], v[164:167], v[216:219], v[24:27]
	v_mfma_i32_16x16x64_i8 v[8:11], v[160:163], v[220:223], 0
	v_mfma_i32_16x16x64_i8 v[8:11], v[164:167], v[224:227], v[8:11]
	v_mfma_i32_16x16x64_i8 v[52:55], v[168:171], v[182:185], 0
	v_mfma_i32_16x16x64_i8 v[52:55], v[178:181], v[186:189], v[52:55]
	v_mfma_i32_16x16x64_i8 v[36:39], v[168:171], v[204:207], 0
	v_mfma_i32_16x16x64_i8 v[36:39], v[178:181], v[208:211], v[36:39]
	v_mfma_i32_16x16x64_i8 v[20:23], v[168:171], v[212:215], 0
	v_mfma_i32_16x16x64_i8 v[20:23], v[178:181], v[216:219], v[20:23]
	v_mfma_i32_16x16x64_i8 v[4:7], v[168:171], v[220:223], 0
	v_mfma_i32_16x16x64_i8 v[4:7], v[178:181], v[224:227], v[4:7]
	s_setprio 0
	s_barrier
	s_add_i32 s50, 0, 0x18000
	s_add_i32 s51, 0, 0x1c000
	v_add_u32_e32 v136, s50, v175
	v_add_u32_e32 v178, s51, v175
	ds_read_b128 v[116:119], v136
	ds_read_b128 v[124:127], v136 offset:1024
	ds_read_b128 v[132:135], v136 offset:2048
	ds_read_b128 v[136:139], v136 offset:3072
	ds_read_b128 v[160:163], v178
	ds_read_b128 v[164:167], v178 offset:1024
	ds_read_b128 v[168:171], v178 offset:2048
	ds_read_b128 v[178:181], v178 offset:3072
	s_add_u32 s40, s40, 0x80000
	s_addc_u32 s41, s41, 0
	s_mov_b32 m0, s46
	v_lshl_add_u64 v[242:243], s[40:41], 0, v[152:153]
	ds_read_b128 v[182:185], v177 offset:32768
	ds_read_b128 v[186:189], v177 offset:33792
	ds_read_b128 v[204:207], v177 offset:34816
	ds_read_b128 v[208:211], v177 offset:35840
	ds_read_b128 v[212:215], v177 offset:36864
	ds_read_b128 v[216:219], v177 offset:37888
	ds_read_b128 v[220:223], v177 offset:38912
	ds_read_b128 v[224:227], v177 offset:39936
	global_load_lds_dwordx4 v[242:243], off
	v_lshl_add_u64 v[242:243], s[40:41], 0, v[150:151]
	s_mov_b32 m0, s47
	s_nop 0
	global_load_lds_dwordx4 v[242:243], off
	s_waitcnt vmcnt(8)
	s_waitcnt lgkmcnt(0)
	s_barrier
	s_setprio 1
	s_waitcnt lgkmcnt(0)
	v_mfma_i32_16x16x64_i8 v[144:147], v[116:119], v[182:185], v[144:147]
	v_mfma_i32_16x16x64_i8 v[144:147], v[124:127], v[186:189], v[144:147]
	v_mfma_i32_16x16x64_i8 v[112:115], v[116:119], v[204:207], v[112:115]
	v_mfma_i32_16x16x64_i8 v[112:115], v[124:127], v[208:211], v[112:115]
	v_mfma_i32_16x16x64_i8 v[96:99], v[116:119], v[212:215], v[96:99]
	v_mfma_i32_16x16x64_i8 v[96:99], v[124:127], v[216:219], v[96:99]
	v_mfma_i32_16x16x64_i8 v[80:83], v[116:119], v[220:223], v[80:83]
	v_mfma_i32_16x16x64_i8 v[80:83], v[124:127], v[224:227], v[80:83]
	v_mfma_i32_16x16x64_i8 v[140:143], v[132:135], v[182:185], v[140:143]
	v_mfma_i32_16x16x64_i8 v[140:143], v[136:139], v[186:189], v[140:143]
	v_mfma_i32_16x16x64_i8 v[108:111], v[132:135], v[204:207], v[108:111]
	v_mfma_i32_16x16x64_i8 v[108:111], v[136:139], v[208:211], v[108:111]
	v_mfma_i32_16x16x64_i8 v[92:95], v[132:135], v[212:215], v[92:95]
	v_mfma_i32_16x16x64_i8 v[92:95], v[136:139], v[216:219], v[92:95]
	v_mfma_i32_16x16x64_i8 v[76:79], v[132:135], v[220:223], v[76:79]
	v_mfma_i32_16x16x64_i8 v[76:79], v[136:139], v[224:227], v[76:79]
	s_setprio 0
	s_setprio 1
	v_mfma_i32_16x16x64_i8 v[128:131], v[160:163], v[182:185], v[128:131]
	v_mfma_i32_16x16x64_i8 v[128:131], v[164:167], v[186:189], v[128:131]
	v_mfma_i32_16x16x64_i8 v[104:107], v[160:163], v[204:207], v[104:107]
	v_mfma_i32_16x16x64_i8 v[104:107], v[164:167], v[208:211], v[104:107]
	v_mfma_i32_16x16x64_i8 v[88:91], v[160:163], v[212:215], v[88:91]
	v_mfma_i32_16x16x64_i8 v[88:91], v[164:167], v[216:219], v[88:91]
	v_mfma_i32_16x16x64_i8 v[72:75], v[160:163], v[220:223], v[72:75]
	v_mfma_i32_16x16x64_i8 v[72:75], v[164:167], v[224:227], v[72:75]
	v_mfma_i32_16x16x64_i8 v[120:123], v[168:171], v[182:185], v[120:123]
	v_mfma_i32_16x16x64_i8 v[120:123], v[178:181], v[186:189], v[120:123]
	v_mfma_i32_16x16x64_i8 v[100:103], v[168:171], v[204:207], v[100:103]
	v_mfma_i32_16x16x64_i8 v[100:103], v[178:181], v[208:211], v[100:103]
	v_mfma_i32_16x16x64_i8 v[84:87], v[168:171], v[212:215], v[84:87]
	v_mfma_i32_16x16x64_i8 v[84:87], v[178:181], v[216:219], v[84:87]
	v_mfma_i32_16x16x64_i8 v[68:71], v[168:171], v[220:223], v[68:71]
	v_mfma_i32_16x16x64_i8 v[68:71], v[178:181], v[224:227], v[68:71]
	s_setprio 0
	s_barrier
; #define PG8_STAGE(bufoff, gbase, voff) do { _Pragma("unroll") for (int _i = 0; _i < 2; ++_i) \
;         __builtin_amdgcn_global_load_lds((const unsigned*)((const char*)(gbase) + (voff)[_i]), (PG8_LAS unsigned*)(lds + (bufoff) + ldsw + _i * 8192), 16, 0, 0); } while (0)
; #define PG8_LDA(dst, b, h) do { _Pragma("unroll") for (int m = 0; m < 4; ++m) _Pragma("unroll") for (int k = 0; k < 2; ++k) dst[m][k] = *(const PG8_LAS bf16x8*)(lds + PG8_SA(b, h) + aoff + m * 2048 + k * 1024); } while (0)
; #define PG8_LDB(dst, b, h) do { _Pragma("unroll") for (int n = 0; n < 2; ++n) _Pragma("unroll") for (int k = 0; k < 2; ++k) dst[n][k] = *(const PG8_LAS bf16x8*)(lds + PG8_SB(b, h) + boff + n * 2048 + k * 1024); } while (0)
; #define PG8_WAIT_V(n) asm volatile("s_waitcnt vmcnt(" #n ")" ::: "memory")
; #define PG8_WAIT_L(n) asm volatile("s_waitcnt lgkmcnt(" #n ")" ::: "memory")
; #define PG8_BAR __builtin_amdgcn_s_barrier()
; #define PG8_SCHED __builtin_amdgcn_sched_barrier(0)
; template <class Epi, class Sched, bool ALIGN_EPI = false, bool SP2 = false, bool I8 = false>
; __device__ __forceinline__ void gemm_phase(PG8_LAS unsigned char* lds, const Gemm g, const Sched& S, const Epi& E) {
;     ...
;         for (int t = 0; t < nt; t += 2) {
;             const bool last = (t == nt - 2);
;             const char* a1 = cA + (size_t)(t + 1) * kstep;
;             const char* a2 = last ? nA : cA + (size_t)(t + 2) * kstep; const char* b2 = last ? nB : cB + (size_t)(t + 2) * kstep;
;             const char* a3 = a2 + kstep; const char* b3 = b2 + kstep;
;             if (last && has_next) S.a_ready(nxt);
;             if constexpr (SP2) {
;             PG8_LDB(B0, 0, 0); PG8_LDB(B1, 0, 1); PG8_SCHED; PG8_LDA(At, 0, 0); PG8_STAGE(PG8_SA(1, 1), a1 + hstep, voffA);
;     ...
;             PG8_WAIT_V(8); PG8_WAIT_L(0); PG8_BAR; PG8_MMA(0, 0, At, B0); PG8_MMA(0, 1, At, B1); PG8_BAR; PG8_SCHED;
;             PG8_LDA(At, 1, 1); PG8_STAGE(PG8_SB(1, 0), b3, voffB); PG8_STAGE(PG8_SB(1, 1), b3 + hstep, voffB); PG8_STAGE(PG8_SA(1, 0), a3, voffA);
;             PG8_WAIT_V(8); PG8_WAIT_L(0); PG8_BAR; PG8_MMA(1, 0, At, B0); PG8_MMA(1, 1, At, B1); PG8_BAR; PG8_SCHED;
	s_add_i32 s40, s50, s43
	v_lshl_add_u64 v[172:173], v[172:173], 0, s[84:85]
	s_mov_b32 m0, s40
	ds_read_b128 v[182:185], v177 offset:49152
	ds_read_b128 v[186:189], v177 offset:50176
	ds_read_b128 v[204:207], v177 offset:51200
	ds_read_b128 v[208:211], v177 offset:52224
	ds_read_b128 v[212:215], v177 offset:53248
	ds_read_b128 v[216:219], v177 offset:54272
	ds_read_b128 v[220:223], v177 offset:55296
	ds_read_b128 v[224:227], v177 offset:56320
	global_load_lds_dwordx4 v[172:173], off
	s_add_i32 m0, s40, 0x2000
	s_add_u32 s36, s36, 0x80080
	v_lshl_add_u64 v[172:173], v[190:191], 0, s[84:85]
	s_addc_u32 s37, s37, 0
	s_add_i32 s40, s51, s43
	global_load_lds_dwordx4 v[172:173], off
	v_lshl_add_u64 v[172:173], s[36:37], 0, v[2:3]
	s_mov_b32 m0, s40
	s_nop 0
	global_load_lds_dwordx4 v[172:173], off
	v_lshl_add_u64 v[172:173], s[36:37], 0, v[148:149]
	s_add_i32 m0, s40, 0x2000
	s_nop 0
	global_load_lds_dwordx4 v[172:173], off
	v_lshl_add_u64 v[172:173], v[228:229], 0, s[84:85]
	s_mov_b32 m0, s52
	s_nop 0
	global_load_lds_dwordx4 v[172:173], off
	v_lshl_add_u64 v[172:173], v[240:241], 0, s[84:85]
	s_mov_b32 m0, s53
	s_nop 0
	global_load_lds_dwordx4 v[172:173], off
	s_waitcnt vmcnt(8)
	s_waitcnt lgkmcnt(0)
	s_barrier
	s_setprio 1
	s_waitcnt lgkmcnt(0)
	v_mfma_i32_16x16x64_i8 v[64:67], v[116:119], v[182:185], v[64:67]
	v_mfma_i32_16x16x64_i8 v[64:67], v[124:127], v[186:189], v[64:67]
	v_mfma_i32_16x16x64_i8 v[48:51], v[116:119], v[204:207], v[48:51]
	v_mfma_i32_16x16x64_i8 v[48:51], v[124:127], v[208:211], v[48:51]
	v_mfma_i32_16x16x64_i8 v[32:35], v[116:119], v[212:215], v[32:35]
	v_mfma_i32_16x16x64_i8 v[32:35], v[124:127], v[216:219], v[32:35]
	v_mfma_i32_16x16x64_i8 v[16:19], v[116:119], v[220:223], v[16:19]
	v_mfma_i32_16x16x64_i8 v[16:19], v[124:127], v[224:227], v[16:19]
	v_mfma_i32_16x16x64_i8 v[60:63], v[132:135], v[182:185], v[60:63]
	v_mfma_i32_16x16x64_i8 v[60:63], v[136:139], v[186:189], v[60:63]
	v_mfma_i32_16x16x64_i8 v[44:47], v[132:135], v[204:207], v[44:47]
	v_mfma_i32_16x16x64_i8 v[44:47], v[136:139], v[208:211], v[44:47]
	v_mfma_i32_16x16x64_i8 v[28:31], v[132:135], v[212:215], v[28:31]
	v_mfma_i32_16x16x64_i8 v[28:31], v[136:139], v[216:219], v[28:31]
	v_mfma_i32_16x16x64_i8 v[12:15], v[132:135], v[220:223], v[12:15]
	v_mfma_i32_16x16x64_i8 v[12:15], v[136:139], v[224:227], v[12:15]
	s_setprio 0
	s_setprio 1
	v_mfma_i32_16x16x64_i8 v[56:59], v[160:163], v[182:185], v[56:59]
	v_mfma_i32_16x16x64_i8 v[56:59], v[164:167], v[186:189], v[56:59]
	v_mfma_i32_16x16x64_i8 v[40:43], v[160:163], v[204:207], v[40:43]
	v_mfma_i32_16x16x64_i8 v[40:43], v[164:167], v[208:211], v[40:43]
	v_mfma_i32_16x16x64_i8 v[24:27], v[160:163], v[212:215], v[24:27]
	v_mfma_i32_16x16x64_i8 v[24:27], v[164:167], v[216:219], v[24:27]
	v_mfma_i32_16x16x64_i8 v[8:11], v[160:163], v[220:223], v[8:11]
	v_mfma_i32_16x16x64_i8 v[8:11], v[164:167], v[224:227], v[8:11]
	v_mfma_i32_16x16x64_i8 v[52:55], v[168:171], v[182:185], v[52:55]
	v_mfma_i32_16x16x64_i8 v[52:55], v[178:181], v[186:189], v[52:55]
	v_mfma_i32_16x16x64_i8 v[36:39], v[168:171], v[204:207], v[36:39]
	v_mfma_i32_16x16x64_i8 v[36:39], v[178:181], v[208:211], v[36:39]
	v_mfma_i32_16x16x64_i8 v[20:23], v[168:171], v[212:215], v[20:23]
	v_mfma_i32_16x16x64_i8 v[20:23], v[178:181], v[216:219], v[20:23]
	v_mfma_i32_16x16x64_i8 v[4:7], v[168:171], v[220:223], v[4:7]
	v_mfma_i32_16x16x64_i8 v[4:7], v[178:181], v[224:227], v[4:7]
	s_setprio 0
	s_barrier
	s_add_i32 s76, s76, 2
	s_add_u32 s26, s26, 0x100
	s_addc_u32 s27, s27, 0
	s_add_u32 s72, s72, 0x100
	s_addc_u32 s73, s73, 0
	s_cmp_gt_u32 s76, 29
	s_cbranch_scc1 .Lkloop_exit_0
.LBB0_208:
	s_add_u32 s36, s26, 0xfff80080
	s_addc_u32 s37, s27, -1
	s_add_i32 s50, 0, 0x10000
	s_cmp_eq_u32 s76, 28
	s_cselect_b32 s41, s19, s37
	s_cselect_b32 s40, s64, s36
	s_cselect_b32 s37, s17, s73
	s_cselect_b32 s36, s65, s72
	s_add_i32 s56, 0, 0x14000
	v_add_u32_e32 v136, s50, v175
	v_add_u32_e32 v172, s56, v175
	ds_read_b128 v[116:119], v136
	ds_read_b128 v[124:127], v136 offset:1024
	ds_read_b128 v[132:135], v136 offset:2048
	ds_read_b128 v[136:139], v136 offset:3072
	ds_read_b128 v[160:163], v172
	ds_read_b128 v[164:167], v172 offset:1024
	ds_read_b128 v[168:171], v172 offset:2048
	ds_read_b128 v[178:181], v172 offset:3072
	v_lshl_add_u64 v[172:173], s[26:27], 0, v[156:157]
	s_add_i32 m0, s44, 0xc000
	ds_read_b128 v[182:185], v177
	ds_read_b128 v[186:189], v177 offset:1024
	ds_read_b128 v[204:207], v177 offset:2048
	ds_read_b128 v[208:211], v177 offset:3072
	ds_read_b128 v[212:215], v177 offset:4096
	ds_read_b128 v[216:219], v177 offset:5120
	ds_read_b128 v[220:223], v177 offset:6144
	ds_read_b128 v[224:227], v177 offset:7168
	global_load_lds_dwordx4 v[172:173], off
	v_lshl_add_u64 v[172:173], s[26:27], 0, v[158:159]
	s_add_i32 m0, s44, 0xe000
	s_nop 0
	global_load_lds_dwordx4 v[172:173], off
	s_waitcnt vmcnt(8)
	s_waitcnt lgkmcnt(0)
	s_barrier
; #define PG8_STAGE(bufoff, gbase, voff) do { _Pragma("unroll") for (int _i = 0; _i < 2; ++_i) \
;         __builtin_amdgcn_global_load_lds((const unsigned*)((const char*)(gbase) + (voff)[_i]), (PG8_LAS unsigned*)(lds + (bufoff) + ldsw + _i * 8192), 16, 0, 0); } while (0)
; #define PG8_LDA(dst, b, h) do { _Pragma("unroll") for (int m = 0; m < 4; ++m) _Pragma("unroll") for (int k = 0; k < 2; ++k) dst[m][k] = *(const PG8_LAS bf16x8*)(lds + PG8_SA(b, h) + aoff + m * 2048 + k * 1024); } while (0)
; #define PG8_LDB(dst, b, h) do { _Pragma("unroll") for (int n = 0; n < 2; ++n) _Pragma("unroll") for (int k = 0; k < 2; ++k) dst[n][k] = *(const PG8_LAS bf16x8*)(lds + PG8_SB(b, h) + boff + n * 2048 + k * 1024); } while (0)
; #define PG8_WAIT_V(n) asm volatile("s_waitcnt vmcnt(" #n ")" ::: "memory")
; #define PG8_WAIT_L(n) asm volatile("s_waitcnt lgkmcnt(" #n ")" ::: "memory")
; #define PG8_BAR __builtin_amdgcn_s_barrier()
; #define PG8_SCHED __builtin_amdgcn_sched_barrier(0)
; template <class Epi, class Sched, bool ALIGN_EPI = false, bool SP2 = false, bool I8 = false>
; __device__ __forceinline__ void gemm_phase(PG8_LAS unsigned char* lds, const Gemm g, const Sched& S, const Epi& E) {
;     ...
;             PG8_LDB(B0, 0, 0); PG8_LDB(B1, 0, 1); PG8_SCHED; PG8_LDA(At, 0, 0); PG8_STAGE(PG8_SA(1, 1), a1 + hstep, voffA);
;             PG8_WAIT_V(8); PG8_WAIT_L(0); PG8_BAR; PG8_MMA(0, 0, At, B0); PG8_MMA(0, 1, At, B1); PG8_BAR; PG8_SCHED;
;             PG8_LDA(At, 0, 1); PG8_STAGE(PG8_SB(0, 0), b2, voffB); PG8_STAGE(PG8_SB(0, 1), b2 + hstep, voffB); PG8_STAGE(PG8_SA(0, 0), a2, voffA);
;             PG8_WAIT_V(8); PG8_WAIT_L(0); PG8_BAR; PG8_MMA(1, 0, At, B0); PG8_MMA(1, 1, At, B1); PG8_BAR; PG8_SCHED;
	s_setprio 1
	s_waitcnt lgkmcnt(0)
	v_mfma_i32_16x16x64_i8 v[144:147], v[116:119], v[182:185], v[144:147]
	v_mfma_i32_16x16x64_i8 v[144:147], v[124:127], v[186:189], v[144:147]
	v_mfma_i32_16x16x64_i8 v[112:115], v[116:119], v[204:207], v[112:115]
	v_mfma_i32_16x16x64_i8 v[112:115], v[124:127], v[208:211], v[112:115]
	v_mfma_i32_16x16x64_i8 v[96:99], v[116:119], v[212:215], v[96:99]
	v_mfma_i32_16x16x64_i8 v[96:99], v[124:127], v[216:219], v[96:99]
	v_mfma_i32_16x16x64_i8 v[80:83], v[116:119], v[220:223], v[80:83]
	v_mfma_i32_16x16x64_i8 v[80:83], v[124:127], v[224:227], v[80:83]
	v_mfma_i32_16x16x64_i8 v[140:143], v[132:135], v[182:185], v[140:143]
	v_mfma_i32_16x16x64_i8 v[140:143], v[136:139], v[186:189], v[140:143]
	v_mfma_i32_16x16x64_i8 v[108:111], v[132:135], v[204:207], v[108:111]
	v_mfma_i32_16x16x64_i8 v[108:111], v[136:139], v[208:211], v[108:111]
	v_mfma_i32_16x16x64_i8 v[92:95], v[132:135], v[212:215], v[92:95]
	v_mfma_i32_16x16x64_i8 v[92:95], v[136:139], v[216:219], v[92:95]
	v_mfma_i32_16x16x64_i8 v[76:79], v[132:135], v[220:223], v[76:79]
	v_mfma_i32_16x16x64_i8 v[76:79], v[136:139], v[224:227], v[76:79]
	s_setprio 0
	s_setprio 1
	v_mfma_i32_16x16x64_i8 v[128:131], v[160:163], v[182:185], v[128:131]
	v_mfma_i32_16x16x64_i8 v[128:131], v[164:167], v[186:189], v[128:131]
	v_mfma_i32_16x16x64_i8 v[104:107], v[160:163], v[204:207], v[104:107]
	v_mfma_i32_16x16x64_i8 v[104:107], v[164:167], v[208:211], v[104:107]
	v_mfma_i32_16x16x64_i8 v[88:91], v[160:163], v[212:215], v[88:91]
	v_mfma_i32_16x16x64_i8 v[88:91], v[164:167], v[216:219], v[88:91]
	v_mfma_i32_16x16x64_i8 v[72:75], v[160:163], v[220:223], v[72:75]
	v_mfma_i32_16x16x64_i8 v[72:75], v[164:167], v[224:227], v[72:75]
	v_mfma_i32_16x16x64_i8 v[120:123], v[168:171], v[182:185], v[120:123]
	v_mfma_i32_16x16x64_i8 v[120:123], v[178:181], v[186:189], v[120:123]
	v_mfma_i32_16x16x64_i8 v[100:103], v[168:171], v[204:207], v[100:103]
	v_mfma_i32_16x16x64_i8 v[100:103], v[178:181], v[208:211], v[100:103]
	v_mfma_i32_16x16x64_i8 v[84:87], v[168:171], v[212:215], v[84:87]
	v_mfma_i32_16x16x64_i8 v[84:87], v[178:181], v[216:219], v[84:87]
	v_mfma_i32_16x16x64_i8 v[68:71], v[168:171], v[220:223], v[68:71]
	v_mfma_i32_16x16x64_i8 v[68:71], v[178:181], v[224:227], v[68:71]
	s_setprio 0
	s_barrier
	s_add_i32 s50, s50, s43
	v_lshl_add_u64 v[172:173], s[36:37], 0, v[2:3]
	s_mov_b32 m0, s50
	ds_read_b128 v[182:185], v177 offset:16384
	ds_read_b128 v[186:189], v177 offset:17408
	ds_read_b128 v[204:207], v177 offset:18432
	ds_read_b128 v[208:211], v177 offset:19456
	ds_read_b128 v[212:215], v177 offset:20480
	ds_read_b128 v[216:219], v177 offset:21504
	ds_read_b128 v[220:223], v177 offset:22528
	ds_read_b128 v[224:227], v177 offset:23552
	global_load_lds_dwordx4 v[172:173], off
	s_add_i32 m0, s50, 0x2000
	s_add_u32 s50, s36, 0x80000
	v_lshl_add_u64 v[190:191], s[36:37], 0, v[148:149]
	s_addc_u32 s51, s37, 0
	s_add_i32 s56, s56, s43
	global_load_lds_dwordx4 v[190:191], off
	v_lshl_add_u64 v[228:229], s[50:51], 0, v[2:3]
	s_mov_b32 m0, s56
	v_lshl_add_u64 v[240:241], s[40:41], 0, v[150:151]
	global_load_lds_dwordx4 v[228:229], off
	v_lshl_add_u64 v[228:229], s[50:51], 0, v[148:149]
	s_add_i32 m0, s56, 0x2000
	s_nop 0
	global_load_lds_dwordx4 v[228:229], off
	v_lshl_add_u64 v[228:229], s[40:41], 0, v[152:153]
	s_mov_b32 m0, s44
	s_nop 0
	global_load_lds_dwordx4 v[228:229], off
	s_mov_b32 m0, s45
	s_nop 0
	global_load_lds_dwordx4 v[240:241], off
	s_waitcnt vmcnt(8)
	s_waitcnt lgkmcnt(0)
	s_barrier
	s_setprio 1
	s_waitcnt lgkmcnt(0)
	v_mfma_i32_16x16x64_i8 v[64:67], v[116:119], v[182:185], v[64:67]
	v_mfma_i32_16x16x64_i8 v[64:67], v[124:127], v[186:189], v[64:67]
	v_mfma_i32_16x16x64_i8 v[48:51], v[116:119], v[204:207], v[48:51]
	v_mfma_i32_16x16x64_i8 v[48:51], v[124:127], v[208:211], v[48:51]
	v_mfma_i32_16x16x64_i8 v[32:35], v[116:119], v[212:215], v[32:35]
	v_mfma_i32_16x16x64_i8 v[32:35], v[124:127], v[216:219], v[32:35]
	v_mfma_i32_16x16x64_i8 v[16:19], v[116:119], v[220:223], v[16:19]
	v_mfma_i32_16x16x64_i8 v[16:19], v[124:127], v[224:227], v[16:19]
	v_mfma_i32_16x16x64_i8 v[60:63], v[132:135], v[182:185], v[60:63]
	v_mfma_i32_16x16x64_i8 v[60:63], v[136:139], v[186:189], v[60:63]
	v_mfma_i32_16x16x64_i8 v[44:47], v[132:135], v[204:207], v[44:47]
	v_mfma_i32_16x16x64_i8 v[44:47], v[136:139], v[208:211], v[44:47]
	v_mfma_i32_16x16x64_i8 v[28:31], v[132:135], v[212:215], v[28:31]
	v_mfma_i32_16x16x64_i8 v[28:31], v[136:139], v[216:219], v[28:31]
	v_mfma_i32_16x16x64_i8 v[12:15], v[132:135], v[220:223], v[12:15]
	v_mfma_i32_16x16x64_i8 v[12:15], v[136:139], v[224:227], v[12:15]
	s_setprio 0
	s_setprio 1
	v_mfma_i32_16x16x64_i8 v[56:59], v[160:163], v[182:185], v[56:59]
	v_mfma_i32_16x16x64_i8 v[56:59], v[164:167], v[186:189], v[56:59]
	v_mfma_i32_16x16x64_i8 v[40:43], v[160:163], v[204:207], v[40:43]
	v_mfma_i32_16x16x64_i8 v[40:43], v[164:167], v[208:211], v[40:43]
	v_mfma_i32_16x16x64_i8 v[24:27], v[160:163], v[212:215], v[24:27]
	v_mfma_i32_16x16x64_i8 v[24:27], v[164:167], v[216:219], v[24:27]
	v_mfma_i32_16x16x64_i8 v[8:11], v[160:163], v[220:223], v[8:11]
	v_mfma_i32_16x16x64_i8 v[8:11], v[164:167], v[224:227], v[8:11]
	v_mfma_i32_16x16x64_i8 v[52:55], v[168:171], v[182:185], v[52:55]
	v_mfma_i32_16x16x64_i8 v[52:55], v[178:181], v[186:189], v[52:55]
	v_mfma_i32_16x16x64_i8 v[36:39], v[168:171], v[204:207], v[36:39]
	v_mfma_i32_16x16x64_i8 v[36:39], v[178:181], v[208:211], v[36:39]
	v_mfma_i32_16x16x64_i8 v[20:23], v[168:171], v[212:215], v[20:23]
	v_mfma_i32_16x16x64_i8 v[20:23], v[178:181], v[216:219], v[20:23]
	v_mfma_i32_16x16x64_i8 v[4:7], v[168:171], v[220:223], v[4:7]
	v_mfma_i32_16x16x64_i8 v[4:7], v[178:181], v[224:227], v[4:7]
	s_setprio 0
	s_barrier
; #define PG8_STAGE(bufoff, gbase, voff) do { _Pragma("unroll") for (int _i = 0; _i < 2; ++_i) \
;         __builtin_amdgcn_global_load_lds((const unsigned*)((const char*)(gbase) + (voff)[_i]), (PG8_LAS unsigned*)(lds + (bufoff) + ldsw + _i * 8192), 16, 0, 0); } while (0)
; #define PG8_LDA(dst, b, h) do { _Pragma("unroll") for (int m = 0; m < 4; ++m) _Pragma("unroll") for (int k = 0; k < 2; ++k) dst[m][k] = *(const PG8_LAS bf16x8*)(lds + PG8_SA(b, h) + aoff + m * 2048 + k * 1024); } while (0)
; #define PG8_LDB(dst, b, h) do { _Pragma("unroll") for (int n = 0; n < 2; ++n) _Pragma("unroll") for (int k = 0; k < 2; ++k) dst[n][k] = *(const PG8_LAS bf16x8*)(lds + PG8_SB(b, h) + boff + n * 2048 + k * 1024); } while (0)
; #define PG8_WAIT_V(n) asm volatile("s_waitcnt vmcnt(" #n ")" ::: "memory")
; #define PG8_WAIT_L(n) asm volatile("s_waitcnt lgkmcnt(" #n ")" ::: "memory")
; #define PG8_BAR __builtin_amdgcn_s_barrier()
; #define PG8_SCHED __builtin_amdgcn_sched_barrier(0)
; template <class Epi, class Sched, bool ALIGN_EPI = false, bool SP2 = false, bool I8 = false>
; __device__ __forceinline__ void gemm_phase(PG8_LAS unsigned char* lds, const Gemm g, const Sched& S, const Epi& E) {
;     ...
;         for (int t = 0; t < nt; t += 2) {
;     ...
;             PG8_LDB(B0, 1, 0); PG8_LDB(B1, 1, 1); PG8_SCHED; PG8_LDA(At, 1, 0); PG8_STAGE(PG8_SA(0, 1), a2 + hstep, voffA);
;             PG8_WAIT_V(8); PG8_WAIT_L(0); PG8_BAR; PG8_MMA(0, 0, At, B0); PG8_MMA(0, 1, At, B1); PG8_BAR; PG8_SCHED;
;             PG8_LDA(At, 1, 1); PG8_STAGE(PG8_SB(1, 0), b3, voffB); PG8_STAGE(PG8_SB(1, 1), b3 + hstep, voffB); PG8_STAGE(PG8_SA(1, 0), a3, voffA);
;             PG8_WAIT_V(8); PG8_WAIT_L(0); PG8_BAR; PG8_MMA(1, 0, At, B0); PG8_MMA(1, 1, At, B1); PG8_BAR; PG8_SCHED;
	s_add_i32 s50, 0, 0x18000
	s_add_i32 s51, 0, 0x1c000
	v_add_u32_e32 v136, s50, v175
	v_add_u32_e32 v178, s51, v175
	ds_read_b128 v[116:119], v136
	ds_read_b128 v[124:127], v136 offset:1024
	ds_read_b128 v[132:135], v136 offset:2048
	ds_read_b128 v[136:139], v136 offset:3072
	ds_read_b128 v[160:163], v178
	ds_read_b128 v[164:167], v178 offset:1024
	ds_read_b128 v[168:171], v178 offset:2048
	ds_read_b128 v[178:181], v178 offset:3072
	s_add_u32 s40, s40, 0x80000
	s_addc_u32 s41, s41, 0
	s_mov_b32 m0, s46
	v_lshl_add_u64 v[242:243], s[40:41], 0, v[152:153]
	ds_read_b128 v[182:185], v177 offset:32768
	ds_read_b128 v[186:189], v177 offset:33792
	ds_read_b128 v[204:207], v177 offset:34816
	ds_read_b128 v[208:211], v177 offset:35840
	ds_read_b128 v[212:215], v177 offset:36864
	ds_read_b128 v[216:219], v177 offset:37888
	ds_read_b128 v[220:223], v177 offset:38912
	ds_read_b128 v[224:227], v177 offset:39936
	global_load_lds_dwordx4 v[242:243], off
	v_lshl_add_u64 v[242:243], s[40:41], 0, v[150:151]
	s_mov_b32 m0, s47
	s_nop 0
	global_load_lds_dwordx4 v[242:243], off
	s_waitcnt vmcnt(8)
	s_waitcnt lgkmcnt(0)
	s_barrier
	s_setprio 1
	s_waitcnt lgkmcnt(0)
	v_mfma_i32_16x16x64_i8 v[144:147], v[116:119], v[182:185], v[144:147]
	v_mfma_i32_16x16x64_i8 v[144:147], v[124:127], v[186:189], v[144:147]
	v_mfma_i32_16x16x64_i8 v[112:115], v[116:119], v[204:207], v[112:115]
	v_mfma_i32_16x16x64_i8 v[112:115], v[124:127], v[208:211], v[112:115]
	v_mfma_i32_16x16x64_i8 v[96:99], v[116:119], v[212:215], v[96:99]
	v_mfma_i32_16x16x64_i8 v[96:99], v[124:127], v[216:219], v[96:99]
	v_mfma_i32_16x16x64_i8 v[80:83], v[116:119], v[220:223], v[80:83]
	v_mfma_i32_16x16x64_i8 v[80:83], v[124:127], v[224:227], v[80:83]
	v_mfma_i32_16x16x64_i8 v[140:143], v[132:135], v[182:185], v[140:143]
	v_mfma_i32_16x16x64_i8 v[140:143], v[136:139], v[186:189], v[140:143]
	v_mfma_i32_16x16x64_i8 v[108:111], v[132:135], v[204:207], v[108:111]
	v_mfma_i32_16x16x64_i8 v[108:111], v[136:139], v[208:211], v[108:111]
	v_mfma_i32_16x16x64_i8 v[92:95], v[132:135], v[212:215], v[92:95]
	v_mfma_i32_16x16x64_i8 v[92:95], v[136:139], v[216:219], v[92:95]
	v_mfma_i32_16x16x64_i8 v[76:79], v[132:135], v[220:223], v[76:79]
	v_mfma_i32_16x16x64_i8 v[76:79], v[136:139], v[224:227], v[76:79]
	s_setprio 0
	s_setprio 1
	v_mfma_i32_16x16x64_i8 v[128:131], v[160:163], v[182:185], v[128:131]
	v_mfma_i32_16x16x64_i8 v[128:131], v[164:167], v[186:189], v[128:131]
	v_mfma_i32_16x16x64_i8 v[104:107], v[160:163], v[204:207], v[104:107]
	v_mfma_i32_16x16x64_i8 v[104:107], v[164:167], v[208:211], v[104:107]
	v_mfma_i32_16x16x64_i8 v[88:91], v[160:163], v[212:215], v[88:91]
	v_mfma_i32_16x16x64_i8 v[88:91], v[164:167], v[216:219], v[88:91]
	v_mfma_i32_16x16x64_i8 v[72:75], v[160:163], v[220:223], v[72:75]
	v_mfma_i32_16x16x64_i8 v[72:75], v[164:167], v[224:227], v[72:75]
	v_mfma_i32_16x16x64_i8 v[120:123], v[168:171], v[182:185], v[120:123]
	v_mfma_i32_16x16x64_i8 v[120:123], v[178:181], v[186:189], v[120:123]
	v_mfma_i32_16x16x64_i8 v[100:103], v[168:171], v[204:207], v[100:103]
	v_mfma_i32_16x16x64_i8 v[100:103], v[178:181], v[208:211], v[100:103]
	v_mfma_i32_16x16x64_i8 v[84:87], v[168:171], v[212:215], v[84:87]
	v_mfma_i32_16x16x64_i8 v[84:87], v[178:181], v[216:219], v[84:87]
	v_mfma_i32_16x16x64_i8 v[68:71], v[168:171], v[220:223], v[68:71]
	v_mfma_i32_16x16x64_i8 v[68:71], v[178:181], v[224:227], v[68:71]
	s_setprio 0
	s_barrier
	s_add_i32 s40, s50, s43
	v_lshl_add_u64 v[172:173], v[172:173], 0, s[84:85]
	s_mov_b32 m0, s40
	ds_read_b128 v[182:185], v177 offset:49152
	ds_read_b128 v[186:189], v177 offset:50176
	ds_read_b128 v[204:207], v177 offset:51200
	ds_read_b128 v[208:211], v177 offset:52224
	ds_read_b128 v[212:215], v177 offset:53248
	ds_read_b128 v[216:219], v177 offset:54272
	ds_read_b128 v[220:223], v177 offset:55296
	ds_read_b128 v[224:227], v177 offset:56320
	global_load_lds_dwordx4 v[172:173], off
	s_add_i32 m0, s40, 0x2000
	s_add_u32 s36, s36, 0x80080
	v_lshl_add_u64 v[172:173], v[190:191], 0, s[84:85]
	s_addc_u32 s37, s37, 0
	s_add_i32 s40, s51, s43
	global_load_lds_dwordx4 v[172:173], off
	v_lshl_add_u64 v[172:173], s[36:37], 0, v[2:3]
	s_mov_b32 m0, s40
	s_nop 0
	global_load_lds_dwordx4 v[172:173], off
	v_lshl_add_u64 v[172:173], s[36:37], 0, v[148:149]
	s_add_i32 m0, s40, 0x2000
	s_nop 0
	global_load_lds_dwordx4 v[172:173], off
	v_lshl_add_u64 v[172:173], v[228:229], 0, s[84:85]
	s_mov_b32 m0, s52
	s_nop 0
	global_load_lds_dwordx4 v[172:173], off
	v_lshl_add_u64 v[172:173], v[240:241], 0, s[84:85]
	s_mov_b32 m0, s53
	s_nop 0
	global_load_lds_dwordx4 v[172:173], off
	s_waitcnt vmcnt(8)
	s_waitcnt lgkmcnt(0)
	s_barrier
	s_setprio 1
	s_waitcnt lgkmcnt(0)
	v_mfma_i32_16x16x64_i8 v[64:67], v[116:119], v[182:185], v[64:67]
	v_mfma_i32_16x16x64_i8 v[64:67], v[124:127], v[186:189], v[64:67]
	v_mfma_i32_16x16x64_i8 v[48:51], v[116:119], v[204:207], v[48:51]
	v_mfma_i32_16x16x64_i8 v[48:51], v[124:127], v[208:211], v[48:51]
	v_mfma_i32_16x16x64_i8 v[32:35], v[116:119], v[212:215], v[32:35]
	v_mfma_i32_16x16x64_i8 v[32:35], v[124:127], v[216:219], v[32:35]
	v_mfma_i32_16x16x64_i8 v[16:19], v[116:119], v[220:223], v[16:19]
	v_mfma_i32_16x16x64_i8 v[16:19], v[124:127], v[224:227], v[16:19]
	v_mfma_i32_16x16x64_i8 v[60:63], v[132:135], v[182:185], v[60:63]
	v_mfma_i32_16x16x64_i8 v[60:63], v[136:139], v[186:189], v[60:63]
	v_mfma_i32_16x16x64_i8 v[44:47], v[132:135], v[204:207], v[44:47]
	v_mfma_i32_16x16x64_i8 v[44:47], v[136:139], v[208:211], v[44:47]
	v_mfma_i32_16x16x64_i8 v[28:31], v[132:135], v[212:215], v[28:31]
	v_mfma_i32_16x16x64_i8 v[28:31], v[136:139], v[216:219], v[28:31]
	v_mfma_i32_16x16x64_i8 v[12:15], v[132:135], v[220:223], v[12:15]
	v_mfma_i32_16x16x64_i8 v[12:15], v[136:139], v[224:227], v[12:15]
	s_setprio 0
	s_setprio 1
	v_mfma_i32_16x16x64_i8 v[56:59], v[160:163], v[182:185], v[56:59]
	v_mfma_i32_16x16x64_i8 v[56:59], v[164:167], v[186:189], v[56:59]
	v_mfma_i32_16x16x64_i8 v[40:43], v[160:163], v[204:207], v[40:43]
	v_mfma_i32_16x16x64_i8 v[40:43], v[164:167], v[208:211], v[40:43]
	v_mfma_i32_16x16x64_i8 v[24:27], v[160:163], v[212:215], v[24:27]
	v_mfma_i32_16x16x64_i8 v[24:27], v[164:167], v[216:219], v[24:27]
	v_mfma_i32_16x16x64_i8 v[8:11], v[160:163], v[220:223], v[8:11]
	v_mfma_i32_16x16x64_i8 v[8:11], v[164:167], v[224:227], v[8:11]
	v_mfma_i32_16x16x64_i8 v[52:55], v[168:171], v[182:185], v[52:55]
	v_mfma_i32_16x16x64_i8 v[52:55], v[178:181], v[186:189], v[52:55]
	v_mfma_i32_16x16x64_i8 v[36:39], v[168:171], v[204:207], v[36:39]
	v_mfma_i32_16x16x64_i8 v[36:39], v[178:181], v[208:211], v[36:39]
	v_mfma_i32_16x16x64_i8 v[20:23], v[168:171], v[212:215], v[20:23]
	v_mfma_i32_16x16x64_i8 v[20:23], v[178:181], v[216:219], v[20:23]
	v_mfma_i32_16x16x64_i8 v[4:7], v[168:171], v[220:223], v[4:7]
	v_mfma_i32_16x16x64_i8 v[4:7], v[178:181], v[224:227], v[4:7]
	s_setprio 0
	s_barrier
	s_add_i32 s76, s76, 2
	s_add_u32 s26, s26, 0x100
	s_addc_u32 s27, s27, 0
	s_add_u32 s72, s72, 0x100
	s_addc_u32 s73, s73, 0
	s_cmp_gt_u32 s76, 29
	s_cbranch_scc0 .LBB0_208

; #define PG8_STAGE(bufoff, gbase, voff) do { _Pragma("unroll") for (int _i = 0; _i < 2; ++_i) \
;         __builtin_amdgcn_global_load_lds((const unsigned*)((const char*)(gbase) + (voff)[_i]), (PG8_LAS unsigned*)(lds + (bufoff) + ldsw + _i * 8192), 16, 0, 0); } while (0)
; #define PG8_LDA(dst, b, h) do { _Pragma("unroll") for (int m = 0; m < 4; ++m) _Pragma("unroll") for (int k = 0; k < 2; ++k) dst[m][k] = *(const PG8_LAS bf16x8*)(lds + PG8_SA(b, h) + aoff + m * 2048 + k * 1024); } while (0)
; #define PG8_LDB(dst, b, h) do { _Pragma("unroll") for (int n = 0; n < 2; ++n) _Pragma("unroll") for (int k = 0; k < 2; ++k) dst[n][k] = *(const PG8_LAS bf16x8*)(lds + PG8_SB(b, h) + boff + n * 2048 + k * 1024); } while (0)
; #define PG8_WAIT_V(n) asm volatile("s_waitcnt vmcnt(" #n ")" ::: "memory")
; #define PG8_WAIT_L(n) asm volatile("s_waitcnt lgkmcnt(" #n ")" ::: "memory")
; #define PG8_BAR __builtin_amdgcn_s_barrier()
; #define PG8_SCHED __builtin_amdgcn_sched_barrier(0)
; template <class Epi, class Sched, bool ALIGN_EPI = false, bool SP2 = false, bool I8 = false>
; __device__ __forceinline__ void gemm_phase(PG8_LAS unsigned char* lds, const Gemm g, const Sched& S, const Epi& E) {
;     ...
;         const bool has_next = S.next(ui + 1, nxt);
;         const char* nA = has_next ? (const char*)g.A + (size_t)nxt.pm * tstep : cA; const char* nB = has_next ? (const char*)g.Bt + (size_t)nxt.pn * tstep : cB;
;         for (int t = 0; t < nt; t += 2) {
;             const bool last = (t == nt - 2);
;             const char* a1 = cA + (size_t)(t + 1) * kstep;
;             const char* a2 = last ? nA : cA + (size_t)(t + 2) * kstep; const char* b2 = last ? nB : cB + (size_t)(t + 2) * kstep;
;             const char* a3 = a2 + kstep; const char* b3 = b2 + kstep;
;             if (last && has_next) S.a_ready(nxt);
;             if constexpr (SP2) {
;             PG8_LDB(B0, 0, 0); PG8_LDB(B1, 0, 1); PG8_SCHED; PG8_LDA(At, 0, 0); PG8_STAGE(PG8_SA(1, 1), a1 + hstep, voffA);
;             PG8_WAIT_V(8); PG8_WAIT_L(0); PG8_BAR; PG8_MMA(0, 0, At, B0); PG8_MMA(0, 1, At, B1); PG8_BAR; PG8_SCHED;
;             PG8_LDA(At, 0, 1); PG8_STAGE(PG8_SB(0, 0), b2, voffB); PG8_STAGE(PG8_SB(0, 1), b2 + hstep, voffB); PG8_STAGE(PG8_SA(0, 0), a2, voffA);
;             PG8_WAIT_V(8); PG8_WAIT_L(0); PG8_BAR; PG8_MMA(1, 0, At, B0); PG8_MMA(1, 1, At, B1); PG8_BAR; PG8_SCHED;
.LBB0_229:
	s_ashr_i32 s37, s36, 31
	s_lshl_b64 s[34:35], s[36:37], 21
	s_add_u32 s40, s42, s34
	s_addc_u32 s41, s43, s35
	s_and_b64 s[34:35], s[8:9], exec
	s_cselect_b32 s11, s41, s13
	s_cselect_b32 s34, s40, s12
	s_ashr_i32 s27, s26, 31
	s_lshl_b64 s[50:51], s[26:27], 21
	s_add_u32 s54, s44, s50
	s_addc_u32 s55, s45, s51
	s_and_b64 s[50:51], s[8:9], exec
	s_cselect_b32 s27, s55, s73
	s_cselect_b32 s35, s54, s72
	s_add_u32 s12, s12, 0x100080
	s_addc_u32 s13, s13, 0
	s_add_u32 s37, s72, 0x100
	s_addc_u32 s61, s73, 0
	s_mov_b32 s97, -2
	s_add_u32 s50, s12, 0xfff00080
	s_addc_u32 s51, s13, -1
	s_add_i32 s56, 0, 0x10000
	s_cmp_eq_u32 s97, 60
	s_cselect_b32 s77, s11, s51
	s_cselect_b32 s76, s34, s50
	s_cselect_b32 s73, s27, s61
	s_cselect_b32 s72, s35, s37
	s_add_i32 s57, 0, 0x14000
	v_add_u32_e32 v156, s56, v171
	v_add_u32_e32 v168, s57, v171
	s_waitcnt vmcnt(0)
	ds_read_b128 v[112:115], v156
	ds_read_b128 v[120:123], v156 offset:1024
	ds_read_b128 v[152:155], v156 offset:2048
	ds_read_b128 v[156:159], v156 offset:3072
	ds_read_b128 v[160:163], v168
	ds_read_b128 v[164:167], v168 offset:1024
	s_waitcnt lgkmcnt(0)
	ds_read_b128 v[176:179], v168 offset:2048
	ds_read_b128 v[180:183], v168 offset:3072
	v_lshl_add_u64 v[168:169], s[12:13], 0, v[148:149]
	s_add_i32 m0, s47, 0xc000
	ds_read_b128 v[184:187], v173
	ds_read_b128 v[188:191], v173 offset:1024
	ds_read_b128 v[204:207], v173 offset:2048
	ds_read_b128 v[208:211], v173 offset:3072
	ds_read_b128 v[212:215], v173 offset:4096
	ds_read_b128 v[216:219], v173 offset:5120
	ds_read_b128 v[220:223], v173 offset:6144
	ds_read_b128 v[224:227], v173 offset:7168
	global_load_lds_dwordx4 v[168:169], off
	v_lshl_add_u64 v[168:169], s[12:13], 0, v[150:151]
	s_add_i32 m0, s47, 0xe000
	s_nop 0
	global_load_lds_dwordx4 v[168:169], off
	s_waitcnt vmcnt(8)
	s_waitcnt lgkmcnt(0)
	s_barrier
	s_setprio 1
	s_waitcnt lgkmcnt(0)
	v_mfma_f32_16x16x32_bf16 v[136:139], v[112:115], v[184:187], 0
	v_mfma_f32_16x16x32_bf16 v[136:139], v[120:123], v[188:191], v[136:139]
	v_mfma_f32_16x16x32_bf16 v[116:119], v[112:115], v[204:207], 0
	v_mfma_f32_16x16x32_bf16 v[116:119], v[120:123], v[208:211], v[116:119]
	v_mfma_f32_16x16x32_bf16 v[96:99], v[112:115], v[212:215], 0
	v_mfma_f32_16x16x32_bf16 v[96:99], v[120:123], v[216:219], v[96:99]
	v_mfma_f32_16x16x32_bf16 v[80:83], v[112:115], v[220:223], 0
	v_mfma_f32_16x16x32_bf16 v[80:83], v[120:123], v[224:227], v[80:83]
	v_mfma_f32_16x16x32_bf16 v[132:135], v[152:155], v[184:187], 0
	v_mfma_f32_16x16x32_bf16 v[132:135], v[156:159], v[188:191], v[132:135]
	v_mfma_f32_16x16x32_bf16 v[108:111], v[152:155], v[204:207], 0
	v_mfma_f32_16x16x32_bf16 v[108:111], v[156:159], v[208:211], v[108:111]
	v_mfma_f32_16x16x32_bf16 v[92:95], v[152:155], v[212:215], 0
	v_mfma_f32_16x16x32_bf16 v[92:95], v[156:159], v[216:219], v[92:95]
	v_mfma_f32_16x16x32_bf16 v[76:79], v[152:155], v[220:223], 0
	v_mfma_f32_16x16x32_bf16 v[76:79], v[156:159], v[224:227], v[76:79]
	s_setprio 0
	s_setprio 1
	v_mfma_f32_16x16x32_bf16 v[128:131], v[160:163], v[184:187], 0
	v_mfma_f32_16x16x32_bf16 v[128:131], v[164:167], v[188:191], v[128:131]
	v_mfma_f32_16x16x32_bf16 v[104:107], v[160:163], v[204:207], 0
	v_mfma_f32_16x16x32_bf16 v[104:107], v[164:167], v[208:211], v[104:107]
	v_mfma_f32_16x16x32_bf16 v[88:91], v[160:163], v[212:215], 0
	v_mfma_f32_16x16x32_bf16 v[88:91], v[164:167], v[216:219], v[88:91]
	v_mfma_f32_16x16x32_bf16 v[72:75], v[160:163], v[220:223], 0
	v_mfma_f32_16x16x32_bf16 v[72:75], v[164:167], v[224:227], v[72:75]
	v_mfma_f32_16x16x32_bf16 v[124:127], v[176:179], v[184:187], 0
	v_mfma_f32_16x16x32_bf16 v[124:127], v[180:183], v[188:191], v[124:127]
	v_mfma_f32_16x16x32_bf16 v[100:103], v[176:179], v[204:207], 0
	v_mfma_f32_16x16x32_bf16 v[100:103], v[180:183], v[208:211], v[100:103]
	v_mfma_f32_16x16x32_bf16 v[84:87], v[176:179], v[212:215], 0
	v_mfma_f32_16x16x32_bf16 v[84:87], v[180:183], v[216:219], v[84:87]
	v_mfma_f32_16x16x32_bf16 v[68:71], v[176:179], v[220:223], 0
	v_mfma_f32_16x16x32_bf16 v[68:71], v[180:183], v[224:227], v[68:71]
	s_setprio 0
	s_barrier
	s_add_i32 s50, s56, s46
	v_lshl_add_u64 v[168:169], s[72:73], 0, v[2:3]
	s_mov_b32 m0, s50
	ds_read_b128 v[184:187], v173 offset:16384
	ds_read_b128 v[188:191], v173 offset:17408
	ds_read_b128 v[204:207], v173 offset:18432
	ds_read_b128 v[208:211], v173 offset:19456
	ds_read_b128 v[212:215], v173 offset:20480
	ds_read_b128 v[216:219], v173 offset:21504
	ds_read_b128 v[220:223], v173 offset:22528
	ds_read_b128 v[224:227], v173 offset:23552
	global_load_lds_dwordx4 v[168:169], off
	s_add_i32 m0, s50, 0x2000
	s_add_u32 s50, s72, 0x100000
	v_lshl_add_u64 v[228:229], s[72:73], 0, v[144:145]
	s_addc_u32 s51, s73, 0
	s_add_i32 s56, s57, s46
	global_load_lds_dwordx4 v[228:229], off
	v_lshl_add_u64 v[240:241], s[50:51], 0, v[2:3]
	s_mov_b32 m0, s56
	v_lshl_add_u64 v[242:243], s[76:77], 0, v[142:143]
	global_load_lds_dwordx4 v[240:241], off
	v_lshl_add_u64 v[240:241], s[50:51], 0, v[144:145]
	s_add_i32 m0, s56, 0x2000
	s_nop 0
	global_load_lds_dwordx4 v[240:241], off
	v_lshl_add_u64 v[240:241], s[76:77], 0, v[140:141]
	s_mov_b32 m0, s47
	s_nop 0
	global_load_lds_dwordx4 v[240:241], off
	s_mov_b32 m0, s52
	s_nop 0
	global_load_lds_dwordx4 v[242:243], off
	s_waitcnt vmcnt(8)
	s_waitcnt lgkmcnt(0)
	s_barrier
; #define PG8_STAGE(bufoff, gbase, voff) do { _Pragma("unroll") for (int _i = 0; _i < 2; ++_i) \
;         __builtin_amdgcn_global_load_lds((const unsigned*)((const char*)(gbase) + (voff)[_i]), (PG8_LAS unsigned*)(lds + (bufoff) + ldsw + _i * 8192), 16, 0, 0); } while (0)
; #define PG8_LDA(dst, b, h) do { _Pragma("unroll") for (int m = 0; m < 4; ++m) _Pragma("unroll") for (int k = 0; k < 2; ++k) dst[m][k] = *(const PG8_LAS bf16x8*)(lds + PG8_SA(b, h) + aoff + m * 2048 + k * 1024); } while (0)
; #define PG8_LDB(dst, b, h) do { _Pragma("unroll") for (int n = 0; n < 2; ++n) _Pragma("unroll") for (int k = 0; k < 2; ++k) dst[n][k] = *(const PG8_LAS bf16x8*)(lds + PG8_SB(b, h) + boff + n * 2048 + k * 1024); } while (0)
; #define PG8_WAIT_V(n) asm volatile("s_waitcnt vmcnt(" #n ")" ::: "memory")
; #define PG8_WAIT_L(n) asm volatile("s_waitcnt lgkmcnt(" #n ")" ::: "memory")
; #define PG8_BAR __builtin_amdgcn_s_barrier()
; #define PG8_SCHED __builtin_amdgcn_sched_barrier(0)
; template <class Epi, class Sched, bool ALIGN_EPI = false, bool SP2 = false, bool I8 = false>
; __device__ __forceinline__ void gemm_phase(PG8_LAS unsigned char* lds, const Gemm g, const Sched& S, const Epi& E) {
;     ...
;             PG8_WAIT_V(8); PG8_WAIT_L(0); PG8_BAR; PG8_MMA(1, 0, At, B0); PG8_MMA(1, 1, At, B1); PG8_BAR; PG8_SCHED;
;             PG8_LDB(B0, 1, 0); PG8_LDB(B1, 1, 1); PG8_SCHED; PG8_LDA(At, 1, 0); PG8_STAGE(PG8_SA(0, 1), a2 + hstep, voffA);
;             PG8_WAIT_V(8); PG8_WAIT_L(0); PG8_BAR; PG8_MMA(0, 0, At, B0); PG8_MMA(0, 1, At, B1); PG8_BAR; PG8_SCHED;
;             PG8_LDA(At, 1, 1); PG8_STAGE(PG8_SB(1, 0), b3, voffB); PG8_STAGE(PG8_SB(1, 1), b3 + hstep, voffB); PG8_STAGE(PG8_SA(1, 0), a3, voffA);
	s_setprio 1
	s_waitcnt lgkmcnt(0)
	v_mfma_f32_16x16x32_bf16 v[64:67], v[112:115], v[184:187], 0
	v_mfma_f32_16x16x32_bf16 v[64:67], v[120:123], v[188:191], v[64:67]
	v_mfma_f32_16x16x32_bf16 v[48:51], v[112:115], v[204:207], 0
	v_mfma_f32_16x16x32_bf16 v[48:51], v[120:123], v[208:211], v[48:51]
	v_mfma_f32_16x16x32_bf16 v[32:35], v[112:115], v[212:215], 0
	v_mfma_f32_16x16x32_bf16 v[32:35], v[120:123], v[216:219], v[32:35]
	v_mfma_f32_16x16x32_bf16 v[16:19], v[112:115], v[220:223], 0
	v_mfma_f32_16x16x32_bf16 v[16:19], v[120:123], v[224:227], v[16:19]
	v_mfma_f32_16x16x32_bf16 v[60:63], v[152:155], v[184:187], 0
	v_mfma_f32_16x16x32_bf16 v[60:63], v[156:159], v[188:191], v[60:63]
	v_mfma_f32_16x16x32_bf16 v[44:47], v[152:155], v[204:207], 0
	v_mfma_f32_16x16x32_bf16 v[44:47], v[156:159], v[208:211], v[44:47]
	v_mfma_f32_16x16x32_bf16 v[28:31], v[152:155], v[212:215], 0
	v_mfma_f32_16x16x32_bf16 v[28:31], v[156:159], v[216:219], v[28:31]
	v_mfma_f32_16x16x32_bf16 v[12:15], v[152:155], v[220:223], 0
	v_mfma_f32_16x16x32_bf16 v[12:15], v[156:159], v[224:227], v[12:15]
	s_setprio 0
	s_setprio 1
	v_mfma_f32_16x16x32_bf16 v[56:59], v[160:163], v[184:187], 0
	v_mfma_f32_16x16x32_bf16 v[56:59], v[164:167], v[188:191], v[56:59]
	v_mfma_f32_16x16x32_bf16 v[40:43], v[160:163], v[204:207], 0
	v_mfma_f32_16x16x32_bf16 v[40:43], v[164:167], v[208:211], v[40:43]
	v_mfma_f32_16x16x32_bf16 v[24:27], v[160:163], v[212:215], 0
	v_mfma_f32_16x16x32_bf16 v[24:27], v[164:167], v[216:219], v[24:27]
	v_mfma_f32_16x16x32_bf16 v[8:11], v[160:163], v[220:223], 0
	v_mfma_f32_16x16x32_bf16 v[8:11], v[164:167], v[224:227], v[8:11]
	v_mfma_f32_16x16x32_bf16 v[52:55], v[176:179], v[184:187], 0
	v_mfma_f32_16x16x32_bf16 v[52:55], v[180:183], v[188:191], v[52:55]
	v_mfma_f32_16x16x32_bf16 v[36:39], v[176:179], v[204:207], 0
	v_mfma_f32_16x16x32_bf16 v[36:39], v[180:183], v[208:211], v[36:39]
	v_mfma_f32_16x16x32_bf16 v[20:23], v[176:179], v[212:215], 0
	v_mfma_f32_16x16x32_bf16 v[20:23], v[180:183], v[216:219], v[20:23]
	v_mfma_f32_16x16x32_bf16 v[4:7], v[176:179], v[220:223], 0
	v_mfma_f32_16x16x32_bf16 v[4:7], v[180:183], v[224:227], v[4:7]
	s_setprio 0
	s_barrier
	s_add_i32 s56, 0, 0x18000
	s_add_i32 s57, 0, 0x1c000
	v_add_u32_e32 v156, s56, v171
	v_add_u32_e32 v175, s57, v171
	ds_read_b128 v[112:115], v156
	ds_read_b128 v[120:123], v156 offset:1024
	ds_read_b128 v[152:155], v156 offset:2048
	ds_read_b128 v[156:159], v156 offset:3072
	ds_read_b128 v[160:163], v175
	ds_read_b128 v[164:167], v175 offset:1024
	ds_read_b128 v[176:179], v175 offset:2048
	ds_read_b128 v[180:183], v175 offset:3072
	s_add_u32 s50, s76, 0x100000
	s_addc_u32 s51, s77, 0
	s_mov_b32 m0, s53
	v_lshl_add_u64 v[244:245], s[50:51], 0, v[140:141]
	ds_read_b128 v[184:187], v173 offset:32768
	ds_read_b128 v[188:191], v173 offset:33792
	ds_read_b128 v[204:207], v173 offset:34816
	ds_read_b128 v[208:211], v173 offset:35840
	ds_read_b128 v[212:215], v173 offset:36864
	ds_read_b128 v[216:219], v173 offset:37888
	ds_read_b128 v[220:223], v173 offset:38912
	ds_read_b128 v[224:227], v173 offset:39936
	global_load_lds_dwordx4 v[244:245], off
	v_lshl_add_u64 v[244:245], s[50:51], 0, v[142:143]
	s_mov_b32 m0, s64
	s_nop 0
	global_load_lds_dwordx4 v[244:245], off
	s_waitcnt vmcnt(8)
	s_waitcnt lgkmcnt(0)
	s_barrier
	s_setprio 1
	s_waitcnt lgkmcnt(0)
	v_mfma_f32_16x16x32_bf16 v[136:139], v[112:115], v[184:187], v[136:139]
	v_mfma_f32_16x16x32_bf16 v[136:139], v[120:123], v[188:191], v[136:139]
	v_mfma_f32_16x16x32_bf16 v[116:119], v[112:115], v[204:207], v[116:119]
	v_mfma_f32_16x16x32_bf16 v[116:119], v[120:123], v[208:211], v[116:119]
	v_mfma_f32_16x16x32_bf16 v[96:99], v[112:115], v[212:215], v[96:99]
	v_mfma_f32_16x16x32_bf16 v[96:99], v[120:123], v[216:219], v[96:99]
	v_mfma_f32_16x16x32_bf16 v[80:83], v[112:115], v[220:223], v[80:83]
	v_mfma_f32_16x16x32_bf16 v[80:83], v[120:123], v[224:227], v[80:83]
	v_mfma_f32_16x16x32_bf16 v[132:135], v[152:155], v[184:187], v[132:135]
	v_mfma_f32_16x16x32_bf16 v[132:135], v[156:159], v[188:191], v[132:135]
	v_mfma_f32_16x16x32_bf16 v[108:111], v[152:155], v[204:207], v[108:111]
	v_mfma_f32_16x16x32_bf16 v[108:111], v[156:159], v[208:211], v[108:111]
	v_mfma_f32_16x16x32_bf16 v[92:95], v[152:155], v[212:215], v[92:95]
	v_mfma_f32_16x16x32_bf16 v[92:95], v[156:159], v[216:219], v[92:95]
	v_mfma_f32_16x16x32_bf16 v[76:79], v[152:155], v[220:223], v[76:79]
	v_mfma_f32_16x16x32_bf16 v[76:79], v[156:159], v[224:227], v[76:79]
	s_setprio 0
	s_setprio 1
	v_mfma_f32_16x16x32_bf16 v[128:131], v[160:163], v[184:187], v[128:131]
	v_mfma_f32_16x16x32_bf16 v[128:131], v[164:167], v[188:191], v[128:131]
	v_mfma_f32_16x16x32_bf16 v[104:107], v[160:163], v[204:207], v[104:107]
	v_mfma_f32_16x16x32_bf16 v[104:107], v[164:167], v[208:211], v[104:107]
	v_mfma_f32_16x16x32_bf16 v[88:91], v[160:163], v[212:215], v[88:91]
	v_mfma_f32_16x16x32_bf16 v[88:91], v[164:167], v[216:219], v[88:91]
	v_mfma_f32_16x16x32_bf16 v[72:75], v[160:163], v[220:223], v[72:75]
	v_mfma_f32_16x16x32_bf16 v[72:75], v[164:167], v[224:227], v[72:75]
	v_mfma_f32_16x16x32_bf16 v[124:127], v[176:179], v[184:187], v[124:127]
	v_mfma_f32_16x16x32_bf16 v[124:127], v[180:183], v[188:191], v[124:127]
	v_mfma_f32_16x16x32_bf16 v[100:103], v[176:179], v[204:207], v[100:103]
	v_mfma_f32_16x16x32_bf16 v[100:103], v[180:183], v[208:211], v[100:103]
	v_mfma_f32_16x16x32_bf16 v[84:87], v[176:179], v[212:215], v[84:87]
	v_mfma_f32_16x16x32_bf16 v[84:87], v[180:183], v[216:219], v[84:87]
	v_mfma_f32_16x16x32_bf16 v[68:71], v[176:179], v[220:223], v[68:71]
	v_mfma_f32_16x16x32_bf16 v[68:71], v[180:183], v[224:227], v[68:71]
	s_setprio 0
	s_barrier
; #define PG8_STAGE(bufoff, gbase, voff) do { _Pragma("unroll") for (int _i = 0; _i < 2; ++_i) \
;         __builtin_amdgcn_global_load_lds((const unsigned*)((const char*)(gbase) + (voff)[_i]), (PG8_LAS unsigned*)(lds + (bufoff) + ldsw + _i * 8192), 16, 0, 0); } while (0)
; #define PG8_LDA(dst, b, h) do { _Pragma("unroll") for (int m = 0; m < 4; ++m) _Pragma("unroll") for (int k = 0; k < 2; ++k) dst[m][k] = *(const PG8_LAS bf16x8*)(lds + PG8_SA(b, h) + aoff + m * 2048 + k * 1024); } while (0)
; #define PG8_LDB(dst, b, h) do { _Pragma("unroll") for (int n = 0; n < 2; ++n) _Pragma("unroll") for (int k = 0; k < 2; ++k) dst[n][k] = *(const PG8_LAS bf16x8*)(lds + PG8_SB(b, h) + boff + n * 2048 + k * 1024); } while (0)
; #define PG8_WAIT_V(n) asm volatile("s_waitcnt vmcnt(" #n ")" ::: "memory")
; #define PG8_WAIT_L(n) asm volatile("s_waitcnt lgkmcnt(" #n ")" ::: "memory")
; #define PG8_BAR __builtin_amdgcn_s_barrier()
; #define PG8_SCHED __builtin_amdgcn_sched_barrier(0)
; template <class Epi, class Sched, bool ALIGN_EPI = false, bool SP2 = false, bool I8 = false>
; __device__ __forceinline__ void gemm_phase(PG8_LAS unsigned char* lds, const Gemm g, const Sched& S, const Epi& E) {
;     ...
;         for (int t = 0; t < nt; t += 2) {
;             const bool last = (t == nt - 2);
;             const char* a1 = cA + (size_t)(t + 1) * kstep;
;             const char* a2 = last ? nA : cA + (size_t)(t + 2) * kstep; const char* b2 = last ? nB : cB + (size_t)(t + 2) * kstep;
;             const char* a3 = a2 + kstep; const char* b3 = b2 + kstep;
;             if (last && has_next) S.a_ready(nxt);
;             if constexpr (SP2) {
;             PG8_LDB(B0, 0, 0); PG8_LDB(B1, 0, 1); PG8_SCHED; PG8_LDA(At, 0, 0); PG8_STAGE(PG8_SA(1, 1), a1 + hstep, voffA);
;     ...
;             PG8_WAIT_V(8); PG8_WAIT_L(0); PG8_BAR; PG8_MMA(0, 0, At, B0); PG8_MMA(0, 1, At, B1); PG8_BAR; PG8_SCHED;
;             PG8_LDA(At, 1, 1); PG8_STAGE(PG8_SB(1, 0), b3, voffB); PG8_STAGE(PG8_SB(1, 1), b3 + hstep, voffB); PG8_STAGE(PG8_SA(1, 0), a3, voffA);
;             PG8_WAIT_V(8); PG8_WAIT_L(0); PG8_BAR; PG8_MMA(1, 0, At, B0); PG8_MMA(1, 1, At, B1); PG8_BAR; PG8_SCHED;
	s_add_i32 s50, s56, s46
	v_lshl_add_u64 v[168:169], v[168:169], 0, s[84:85]
	s_mov_b32 m0, s50
	ds_read_b128 v[184:187], v173 offset:49152
	ds_read_b128 v[188:191], v173 offset:50176
	ds_read_b128 v[204:207], v173 offset:51200
	ds_read_b128 v[208:211], v173 offset:52224
	ds_read_b128 v[212:215], v173 offset:53248
	ds_read_b128 v[216:219], v173 offset:54272
	ds_read_b128 v[220:223], v173 offset:55296
	ds_read_b128 v[224:227], v173 offset:56320
	global_load_lds_dwordx4 v[168:169], off
	s_add_i32 m0, s50, 0x2000
	s_add_u32 s50, s72, 0x100080
	v_lshl_add_u64 v[168:169], v[228:229], 0, s[84:85]
	s_addc_u32 s51, s73, 0
	s_add_i32 s56, s57, s46
	global_load_lds_dwordx4 v[168:169], off
	v_lshl_add_u64 v[168:169], s[50:51], 0, v[2:3]
	s_mov_b32 m0, s56
	s_nop 0
	global_load_lds_dwordx4 v[168:169], off
	v_lshl_add_u64 v[168:169], s[50:51], 0, v[144:145]
	s_add_i32 m0, s56, 0x2000
	s_nop 0
	global_load_lds_dwordx4 v[168:169], off
	v_lshl_add_u64 v[168:169], v[240:241], 0, s[84:85]
	s_mov_b32 m0, s28
	s_nop 0
	global_load_lds_dwordx4 v[168:169], off
	v_lshl_add_u64 v[168:169], v[242:243], 0, s[84:85]
	s_mov_b32 m0, s65
	s_nop 0
	global_load_lds_dwordx4 v[168:169], off
	s_waitcnt vmcnt(8)
	s_waitcnt lgkmcnt(0)
	s_barrier
	s_setprio 1
	s_waitcnt lgkmcnt(0)
	v_mfma_f32_16x16x32_bf16 v[64:67], v[112:115], v[184:187], v[64:67]
	v_mfma_f32_16x16x32_bf16 v[64:67], v[120:123], v[188:191], v[64:67]
	v_mfma_f32_16x16x32_bf16 v[48:51], v[112:115], v[204:207], v[48:51]
	v_mfma_f32_16x16x32_bf16 v[48:51], v[120:123], v[208:211], v[48:51]
	v_mfma_f32_16x16x32_bf16 v[32:35], v[112:115], v[212:215], v[32:35]
	v_mfma_f32_16x16x32_bf16 v[32:35], v[120:123], v[216:219], v[32:35]
	v_mfma_f32_16x16x32_bf16 v[16:19], v[112:115], v[220:223], v[16:19]
	v_mfma_f32_16x16x32_bf16 v[16:19], v[120:123], v[224:227], v[16:19]
	v_mfma_f32_16x16x32_bf16 v[60:63], v[152:155], v[184:187], v[60:63]
	v_mfma_f32_16x16x32_bf16 v[60:63], v[156:159], v[188:191], v[60:63]
	v_mfma_f32_16x16x32_bf16 v[44:47], v[152:155], v[204:207], v[44:47]
	v_mfma_f32_16x16x32_bf16 v[44:47], v[156:159], v[208:211], v[44:47]
	v_mfma_f32_16x16x32_bf16 v[28:31], v[152:155], v[212:215], v[28:31]
	v_mfma_f32_16x16x32_bf16 v[28:31], v[156:159], v[216:219], v[28:31]
	v_mfma_f32_16x16x32_bf16 v[12:15], v[152:155], v[220:223], v[12:15]
	v_mfma_f32_16x16x32_bf16 v[12:15], v[156:159], v[224:227], v[12:15]
	s_setprio 0
	s_setprio 1
	v_mfma_f32_16x16x32_bf16 v[56:59], v[160:163], v[184:187], v[56:59]
	v_mfma_f32_16x16x32_bf16 v[56:59], v[164:167], v[188:191], v[56:59]
	v_mfma_f32_16x16x32_bf16 v[40:43], v[160:163], v[204:207], v[40:43]
	v_mfma_f32_16x16x32_bf16 v[40:43], v[164:167], v[208:211], v[40:43]
	v_mfma_f32_16x16x32_bf16 v[24:27], v[160:163], v[212:215], v[24:27]
	v_mfma_f32_16x16x32_bf16 v[24:27], v[164:167], v[216:219], v[24:27]
	v_mfma_f32_16x16x32_bf16 v[8:11], v[160:163], v[220:223], v[8:11]
	v_mfma_f32_16x16x32_bf16 v[8:11], v[164:167], v[224:227], v[8:11]
	v_mfma_f32_16x16x32_bf16 v[52:55], v[176:179], v[184:187], v[52:55]
	v_mfma_f32_16x16x32_bf16 v[52:55], v[180:183], v[188:191], v[52:55]
	v_mfma_f32_16x16x32_bf16 v[36:39], v[176:179], v[204:207], v[36:39]
	v_mfma_f32_16x16x32_bf16 v[36:39], v[180:183], v[208:211], v[36:39]
	v_mfma_f32_16x16x32_bf16 v[20:23], v[176:179], v[212:215], v[20:23]
	v_mfma_f32_16x16x32_bf16 v[20:23], v[180:183], v[216:219], v[20:23]
	v_mfma_f32_16x16x32_bf16 v[4:7], v[176:179], v[220:223], v[4:7]
	v_mfma_f32_16x16x32_bf16 v[4:7], v[180:183], v[224:227], v[4:7]
	s_setprio 0
	s_barrier
	s_add_i32 s97, s97, 2
	s_add_u32 s12, s12, 0x100
	s_addc_u32 s13, s13, 0
	s_add_u32 s37, s37, 0x100
	s_addc_u32 s61, s61, 0
	s_cmp_gt_u32 s97, 61
	s_cbranch_scc1 .Lkloop_exit_1
.LBB0_230:
	s_add_u32 s50, s12, 0xfff00080
	s_addc_u32 s51, s13, -1
	s_add_i32 s56, 0, 0x10000
	s_cmp_eq_u32 s97, 60
	s_cselect_b32 s77, s11, s51
	s_cselect_b32 s76, s34, s50
	s_cselect_b32 s73, s27, s61
	s_cselect_b32 s72, s35, s37
	s_add_i32 s57, 0, 0x14000
	v_add_u32_e32 v156, s56, v171
	v_add_u32_e32 v168, s57, v171
	s_waitcnt vmcnt(0)
	ds_read_b128 v[112:115], v156
	ds_read_b128 v[120:123], v156 offset:1024
	ds_read_b128 v[152:155], v156 offset:2048
	ds_read_b128 v[156:159], v156 offset:3072
	ds_read_b128 v[160:163], v168
	ds_read_b128 v[164:167], v168 offset:1024
	s_waitcnt lgkmcnt(0)
	ds_read_b128 v[176:179], v168 offset:2048
	ds_read_b128 v[180:183], v168 offset:3072
	v_lshl_add_u64 v[168:169], s[12:13], 0, v[148:149]
	s_add_i32 m0, s47, 0xc000
	ds_read_b128 v[184:187], v173
	ds_read_b128 v[188:191], v173 offset:1024
	ds_read_b128 v[204:207], v173 offset:2048
	ds_read_b128 v[208:211], v173 offset:3072
	ds_read_b128 v[212:215], v173 offset:4096
	ds_read_b128 v[216:219], v173 offset:5120
	ds_read_b128 v[220:223], v173 offset:6144
	ds_read_b128 v[224:227], v173 offset:7168
	global_load_lds_dwordx4 v[168:169], off
	v_lshl_add_u64 v[168:169], s[12:13], 0, v[150:151]
	s_add_i32 m0, s47, 0xe000
	s_nop 0
	global_load_lds_dwordx4 v[168:169], off
	s_waitcnt vmcnt(8)
	s_waitcnt lgkmcnt(0)
	s_barrier
; #define PG8_STAGE(bufoff, gbase, voff) do { _Pragma("unroll") for (int _i = 0; _i < 2; ++_i) \
;         __builtin_amdgcn_global_load_lds((const unsigned*)((const char*)(gbase) + (voff)[_i]), (PG8_LAS unsigned*)(lds + (bufoff) + ldsw + _i * 8192), 16, 0, 0); } while (0)
; #define PG8_LDA(dst, b, h) do { _Pragma("unroll") for (int m = 0; m < 4; ++m) _Pragma("unroll") for (int k = 0; k < 2; ++k) dst[m][k] = *(const PG8_LAS bf16x8*)(lds + PG8_SA(b, h) + aoff + m * 2048 + k * 1024); } while (0)
; #define PG8_LDB(dst, b, h) do { _Pragma("unroll") for (int n = 0; n < 2; ++n) _Pragma("unroll") for (int k = 0; k < 2; ++k) dst[n][k] = *(const PG8_LAS bf16x8*)(lds + PG8_SB(b, h) + boff + n * 2048 + k * 1024); } while (0)
; #define PG8_WAIT_V(n) asm volatile("s_waitcnt vmcnt(" #n ")" ::: "memory")
; #define PG8_WAIT_L(n) asm volatile("s_waitcnt lgkmcnt(" #n ")" ::: "memory")
; #define PG8_BAR __builtin_amdgcn_s_barrier()
; #define PG8_SCHED __builtin_amdgcn_sched_barrier(0)
; template <class Epi, class Sched, bool ALIGN_EPI = false, bool SP2 = false, bool I8 = false>
; __device__ __forceinline__ void gemm_phase(PG8_LAS unsigned char* lds, const Gemm g, const Sched& S, const Epi& E) {
;     ...
;             PG8_LDB(B0, 0, 0); PG8_LDB(B1, 0, 1); PG8_SCHED; PG8_LDA(At, 0, 0); PG8_STAGE(PG8_SA(1, 1), a1 + hstep, voffA);
;             PG8_WAIT_V(8); PG8_WAIT_L(0); PG8_BAR; PG8_MMA(0, 0, At, B0); PG8_MMA(0, 1, At, B1); PG8_BAR; PG8_SCHED;
;             PG8_LDA(At, 0, 1); PG8_STAGE(PG8_SB(0, 0), b2, voffB); PG8_STAGE(PG8_SB(0, 1), b2 + hstep, voffB); PG8_STAGE(PG8_SA(0, 0), a2, voffA);
;             PG8_WAIT_V(8); PG8_WAIT_L(0); PG8_BAR; PG8_MMA(1, 0, At, B0); PG8_MMA(1, 1, At, B1); PG8_BAR; PG8_SCHED;
	s_setprio 1
	s_waitcnt lgkmcnt(0)
	v_mfma_f32_16x16x32_bf16 v[136:139], v[112:115], v[184:187], v[136:139]
	v_mfma_f32_16x16x32_bf16 v[136:139], v[120:123], v[188:191], v[136:139]
	v_mfma_f32_16x16x32_bf16 v[116:119], v[112:115], v[204:207], v[116:119]
	v_mfma_f32_16x16x32_bf16 v[116:119], v[120:123], v[208:211], v[116:119]
	v_mfma_f32_16x16x32_bf16 v[96:99], v[112:115], v[212:215], v[96:99]
	v_mfma_f32_16x16x32_bf16 v[96:99], v[120:123], v[216:219], v[96:99]
	v_mfma_f32_16x16x32_bf16 v[80:83], v[112:115], v[220:223], v[80:83]
	v_mfma_f32_16x16x32_bf16 v[80:83], v[120:123], v[224:227], v[80:83]
	v_mfma_f32_16x16x32_bf16 v[132:135], v[152:155], v[184:187], v[132:135]
	v_mfma_f32_16x16x32_bf16 v[132:135], v[156:159], v[188:191], v[132:135]
	v_mfma_f32_16x16x32_bf16 v[108:111], v[152:155], v[204:207], v[108:111]
	v_mfma_f32_16x16x32_bf16 v[108:111], v[156:159], v[208:211], v[108:111]
	v_mfma_f32_16x16x32_bf16 v[92:95], v[152:155], v[212:215], v[92:95]
	v_mfma_f32_16x16x32_bf16 v[92:95], v[156:159], v[216:219], v[92:95]
	v_mfma_f32_16x16x32_bf16 v[76:79], v[152:155], v[220:223], v[76:79]
	v_mfma_f32_16x16x32_bf16 v[76:79], v[156:159], v[224:227], v[76:79]
	s_setprio 0
	s_setprio 1
	v_mfma_f32_16x16x32_bf16 v[128:131], v[160:163], v[184:187], v[128:131]
	v_mfma_f32_16x16x32_bf16 v[128:131], v[164:167], v[188:191], v[128:131]
	v_mfma_f32_16x16x32_bf16 v[104:107], v[160:163], v[204:207], v[104:107]
	v_mfma_f32_16x16x32_bf16 v[104:107], v[164:167], v[208:211], v[104:107]
	v_mfma_f32_16x16x32_bf16 v[88:91], v[160:163], v[212:215], v[88:91]
	v_mfma_f32_16x16x32_bf16 v[88:91], v[164:167], v[216:219], v[88:91]
	v_mfma_f32_16x16x32_bf16 v[72:75], v[160:163], v[220:223], v[72:75]
	v_mfma_f32_16x16x32_bf16 v[72:75], v[164:167], v[224:227], v[72:75]
	v_mfma_f32_16x16x32_bf16 v[124:127], v[176:179], v[184:187], v[124:127]
	v_mfma_f32_16x16x32_bf16 v[124:127], v[180:183], v[188:191], v[124:127]
	v_mfma_f32_16x16x32_bf16 v[100:103], v[176:179], v[204:207], v[100:103]
	v_mfma_f32_16x16x32_bf16 v[100:103], v[180:183], v[208:211], v[100:103]
	v_mfma_f32_16x16x32_bf16 v[84:87], v[176:179], v[212:215], v[84:87]
	v_mfma_f32_16x16x32_bf16 v[84:87], v[180:183], v[216:219], v[84:87]
	v_mfma_f32_16x16x32_bf16 v[68:71], v[176:179], v[220:223], v[68:71]
	v_mfma_f32_16x16x32_bf16 v[68:71], v[180:183], v[224:227], v[68:71]
	s_setprio 0
	s_barrier
	s_add_i32 s50, s56, s46
	v_lshl_add_u64 v[168:169], s[72:73], 0, v[2:3]
	s_mov_b32 m0, s50
	ds_read_b128 v[184:187], v173 offset:16384
	ds_read_b128 v[188:191], v173 offset:17408
	ds_read_b128 v[204:207], v173 offset:18432
	ds_read_b128 v[208:211], v173 offset:19456
	ds_read_b128 v[212:215], v173 offset:20480
	ds_read_b128 v[216:219], v173 offset:21504
	ds_read_b128 v[220:223], v173 offset:22528
	ds_read_b128 v[224:227], v173 offset:23552
	global_load_lds_dwordx4 v[168:169], off
	s_add_i32 m0, s50, 0x2000
	s_add_u32 s50, s72, 0x100000
	v_lshl_add_u64 v[228:229], s[72:73], 0, v[144:145]
	s_addc_u32 s51, s73, 0
	s_add_i32 s56, s57, s46
	global_load_lds_dwordx4 v[228:229], off
	v_lshl_add_u64 v[240:241], s[50:51], 0, v[2:3]
	s_mov_b32 m0, s56
	v_lshl_add_u64 v[242:243], s[76:77], 0, v[142:143]
	global_load_lds_dwordx4 v[240:241], off
	v_lshl_add_u64 v[240:241], s[50:51], 0, v[144:145]
	s_add_i32 m0, s56, 0x2000
	s_nop 0
	global_load_lds_dwordx4 v[240:241], off
	v_lshl_add_u64 v[240:241], s[76:77], 0, v[140:141]
	s_mov_b32 m0, s47
	s_nop 0
	global_load_lds_dwordx4 v[240:241], off
	s_mov_b32 m0, s52
	s_nop 0
	global_load_lds_dwordx4 v[242:243], off
	s_waitcnt vmcnt(8)
	s_waitcnt lgkmcnt(0)
	s_barrier
	s_setprio 1
	s_waitcnt lgkmcnt(0)
	v_mfma_f32_16x16x32_bf16 v[64:67], v[112:115], v[184:187], v[64:67]
	v_mfma_f32_16x16x32_bf16 v[64:67], v[120:123], v[188:191], v[64:67]
	v_mfma_f32_16x16x32_bf16 v[48:51], v[112:115], v[204:207], v[48:51]
	v_mfma_f32_16x16x32_bf16 v[48:51], v[120:123], v[208:211], v[48:51]
	v_mfma_f32_16x16x32_bf16 v[32:35], v[112:115], v[212:215], v[32:35]
	v_mfma_f32_16x16x32_bf16 v[32:35], v[120:123], v[216:219], v[32:35]
	v_mfma_f32_16x16x32_bf16 v[16:19], v[112:115], v[220:223], v[16:19]
	v_mfma_f32_16x16x32_bf16 v[16:19], v[120:123], v[224:227], v[16:19]
	v_mfma_f32_16x16x32_bf16 v[60:63], v[152:155], v[184:187], v[60:63]
	v_mfma_f32_16x16x32_bf16 v[60:63], v[156:159], v[188:191], v[60:63]
	v_mfma_f32_16x16x32_bf16 v[44:47], v[152:155], v[204:207], v[44:47]
	v_mfma_f32_16x16x32_bf16 v[44:47], v[156:159], v[208:211], v[44:47]
	v_mfma_f32_16x16x32_bf16 v[28:31], v[152:155], v[212:215], v[28:31]
	v_mfma_f32_16x16x32_bf16 v[28:31], v[156:159], v[216:219], v[28:31]
	v_mfma_f32_16x16x32_bf16 v[12:15], v[152:155], v[220:223], v[12:15]
	v_mfma_f32_16x16x32_bf16 v[12:15], v[156:159], v[224:227], v[12:15]
	s_setprio 0
	s_setprio 1
	v_mfma_f32_16x16x32_bf16 v[56:59], v[160:163], v[184:187], v[56:59]
	v_mfma_f32_16x16x32_bf16 v[56:59], v[164:167], v[188:191], v[56:59]
	v_mfma_f32_16x16x32_bf16 v[40:43], v[160:163], v[204:207], v[40:43]
	v_mfma_f32_16x16x32_bf16 v[40:43], v[164:167], v[208:211], v[40:43]
	v_mfma_f32_16x16x32_bf16 v[24:27], v[160:163], v[212:215], v[24:27]
	v_mfma_f32_16x16x32_bf16 v[24:27], v[164:167], v[216:219], v[24:27]
	v_mfma_f32_16x16x32_bf16 v[8:11], v[160:163], v[220:223], v[8:11]
	v_mfma_f32_16x16x32_bf16 v[8:11], v[164:167], v[224:227], v[8:11]
	v_mfma_f32_16x16x32_bf16 v[52:55], v[176:179], v[184:187], v[52:55]
	v_mfma_f32_16x16x32_bf16 v[52:55], v[180:183], v[188:191], v[52:55]
	v_mfma_f32_16x16x32_bf16 v[36:39], v[176:179], v[204:207], v[36:39]
	v_mfma_f32_16x16x32_bf16 v[36:39], v[180:183], v[208:211], v[36:39]
	v_mfma_f32_16x16x32_bf16 v[20:23], v[176:179], v[212:215], v[20:23]
	v_mfma_f32_16x16x32_bf16 v[20:23], v[180:183], v[216:219], v[20:23]
	v_mfma_f32_16x16x32_bf16 v[4:7], v[176:179], v[220:223], v[4:7]
	v_mfma_f32_16x16x32_bf16 v[4:7], v[180:183], v[224:227], v[4:7]
	s_setprio 0
	s_barrier
; #define PG8_STAGE(bufoff, gbase, voff) do { _Pragma("unroll") for (int _i = 0; _i < 2; ++_i) \
;         __builtin_amdgcn_global_load_lds((const unsigned*)((const char*)(gbase) + (voff)[_i]), (PG8_LAS unsigned*)(lds + (bufoff) + ldsw + _i * 8192), 16, 0, 0); } while (0)
; #define PG8_LDA(dst, b, h) do { _Pragma("unroll") for (int m = 0; m < 4; ++m) _Pragma("unroll") for (int k = 0; k < 2; ++k) dst[m][k] = *(const PG8_LAS bf16x8*)(lds + PG8_SA(b, h) + aoff + m * 2048 + k * 1024); } while (0)
; #define PG8_LDB(dst, b, h) do { _Pragma("unroll") for (int n = 0; n < 2; ++n) _Pragma("unroll") for (int k = 0; k < 2; ++k) dst[n][k] = *(const PG8_LAS bf16x8*)(lds + PG8_SB(b, h) + boff + n * 2048 + k * 1024); } while (0)
; #define PG8_WAIT_V(n) asm volatile("s_waitcnt vmcnt(" #n ")" ::: "memory")
; #define PG8_WAIT_L(n) asm volatile("s_waitcnt lgkmcnt(" #n ")" ::: "memory")
; #define PG8_BAR __builtin_amdgcn_s_barrier()
; #define PG8_SCHED __builtin_amdgcn_sched_barrier(0)
; template <class Epi, class Sched, bool ALIGN_EPI = false, bool SP2 = false, bool I8 = false>
; __device__ __forceinline__ void gemm_phase(PG8_LAS unsigned char* lds, const Gemm g, const Sched& S, const Epi& E) {
;     ...
;             PG8_LDB(B0, 1, 0); PG8_LDB(B1, 1, 1); PG8_SCHED; PG8_LDA(At, 1, 0); PG8_STAGE(PG8_SA(0, 1), a2 + hstep, voffA);
;             PG8_WAIT_V(8); PG8_WAIT_L(0); PG8_BAR; PG8_MMA(0, 0, At, B0); PG8_MMA(0, 1, At, B1); PG8_BAR; PG8_SCHED;
	s_add_i32 s56, 0, 0x18000
	s_add_i32 s57, 0, 0x1c000
	v_add_u32_e32 v156, s56, v171
	v_add_u32_e32 v175, s57, v171
	ds_read_b128 v[112:115], v156
	ds_read_b128 v[120:123], v156 offset:1024
	ds_read_b128 v[152:155], v156 offset:2048
	ds_read_b128 v[156:159], v156 offset:3072
	ds_read_b128 v[160:163], v175
	ds_read_b128 v[164:167], v175 offset:1024
	ds_read_b128 v[176:179], v175 offset:2048
	ds_read_b128 v[180:183], v175 offset:3072
	s_add_u32 s50, s76, 0x100000
	s_addc_u32 s51, s77, 0
	s_mov_b32 m0, s53
	v_lshl_add_u64 v[244:245], s[50:51], 0, v[140:141]
	ds_read_b128 v[184:187], v173 offset:32768
	ds_read_b128 v[188:191], v173 offset:33792
	ds_read_b128 v[204:207], v173 offset:34816
	ds_read_b128 v[208:211], v173 offset:35840
	ds_read_b128 v[212:215], v173 offset:36864
	ds_read_b128 v[216:219], v173 offset:37888
	ds_read_b128 v[220:223], v173 offset:38912
	ds_read_b128 v[224:227], v173 offset:39936
	global_load_lds_dwordx4 v[244:245], off
	v_lshl_add_u64 v[244:245], s[50:51], 0, v[142:143]
	s_mov_b32 m0, s64
	s_nop 0
	global_load_lds_dwordx4 v[244:245], off
	s_waitcnt vmcnt(8)
	s_waitcnt lgkmcnt(0)
	s_barrier
	s_setprio 1
	s_waitcnt lgkmcnt(0)
	v_mfma_f32_16x16x32_bf16 v[136:139], v[112:115], v[184:187], v[136:139]
	v_mfma_f32_16x16x32_bf16 v[136:139], v[120:123], v[188:191], v[136:139]
	v_mfma_f32_16x16x32_bf16 v[116:119], v[112:115], v[204:207], v[116:119]
	v_mfma_f32_16x16x32_bf16 v[116:119], v[120:123], v[208:211], v[116:119]
	v_mfma_f32_16x16x32_bf16 v[96:99], v[112:115], v[212:215], v[96:99]
	v_mfma_f32_16x16x32_bf16 v[96:99], v[120:123], v[216:219], v[96:99]
	v_mfma_f32_16x16x32_bf16 v[80:83], v[112:115], v[220:223], v[80:83]
	v_mfma_f32_16x16x32_bf16 v[80:83], v[120:123], v[224:227], v[80:83]
	v_mfma_f32_16x16x32_bf16 v[132:135], v[152:155], v[184:187], v[132:135]
	v_mfma_f32_16x16x32_bf16 v[132:135], v[156:159], v[188:191], v[132:135]
	v_mfma_f32_16x16x32_bf16 v[108:111], v[152:155], v[204:207], v[108:111]
	v_mfma_f32_16x16x32_bf16 v[108:111], v[156:159], v[208:211], v[108:111]
	v_mfma_f32_16x16x32_bf16 v[92:95], v[152:155], v[212:215], v[92:95]
	v_mfma_f32_16x16x32_bf16 v[92:95], v[156:159], v[216:219], v[92:95]
	v_mfma_f32_16x16x32_bf16 v[76:79], v[152:155], v[220:223], v[76:79]
	v_mfma_f32_16x16x32_bf16 v[76:79], v[156:159], v[224:227], v[76:79]
	s_setprio 0
	s_setprio 1
	v_mfma_f32_16x16x32_bf16 v[128:131], v[160:163], v[184:187], v[128:131]
	v_mfma_f32_16x16x32_bf16 v[128:131], v[164:167], v[188:191], v[128:131]
	v_mfma_f32_16x16x32_bf16 v[104:107], v[160:163], v[204:207], v[104:107]
	v_mfma_f32_16x16x32_bf16 v[104:107], v[164:167], v[208:211], v[104:107]
	v_mfma_f32_16x16x32_bf16 v[88:91], v[160:163], v[212:215], v[88:91]
	v_mfma_f32_16x16x32_bf16 v[88:91], v[164:167], v[216:219], v[88:91]
	v_mfma_f32_16x16x32_bf16 v[72:75], v[160:163], v[220:223], v[72:75]
	v_mfma_f32_16x16x32_bf16 v[72:75], v[164:167], v[224:227], v[72:75]
	v_mfma_f32_16x16x32_bf16 v[124:127], v[176:179], v[184:187], v[124:127]
	v_mfma_f32_16x16x32_bf16 v[124:127], v[180:183], v[188:191], v[124:127]
	v_mfma_f32_16x16x32_bf16 v[100:103], v[176:179], v[204:207], v[100:103]
	v_mfma_f32_16x16x32_bf16 v[100:103], v[180:183], v[208:211], v[100:103]
	v_mfma_f32_16x16x32_bf16 v[84:87], v[176:179], v[212:215], v[84:87]
	v_mfma_f32_16x16x32_bf16 v[84:87], v[180:183], v[216:219], v[84:87]
	v_mfma_f32_16x16x32_bf16 v[68:71], v[176:179], v[220:223], v[68:71]
	v_mfma_f32_16x16x32_bf16 v[68:71], v[180:183], v[224:227], v[68:71]
	s_setprio 0
	s_barrier
; #define PG8_STAGE(bufoff, gbase, voff) do { _Pragma("unroll") for (int _i = 0; _i < 2; ++_i) \
;         __builtin_amdgcn_global_load_lds((const unsigned*)((const char*)(gbase) + (voff)[_i]), (PG8_LAS unsigned*)(lds + (bufoff) + ldsw + _i * 8192), 16, 0, 0); } while (0)
; #define PG8_LDA(dst, b, h) do { _Pragma("unroll") for (int m = 0; m < 4; ++m) _Pragma("unroll") for (int k = 0; k < 2; ++k) dst[m][k] = *(const PG8_LAS bf16x8*)(lds + PG8_SA(b, h) + aoff + m * 2048 + k * 1024); } while (0)
; #define PG8_WAIT_V(n) asm volatile("s_waitcnt vmcnt(" #n ")" ::: "memory")
; #define PG8_WAIT_L(n) asm volatile("s_waitcnt lgkmcnt(" #n ")" ::: "memory")
; #define PG8_BAR __builtin_amdgcn_s_barrier()
; #define PG8_SCHED __builtin_amdgcn_sched_barrier(0)
; template <class Epi, class Sched, bool ALIGN_EPI = false, bool SP2 = false, bool I8 = false>
; __device__ __forceinline__ void gemm_phase(PG8_LAS unsigned char* lds, const Gemm g, const Sched& S, const Epi& E) {
;     ...
;         for (int t = 0; t < nt; t += 2) {
;     ...
;             PG8_LDA(At, 1, 1); PG8_STAGE(PG8_SB(1, 0), b3, voffB); PG8_STAGE(PG8_SB(1, 1), b3 + hstep, voffB); PG8_STAGE(PG8_SA(1, 0), a3, voffA);
;             PG8_WAIT_V(8); PG8_WAIT_L(0); PG8_BAR; PG8_MMA(1, 0, At, B0); PG8_MMA(1, 1, At, B1); PG8_BAR; PG8_SCHED;
	s_add_i32 s50, s56, s46
	v_lshl_add_u64 v[168:169], v[168:169], 0, s[84:85]
	s_mov_b32 m0, s50
	ds_read_b128 v[184:187], v173 offset:49152
	ds_read_b128 v[188:191], v173 offset:50176
	ds_read_b128 v[204:207], v173 offset:51200
	ds_read_b128 v[208:211], v173 offset:52224
	ds_read_b128 v[212:215], v173 offset:53248
	ds_read_b128 v[216:219], v173 offset:54272
	ds_read_b128 v[220:223], v173 offset:55296
	ds_read_b128 v[224:227], v173 offset:56320
	global_load_lds_dwordx4 v[168:169], off
	s_add_i32 m0, s50, 0x2000
	s_add_u32 s50, s72, 0x100080
	v_lshl_add_u64 v[168:169], v[228:229], 0, s[84:85]
	s_addc_u32 s51, s73, 0
	s_add_i32 s56, s57, s46
	global_load_lds_dwordx4 v[168:169], off
	v_lshl_add_u64 v[168:169], s[50:51], 0, v[2:3]
	s_mov_b32 m0, s56
	s_nop 0
	global_load_lds_dwordx4 v[168:169], off
	v_lshl_add_u64 v[168:169], s[50:51], 0, v[144:145]
	s_add_i32 m0, s56, 0x2000
	s_nop 0
	global_load_lds_dwordx4 v[168:169], off
	v_lshl_add_u64 v[168:169], v[240:241], 0, s[84:85]
	s_mov_b32 m0, s28
	s_nop 0
	global_load_lds_dwordx4 v[168:169], off
	v_lshl_add_u64 v[168:169], v[242:243], 0, s[84:85]
	s_mov_b32 m0, s65
	s_nop 0
	global_load_lds_dwordx4 v[168:169], off
	s_waitcnt vmcnt(8)
	s_waitcnt lgkmcnt(0)
	s_barrier
	s_setprio 1
	s_waitcnt lgkmcnt(0)
	v_mfma_f32_16x16x32_bf16 v[64:67], v[112:115], v[184:187], v[64:67]
	v_mfma_f32_16x16x32_bf16 v[64:67], v[120:123], v[188:191], v[64:67]
	v_mfma_f32_16x16x32_bf16 v[48:51], v[112:115], v[204:207], v[48:51]
	v_mfma_f32_16x16x32_bf16 v[48:51], v[120:123], v[208:211], v[48:51]
	v_mfma_f32_16x16x32_bf16 v[32:35], v[112:115], v[212:215], v[32:35]
	v_mfma_f32_16x16x32_bf16 v[32:35], v[120:123], v[216:219], v[32:35]
	v_mfma_f32_16x16x32_bf16 v[16:19], v[112:115], v[220:223], v[16:19]
	v_mfma_f32_16x16x32_bf16 v[16:19], v[120:123], v[224:227], v[16:19]
	v_mfma_f32_16x16x32_bf16 v[60:63], v[152:155], v[184:187], v[60:63]
	v_mfma_f32_16x16x32_bf16 v[60:63], v[156:159], v[188:191], v[60:63]
	v_mfma_f32_16x16x32_bf16 v[44:47], v[152:155], v[204:207], v[44:47]
	v_mfma_f32_16x16x32_bf16 v[44:47], v[156:159], v[208:211], v[44:47]
	v_mfma_f32_16x16x32_bf16 v[28:31], v[152:155], v[212:215], v[28:31]
	v_mfma_f32_16x16x32_bf16 v[28:31], v[156:159], v[216:219], v[28:31]
	v_mfma_f32_16x16x32_bf16 v[12:15], v[152:155], v[220:223], v[12:15]
	v_mfma_f32_16x16x32_bf16 v[12:15], v[156:159], v[224:227], v[12:15]
	s_setprio 0
	s_setprio 1
	v_mfma_f32_16x16x32_bf16 v[56:59], v[160:163], v[184:187], v[56:59]
	v_mfma_f32_16x16x32_bf16 v[56:59], v[164:167], v[188:191], v[56:59]
	v_mfma_f32_16x16x32_bf16 v[40:43], v[160:163], v[204:207], v[40:43]
	v_mfma_f32_16x16x32_bf16 v[40:43], v[164:167], v[208:211], v[40:43]
	v_mfma_f32_16x16x32_bf16 v[24:27], v[160:163], v[212:215], v[24:27]
	v_mfma_f32_16x16x32_bf16 v[24:27], v[164:167], v[216:219], v[24:27]
	v_mfma_f32_16x16x32_bf16 v[8:11], v[160:163], v[220:223], v[8:11]
	v_mfma_f32_16x16x32_bf16 v[8:11], v[164:167], v[224:227], v[8:11]
	v_mfma_f32_16x16x32_bf16 v[52:55], v[176:179], v[184:187], v[52:55]
	v_mfma_f32_16x16x32_bf16 v[52:55], v[180:183], v[188:191], v[52:55]
	v_mfma_f32_16x16x32_bf16 v[36:39], v[176:179], v[204:207], v[36:39]
	v_mfma_f32_16x16x32_bf16 v[36:39], v[180:183], v[208:211], v[36:39]
	v_mfma_f32_16x16x32_bf16 v[20:23], v[176:179], v[212:215], v[20:23]
	v_mfma_f32_16x16x32_bf16 v[20:23], v[180:183], v[216:219], v[20:23]
	v_mfma_f32_16x16x32_bf16 v[4:7], v[176:179], v[220:223], v[4:7]
	v_mfma_f32_16x16x32_bf16 v[4:7], v[180:183], v[224:227], v[4:7]
	s_setprio 0
	s_barrier
	s_add_i32 s97, s97, 2
	s_add_u32 s12, s12, 0x100
	s_addc_u32 s13, s13, 0
	s_add_u32 s37, s37, 0x100
	s_addc_u32 s61, s61, 0
	s_cmp_gt_u32 s97, 61
	s_cbranch_scc0 .LBB0_230

; #define PG8_STAGE(bufoff, gbase, voff) do { _Pragma("unroll") for (int _i = 0; _i < 2; ++_i) \
;         __builtin_amdgcn_global_load_lds((const unsigned*)((const char*)(gbase) + (voff)[_i]), (PG8_LAS unsigned*)(lds + (bufoff) + ldsw + _i * 8192), 16, 0, 0); } while (0)
; #define PG8_LDA(dst, b, h) do { _Pragma("unroll") for (int m = 0; m < 4; ++m) _Pragma("unroll") for (int k = 0; k < 2; ++k) dst[m][k] = *(const PG8_LAS bf16x8*)(lds + PG8_SA(b, h) + aoff + m * 2048 + k * 1024); } while (0)
; #define PG8_LDB(dst, b, h) do { _Pragma("unroll") for (int n = 0; n < 2; ++n) _Pragma("unroll") for (int k = 0; k < 2; ++k) dst[n][k] = *(const PG8_LAS bf16x8*)(lds + PG8_SB(b, h) + boff + n * 2048 + k * 1024); } while (0)
; #define PG8_WAIT_V(n) asm volatile("s_waitcnt vmcnt(" #n ")" ::: "memory")
; #define PG8_WAIT_L(n) asm volatile("s_waitcnt lgkmcnt(" #n ")" ::: "memory")
; #define PG8_BAR __builtin_amdgcn_s_barrier()
; #define PG8_SCHED __builtin_amdgcn_sched_barrier(0)
; template <class Epi, class Sched, bool ALIGN_EPI = false, bool SP2 = false, bool I8 = false>
; __device__ __forceinline__ void gemm_phase(PG8_LAS unsigned char* lds, const Gemm g, const Sched& S, const Epi& E) {
;     ...
;         const bool has_next = S.next(ui + 1, nxt);
;         const char* nA = has_next ? (const char*)g.A + (size_t)nxt.pm * tstep : cA; const char* nB = has_next ? (const char*)g.Bt + (size_t)nxt.pn * tstep : cB;
;         for (int t = 0; t < nt; t += 2) {
;             const bool last = (t == nt - 2);
;             const char* a1 = cA + (size_t)(t + 1) * kstep;
;             const char* a2 = last ? nA : cA + (size_t)(t + 2) * kstep; const char* b2 = last ? nB : cB + (size_t)(t + 2) * kstep;
;             const char* a3 = a2 + kstep; const char* b3 = b2 + kstep;
;             if (last && has_next) S.a_ready(nxt);
;             if constexpr (SP2) {
;             PG8_LDB(B0, 0, 0); PG8_LDB(B1, 0, 1); PG8_SCHED; PG8_LDA(At, 0, 0); PG8_STAGE(PG8_SA(1, 1), a1 + hstep, voffA);
;             PG8_WAIT_V(8); PG8_WAIT_L(0); PG8_BAR; PG8_MMA(0, 0, At, B0); PG8_MMA(0, 1, At, B1); PG8_BAR; PG8_SCHED;
;             PG8_LDA(At, 0, 1); PG8_STAGE(PG8_SB(0, 0), b2, voffB); PG8_STAGE(PG8_SB(0, 1), b2 + hstep, voffB); PG8_STAGE(PG8_SA(0, 0), a2, voffA);
;             PG8_WAIT_V(8); PG8_WAIT_L(0); PG8_BAR; PG8_MMA(1, 0, At, B0); PG8_MMA(1, 1, At, B1); PG8_BAR; PG8_SCHED;
.LBB0_1455:
	s_ashr_i32 s17, s16, 31
	s_lshl_b64 s[20:21], s[16:17], 21
	s_add_u32 s20, s28, s20
	s_addc_u32 s21, s34, s21
	s_and_b64 s[22:23], s[8:9], exec
	s_cselect_b32 s17, s21, s25
	s_cselect_b32 s51, s20, s24
	s_ashr_i32 s19, s18, 31
	s_lshl_b64 s[22:23], s[18:19], 21
	s_add_u32 s22, s35, s22
	s_addc_u32 s23, s39, s23
	s_and_b64 s[36:37], s[8:9], exec
	s_cselect_b32 s19, s23, s27
	s_cselect_b32 s52, s22, s26
	s_add_u32 s24, s24, 0x100080
	s_addc_u32 s25, s25, 0
	s_add_u32 s53, s26, 0x100
	s_addc_u32 s54, s27, 0
	s_mov_b32 s55, -2
	s_waitcnt vmcnt(0)
	s_add_u32 s26, s24, 0xfff00080
	s_addc_u32 s27, s25, -1
	s_add_i32 s56, 0, 0x10000
	s_cmp_eq_u32 s55, 60
	s_cselect_b32 s37, s17, s27
	s_cselect_b32 s36, s51, s26
	s_cselect_b32 s27, s19, s54
	s_cselect_b32 s26, s52, s53
	s_add_i32 s58, 0, 0x14000
	v_add_u32_e32 v144, s56, v240
	v_add_u32_e32 v160, s58, v240
	ds_read_b128 v[124:127], v144
	ds_read_b128 v[128:131], v144 offset:1024
	ds_read_b128 v[132:135], v144 offset:2048
	ds_read_b128 v[144:147], v144 offset:3072
	ds_read_b128 v[148:151], v160
	ds_read_b128 v[152:155], v160 offset:1024
	ds_read_b128 v[156:159], v160 offset:2048
	ds_read_b128 v[160:163], v160 offset:3072
	v_lshl_add_u64 v[218:219], s[24:25], 0, v[210:211]
	s_add_i32 m0, s41, 0xc000
	ds_read_b128 v[164:167], v242
	ds_read_b128 v[168:171], v242 offset:1024
	ds_read_b128 v[172:175], v242 offset:2048
	ds_read_b128 v[176:179], v242 offset:3072
	ds_read_b128 v[180:183], v242 offset:4096
	ds_read_b128 v[184:187], v242 offset:5120
	ds_read_b128 v[188:191], v242 offset:6144
	ds_read_b128 v[214:217], v242 offset:7168
	global_load_lds_dwordx4 v[218:219], off
	v_lshl_add_u64 v[218:219], s[24:25], 0, v[212:213]
	s_add_i32 m0, s41, 0xe000
	s_nop 0
	global_load_lds_dwordx4 v[218:219], off
	s_waitcnt vmcnt(8)
	s_waitcnt lgkmcnt(0)
	s_barrier
	s_setprio 1
	s_waitcnt lgkmcnt(0)
	v_mfma_f32_16x16x32_bf16 v[140:143], v[124:127], v[164:167], 0
	v_mfma_f32_16x16x32_bf16 v[140:143], v[128:131], v[168:171], v[140:143]
	v_mfma_f32_16x16x32_bf16 v[112:115], v[124:127], v[172:175], 0
	v_mfma_f32_16x16x32_bf16 v[112:115], v[128:131], v[176:179], v[112:115]
	v_mfma_f32_16x16x32_bf16 v[96:99], v[124:127], v[180:183], 0
	v_mfma_f32_16x16x32_bf16 v[96:99], v[128:131], v[184:187], v[96:99]
	v_mfma_f32_16x16x32_bf16 v[80:83], v[124:127], v[188:191], 0
	v_mfma_f32_16x16x32_bf16 v[80:83], v[128:131], v[214:217], v[80:83]
	v_mfma_f32_16x16x32_bf16 v[136:139], v[132:135], v[164:167], 0
	v_mfma_f32_16x16x32_bf16 v[136:139], v[144:147], v[168:171], v[136:139]
	v_mfma_f32_16x16x32_bf16 v[108:111], v[132:135], v[172:175], 0
	v_mfma_f32_16x16x32_bf16 v[108:111], v[144:147], v[176:179], v[108:111]
	v_mfma_f32_16x16x32_bf16 v[92:95], v[132:135], v[180:183], 0
	v_mfma_f32_16x16x32_bf16 v[92:95], v[144:147], v[184:187], v[92:95]
	v_mfma_f32_16x16x32_bf16 v[76:79], v[132:135], v[188:191], 0
	v_mfma_f32_16x16x32_bf16 v[76:79], v[144:147], v[214:217], v[76:79]
	s_setprio 0
	s_setprio 1
	v_mfma_f32_16x16x32_bf16 v[120:123], v[148:151], v[164:167], 0
	v_mfma_f32_16x16x32_bf16 v[120:123], v[152:155], v[168:171], v[120:123]
	v_mfma_f32_16x16x32_bf16 v[104:107], v[148:151], v[172:175], 0
	v_mfma_f32_16x16x32_bf16 v[104:107], v[152:155], v[176:179], v[104:107]
	v_mfma_f32_16x16x32_bf16 v[88:91], v[148:151], v[180:183], 0
	v_mfma_f32_16x16x32_bf16 v[88:91], v[152:155], v[184:187], v[88:91]
	v_mfma_f32_16x16x32_bf16 v[72:75], v[148:151], v[188:191], 0
	v_mfma_f32_16x16x32_bf16 v[72:75], v[152:155], v[214:217], v[72:75]
	v_mfma_f32_16x16x32_bf16 v[116:119], v[156:159], v[164:167], 0
	v_mfma_f32_16x16x32_bf16 v[116:119], v[160:163], v[168:171], v[116:119]
	v_mfma_f32_16x16x32_bf16 v[100:103], v[156:159], v[172:175], 0
	v_mfma_f32_16x16x32_bf16 v[100:103], v[160:163], v[176:179], v[100:103]
	v_mfma_f32_16x16x32_bf16 v[84:87], v[156:159], v[180:183], 0
	v_mfma_f32_16x16x32_bf16 v[84:87], v[160:163], v[184:187], v[84:87]
	v_mfma_f32_16x16x32_bf16 v[68:71], v[156:159], v[188:191], 0
	v_mfma_f32_16x16x32_bf16 v[68:71], v[160:163], v[214:217], v[68:71]
	s_setprio 0
	s_barrier
	s_add_i32 s56, s56, s40
	v_lshl_add_u64 v[218:219], s[26:27], 0, v[2:3]
	s_mov_b32 m0, s56
	ds_read_b128 v[164:167], v242 offset:16384
	ds_read_b128 v[168:171], v242 offset:17408
	ds_read_b128 v[172:175], v242 offset:18432
	ds_read_b128 v[176:179], v242 offset:19456
	ds_read_b128 v[180:183], v242 offset:20480
	ds_read_b128 v[184:187], v242 offset:21504
	ds_read_b128 v[188:191], v242 offset:22528
	ds_read_b128 v[214:217], v242 offset:23552
	global_load_lds_dwordx4 v[218:219], off
	s_add_i32 m0, s56, 0x2000
	s_add_u32 s56, s26, 0x100000
	v_lshl_add_u64 v[220:221], s[26:27], 0, v[204:205]
	s_addc_u32 s57, s27, 0
	s_add_i32 s58, s58, s40
	global_load_lds_dwordx4 v[220:221], off
	v_lshl_add_u64 v[222:223], s[56:57], 0, v[2:3]
	s_mov_b32 m0, s58
	v_lshl_add_u64 v[224:225], s[36:37], 0, v[206:207]
	global_load_lds_dwordx4 v[222:223], off
	v_lshl_add_u64 v[222:223], s[56:57], 0, v[204:205]
	s_add_i32 m0, s58, 0x2000
	s_nop 0
	global_load_lds_dwordx4 v[222:223], off
	v_lshl_add_u64 v[222:223], s[36:37], 0, v[208:209]
	s_mov_b32 m0, s41
	s_nop 0
	global_load_lds_dwordx4 v[222:223], off
	s_mov_b32 m0, s42
	s_nop 0
	global_load_lds_dwordx4 v[224:225], off
	s_waitcnt vmcnt(8)
	s_waitcnt lgkmcnt(0)
	s_barrier
; #define PG8_STAGE(bufoff, gbase, voff) do { _Pragma("unroll") for (int _i = 0; _i < 2; ++_i) \
;         __builtin_amdgcn_global_load_lds((const unsigned*)((const char*)(gbase) + (voff)[_i]), (PG8_LAS unsigned*)(lds + (bufoff) + ldsw + _i * 8192), 16, 0, 0); } while (0)
; #define PG8_LDA(dst, b, h) do { _Pragma("unroll") for (int m = 0; m < 4; ++m) _Pragma("unroll") for (int k = 0; k < 2; ++k) dst[m][k] = *(const PG8_LAS bf16x8*)(lds + PG8_SA(b, h) + aoff + m * 2048 + k * 1024); } while (0)
; #define PG8_LDB(dst, b, h) do { _Pragma("unroll") for (int n = 0; n < 2; ++n) _Pragma("unroll") for (int k = 0; k < 2; ++k) dst[n][k] = *(const PG8_LAS bf16x8*)(lds + PG8_SB(b, h) + boff + n * 2048 + k * 1024); } while (0)
; #define PG8_WAIT_V(n) asm volatile("s_waitcnt vmcnt(" #n ")" ::: "memory")
; #define PG8_WAIT_L(n) asm volatile("s_waitcnt lgkmcnt(" #n ")" ::: "memory")
; #define PG8_BAR __builtin_amdgcn_s_barrier()
; #define PG8_SCHED __builtin_amdgcn_sched_barrier(0)
; template <class Epi, class Sched, bool ALIGN_EPI = false, bool SP2 = false, bool I8 = false>
; __device__ __forceinline__ void gemm_phase(PG8_LAS unsigned char* lds, const Gemm g, const Sched& S, const Epi& E) {
;     ...
;             PG8_WAIT_V(8); PG8_WAIT_L(0); PG8_BAR; PG8_MMA(1, 0, At, B0); PG8_MMA(1, 1, At, B1); PG8_BAR; PG8_SCHED;
;             PG8_LDB(B0, 1, 0); PG8_LDB(B1, 1, 1); PG8_SCHED; PG8_LDA(At, 1, 0); PG8_STAGE(PG8_SA(0, 1), a2 + hstep, voffA);
;             PG8_WAIT_V(8); PG8_WAIT_L(0); PG8_BAR; PG8_MMA(0, 0, At, B0); PG8_MMA(0, 1, At, B1); PG8_BAR; PG8_SCHED;
;             PG8_LDA(At, 1, 1); PG8_STAGE(PG8_SB(1, 0), b3, voffB); PG8_STAGE(PG8_SB(1, 1), b3 + hstep, voffB); PG8_STAGE(PG8_SA(1, 0), a3, voffA);
	s_setprio 1
	s_waitcnt lgkmcnt(0)
	v_mfma_f32_16x16x32_bf16 v[64:67], v[124:127], v[164:167], 0
	v_mfma_f32_16x16x32_bf16 v[64:67], v[128:131], v[168:171], v[64:67]
	v_mfma_f32_16x16x32_bf16 v[48:51], v[124:127], v[172:175], 0
	v_mfma_f32_16x16x32_bf16 v[48:51], v[128:131], v[176:179], v[48:51]
	v_mfma_f32_16x16x32_bf16 v[32:35], v[124:127], v[180:183], 0
	v_mfma_f32_16x16x32_bf16 v[32:35], v[128:131], v[184:187], v[32:35]
	v_mfma_f32_16x16x32_bf16 v[16:19], v[124:127], v[188:191], 0
	v_mfma_f32_16x16x32_bf16 v[16:19], v[128:131], v[214:217], v[16:19]
	v_mfma_f32_16x16x32_bf16 v[60:63], v[132:135], v[164:167], 0
	v_mfma_f32_16x16x32_bf16 v[60:63], v[144:147], v[168:171], v[60:63]
	v_mfma_f32_16x16x32_bf16 v[44:47], v[132:135], v[172:175], 0
	v_mfma_f32_16x16x32_bf16 v[44:47], v[144:147], v[176:179], v[44:47]
	v_mfma_f32_16x16x32_bf16 v[28:31], v[132:135], v[180:183], 0
	v_mfma_f32_16x16x32_bf16 v[28:31], v[144:147], v[184:187], v[28:31]
	v_mfma_f32_16x16x32_bf16 v[12:15], v[132:135], v[188:191], 0
	v_mfma_f32_16x16x32_bf16 v[12:15], v[144:147], v[214:217], v[12:15]
	s_setprio 0
	s_setprio 1
	v_mfma_f32_16x16x32_bf16 v[56:59], v[148:151], v[164:167], 0
	v_mfma_f32_16x16x32_bf16 v[56:59], v[152:155], v[168:171], v[56:59]
	v_mfma_f32_16x16x32_bf16 v[40:43], v[148:151], v[172:175], 0
	v_mfma_f32_16x16x32_bf16 v[40:43], v[152:155], v[176:179], v[40:43]
	v_mfma_f32_16x16x32_bf16 v[24:27], v[148:151], v[180:183], 0
	v_mfma_f32_16x16x32_bf16 v[24:27], v[152:155], v[184:187], v[24:27]
	v_mfma_f32_16x16x32_bf16 v[8:11], v[148:151], v[188:191], 0
	v_mfma_f32_16x16x32_bf16 v[8:11], v[152:155], v[214:217], v[8:11]
	v_mfma_f32_16x16x32_bf16 v[52:55], v[156:159], v[164:167], 0
	v_mfma_f32_16x16x32_bf16 v[52:55], v[160:163], v[168:171], v[52:55]
	v_mfma_f32_16x16x32_bf16 v[36:39], v[156:159], v[172:175], 0
	v_mfma_f32_16x16x32_bf16 v[36:39], v[160:163], v[176:179], v[36:39]
	v_mfma_f32_16x16x32_bf16 v[20:23], v[156:159], v[180:183], 0
	v_mfma_f32_16x16x32_bf16 v[20:23], v[160:163], v[184:187], v[20:23]
	v_mfma_f32_16x16x32_bf16 v[4:7], v[156:159], v[188:191], 0
	v_mfma_f32_16x16x32_bf16 v[4:7], v[160:163], v[214:217], v[4:7]
	s_setprio 0
	s_barrier
	s_add_i32 s56, 0, 0x18000
	s_add_i32 s57, 0, 0x1c000
	v_add_u32_e32 v144, s56, v240
	v_add_u32_e32 v160, s57, v240
	ds_read_b128 v[124:127], v144
	ds_read_b128 v[128:131], v144 offset:1024
	ds_read_b128 v[132:135], v144 offset:2048
	ds_read_b128 v[144:147], v144 offset:3072
	ds_read_b128 v[148:151], v160
	ds_read_b128 v[152:155], v160 offset:1024
	ds_read_b128 v[156:159], v160 offset:2048
	ds_read_b128 v[160:163], v160 offset:3072
	s_add_u32 s36, s36, 0x100000
	s_addc_u32 s37, s37, 0
	s_mov_b32 m0, s43
	v_lshl_add_u64 v[226:227], s[36:37], 0, v[208:209]
	ds_read_b128 v[164:167], v242 offset:32768
	ds_read_b128 v[168:171], v242 offset:33792
	ds_read_b128 v[172:175], v242 offset:34816
	ds_read_b128 v[176:179], v242 offset:35840
	ds_read_b128 v[180:183], v242 offset:36864
	ds_read_b128 v[184:187], v242 offset:37888
	ds_read_b128 v[188:191], v242 offset:38912
	ds_read_b128 v[214:217], v242 offset:39936
	global_load_lds_dwordx4 v[226:227], off
	v_lshl_add_u64 v[226:227], s[36:37], 0, v[206:207]
	s_mov_b32 m0, s44
	s_nop 0
	global_load_lds_dwordx4 v[226:227], off
	s_waitcnt vmcnt(8)
	s_waitcnt lgkmcnt(0)
	s_barrier
	s_setprio 1
	s_waitcnt lgkmcnt(0)
	v_mfma_f32_16x16x32_bf16 v[140:143], v[124:127], v[164:167], v[140:143]
	v_mfma_f32_16x16x32_bf16 v[140:143], v[128:131], v[168:171], v[140:143]
	v_mfma_f32_16x16x32_bf16 v[112:115], v[124:127], v[172:175], v[112:115]
	v_mfma_f32_16x16x32_bf16 v[112:115], v[128:131], v[176:179], v[112:115]
	v_mfma_f32_16x16x32_bf16 v[96:99], v[124:127], v[180:183], v[96:99]
	v_mfma_f32_16x16x32_bf16 v[96:99], v[128:131], v[184:187], v[96:99]
	v_mfma_f32_16x16x32_bf16 v[80:83], v[124:127], v[188:191], v[80:83]
	v_mfma_f32_16x16x32_bf16 v[80:83], v[128:131], v[214:217], v[80:83]
	v_mfma_f32_16x16x32_bf16 v[136:139], v[132:135], v[164:167], v[136:139]
	v_mfma_f32_16x16x32_bf16 v[136:139], v[144:147], v[168:171], v[136:139]
	v_mfma_f32_16x16x32_bf16 v[108:111], v[132:135], v[172:175], v[108:111]
	v_mfma_f32_16x16x32_bf16 v[108:111], v[144:147], v[176:179], v[108:111]
	v_mfma_f32_16x16x32_bf16 v[92:95], v[132:135], v[180:183], v[92:95]
	v_mfma_f32_16x16x32_bf16 v[92:95], v[144:147], v[184:187], v[92:95]
	v_mfma_f32_16x16x32_bf16 v[76:79], v[132:135], v[188:191], v[76:79]
	v_mfma_f32_16x16x32_bf16 v[76:79], v[144:147], v[214:217], v[76:79]
	s_setprio 0
	s_setprio 1
	v_mfma_f32_16x16x32_bf16 v[120:123], v[148:151], v[164:167], v[120:123]
	v_mfma_f32_16x16x32_bf16 v[120:123], v[152:155], v[168:171], v[120:123]
	v_mfma_f32_16x16x32_bf16 v[104:107], v[148:151], v[172:175], v[104:107]
	v_mfma_f32_16x16x32_bf16 v[104:107], v[152:155], v[176:179], v[104:107]
	v_mfma_f32_16x16x32_bf16 v[88:91], v[148:151], v[180:183], v[88:91]
	v_mfma_f32_16x16x32_bf16 v[88:91], v[152:155], v[184:187], v[88:91]
	v_mfma_f32_16x16x32_bf16 v[72:75], v[148:151], v[188:191], v[72:75]
	v_mfma_f32_16x16x32_bf16 v[72:75], v[152:155], v[214:217], v[72:75]
	v_mfma_f32_16x16x32_bf16 v[116:119], v[156:159], v[164:167], v[116:119]
	v_mfma_f32_16x16x32_bf16 v[116:119], v[160:163], v[168:171], v[116:119]
	v_mfma_f32_16x16x32_bf16 v[100:103], v[156:159], v[172:175], v[100:103]
	v_mfma_f32_16x16x32_bf16 v[100:103], v[160:163], v[176:179], v[100:103]
	v_mfma_f32_16x16x32_bf16 v[84:87], v[156:159], v[180:183], v[84:87]
	v_mfma_f32_16x16x32_bf16 v[84:87], v[160:163], v[184:187], v[84:87]
	v_mfma_f32_16x16x32_bf16 v[68:71], v[156:159], v[188:191], v[68:71]
	v_mfma_f32_16x16x32_bf16 v[68:71], v[160:163], v[214:217], v[68:71]
	s_setprio 0
	s_barrier
; #define PG8_STAGE(bufoff, gbase, voff) do { _Pragma("unroll") for (int _i = 0; _i < 2; ++_i) \
;         __builtin_amdgcn_global_load_lds((const unsigned*)((const char*)(gbase) + (voff)[_i]), (PG8_LAS unsigned*)(lds + (bufoff) + ldsw + _i * 8192), 16, 0, 0); } while (0)
; #define PG8_LDA(dst, b, h) do { _Pragma("unroll") for (int m = 0; m < 4; ++m) _Pragma("unroll") for (int k = 0; k < 2; ++k) dst[m][k] = *(const PG8_LAS bf16x8*)(lds + PG8_SA(b, h) + aoff + m * 2048 + k * 1024); } while (0)
; #define PG8_LDB(dst, b, h) do { _Pragma("unroll") for (int n = 0; n < 2; ++n) _Pragma("unroll") for (int k = 0; k < 2; ++k) dst[n][k] = *(const PG8_LAS bf16x8*)(lds + PG8_SB(b, h) + boff + n * 2048 + k * 1024); } while (0)
; #define PG8_WAIT_V(n) asm volatile("s_waitcnt vmcnt(" #n ")" ::: "memory")
; #define PG8_WAIT_L(n) asm volatile("s_waitcnt lgkmcnt(" #n ")" ::: "memory")
; #define PG8_BAR __builtin_amdgcn_s_barrier()
; #define PG8_SCHED __builtin_amdgcn_sched_barrier(0)
; template <class Epi, class Sched, bool ALIGN_EPI = false, bool SP2 = false, bool I8 = false>
; __device__ __forceinline__ void gemm_phase(PG8_LAS unsigned char* lds, const Gemm g, const Sched& S, const Epi& E) {
;     ...
;         for (int t = 0; t < nt; t += 2) {
;             const bool last = (t == nt - 2);
;             const char* a1 = cA + (size_t)(t + 1) * kstep;
;             const char* a2 = last ? nA : cA + (size_t)(t + 2) * kstep; const char* b2 = last ? nB : cB + (size_t)(t + 2) * kstep;
;             const char* a3 = a2 + kstep; const char* b3 = b2 + kstep;
;             if (last && has_next) S.a_ready(nxt);
;             if constexpr (SP2) {
;             PG8_LDB(B0, 0, 0); PG8_LDB(B1, 0, 1); PG8_SCHED; PG8_LDA(At, 0, 0); PG8_STAGE(PG8_SA(1, 1), a1 + hstep, voffA);
;     ...
;             PG8_WAIT_V(8); PG8_WAIT_L(0); PG8_BAR; PG8_MMA(0, 0, At, B0); PG8_MMA(0, 1, At, B1); PG8_BAR; PG8_SCHED;
;             PG8_LDA(At, 1, 1); PG8_STAGE(PG8_SB(1, 0), b3, voffB); PG8_STAGE(PG8_SB(1, 1), b3 + hstep, voffB); PG8_STAGE(PG8_SA(1, 0), a3, voffA);
;             PG8_WAIT_V(8); PG8_WAIT_L(0); PG8_BAR; PG8_MMA(1, 0, At, B0); PG8_MMA(1, 1, At, B1); PG8_BAR; PG8_SCHED;
	s_add_i32 s36, s56, s40
	v_lshl_add_u64 v[218:219], v[218:219], 0, s[84:85]
	s_mov_b32 m0, s36
	ds_read_b128 v[164:167], v242 offset:49152
	ds_read_b128 v[168:171], v242 offset:50176
	ds_read_b128 v[172:175], v242 offset:51200
	ds_read_b128 v[176:179], v242 offset:52224
	ds_read_b128 v[180:183], v242 offset:53248
	ds_read_b128 v[184:187], v242 offset:54272
	ds_read_b128 v[188:191], v242 offset:55296
	ds_read_b128 v[214:217], v242 offset:56320
	global_load_lds_dwordx4 v[218:219], off
	s_add_i32 m0, s36, 0x2000
	s_add_u32 s26, s26, 0x100080
	v_lshl_add_u64 v[218:219], v[220:221], 0, s[84:85]
	s_addc_u32 s27, s27, 0
	s_add_i32 s36, s57, s40
	global_load_lds_dwordx4 v[218:219], off
	v_lshl_add_u64 v[218:219], s[26:27], 0, v[2:3]
	s_mov_b32 m0, s36
	s_nop 0
	global_load_lds_dwordx4 v[218:219], off
	v_lshl_add_u64 v[218:219], s[26:27], 0, v[204:205]
	s_add_i32 m0, s36, 0x2000
	s_nop 0
	global_load_lds_dwordx4 v[218:219], off
	v_lshl_add_u64 v[218:219], v[222:223], 0, s[84:85]
	s_mov_b32 m0, s45
	s_nop 0
	global_load_lds_dwordx4 v[218:219], off
	v_lshl_add_u64 v[218:219], v[224:225], 0, s[84:85]
	s_mov_b32 m0, s46
	s_nop 0
	global_load_lds_dwordx4 v[218:219], off
	s_waitcnt vmcnt(8)
	s_waitcnt lgkmcnt(0)
	s_barrier
	s_setprio 1
	s_waitcnt lgkmcnt(0)
	v_mfma_f32_16x16x32_bf16 v[64:67], v[124:127], v[164:167], v[64:67]
	v_mfma_f32_16x16x32_bf16 v[64:67], v[128:131], v[168:171], v[64:67]
	v_mfma_f32_16x16x32_bf16 v[48:51], v[124:127], v[172:175], v[48:51]
	v_mfma_f32_16x16x32_bf16 v[48:51], v[128:131], v[176:179], v[48:51]
	v_mfma_f32_16x16x32_bf16 v[32:35], v[124:127], v[180:183], v[32:35]
	v_mfma_f32_16x16x32_bf16 v[32:35], v[128:131], v[184:187], v[32:35]
	v_mfma_f32_16x16x32_bf16 v[16:19], v[124:127], v[188:191], v[16:19]
	v_mfma_f32_16x16x32_bf16 v[16:19], v[128:131], v[214:217], v[16:19]
	v_mfma_f32_16x16x32_bf16 v[60:63], v[132:135], v[164:167], v[60:63]
	v_mfma_f32_16x16x32_bf16 v[60:63], v[144:147], v[168:171], v[60:63]
	v_mfma_f32_16x16x32_bf16 v[44:47], v[132:135], v[172:175], v[44:47]
	v_mfma_f32_16x16x32_bf16 v[44:47], v[144:147], v[176:179], v[44:47]
	v_mfma_f32_16x16x32_bf16 v[28:31], v[132:135], v[180:183], v[28:31]
	v_mfma_f32_16x16x32_bf16 v[28:31], v[144:147], v[184:187], v[28:31]
	v_mfma_f32_16x16x32_bf16 v[12:15], v[132:135], v[188:191], v[12:15]
	v_mfma_f32_16x16x32_bf16 v[12:15], v[144:147], v[214:217], v[12:15]
	s_setprio 0
	s_setprio 1
	v_mfma_f32_16x16x32_bf16 v[56:59], v[148:151], v[164:167], v[56:59]
	v_mfma_f32_16x16x32_bf16 v[56:59], v[152:155], v[168:171], v[56:59]
	v_mfma_f32_16x16x32_bf16 v[40:43], v[148:151], v[172:175], v[40:43]
	v_mfma_f32_16x16x32_bf16 v[40:43], v[152:155], v[176:179], v[40:43]
	v_mfma_f32_16x16x32_bf16 v[24:27], v[148:151], v[180:183], v[24:27]
	v_mfma_f32_16x16x32_bf16 v[24:27], v[152:155], v[184:187], v[24:27]
	v_mfma_f32_16x16x32_bf16 v[8:11], v[148:151], v[188:191], v[8:11]
	v_mfma_f32_16x16x32_bf16 v[8:11], v[152:155], v[214:217], v[8:11]
	v_mfma_f32_16x16x32_bf16 v[52:55], v[156:159], v[164:167], v[52:55]
	v_mfma_f32_16x16x32_bf16 v[52:55], v[160:163], v[168:171], v[52:55]
	v_mfma_f32_16x16x32_bf16 v[36:39], v[156:159], v[172:175], v[36:39]
	v_mfma_f32_16x16x32_bf16 v[36:39], v[160:163], v[176:179], v[36:39]
	v_mfma_f32_16x16x32_bf16 v[20:23], v[156:159], v[180:183], v[20:23]
	v_mfma_f32_16x16x32_bf16 v[20:23], v[160:163], v[184:187], v[20:23]
	v_mfma_f32_16x16x32_bf16 v[4:7], v[156:159], v[188:191], v[4:7]
	v_mfma_f32_16x16x32_bf16 v[4:7], v[160:163], v[214:217], v[4:7]
	s_setprio 0
	s_barrier
	s_add_i32 s55, s55, 2
	s_add_u32 s24, s24, 0x100
	s_addc_u32 s25, s25, 0
	s_add_u32 s53, s53, 0x100
	s_addc_u32 s54, s54, 0
	s_cmp_gt_u32 s55, 61
	s_cbranch_scc1 .Lkloop_exit_2
.LBB0_1456:
	s_add_u32 s26, s24, 0xfff00080
	s_addc_u32 s27, s25, -1
	s_add_i32 s56, 0, 0x10000
	s_cmp_eq_u32 s55, 60
	s_cselect_b32 s37, s17, s27
	s_cselect_b32 s36, s51, s26
	s_cselect_b32 s27, s19, s54
	s_cselect_b32 s26, s52, s53
	s_add_i32 s58, 0, 0x14000
	v_add_u32_e32 v144, s56, v240
	v_add_u32_e32 v160, s58, v240
	ds_read_b128 v[124:127], v144
	ds_read_b128 v[128:131], v144 offset:1024
	ds_read_b128 v[132:135], v144 offset:2048
	ds_read_b128 v[144:147], v144 offset:3072
	ds_read_b128 v[148:151], v160
	ds_read_b128 v[152:155], v160 offset:1024
	ds_read_b128 v[156:159], v160 offset:2048
	ds_read_b128 v[160:163], v160 offset:3072
	v_lshl_add_u64 v[218:219], s[24:25], 0, v[210:211]
	s_add_i32 m0, s41, 0xc000
	ds_read_b128 v[164:167], v242
	ds_read_b128 v[168:171], v242 offset:1024
	ds_read_b128 v[172:175], v242 offset:2048
	ds_read_b128 v[176:179], v242 offset:3072
	ds_read_b128 v[180:183], v242 offset:4096
	ds_read_b128 v[184:187], v242 offset:5120
	ds_read_b128 v[188:191], v242 offset:6144
	ds_read_b128 v[214:217], v242 offset:7168
	global_load_lds_dwordx4 v[218:219], off
	v_lshl_add_u64 v[218:219], s[24:25], 0, v[212:213]
	s_add_i32 m0, s41, 0xe000
	s_nop 0
	global_load_lds_dwordx4 v[218:219], off
	s_waitcnt vmcnt(8)
	s_waitcnt lgkmcnt(0)
	s_barrier
; #define PG8_STAGE(bufoff, gbase, voff) do { _Pragma("unroll") for (int _i = 0; _i < 2; ++_i) \
;         __builtin_amdgcn_global_load_lds((const unsigned*)((const char*)(gbase) + (voff)[_i]), (PG8_LAS unsigned*)(lds + (bufoff) + ldsw + _i * 8192), 16, 0, 0); } while (0)
; #define PG8_LDA(dst, b, h) do { _Pragma("unroll") for (int m = 0; m < 4; ++m) _Pragma("unroll") for (int k = 0; k < 2; ++k) dst[m][k] = *(const PG8_LAS bf16x8*)(lds + PG8_SA(b, h) + aoff + m * 2048 + k * 1024); } while (0)
; #define PG8_LDB(dst, b, h) do { _Pragma("unroll") for (int n = 0; n < 2; ++n) _Pragma("unroll") for (int k = 0; k < 2; ++k) dst[n][k] = *(const PG8_LAS bf16x8*)(lds + PG8_SB(b, h) + boff + n * 2048 + k * 1024); } while (0)
; #define PG8_WAIT_V(n) asm volatile("s_waitcnt vmcnt(" #n ")" ::: "memory")
; #define PG8_WAIT_L(n) asm volatile("s_waitcnt lgkmcnt(" #n ")" ::: "memory")
; #define PG8_BAR __builtin_amdgcn_s_barrier()
; #define PG8_SCHED __builtin_amdgcn_sched_barrier(0)
; template <class Epi, class Sched, bool ALIGN_EPI = false, bool SP2 = false, bool I8 = false>
; __device__ __forceinline__ void gemm_phase(PG8_LAS unsigned char* lds, const Gemm g, const Sched& S, const Epi& E) {
;     ...
;             PG8_LDB(B0, 0, 0); PG8_LDB(B1, 0, 1); PG8_SCHED; PG8_LDA(At, 0, 0); PG8_STAGE(PG8_SA(1, 1), a1 + hstep, voffA);
;             PG8_WAIT_V(8); PG8_WAIT_L(0); PG8_BAR; PG8_MMA(0, 0, At, B0); PG8_MMA(0, 1, At, B1); PG8_BAR; PG8_SCHED;
;             PG8_LDA(At, 0, 1); PG8_STAGE(PG8_SB(0, 0), b2, voffB); PG8_STAGE(PG8_SB(0, 1), b2 + hstep, voffB); PG8_STAGE(PG8_SA(0, 0), a2, voffA);
;             PG8_WAIT_V(8); PG8_WAIT_L(0); PG8_BAR; PG8_MMA(1, 0, At, B0); PG8_MMA(1, 1, At, B1); PG8_BAR; PG8_SCHED;
	s_setprio 1
	s_waitcnt lgkmcnt(0)
	v_mfma_f32_16x16x32_bf16 v[140:143], v[124:127], v[164:167], v[140:143]
	v_mfma_f32_16x16x32_bf16 v[140:143], v[128:131], v[168:171], v[140:143]
	v_mfma_f32_16x16x32_bf16 v[112:115], v[124:127], v[172:175], v[112:115]
	v_mfma_f32_16x16x32_bf16 v[112:115], v[128:131], v[176:179], v[112:115]
	v_mfma_f32_16x16x32_bf16 v[96:99], v[124:127], v[180:183], v[96:99]
	v_mfma_f32_16x16x32_bf16 v[96:99], v[128:131], v[184:187], v[96:99]
	v_mfma_f32_16x16x32_bf16 v[80:83], v[124:127], v[188:191], v[80:83]
	v_mfma_f32_16x16x32_bf16 v[80:83], v[128:131], v[214:217], v[80:83]
	v_mfma_f32_16x16x32_bf16 v[136:139], v[132:135], v[164:167], v[136:139]
	v_mfma_f32_16x16x32_bf16 v[136:139], v[144:147], v[168:171], v[136:139]
	v_mfma_f32_16x16x32_bf16 v[108:111], v[132:135], v[172:175], v[108:111]
	v_mfma_f32_16x16x32_bf16 v[108:111], v[144:147], v[176:179], v[108:111]
	v_mfma_f32_16x16x32_bf16 v[92:95], v[132:135], v[180:183], v[92:95]
	v_mfma_f32_16x16x32_bf16 v[92:95], v[144:147], v[184:187], v[92:95]
	v_mfma_f32_16x16x32_bf16 v[76:79], v[132:135], v[188:191], v[76:79]
	v_mfma_f32_16x16x32_bf16 v[76:79], v[144:147], v[214:217], v[76:79]
	s_setprio 0
	s_setprio 1
	v_mfma_f32_16x16x32_bf16 v[120:123], v[148:151], v[164:167], v[120:123]
	v_mfma_f32_16x16x32_bf16 v[120:123], v[152:155], v[168:171], v[120:123]
	v_mfma_f32_16x16x32_bf16 v[104:107], v[148:151], v[172:175], v[104:107]
	v_mfma_f32_16x16x32_bf16 v[104:107], v[152:155], v[176:179], v[104:107]
	v_mfma_f32_16x16x32_bf16 v[88:91], v[148:151], v[180:183], v[88:91]
	v_mfma_f32_16x16x32_bf16 v[88:91], v[152:155], v[184:187], v[88:91]
	v_mfma_f32_16x16x32_bf16 v[72:75], v[148:151], v[188:191], v[72:75]
	v_mfma_f32_16x16x32_bf16 v[72:75], v[152:155], v[214:217], v[72:75]
	v_mfma_f32_16x16x32_bf16 v[116:119], v[156:159], v[164:167], v[116:119]
	v_mfma_f32_16x16x32_bf16 v[116:119], v[160:163], v[168:171], v[116:119]
	v_mfma_f32_16x16x32_bf16 v[100:103], v[156:159], v[172:175], v[100:103]
	v_mfma_f32_16x16x32_bf16 v[100:103], v[160:163], v[176:179], v[100:103]
	v_mfma_f32_16x16x32_bf16 v[84:87], v[156:159], v[180:183], v[84:87]
	v_mfma_f32_16x16x32_bf16 v[84:87], v[160:163], v[184:187], v[84:87]
	v_mfma_f32_16x16x32_bf16 v[68:71], v[156:159], v[188:191], v[68:71]
	v_mfma_f32_16x16x32_bf16 v[68:71], v[160:163], v[214:217], v[68:71]
	s_setprio 0
	s_barrier
	s_add_i32 s56, s56, s40
	v_lshl_add_u64 v[218:219], s[26:27], 0, v[2:3]
	s_mov_b32 m0, s56
	ds_read_b128 v[164:167], v242 offset:16384
	ds_read_b128 v[168:171], v242 offset:17408
	ds_read_b128 v[172:175], v242 offset:18432
	ds_read_b128 v[176:179], v242 offset:19456
	ds_read_b128 v[180:183], v242 offset:20480
	ds_read_b128 v[184:187], v242 offset:21504
	ds_read_b128 v[188:191], v242 offset:22528
	ds_read_b128 v[214:217], v242 offset:23552
	global_load_lds_dwordx4 v[218:219], off
	s_add_i32 m0, s56, 0x2000
	s_add_u32 s56, s26, 0x100000
	v_lshl_add_u64 v[220:221], s[26:27], 0, v[204:205]
	s_addc_u32 s57, s27, 0
	s_add_i32 s58, s58, s40
	global_load_lds_dwordx4 v[220:221], off
	v_lshl_add_u64 v[222:223], s[56:57], 0, v[2:3]
	s_mov_b32 m0, s58
	v_lshl_add_u64 v[224:225], s[36:37], 0, v[206:207]
	global_load_lds_dwordx4 v[222:223], off
	v_lshl_add_u64 v[222:223], s[56:57], 0, v[204:205]
	s_add_i32 m0, s58, 0x2000
	s_nop 0
	global_load_lds_dwordx4 v[222:223], off
	v_lshl_add_u64 v[222:223], s[36:37], 0, v[208:209]
	s_mov_b32 m0, s41
	s_nop 0
	global_load_lds_dwordx4 v[222:223], off
	s_mov_b32 m0, s42
	s_nop 0
	global_load_lds_dwordx4 v[224:225], off
	s_waitcnt vmcnt(8)
	s_waitcnt lgkmcnt(0)
	s_barrier
	s_setprio 1
	s_waitcnt lgkmcnt(0)
	v_mfma_f32_16x16x32_bf16 v[64:67], v[124:127], v[164:167], v[64:67]
	v_mfma_f32_16x16x32_bf16 v[64:67], v[128:131], v[168:171], v[64:67]
	v_mfma_f32_16x16x32_bf16 v[48:51], v[124:127], v[172:175], v[48:51]
	v_mfma_f32_16x16x32_bf16 v[48:51], v[128:131], v[176:179], v[48:51]
	v_mfma_f32_16x16x32_bf16 v[32:35], v[124:127], v[180:183], v[32:35]
	v_mfma_f32_16x16x32_bf16 v[32:35], v[128:131], v[184:187], v[32:35]
	v_mfma_f32_16x16x32_bf16 v[16:19], v[124:127], v[188:191], v[16:19]
	v_mfma_f32_16x16x32_bf16 v[16:19], v[128:131], v[214:217], v[16:19]
	v_mfma_f32_16x16x32_bf16 v[60:63], v[132:135], v[164:167], v[60:63]
	v_mfma_f32_16x16x32_bf16 v[60:63], v[144:147], v[168:171], v[60:63]
	v_mfma_f32_16x16x32_bf16 v[44:47], v[132:135], v[172:175], v[44:47]
	v_mfma_f32_16x16x32_bf16 v[44:47], v[144:147], v[176:179], v[44:47]
	v_mfma_f32_16x16x32_bf16 v[28:31], v[132:135], v[180:183], v[28:31]
	v_mfma_f32_16x16x32_bf16 v[28:31], v[144:147], v[184:187], v[28:31]
	v_mfma_f32_16x16x32_bf16 v[12:15], v[132:135], v[188:191], v[12:15]
	v_mfma_f32_16x16x32_bf16 v[12:15], v[144:147], v[214:217], v[12:15]
	s_setprio 0
	s_setprio 1
	v_mfma_f32_16x16x32_bf16 v[56:59], v[148:151], v[164:167], v[56:59]
	v_mfma_f32_16x16x32_bf16 v[56:59], v[152:155], v[168:171], v[56:59]
	v_mfma_f32_16x16x32_bf16 v[40:43], v[148:151], v[172:175], v[40:43]
	v_mfma_f32_16x16x32_bf16 v[40:43], v[152:155], v[176:179], v[40:43]
	v_mfma_f32_16x16x32_bf16 v[24:27], v[148:151], v[180:183], v[24:27]
	v_mfma_f32_16x16x32_bf16 v[24:27], v[152:155], v[184:187], v[24:27]
	v_mfma_f32_16x16x32_bf16 v[8:11], v[148:151], v[188:191], v[8:11]
	v_mfma_f32_16x16x32_bf16 v[8:11], v[152:155], v[214:217], v[8:11]
	v_mfma_f32_16x16x32_bf16 v[52:55], v[156:159], v[164:167], v[52:55]
	v_mfma_f32_16x16x32_bf16 v[52:55], v[160:163], v[168:171], v[52:55]
	v_mfma_f32_16x16x32_bf16 v[36:39], v[156:159], v[172:175], v[36:39]
	v_mfma_f32_16x16x32_bf16 v[36:39], v[160:163], v[176:179], v[36:39]
	v_mfma_f32_16x16x32_bf16 v[20:23], v[156:159], v[180:183], v[20:23]
	v_mfma_f32_16x16x32_bf16 v[20:23], v[160:163], v[184:187], v[20:23]
	v_mfma_f32_16x16x32_bf16 v[4:7], v[156:159], v[188:191], v[4:7]
	v_mfma_f32_16x16x32_bf16 v[4:7], v[160:163], v[214:217], v[4:7]
	s_setprio 0
	s_barrier
; #define PG8_STAGE(bufoff, gbase, voff) do { _Pragma("unroll") for (int _i = 0; _i < 2; ++_i) \
;         __builtin_amdgcn_global_load_lds((const unsigned*)((const char*)(gbase) + (voff)[_i]), (PG8_LAS unsigned*)(lds + (bufoff) + ldsw + _i * 8192), 16, 0, 0); } while (0)
; #define PG8_LDA(dst, b, h) do { _Pragma("unroll") for (int m = 0; m < 4; ++m) _Pragma("unroll") for (int k = 0; k < 2; ++k) dst[m][k] = *(const PG8_LAS bf16x8*)(lds + PG8_SA(b, h) + aoff + m * 2048 + k * 1024); } while (0)
; #define PG8_LDB(dst, b, h) do { _Pragma("unroll") for (int n = 0; n < 2; ++n) _Pragma("unroll") for (int k = 0; k < 2; ++k) dst[n][k] = *(const PG8_LAS bf16x8*)(lds + PG8_SB(b, h) + boff + n * 2048 + k * 1024); } while (0)
; #define PG8_WAIT_V(n) asm volatile("s_waitcnt vmcnt(" #n ")" ::: "memory")
; #define PG8_WAIT_L(n) asm volatile("s_waitcnt lgkmcnt(" #n ")" ::: "memory")
; #define PG8_BAR __builtin_amdgcn_s_barrier()
; #define PG8_SCHED __builtin_amdgcn_sched_barrier(0)
; template <class Epi, class Sched, bool ALIGN_EPI = false, bool SP2 = false, bool I8 = false>
; __device__ __forceinline__ void gemm_phase(PG8_LAS unsigned char* lds, const Gemm g, const Sched& S, const Epi& E) {
;     ...
;             PG8_LDB(B0, 1, 0); PG8_LDB(B1, 1, 1); PG8_SCHED; PG8_LDA(At, 1, 0); PG8_STAGE(PG8_SA(0, 1), a2 + hstep, voffA);
;             PG8_WAIT_V(8); PG8_WAIT_L(0); PG8_BAR; PG8_MMA(0, 0, At, B0); PG8_MMA(0, 1, At, B1); PG8_BAR; PG8_SCHED;
	s_add_i32 s56, 0, 0x18000
	s_add_i32 s57, 0, 0x1c000
	v_add_u32_e32 v144, s56, v240
	v_add_u32_e32 v160, s57, v240
	ds_read_b128 v[124:127], v144
	ds_read_b128 v[128:131], v144 offset:1024
	ds_read_b128 v[132:135], v144 offset:2048
	ds_read_b128 v[144:147], v144 offset:3072
	ds_read_b128 v[148:151], v160
	ds_read_b128 v[152:155], v160 offset:1024
	ds_read_b128 v[156:159], v160 offset:2048
	ds_read_b128 v[160:163], v160 offset:3072
	s_add_u32 s36, s36, 0x100000
	s_addc_u32 s37, s37, 0
	s_mov_b32 m0, s43
	v_lshl_add_u64 v[226:227], s[36:37], 0, v[208:209]
	ds_read_b128 v[164:167], v242 offset:32768
	ds_read_b128 v[168:171], v242 offset:33792
	ds_read_b128 v[172:175], v242 offset:34816
	ds_read_b128 v[176:179], v242 offset:35840
	ds_read_b128 v[180:183], v242 offset:36864
	ds_read_b128 v[184:187], v242 offset:37888
	ds_read_b128 v[188:191], v242 offset:38912
	ds_read_b128 v[214:217], v242 offset:39936
	global_load_lds_dwordx4 v[226:227], off
	v_lshl_add_u64 v[226:227], s[36:37], 0, v[206:207]
	s_mov_b32 m0, s44
	s_nop 0
	global_load_lds_dwordx4 v[226:227], off
	s_waitcnt vmcnt(8)
	s_waitcnt lgkmcnt(0)
	s_barrier
	s_setprio 1
	s_waitcnt lgkmcnt(0)
	v_mfma_f32_16x16x32_bf16 v[140:143], v[124:127], v[164:167], v[140:143]
	v_mfma_f32_16x16x32_bf16 v[140:143], v[128:131], v[168:171], v[140:143]
	v_mfma_f32_16x16x32_bf16 v[112:115], v[124:127], v[172:175], v[112:115]
	v_mfma_f32_16x16x32_bf16 v[112:115], v[128:131], v[176:179], v[112:115]
	v_mfma_f32_16x16x32_bf16 v[96:99], v[124:127], v[180:183], v[96:99]
	v_mfma_f32_16x16x32_bf16 v[96:99], v[128:131], v[184:187], v[96:99]
	v_mfma_f32_16x16x32_bf16 v[80:83], v[124:127], v[188:191], v[80:83]
	v_mfma_f32_16x16x32_bf16 v[80:83], v[128:131], v[214:217], v[80:83]
	v_mfma_f32_16x16x32_bf16 v[136:139], v[132:135], v[164:167], v[136:139]
	v_mfma_f32_16x16x32_bf16 v[136:139], v[144:147], v[168:171], v[136:139]
	v_mfma_f32_16x16x32_bf16 v[108:111], v[132:135], v[172:175], v[108:111]
	v_mfma_f32_16x16x32_bf16 v[108:111], v[144:147], v[176:179], v[108:111]
	v_mfma_f32_16x16x32_bf16 v[92:95], v[132:135], v[180:183], v[92:95]
	v_mfma_f32_16x16x32_bf16 v[92:95], v[144:147], v[184:187], v[92:95]
	v_mfma_f32_16x16x32_bf16 v[76:79], v[132:135], v[188:191], v[76:79]
	v_mfma_f32_16x16x32_bf16 v[76:79], v[144:147], v[214:217], v[76:79]
	s_setprio 0
	s_setprio 1
	v_mfma_f32_16x16x32_bf16 v[120:123], v[148:151], v[164:167], v[120:123]
	v_mfma_f32_16x16x32_bf16 v[120:123], v[152:155], v[168:171], v[120:123]
	v_mfma_f32_16x16x32_bf16 v[104:107], v[148:151], v[172:175], v[104:107]
	v_mfma_f32_16x16x32_bf16 v[104:107], v[152:155], v[176:179], v[104:107]
	v_mfma_f32_16x16x32_bf16 v[88:91], v[148:151], v[180:183], v[88:91]
	v_mfma_f32_16x16x32_bf16 v[88:91], v[152:155], v[184:187], v[88:91]
	v_mfma_f32_16x16x32_bf16 v[72:75], v[148:151], v[188:191], v[72:75]
	v_mfma_f32_16x16x32_bf16 v[72:75], v[152:155], v[214:217], v[72:75]
	v_mfma_f32_16x16x32_bf16 v[116:119], v[156:159], v[164:167], v[116:119]
	v_mfma_f32_16x16x32_bf16 v[116:119], v[160:163], v[168:171], v[116:119]
	v_mfma_f32_16x16x32_bf16 v[100:103], v[156:159], v[172:175], v[100:103]
	v_mfma_f32_16x16x32_bf16 v[100:103], v[160:163], v[176:179], v[100:103]
	v_mfma_f32_16x16x32_bf16 v[84:87], v[156:159], v[180:183], v[84:87]
	v_mfma_f32_16x16x32_bf16 v[84:87], v[160:163], v[184:187], v[84:87]
	v_mfma_f32_16x16x32_bf16 v[68:71], v[156:159], v[188:191], v[68:71]
	v_mfma_f32_16x16x32_bf16 v[68:71], v[160:163], v[214:217], v[68:71]
	s_setprio 0
	s_barrier
; #define PG8_STAGE(bufoff, gbase, voff) do { _Pragma("unroll") for (int _i = 0; _i < 2; ++_i) \
;         __builtin_amdgcn_global_load_lds((const unsigned*)((const char*)(gbase) + (voff)[_i]), (PG8_LAS unsigned*)(lds + (bufoff) + ldsw + _i * 8192), 16, 0, 0); } while (0)
; #define PG8_LDA(dst, b, h) do { _Pragma("unroll") for (int m = 0; m < 4; ++m) _Pragma("unroll") for (int k = 0; k < 2; ++k) dst[m][k] = *(const PG8_LAS bf16x8*)(lds + PG8_SA(b, h) + aoff + m * 2048 + k * 1024); } while (0)
; #define PG8_WAIT_V(n) asm volatile("s_waitcnt vmcnt(" #n ")" ::: "memory")
; #define PG8_WAIT_L(n) asm volatile("s_waitcnt lgkmcnt(" #n ")" ::: "memory")
; #define PG8_BAR __builtin_amdgcn_s_barrier()
; #define PG8_SCHED __builtin_amdgcn_sched_barrier(0)
; template <class Epi, class Sched, bool ALIGN_EPI = false, bool SP2 = false, bool I8 = false>
; __device__ __forceinline__ void gemm_phase(PG8_LAS unsigned char* lds, const Gemm g, const Sched& S, const Epi& E) {
;     ...
;         for (int t = 0; t < nt; t += 2) {
;     ...
;             PG8_LDA(At, 1, 1); PG8_STAGE(PG8_SB(1, 0), b3, voffB); PG8_STAGE(PG8_SB(1, 1), b3 + hstep, voffB); PG8_STAGE(PG8_SA(1, 0), a3, voffA);
;             PG8_WAIT_V(8); PG8_WAIT_L(0); PG8_BAR; PG8_MMA(1, 0, At, B0); PG8_MMA(1, 1, At, B1); PG8_BAR; PG8_SCHED;
	s_add_i32 s36, s56, s40
	v_lshl_add_u64 v[218:219], v[218:219], 0, s[84:85]
	s_mov_b32 m0, s36
	ds_read_b128 v[164:167], v242 offset:49152
	ds_read_b128 v[168:171], v242 offset:50176
	ds_read_b128 v[172:175], v242 offset:51200
	ds_read_b128 v[176:179], v242 offset:52224
	ds_read_b128 v[180:183], v242 offset:53248
	ds_read_b128 v[184:187], v242 offset:54272
	ds_read_b128 v[188:191], v242 offset:55296
	ds_read_b128 v[214:217], v242 offset:56320
	global_load_lds_dwordx4 v[218:219], off
	s_add_i32 m0, s36, 0x2000
	s_add_u32 s26, s26, 0x100080
	v_lshl_add_u64 v[218:219], v[220:221], 0, s[84:85]
	s_addc_u32 s27, s27, 0
	s_add_i32 s36, s57, s40
	global_load_lds_dwordx4 v[218:219], off
	v_lshl_add_u64 v[218:219], s[26:27], 0, v[2:3]
	s_mov_b32 m0, s36
	s_nop 0
	global_load_lds_dwordx4 v[218:219], off
	v_lshl_add_u64 v[218:219], s[26:27], 0, v[204:205]
	s_add_i32 m0, s36, 0x2000
	s_nop 0
	global_load_lds_dwordx4 v[218:219], off
	v_lshl_add_u64 v[218:219], v[222:223], 0, s[84:85]
	s_mov_b32 m0, s45
	s_nop 0
	global_load_lds_dwordx4 v[218:219], off
	v_lshl_add_u64 v[218:219], v[224:225], 0, s[84:85]
	s_mov_b32 m0, s46
	s_nop 0
	global_load_lds_dwordx4 v[218:219], off
	s_waitcnt vmcnt(8)
	s_waitcnt lgkmcnt(0)
	s_barrier
	s_setprio 1
	s_waitcnt lgkmcnt(0)
	v_mfma_f32_16x16x32_bf16 v[64:67], v[124:127], v[164:167], v[64:67]
	v_mfma_f32_16x16x32_bf16 v[64:67], v[128:131], v[168:171], v[64:67]
	v_mfma_f32_16x16x32_bf16 v[48:51], v[124:127], v[172:175], v[48:51]
	v_mfma_f32_16x16x32_bf16 v[48:51], v[128:131], v[176:179], v[48:51]
	v_mfma_f32_16x16x32_bf16 v[32:35], v[124:127], v[180:183], v[32:35]
	v_mfma_f32_16x16x32_bf16 v[32:35], v[128:131], v[184:187], v[32:35]
	v_mfma_f32_16x16x32_bf16 v[16:19], v[124:127], v[188:191], v[16:19]
	v_mfma_f32_16x16x32_bf16 v[16:19], v[128:131], v[214:217], v[16:19]
	v_mfma_f32_16x16x32_bf16 v[60:63], v[132:135], v[164:167], v[60:63]
	v_mfma_f32_16x16x32_bf16 v[60:63], v[144:147], v[168:171], v[60:63]
	v_mfma_f32_16x16x32_bf16 v[44:47], v[132:135], v[172:175], v[44:47]
	v_mfma_f32_16x16x32_bf16 v[44:47], v[144:147], v[176:179], v[44:47]
	v_mfma_f32_16x16x32_bf16 v[28:31], v[132:135], v[180:183], v[28:31]
	v_mfma_f32_16x16x32_bf16 v[28:31], v[144:147], v[184:187], v[28:31]
	v_mfma_f32_16x16x32_bf16 v[12:15], v[132:135], v[188:191], v[12:15]
	v_mfma_f32_16x16x32_bf16 v[12:15], v[144:147], v[214:217], v[12:15]
	s_setprio 0
	s_setprio 1
	v_mfma_f32_16x16x32_bf16 v[56:59], v[148:151], v[164:167], v[56:59]
	v_mfma_f32_16x16x32_bf16 v[56:59], v[152:155], v[168:171], v[56:59]
	v_mfma_f32_16x16x32_bf16 v[40:43], v[148:151], v[172:175], v[40:43]
	v_mfma_f32_16x16x32_bf16 v[40:43], v[152:155], v[176:179], v[40:43]
	v_mfma_f32_16x16x32_bf16 v[24:27], v[148:151], v[180:183], v[24:27]
	v_mfma_f32_16x16x32_bf16 v[24:27], v[152:155], v[184:187], v[24:27]
	v_mfma_f32_16x16x32_bf16 v[8:11], v[148:151], v[188:191], v[8:11]
	v_mfma_f32_16x16x32_bf16 v[8:11], v[152:155], v[214:217], v[8:11]
	v_mfma_f32_16x16x32_bf16 v[52:55], v[156:159], v[164:167], v[52:55]
	v_mfma_f32_16x16x32_bf16 v[52:55], v[160:163], v[168:171], v[52:55]
	v_mfma_f32_16x16x32_bf16 v[36:39], v[156:159], v[172:175], v[36:39]
	v_mfma_f32_16x16x32_bf16 v[36:39], v[160:163], v[176:179], v[36:39]
	v_mfma_f32_16x16x32_bf16 v[20:23], v[156:159], v[180:183], v[20:23]
	v_mfma_f32_16x16x32_bf16 v[20:23], v[160:163], v[184:187], v[20:23]
	v_mfma_f32_16x16x32_bf16 v[4:7], v[156:159], v[188:191], v[4:7]
	v_mfma_f32_16x16x32_bf16 v[4:7], v[160:163], v[214:217], v[4:7]
	s_setprio 0
	s_barrier
	s_add_i32 s55, s55, 2
	s_add_u32 s24, s24, 0x100
	s_addc_u32 s25, s25, 0
	s_add_u32 s53, s53, 0x100
	s_addc_u32 s54, s54, 0
	s_cmp_gt_u32 s55, 61
	s_cbranch_scc0 .LBB0_1456

; #define PG8_STAGE(bufoff, gbase, voff) do { _Pragma("unroll") for (int _i = 0; _i < 2; ++_i) \
;         __builtin_amdgcn_global_load_lds((const unsigned*)((const char*)(gbase) + (voff)[_i]), (PG8_LAS unsigned*)(lds + (bufoff) + ldsw + _i * 8192), 16, 0, 0); } while (0)
; #define PG8_LDA(dst, b, h) do { _Pragma("unroll") for (int m = 0; m < 4; ++m) _Pragma("unroll") for (int k = 0; k < 2; ++k) dst[m][k] = *(const PG8_LAS bf16x8*)(lds + PG8_SA(b, h) + aoff + m * 2048 + k * 1024); } while (0)
; #define PG8_LDB(dst, b, h) do { _Pragma("unroll") for (int n = 0; n < 2; ++n) _Pragma("unroll") for (int k = 0; k < 2; ++k) dst[n][k] = *(const PG8_LAS bf16x8*)(lds + PG8_SB(b, h) + boff + n * 2048 + k * 1024); } while (0)
; #define PG8_WAIT_V(n) asm volatile("s_waitcnt vmcnt(" #n ")" ::: "memory")
; #define PG8_WAIT_L(n) asm volatile("s_waitcnt lgkmcnt(" #n ")" ::: "memory")
; #define PG8_BAR __builtin_amdgcn_s_barrier()
; #define PG8_SCHED __builtin_amdgcn_sched_barrier(0)
; template <class Epi, class Sched, bool ALIGN_EPI = false, bool SP2 = false, bool I8 = false>
; __device__ __forceinline__ void gemm_phase(PG8_LAS unsigned char* lds, const Gemm g, const Sched& S, const Epi& E) {
;     ...
;         const bool has_next = S.next(ui + 1, nxt);
;         const char* nA = has_next ? (const char*)g.A + (size_t)nxt.pm * tstep : cA; const char* nB = has_next ? (const char*)g.Bt + (size_t)nxt.pn * tstep : cB;
;         for (int t = 0; t < nt; t += 2) {
;             const bool last = (t == nt - 2);
;             const char* a1 = cA + (size_t)(t + 1) * kstep;
;             const char* a2 = last ? nA : cA + (size_t)(t + 2) * kstep; const char* b2 = last ? nB : cB + (size_t)(t + 2) * kstep;
;             const char* a3 = a2 + kstep; const char* b3 = b2 + kstep;
;             if (last && has_next) S.a_ready(nxt);
;             if constexpr (SP2) {
;             PG8_LDB(B0, 0, 0); PG8_LDB(B1, 0, 1); PG8_SCHED; PG8_LDA(At, 0, 0); PG8_STAGE(PG8_SA(1, 1), a1 + hstep, voffA);
;             PG8_WAIT_V(8); PG8_WAIT_L(0); PG8_BAR; PG8_MMA(0, 0, At, B0); PG8_MMA(0, 1, At, B1); PG8_BAR; PG8_SCHED;
;             PG8_LDA(At, 0, 1); PG8_STAGE(PG8_SB(0, 0), b2, voffB); PG8_STAGE(PG8_SB(0, 1), b2 + hstep, voffB); PG8_STAGE(PG8_SA(0, 0), a2, voffA);
;             PG8_WAIT_V(8); PG8_WAIT_L(0); PG8_BAR; PG8_MMA(1, 0, At, B0); PG8_MMA(1, 1, At, B1); PG8_BAR; PG8_SCHED;
.LBB0_1590:
	s_ashr_i32 s25, s24, 31
	s_lshl_b64 s[26:27], s[24:25], 20
	s_add_u32 s26, s28, s26
	s_addc_u32 s27, s42, s27
	s_and_b64 s[36:37], s[10:11], exec
	s_cselect_b32 s25, s27, s41
	s_cselect_b32 s57, s26, s40
	s_ashr_i32 s23, s22, 31
	s_lshl_b64 s[36:37], s[22:23], 20
	s_add_u32 s36, s43, s36
	s_addc_u32 s37, s46, s37
	s_and_b64 s[48:49], s[10:11], exec
	s_cselect_b32 s23, s37, s45
	s_cselect_b32 s58, s36, s44
	s_add_u32 s40, s40, 0x80080
	s_addc_u32 s41, s41, 0
	s_add_u32 s59, s44, 0x100
	s_addc_u32 s60, s45, 0
	s_mov_b32 s61, -2
	s_add_u32 s44, s40, 0xfff80080
	s_addc_u32 s45, s41, -1
	s_add_i32 s64, 0, 0x10000
	s_cmp_eq_u32 s61, 28
	s_cselect_b32 s49, s25, s45
	s_cselect_b32 s48, s57, s44
	s_cselect_b32 s45, s23, s60
	s_cselect_b32 s44, s58, s59
	s_add_i32 s67, 0, 0x14000
	v_add_u32_e32 v144, s64, v167
	v_add_u32_e32 v158, s67, v167
	ds_read_b128 v[36:39], v144
	ds_read_b128 v[44:47], v144 offset:1024
	ds_read_b128 v[140:143], v144 offset:2048
	ds_read_b128 v[144:147], v144 offset:3072
	ds_read_b128 v[160:163], v158
	ds_read_b128 v[172:175], v158 offset:1024
	ds_read_b128 v[176:179], v158 offset:2048
	ds_read_b128 v[180:183], v158 offset:3072
	v_lshl_add_u64 v[164:165], s[40:41], 0, v[154:155]
	s_add_i32 m0, s50, 0xc000
	ds_read_b128 v[184:187], v171
	ds_read_b128 v[188:191], v171 offset:1024
	ds_read_b128 v[204:207], v171 offset:2048
	ds_read_b128 v[208:211], v171 offset:3072
	ds_read_b128 v[212:215], v171 offset:4096
	ds_read_b128 v[216:219], v171 offset:5120
	ds_read_b128 v[220:223], v171 offset:6144
	ds_read_b128 v[224:227], v171 offset:7168
	global_load_lds_dwordx4 v[164:165], off
	v_lshl_add_u64 v[164:165], s[40:41], 0, v[156:157]
	s_add_i32 m0, s50, 0xe000
	s_nop 0
	global_load_lds_dwordx4 v[164:165], off
	s_waitcnt vmcnt(8)
	s_waitcnt lgkmcnt(0)
	s_barrier
	s_setprio 1
	s_waitcnt lgkmcnt(0)
	v_mfma_i32_16x16x64_i8 v[136:139], v[36:39], v[184:187], 0
	v_mfma_i32_16x16x64_i8 v[136:139], v[44:47], v[188:191], v[136:139]
	v_mfma_i32_16x16x64_i8 v[120:123], v[36:39], v[204:207], 0
	v_mfma_i32_16x16x64_i8 v[120:123], v[44:47], v[208:211], v[120:123]
	v_mfma_i32_16x16x64_i8 v[104:107], v[36:39], v[212:215], 0
	v_mfma_i32_16x16x64_i8 v[104:107], v[44:47], v[216:219], v[104:107]
	v_mfma_i32_16x16x64_i8 v[88:91], v[36:39], v[220:223], 0
	v_mfma_i32_16x16x64_i8 v[88:91], v[44:47], v[224:227], v[88:91]
	v_mfma_i32_16x16x64_i8 v[128:131], v[140:143], v[184:187], 0
	v_mfma_i32_16x16x64_i8 v[128:131], v[144:147], v[188:191], v[128:131]
	v_mfma_i32_16x16x64_i8 v[112:115], v[140:143], v[204:207], 0
	v_mfma_i32_16x16x64_i8 v[112:115], v[144:147], v[208:211], v[112:115]
	v_mfma_i32_16x16x64_i8 v[96:99], v[140:143], v[212:215], 0
	v_mfma_i32_16x16x64_i8 v[96:99], v[144:147], v[216:219], v[96:99]
	v_mfma_i32_16x16x64_i8 v[80:83], v[140:143], v[220:223], 0
	v_mfma_i32_16x16x64_i8 v[80:83], v[144:147], v[224:227], v[80:83]
	s_setprio 0
	s_setprio 1
	v_mfma_i32_16x16x64_i8 v[132:135], v[160:163], v[184:187], 0
	v_mfma_i32_16x16x64_i8 v[132:135], v[172:175], v[188:191], v[132:135]
	v_mfma_i32_16x16x64_i8 v[116:119], v[160:163], v[204:207], 0
	v_mfma_i32_16x16x64_i8 v[116:119], v[172:175], v[208:211], v[116:119]
	v_mfma_i32_16x16x64_i8 v[100:103], v[160:163], v[212:215], 0
	v_mfma_i32_16x16x64_i8 v[100:103], v[172:175], v[216:219], v[100:103]
	v_mfma_i32_16x16x64_i8 v[84:87], v[160:163], v[220:223], 0
	v_mfma_i32_16x16x64_i8 v[84:87], v[172:175], v[224:227], v[84:87]
	v_mfma_i32_16x16x64_i8 v[124:127], v[176:179], v[184:187], 0
	v_mfma_i32_16x16x64_i8 v[124:127], v[180:183], v[188:191], v[124:127]
	v_mfma_i32_16x16x64_i8 v[108:111], v[176:179], v[204:207], 0
	v_mfma_i32_16x16x64_i8 v[108:111], v[180:183], v[208:211], v[108:111]
	v_mfma_i32_16x16x64_i8 v[92:95], v[176:179], v[212:215], 0
	v_mfma_i32_16x16x64_i8 v[92:95], v[180:183], v[216:219], v[92:95]
	v_mfma_i32_16x16x64_i8 v[76:79], v[176:179], v[220:223], 0
	v_mfma_i32_16x16x64_i8 v[76:79], v[180:183], v[224:227], v[76:79]
	s_setprio 0
	s_barrier
	s_add_i32 s64, s64, s47
	v_lshl_add_u64 v[164:165], s[44:45], 0, v[2:3]
	s_mov_b32 m0, s64
	ds_read_b128 v[184:187], v171 offset:16384
	ds_read_b128 v[188:191], v171 offset:17408
	ds_read_b128 v[204:207], v171 offset:18432
	ds_read_b128 v[208:211], v171 offset:19456
	ds_read_b128 v[212:215], v171 offset:20480
	ds_read_b128 v[216:219], v171 offset:21504
	ds_read_b128 v[220:223], v171 offset:22528
	ds_read_b128 v[224:227], v171 offset:23552
	global_load_lds_dwordx4 v[164:165], off
	s_add_i32 m0, s64, 0x2000
	s_add_u32 s64, s44, 0x80000
	v_lshl_add_u64 v[228:229], s[44:45], 0, v[148:149]
	s_addc_u32 s65, s45, 0
	s_add_i32 s67, s67, s47
	global_load_lds_dwordx4 v[228:229], off
	v_lshl_add_u64 v[240:241], s[64:65], 0, v[2:3]
	s_mov_b32 m0, s67
	v_lshl_add_u64 v[242:243], s[48:49], 0, v[150:151]
	global_load_lds_dwordx4 v[240:241], off
	v_lshl_add_u64 v[240:241], s[64:65], 0, v[148:149]
	s_add_i32 m0, s67, 0x2000
	s_nop 0
	global_load_lds_dwordx4 v[240:241], off
	v_lshl_add_u64 v[240:241], s[48:49], 0, v[152:153]
	s_mov_b32 m0, s50
	s_nop 0
	global_load_lds_dwordx4 v[240:241], off
	s_mov_b32 m0, s51
	s_nop 0
	global_load_lds_dwordx4 v[242:243], off
	s_waitcnt vmcnt(8)
	s_waitcnt lgkmcnt(0)
	s_barrier
; #define PG8_STAGE(bufoff, gbase, voff) do { _Pragma("unroll") for (int _i = 0; _i < 2; ++_i) \
;         __builtin_amdgcn_global_load_lds((const unsigned*)((const char*)(gbase) + (voff)[_i]), (PG8_LAS unsigned*)(lds + (bufoff) + ldsw + _i * 8192), 16, 0, 0); } while (0)
; #define PG8_LDA(dst, b, h) do { _Pragma("unroll") for (int m = 0; m < 4; ++m) _Pragma("unroll") for (int k = 0; k < 2; ++k) dst[m][k] = *(const PG8_LAS bf16x8*)(lds + PG8_SA(b, h) + aoff + m * 2048 + k * 1024); } while (0)
; #define PG8_LDB(dst, b, h) do { _Pragma("unroll") for (int n = 0; n < 2; ++n) _Pragma("unroll") for (int k = 0; k < 2; ++k) dst[n][k] = *(const PG8_LAS bf16x8*)(lds + PG8_SB(b, h) + boff + n * 2048 + k * 1024); } while (0)
; #define PG8_WAIT_V(n) asm volatile("s_waitcnt vmcnt(" #n ")" ::: "memory")
; #define PG8_WAIT_L(n) asm volatile("s_waitcnt lgkmcnt(" #n ")" ::: "memory")
; #define PG8_BAR __builtin_amdgcn_s_barrier()
; #define PG8_SCHED __builtin_amdgcn_sched_barrier(0)
; template <class Epi, class Sched, bool ALIGN_EPI = false, bool SP2 = false, bool I8 = false>
; __device__ __forceinline__ void gemm_phase(PG8_LAS unsigned char* lds, const Gemm g, const Sched& S, const Epi& E) {
;     ...
;             if constexpr (SP2) {
;             PG8_LDB(B0, 0, 0); PG8_LDB(B1, 0, 1); PG8_SCHED; PG8_LDA(At, 0, 0); PG8_STAGE(PG8_SA(1, 1), a1 + hstep, voffA);
;             PG8_WAIT_V(8); PG8_WAIT_L(0); PG8_BAR; PG8_MMA(0, 0, At, B0); PG8_MMA(0, 1, At, B1); PG8_BAR; PG8_SCHED;
;             PG8_LDA(At, 0, 1); PG8_STAGE(PG8_SB(0, 0), b2, voffB); PG8_STAGE(PG8_SB(0, 1), b2 + hstep, voffB); PG8_STAGE(PG8_SA(0, 0), a2, voffA);
;             PG8_WAIT_V(8); PG8_WAIT_L(0); PG8_BAR; PG8_MMA(1, 0, At, B0); PG8_MMA(1, 1, At, B1); PG8_BAR; PG8_SCHED;
;             PG8_LDB(B0, 1, 0); PG8_LDB(B1, 1, 1); PG8_SCHED; PG8_LDA(At, 1, 0); PG8_STAGE(PG8_SA(0, 1), a2 + hstep, voffA);
;             PG8_WAIT_V(8); PG8_WAIT_L(0); PG8_BAR; PG8_MMA(0, 0, At, B0); PG8_MMA(0, 1, At, B1); PG8_BAR; PG8_SCHED;
;             PG8_LDA(At, 1, 1); PG8_STAGE(PG8_SB(1, 0), b3, voffB); PG8_STAGE(PG8_SB(1, 1), b3 + hstep, voffB); PG8_STAGE(PG8_SA(1, 0), a3, voffA);
;             PG8_WAIT_V(8); PG8_WAIT_L(0); PG8_BAR; PG8_MMA(1, 0, At, B0); PG8_MMA(1, 1, At, B1); PG8_BAR; PG8_SCHED;
	s_setprio 1
	s_waitcnt lgkmcnt(0)
	v_mfma_i32_16x16x64_i8 v[72:75], v[36:39], v[184:187], 0
	v_mfma_i32_16x16x64_i8 v[72:75], v[44:47], v[188:191], v[72:75]
	v_mfma_i32_16x16x64_i8 v[56:59], v[36:39], v[204:207], 0
	v_mfma_i32_16x16x64_i8 v[56:59], v[44:47], v[208:211], v[56:59]
	v_mfma_i32_16x16x64_i8 v[32:35], v[36:39], v[212:215], 0
	v_mfma_i32_16x16x64_i8 v[32:35], v[44:47], v[216:219], v[32:35]
	v_mfma_i32_16x16x64_i8 v[16:19], v[36:39], v[220:223], 0
	v_mfma_i32_16x16x64_i8 v[16:19], v[44:47], v[224:227], v[16:19]
	v_mfma_i32_16x16x64_i8 v[64:67], v[140:143], v[184:187], 0
	v_mfma_i32_16x16x64_i8 v[64:67], v[144:147], v[188:191], v[64:67]
	v_mfma_i32_16x16x64_i8 v[48:51], v[140:143], v[204:207], 0
	v_mfma_i32_16x16x64_i8 v[48:51], v[144:147], v[208:211], v[48:51]
	v_mfma_i32_16x16x64_i8 v[24:27], v[140:143], v[212:215], 0
	v_mfma_i32_16x16x64_i8 v[24:27], v[144:147], v[216:219], v[24:27]
	v_mfma_i32_16x16x64_i8 v[8:11], v[140:143], v[220:223], 0
	v_mfma_i32_16x16x64_i8 v[8:11], v[144:147], v[224:227], v[8:11]
	s_setprio 0
	s_setprio 1
	v_mfma_i32_16x16x64_i8 v[52:55], v[160:163], v[204:207], 0
	v_mfma_i32_16x16x64_i8 v[52:55], v[172:175], v[208:211], v[52:55]
	v_mfma_i32_16x16x64_i8 v[28:31], v[160:163], v[212:215], 0
	v_mfma_i32_16x16x64_i8 v[28:31], v[172:175], v[216:219], v[28:31]
	v_mfma_i32_16x16x64_i8 v[12:15], v[160:163], v[220:223], 0
	v_mfma_i32_16x16x64_i8 v[12:15], v[172:175], v[224:227], v[12:15]
	v_mfma_i32_16x16x64_i8 v[36:39], v[160:163], v[184:187], 0
	v_mfma_i32_16x16x64_i8 v[36:39], v[172:175], v[188:191], v[36:39]
	v_mfma_i32_16x16x64_i8 v[40:43], v[176:179], v[204:207], 0
	v_mfma_i32_16x16x64_i8 v[40:43], v[180:183], v[208:211], v[40:43]
	v_mfma_i32_16x16x64_i8 v[20:23], v[176:179], v[212:215], 0
	v_mfma_i32_16x16x64_i8 v[20:23], v[180:183], v[216:219], v[20:23]
	v_mfma_i32_16x16x64_i8 v[4:7], v[176:179], v[220:223], 0
	v_mfma_i32_16x16x64_i8 v[4:7], v[180:183], v[224:227], v[4:7]
	v_mfma_i32_16x16x64_i8 v[44:47], v[176:179], v[184:187], 0
	v_mfma_i32_16x16x64_i8 v[44:47], v[180:183], v[188:191], v[44:47]
	s_setprio 0
	s_barrier
	s_add_i32 s64, 0, 0x18000
	s_add_i32 s65, 0, 0x1c000
	v_add_u32_e32 v144, s64, v167
	v_add_u32_e32 v158, s65, v167
	ds_read_b128 v[60:63], v144
	ds_read_b128 v[68:71], v144 offset:1024
	ds_read_b128 v[140:143], v144 offset:2048
	ds_read_b128 v[144:147], v144 offset:3072
	ds_read_b128 v[160:163], v158
	ds_read_b128 v[172:175], v158 offset:1024
	ds_read_b128 v[176:179], v158 offset:2048
	ds_read_b128 v[180:183], v158 offset:3072
	s_add_u32 s48, s48, 0x80000
	s_addc_u32 s49, s49, 0
	s_mov_b32 m0, s52
	v_lshl_add_u64 v[244:245], s[48:49], 0, v[152:153]
	ds_read_b128 v[184:187], v171 offset:32768
	ds_read_b128 v[188:191], v171 offset:33792
	ds_read_b128 v[204:207], v171 offset:34816
	ds_read_b128 v[208:211], v171 offset:35840
	ds_read_b128 v[212:215], v171 offset:36864
	ds_read_b128 v[216:219], v171 offset:37888
	ds_read_b128 v[220:223], v171 offset:38912
	ds_read_b128 v[224:227], v171 offset:39936
	global_load_lds_dwordx4 v[244:245], off
	v_lshl_add_u64 v[244:245], s[48:49], 0, v[150:151]
	s_mov_b32 m0, s53
	s_nop 0
	global_load_lds_dwordx4 v[244:245], off
	s_waitcnt vmcnt(8)
	s_waitcnt lgkmcnt(0)
	s_barrier
	s_setprio 1
	s_waitcnt lgkmcnt(0)
	v_mfma_i32_16x16x64_i8 v[136:139], v[60:63], v[184:187], v[136:139]
	v_mfma_i32_16x16x64_i8 v[136:139], v[68:71], v[188:191], v[136:139]
	v_mfma_i32_16x16x64_i8 v[120:123], v[60:63], v[204:207], v[120:123]
	v_mfma_i32_16x16x64_i8 v[120:123], v[68:71], v[208:211], v[120:123]
	v_mfma_i32_16x16x64_i8 v[104:107], v[60:63], v[212:215], v[104:107]
	v_mfma_i32_16x16x64_i8 v[104:107], v[68:71], v[216:219], v[104:107]
	v_mfma_i32_16x16x64_i8 v[88:91], v[60:63], v[220:223], v[88:91]
	v_mfma_i32_16x16x64_i8 v[88:91], v[68:71], v[224:227], v[88:91]
	v_mfma_i32_16x16x64_i8 v[128:131], v[140:143], v[184:187], v[128:131]
	v_mfma_i32_16x16x64_i8 v[128:131], v[144:147], v[188:191], v[128:131]
	v_mfma_i32_16x16x64_i8 v[112:115], v[140:143], v[204:207], v[112:115]
	v_mfma_i32_16x16x64_i8 v[112:115], v[144:147], v[208:211], v[112:115]
	v_mfma_i32_16x16x64_i8 v[96:99], v[140:143], v[212:215], v[96:99]
	v_mfma_i32_16x16x64_i8 v[96:99], v[144:147], v[216:219], v[96:99]
	v_mfma_i32_16x16x64_i8 v[80:83], v[140:143], v[220:223], v[80:83]
	v_mfma_i32_16x16x64_i8 v[80:83], v[144:147], v[224:227], v[80:83]
	s_setprio 0
	s_setprio 1
	v_mfma_i32_16x16x64_i8 v[132:135], v[160:163], v[184:187], v[132:135]
	v_mfma_i32_16x16x64_i8 v[132:135], v[172:175], v[188:191], v[132:135]
	v_mfma_i32_16x16x64_i8 v[116:119], v[160:163], v[204:207], v[116:119]
	v_mfma_i32_16x16x64_i8 v[116:119], v[172:175], v[208:211], v[116:119]
	v_mfma_i32_16x16x64_i8 v[100:103], v[160:163], v[212:215], v[100:103]
	v_mfma_i32_16x16x64_i8 v[100:103], v[172:175], v[216:219], v[100:103]
	v_mfma_i32_16x16x64_i8 v[84:87], v[160:163], v[220:223], v[84:87]
	v_mfma_i32_16x16x64_i8 v[84:87], v[172:175], v[224:227], v[84:87]
	v_mfma_i32_16x16x64_i8 v[124:127], v[176:179], v[184:187], v[124:127]
	v_mfma_i32_16x16x64_i8 v[124:127], v[180:183], v[188:191], v[124:127]
	v_mfma_i32_16x16x64_i8 v[108:111], v[176:179], v[204:207], v[108:111]
	v_mfma_i32_16x16x64_i8 v[108:111], v[180:183], v[208:211], v[108:111]
	v_mfma_i32_16x16x64_i8 v[92:95], v[176:179], v[212:215], v[92:95]
	v_mfma_i32_16x16x64_i8 v[92:95], v[180:183], v[216:219], v[92:95]
	v_mfma_i32_16x16x64_i8 v[76:79], v[176:179], v[220:223], v[76:79]
	v_mfma_i32_16x16x64_i8 v[76:79], v[180:183], v[224:227], v[76:79]
	s_setprio 0
	s_barrier
; #define PG8_STAGE(bufoff, gbase, voff) do { _Pragma("unroll") for (int _i = 0; _i < 2; ++_i) \
;         __builtin_amdgcn_global_load_lds((const unsigned*)((const char*)(gbase) + (voff)[_i]), (PG8_LAS unsigned*)(lds + (bufoff) + ldsw + _i * 8192), 16, 0, 0); } while (0)
; #define PG8_LDA(dst, b, h) do { _Pragma("unroll") for (int m = 0; m < 4; ++m) _Pragma("unroll") for (int k = 0; k < 2; ++k) dst[m][k] = *(const PG8_LAS bf16x8*)(lds + PG8_SA(b, h) + aoff + m * 2048 + k * 1024); } while (0)
; #define PG8_LDB(dst, b, h) do { _Pragma("unroll") for (int n = 0; n < 2; ++n) _Pragma("unroll") for (int k = 0; k < 2; ++k) dst[n][k] = *(const PG8_LAS bf16x8*)(lds + PG8_SB(b, h) + boff + n * 2048 + k * 1024); } while (0)
; #define PG8_WAIT_V(n) asm volatile("s_waitcnt vmcnt(" #n ")" ::: "memory")
; #define PG8_WAIT_L(n) asm volatile("s_waitcnt lgkmcnt(" #n ")" ::: "memory")
; #define PG8_BAR __builtin_amdgcn_s_barrier()
; #define PG8_SCHED __builtin_amdgcn_sched_barrier(0)
; template <class Epi, class Sched, bool ALIGN_EPI = false, bool SP2 = false, bool I8 = false>
; __device__ __forceinline__ void gemm_phase(PG8_LAS unsigned char* lds, const Gemm g, const Sched& S, const Epi& E) {
;     ...
;             if constexpr (SP2) {
;             PG8_LDB(B0, 0, 0); PG8_LDB(B1, 0, 1); PG8_SCHED; PG8_LDA(At, 0, 0); PG8_STAGE(PG8_SA(1, 1), a1 + hstep, voffA);
;             PG8_WAIT_V(8); PG8_WAIT_L(0); PG8_BAR; PG8_MMA(0, 0, At, B0); PG8_MMA(0, 1, At, B1); PG8_BAR; PG8_SCHED;
;             PG8_LDA(At, 0, 1); PG8_STAGE(PG8_SB(0, 0), b2, voffB); PG8_STAGE(PG8_SB(0, 1), b2 + hstep, voffB); PG8_STAGE(PG8_SA(0, 0), a2, voffA);
;             PG8_WAIT_V(8); PG8_WAIT_L(0); PG8_BAR; PG8_MMA(1, 0, At, B0); PG8_MMA(1, 1, At, B1); PG8_BAR; PG8_SCHED;
;             PG8_LDB(B0, 1, 0); PG8_LDB(B1, 1, 1); PG8_SCHED; PG8_LDA(At, 1, 0); PG8_STAGE(PG8_SA(0, 1), a2 + hstep, voffA);
;             PG8_WAIT_V(8); PG8_WAIT_L(0); PG8_BAR; PG8_MMA(0, 0, At, B0); PG8_MMA(0, 1, At, B1); PG8_BAR; PG8_SCHED;
;             PG8_LDA(At, 1, 1); PG8_STAGE(PG8_SB(1, 0), b3, voffB); PG8_STAGE(PG8_SB(1, 1), b3 + hstep, voffB); PG8_STAGE(PG8_SA(1, 0), a3, voffA);
;             PG8_WAIT_V(8); PG8_WAIT_L(0); PG8_BAR; PG8_MMA(1, 0, At, B0); PG8_MMA(1, 1, At, B1); PG8_BAR; PG8_SCHED;
	s_add_i32 s48, s64, s47
	v_lshl_add_u64 v[164:165], v[164:165], 0, s[84:85]
	s_mov_b32 m0, s48
	ds_read_b128 v[184:187], v171 offset:49152
	ds_read_b128 v[188:191], v171 offset:50176
	ds_read_b128 v[204:207], v171 offset:51200
	ds_read_b128 v[208:211], v171 offset:52224
	ds_read_b128 v[212:215], v171 offset:53248
	ds_read_b128 v[216:219], v171 offset:54272
	ds_read_b128 v[220:223], v171 offset:55296
	ds_read_b128 v[224:227], v171 offset:56320
	global_load_lds_dwordx4 v[164:165], off
	s_add_i32 m0, s48, 0x2000
	s_add_u32 s44, s44, 0x80080
	v_lshl_add_u64 v[164:165], v[228:229], 0, s[84:85]
	s_addc_u32 s45, s45, 0
	s_add_i32 s48, s65, s47
	global_load_lds_dwordx4 v[164:165], off
	v_lshl_add_u64 v[164:165], s[44:45], 0, v[2:3]
	s_mov_b32 m0, s48
	s_nop 0
	global_load_lds_dwordx4 v[164:165], off
	v_lshl_add_u64 v[164:165], s[44:45], 0, v[148:149]
	s_add_i32 m0, s48, 0x2000
	s_nop 0
	global_load_lds_dwordx4 v[164:165], off
	v_lshl_add_u64 v[164:165], v[240:241], 0, s[84:85]
	s_mov_b32 m0, s54
	s_nop 0
	global_load_lds_dwordx4 v[164:165], off
	v_lshl_add_u64 v[164:165], v[242:243], 0, s[84:85]
	s_mov_b32 m0, s55
	s_nop 0
	global_load_lds_dwordx4 v[164:165], off
	s_waitcnt vmcnt(8)
	s_waitcnt lgkmcnt(0)
	s_barrier
	s_setprio 1
	s_waitcnt lgkmcnt(0)
	v_mfma_i32_16x16x64_i8 v[72:75], v[60:63], v[184:187], v[72:75]
	v_mfma_i32_16x16x64_i8 v[72:75], v[68:71], v[188:191], v[72:75]
	v_mfma_i32_16x16x64_i8 v[56:59], v[60:63], v[204:207], v[56:59]
	v_mfma_i32_16x16x64_i8 v[56:59], v[68:71], v[208:211], v[56:59]
	v_mfma_i32_16x16x64_i8 v[32:35], v[60:63], v[212:215], v[32:35]
	v_mfma_i32_16x16x64_i8 v[32:35], v[68:71], v[216:219], v[32:35]
	v_mfma_i32_16x16x64_i8 v[16:19], v[60:63], v[220:223], v[16:19]
	v_mfma_i32_16x16x64_i8 v[16:19], v[68:71], v[224:227], v[16:19]
	v_mfma_i32_16x16x64_i8 v[64:67], v[140:143], v[184:187], v[64:67]
	v_mfma_i32_16x16x64_i8 v[64:67], v[144:147], v[188:191], v[64:67]
	v_mfma_i32_16x16x64_i8 v[48:51], v[140:143], v[204:207], v[48:51]
	v_mfma_i32_16x16x64_i8 v[48:51], v[144:147], v[208:211], v[48:51]
	v_mfma_i32_16x16x64_i8 v[24:27], v[140:143], v[212:215], v[24:27]
	v_mfma_i32_16x16x64_i8 v[24:27], v[144:147], v[216:219], v[24:27]
	v_mfma_i32_16x16x64_i8 v[8:11], v[140:143], v[220:223], v[8:11]
	v_mfma_i32_16x16x64_i8 v[8:11], v[144:147], v[224:227], v[8:11]
	s_setprio 0
	s_setprio 1
	v_mfma_i32_16x16x64_i8 v[36:39], v[160:163], v[184:187], v[36:39]
	v_mfma_i32_16x16x64_i8 v[68:71], v[172:175], v[188:191], v[36:39]
	v_mfma_i32_16x16x64_i8 v[36:39], v[160:163], v[204:207], v[52:55]
	v_mfma_i32_16x16x64_i8 v[52:55], v[172:175], v[208:211], v[36:39]
	v_mfma_i32_16x16x64_i8 v[28:31], v[160:163], v[212:215], v[28:31]
	v_mfma_i32_16x16x64_i8 v[28:31], v[172:175], v[216:219], v[28:31]
	v_mfma_i32_16x16x64_i8 v[12:15], v[160:163], v[220:223], v[12:15]
	v_mfma_i32_16x16x64_i8 v[12:15], v[172:175], v[224:227], v[12:15]
	v_mfma_i32_16x16x64_i8 v[36:39], v[176:179], v[184:187], v[44:47]
	v_mfma_i32_16x16x64_i8 v[60:63], v[180:183], v[188:191], v[36:39]
	v_mfma_i32_16x16x64_i8 v[36:39], v[176:179], v[204:207], v[40:43]
	v_mfma_i32_16x16x64_i8 v[40:43], v[180:183], v[208:211], v[36:39]
	v_mfma_i32_16x16x64_i8 v[20:23], v[176:179], v[212:215], v[20:23]
	v_mfma_i32_16x16x64_i8 v[20:23], v[180:183], v[216:219], v[20:23]
	v_mfma_i32_16x16x64_i8 v[4:7], v[176:179], v[220:223], v[4:7]
	v_mfma_i32_16x16x64_i8 v[4:7], v[180:183], v[224:227], v[4:7]
	s_setprio 0
	s_barrier
	s_add_i32 s61, s61, 2
	s_add_u32 s40, s40, 0x100
	s_addc_u32 s41, s41, 0
	s_add_u32 s59, s59, 0x100
	s_addc_u32 s60, s60, 0
	s_cmp_gt_u32 s61, 29
	s_cbranch_scc1 .Lkloop_exit_3
.LBB0_1591:
	s_add_u32 s44, s40, 0xfff80080
	s_addc_u32 s45, s41, -1
	s_add_i32 s64, 0, 0x10000
	s_cmp_eq_u32 s61, 28
	s_cselect_b32 s49, s25, s45
	s_cselect_b32 s48, s57, s44
	s_cselect_b32 s45, s23, s60
	s_cselect_b32 s44, s58, s59
	s_add_i32 s67, 0, 0x14000
	v_add_u32_e32 v144, s64, v167
	v_add_u32_e32 v158, s67, v167
	ds_read_b128 v[36:39], v144
	ds_read_b128 v[44:47], v144 offset:1024
	ds_read_b128 v[140:143], v144 offset:2048
	ds_read_b128 v[144:147], v144 offset:3072
	ds_read_b128 v[160:163], v158
	ds_read_b128 v[172:175], v158 offset:1024
	ds_read_b128 v[176:179], v158 offset:2048
	ds_read_b128 v[180:183], v158 offset:3072
	v_lshl_add_u64 v[164:165], s[40:41], 0, v[154:155]
	s_add_i32 m0, s50, 0xc000
	ds_read_b128 v[184:187], v171
	ds_read_b128 v[188:191], v171 offset:1024
	ds_read_b128 v[204:207], v171 offset:2048
	ds_read_b128 v[208:211], v171 offset:3072
	ds_read_b128 v[212:215], v171 offset:4096
	ds_read_b128 v[216:219], v171 offset:5120
	ds_read_b128 v[220:223], v171 offset:6144
	ds_read_b128 v[224:227], v171 offset:7168
	global_load_lds_dwordx4 v[164:165], off
	v_lshl_add_u64 v[164:165], s[40:41], 0, v[156:157]
	s_add_i32 m0, s50, 0xe000
	s_nop 0
	global_load_lds_dwordx4 v[164:165], off
	s_waitcnt vmcnt(8)
	s_waitcnt lgkmcnt(0)
	s_barrier
; #define PG8_STAGE(bufoff, gbase, voff) do { _Pragma("unroll") for (int _i = 0; _i < 2; ++_i) \
;         __builtin_amdgcn_global_load_lds((const unsigned*)((const char*)(gbase) + (voff)[_i]), (PG8_LAS unsigned*)(lds + (bufoff) + ldsw + _i * 8192), 16, 0, 0); } while (0)
; #define PG8_LDA(dst, b, h) do { _Pragma("unroll") for (int m = 0; m < 4; ++m) _Pragma("unroll") for (int k = 0; k < 2; ++k) dst[m][k] = *(const PG8_LAS bf16x8*)(lds + PG8_SA(b, h) + aoff + m * 2048 + k * 1024); } while (0)
; #define PG8_LDB(dst, b, h) do { _Pragma("unroll") for (int n = 0; n < 2; ++n) _Pragma("unroll") for (int k = 0; k < 2; ++k) dst[n][k] = *(const PG8_LAS bf16x8*)(lds + PG8_SB(b, h) + boff + n * 2048 + k * 1024); } while (0)
; #define PG8_WAIT_V(n) asm volatile("s_waitcnt vmcnt(" #n ")" ::: "memory")
; #define PG8_WAIT_L(n) asm volatile("s_waitcnt lgkmcnt(" #n ")" ::: "memory")
; #define PG8_BAR __builtin_amdgcn_s_barrier()
; #define PG8_SCHED __builtin_amdgcn_sched_barrier(0)
; template <class Epi, class Sched, bool ALIGN_EPI = false, bool SP2 = false, bool I8 = false>
; __device__ __forceinline__ void gemm_phase(PG8_LAS unsigned char* lds, const Gemm g, const Sched& S, const Epi& E) {
;     ...
;             if constexpr (SP2) {
;             PG8_LDB(B0, 0, 0); PG8_LDB(B1, 0, 1); PG8_SCHED; PG8_LDA(At, 0, 0); PG8_STAGE(PG8_SA(1, 1), a1 + hstep, voffA);
;             PG8_WAIT_V(8); PG8_WAIT_L(0); PG8_BAR; PG8_MMA(0, 0, At, B0); PG8_MMA(0, 1, At, B1); PG8_BAR; PG8_SCHED;
;             PG8_LDA(At, 0, 1); PG8_STAGE(PG8_SB(0, 0), b2, voffB); PG8_STAGE(PG8_SB(0, 1), b2 + hstep, voffB); PG8_STAGE(PG8_SA(0, 0), a2, voffA);
;             PG8_WAIT_V(8); PG8_WAIT_L(0); PG8_BAR; PG8_MMA(1, 0, At, B0); PG8_MMA(1, 1, At, B1); PG8_BAR; PG8_SCHED;
;             PG8_LDB(B0, 1, 0); PG8_LDB(B1, 1, 1); PG8_SCHED; PG8_LDA(At, 1, 0); PG8_STAGE(PG8_SA(0, 1), a2 + hstep, voffA);
;             PG8_WAIT_V(8); PG8_WAIT_L(0); PG8_BAR; PG8_MMA(0, 0, At, B0); PG8_MMA(0, 1, At, B1); PG8_BAR; PG8_SCHED;
;             PG8_LDA(At, 1, 1); PG8_STAGE(PG8_SB(1, 0), b3, voffB); PG8_STAGE(PG8_SB(1, 1), b3 + hstep, voffB); PG8_STAGE(PG8_SA(1, 0), a3, voffA);
;             PG8_WAIT_V(8); PG8_WAIT_L(0); PG8_BAR; PG8_MMA(1, 0, At, B0); PG8_MMA(1, 1, At, B1); PG8_BAR; PG8_SCHED;
	s_setprio 1
	s_waitcnt lgkmcnt(0)
	v_mfma_i32_16x16x64_i8 v[136:139], v[36:39], v[184:187], v[136:139]
	v_mfma_i32_16x16x64_i8 v[136:139], v[44:47], v[188:191], v[136:139]
	v_mfma_i32_16x16x64_i8 v[120:123], v[36:39], v[204:207], v[120:123]
	v_mfma_i32_16x16x64_i8 v[120:123], v[44:47], v[208:211], v[120:123]
	v_mfma_i32_16x16x64_i8 v[104:107], v[36:39], v[212:215], v[104:107]
	v_mfma_i32_16x16x64_i8 v[104:107], v[44:47], v[216:219], v[104:107]
	v_mfma_i32_16x16x64_i8 v[88:91], v[36:39], v[220:223], v[88:91]
	v_mfma_i32_16x16x64_i8 v[88:91], v[44:47], v[224:227], v[88:91]
	v_mfma_i32_16x16x64_i8 v[128:131], v[140:143], v[184:187], v[128:131]
	v_mfma_i32_16x16x64_i8 v[128:131], v[144:147], v[188:191], v[128:131]
	v_mfma_i32_16x16x64_i8 v[112:115], v[140:143], v[204:207], v[112:115]
	v_mfma_i32_16x16x64_i8 v[112:115], v[144:147], v[208:211], v[112:115]
	v_mfma_i32_16x16x64_i8 v[96:99], v[140:143], v[212:215], v[96:99]
	v_mfma_i32_16x16x64_i8 v[96:99], v[144:147], v[216:219], v[96:99]
	v_mfma_i32_16x16x64_i8 v[80:83], v[140:143], v[220:223], v[80:83]
	v_mfma_i32_16x16x64_i8 v[80:83], v[144:147], v[224:227], v[80:83]
	s_setprio 0
	s_setprio 1
	v_mfma_i32_16x16x64_i8 v[132:135], v[160:163], v[184:187], v[132:135]
	v_mfma_i32_16x16x64_i8 v[132:135], v[172:175], v[188:191], v[132:135]
	v_mfma_i32_16x16x64_i8 v[116:119], v[160:163], v[204:207], v[116:119]
	v_mfma_i32_16x16x64_i8 v[116:119], v[172:175], v[208:211], v[116:119]
	v_mfma_i32_16x16x64_i8 v[100:103], v[160:163], v[212:215], v[100:103]
	v_mfma_i32_16x16x64_i8 v[100:103], v[172:175], v[216:219], v[100:103]
	v_mfma_i32_16x16x64_i8 v[84:87], v[160:163], v[220:223], v[84:87]
	v_mfma_i32_16x16x64_i8 v[84:87], v[172:175], v[224:227], v[84:87]
	v_mfma_i32_16x16x64_i8 v[124:127], v[176:179], v[184:187], v[124:127]
	v_mfma_i32_16x16x64_i8 v[124:127], v[180:183], v[188:191], v[124:127]
	v_mfma_i32_16x16x64_i8 v[108:111], v[176:179], v[204:207], v[108:111]
	v_mfma_i32_16x16x64_i8 v[108:111], v[180:183], v[208:211], v[108:111]
	v_mfma_i32_16x16x64_i8 v[92:95], v[176:179], v[212:215], v[92:95]
	v_mfma_i32_16x16x64_i8 v[92:95], v[180:183], v[216:219], v[92:95]
	v_mfma_i32_16x16x64_i8 v[76:79], v[176:179], v[220:223], v[76:79]
	v_mfma_i32_16x16x64_i8 v[76:79], v[180:183], v[224:227], v[76:79]
	s_setprio 0
	s_barrier
	s_add_i32 s64, s64, s47
	v_lshl_add_u64 v[164:165], s[44:45], 0, v[2:3]
	s_mov_b32 m0, s64
	ds_read_b128 v[184:187], v171 offset:16384
	ds_read_b128 v[188:191], v171 offset:17408
	ds_read_b128 v[204:207], v171 offset:18432
	ds_read_b128 v[208:211], v171 offset:19456
	ds_read_b128 v[212:215], v171 offset:20480
	ds_read_b128 v[216:219], v171 offset:21504
	ds_read_b128 v[220:223], v171 offset:22528
	ds_read_b128 v[224:227], v171 offset:23552
	global_load_lds_dwordx4 v[164:165], off
	s_add_i32 m0, s64, 0x2000
	s_add_u32 s64, s44, 0x80000
	v_lshl_add_u64 v[228:229], s[44:45], 0, v[148:149]
	s_addc_u32 s65, s45, 0
	s_add_i32 s67, s67, s47
	global_load_lds_dwordx4 v[228:229], off
	v_lshl_add_u64 v[240:241], s[64:65], 0, v[2:3]
	s_mov_b32 m0, s67
	v_lshl_add_u64 v[242:243], s[48:49], 0, v[150:151]
	global_load_lds_dwordx4 v[240:241], off
	v_lshl_add_u64 v[240:241], s[64:65], 0, v[148:149]
	s_add_i32 m0, s67, 0x2000
	s_nop 0
	global_load_lds_dwordx4 v[240:241], off
	v_lshl_add_u64 v[240:241], s[48:49], 0, v[152:153]
	s_mov_b32 m0, s50
	s_nop 0
	global_load_lds_dwordx4 v[240:241], off
	s_mov_b32 m0, s51
	s_nop 0
	global_load_lds_dwordx4 v[242:243], off
	s_waitcnt vmcnt(8)
	s_waitcnt lgkmcnt(0)
	s_barrier
	s_setprio 1
	s_waitcnt lgkmcnt(0)
	v_mfma_i32_16x16x64_i8 v[72:75], v[36:39], v[184:187], v[72:75]
	v_mfma_i32_16x16x64_i8 v[72:75], v[44:47], v[188:191], v[72:75]
	v_mfma_i32_16x16x64_i8 v[56:59], v[36:39], v[204:207], v[56:59]
	v_mfma_i32_16x16x64_i8 v[56:59], v[44:47], v[208:211], v[56:59]
	v_mfma_i32_16x16x64_i8 v[32:35], v[36:39], v[212:215], v[32:35]
	v_mfma_i32_16x16x64_i8 v[32:35], v[44:47], v[216:219], v[32:35]
	v_mfma_i32_16x16x64_i8 v[16:19], v[36:39], v[220:223], v[16:19]
	v_mfma_i32_16x16x64_i8 v[16:19], v[44:47], v[224:227], v[16:19]
	v_mfma_i32_16x16x64_i8 v[64:67], v[140:143], v[184:187], v[64:67]
	v_mfma_i32_16x16x64_i8 v[64:67], v[144:147], v[188:191], v[64:67]
	v_mfma_i32_16x16x64_i8 v[48:51], v[140:143], v[204:207], v[48:51]
	v_mfma_i32_16x16x64_i8 v[48:51], v[144:147], v[208:211], v[48:51]
	v_mfma_i32_16x16x64_i8 v[24:27], v[140:143], v[212:215], v[24:27]
	v_mfma_i32_16x16x64_i8 v[24:27], v[144:147], v[216:219], v[24:27]
	v_mfma_i32_16x16x64_i8 v[8:11], v[140:143], v[220:223], v[8:11]
	v_mfma_i32_16x16x64_i8 v[8:11], v[144:147], v[224:227], v[8:11]
	s_setprio 0
	s_setprio 1
	v_mfma_i32_16x16x64_i8 v[52:55], v[160:163], v[204:207], v[52:55]
	v_mfma_i32_16x16x64_i8 v[52:55], v[172:175], v[208:211], v[52:55]
	v_mfma_i32_16x16x64_i8 v[28:31], v[160:163], v[212:215], v[28:31]
	v_mfma_i32_16x16x64_i8 v[28:31], v[172:175], v[216:219], v[28:31]
	v_mfma_i32_16x16x64_i8 v[12:15], v[160:163], v[220:223], v[12:15]
	v_mfma_i32_16x16x64_i8 v[12:15], v[172:175], v[224:227], v[12:15]
	v_mfma_i32_16x16x64_i8 v[36:39], v[160:163], v[184:187], v[68:71]
	v_mfma_i32_16x16x64_i8 v[36:39], v[172:175], v[188:191], v[36:39]
	v_mfma_i32_16x16x64_i8 v[40:43], v[176:179], v[204:207], v[40:43]
	v_mfma_i32_16x16x64_i8 v[40:43], v[180:183], v[208:211], v[40:43]
	v_mfma_i32_16x16x64_i8 v[20:23], v[176:179], v[212:215], v[20:23]
	v_mfma_i32_16x16x64_i8 v[20:23], v[180:183], v[216:219], v[20:23]
	v_mfma_i32_16x16x64_i8 v[4:7], v[176:179], v[220:223], v[4:7]
	v_mfma_i32_16x16x64_i8 v[4:7], v[180:183], v[224:227], v[4:7]
	v_mfma_i32_16x16x64_i8 v[44:47], v[176:179], v[184:187], v[60:63]
	v_mfma_i32_16x16x64_i8 v[44:47], v[180:183], v[188:191], v[44:47]
	s_setprio 0
	s_barrier
; #define PG8_STAGE(bufoff, gbase, voff) do { _Pragma("unroll") for (int _i = 0; _i < 2; ++_i) \
;         __builtin_amdgcn_global_load_lds((const unsigned*)((const char*)(gbase) + (voff)[_i]), (PG8_LAS unsigned*)(lds + (bufoff) + ldsw + _i * 8192), 16, 0, 0); } while (0)
; #define PG8_LDA(dst, b, h) do { _Pragma("unroll") for (int m = 0; m < 4; ++m) _Pragma("unroll") for (int k = 0; k < 2; ++k) dst[m][k] = *(const PG8_LAS bf16x8*)(lds + PG8_SA(b, h) + aoff + m * 2048 + k * 1024); } while (0)
; #define PG8_LDB(dst, b, h) do { _Pragma("unroll") for (int n = 0; n < 2; ++n) _Pragma("unroll") for (int k = 0; k < 2; ++k) dst[n][k] = *(const PG8_LAS bf16x8*)(lds + PG8_SB(b, h) + boff + n * 2048 + k * 1024); } while (0)
; #define PG8_WAIT_V(n) asm volatile("s_waitcnt vmcnt(" #n ")" ::: "memory")
; #define PG8_WAIT_L(n) asm volatile("s_waitcnt lgkmcnt(" #n ")" ::: "memory")
; #define PG8_BAR __builtin_amdgcn_s_barrier()
; #define PG8_SCHED __builtin_amdgcn_sched_barrier(0)
; template <class Epi, class Sched, bool ALIGN_EPI = false, bool SP2 = false, bool I8 = false>
; __device__ __forceinline__ void gemm_phase(PG8_LAS unsigned char* lds, const Gemm g, const Sched& S, const Epi& E) {
;     ...
;             if constexpr (SP2) {
;             PG8_LDB(B0, 0, 0); PG8_LDB(B1, 0, 1); PG8_SCHED; PG8_LDA(At, 0, 0); PG8_STAGE(PG8_SA(1, 1), a1 + hstep, voffA);
;             PG8_WAIT_V(8); PG8_WAIT_L(0); PG8_BAR; PG8_MMA(0, 0, At, B0); PG8_MMA(0, 1, At, B1); PG8_BAR; PG8_SCHED;
;             PG8_LDA(At, 0, 1); PG8_STAGE(PG8_SB(0, 0), b2, voffB); PG8_STAGE(PG8_SB(0, 1), b2 + hstep, voffB); PG8_STAGE(PG8_SA(0, 0), a2, voffA);
;             PG8_WAIT_V(8); PG8_WAIT_L(0); PG8_BAR; PG8_MMA(1, 0, At, B0); PG8_MMA(1, 1, At, B1); PG8_BAR; PG8_SCHED;
;             PG8_LDB(B0, 1, 0); PG8_LDB(B1, 1, 1); PG8_SCHED; PG8_LDA(At, 1, 0); PG8_STAGE(PG8_SA(0, 1), a2 + hstep, voffA);
;             PG8_WAIT_V(8); PG8_WAIT_L(0); PG8_BAR; PG8_MMA(0, 0, At, B0); PG8_MMA(0, 1, At, B1); PG8_BAR; PG8_SCHED;
;             PG8_LDA(At, 1, 1); PG8_STAGE(PG8_SB(1, 0), b3, voffB); PG8_STAGE(PG8_SB(1, 1), b3 + hstep, voffB); PG8_STAGE(PG8_SA(1, 0), a3, voffA);
;             PG8_WAIT_V(8); PG8_WAIT_L(0); PG8_BAR; PG8_MMA(1, 0, At, B0); PG8_MMA(1, 1, At, B1); PG8_BAR; PG8_SCHED;
	s_add_i32 s64, 0, 0x18000
	s_add_i32 s65, 0, 0x1c000
	v_add_u32_e32 v144, s64, v167
	v_add_u32_e32 v158, s65, v167
	ds_read_b128 v[60:63], v144
	ds_read_b128 v[68:71], v144 offset:1024
	ds_read_b128 v[140:143], v144 offset:2048
	ds_read_b128 v[144:147], v144 offset:3072
	ds_read_b128 v[160:163], v158
	ds_read_b128 v[172:175], v158 offset:1024
	ds_read_b128 v[176:179], v158 offset:2048
	ds_read_b128 v[180:183], v158 offset:3072
	s_add_u32 s48, s48, 0x80000
	s_addc_u32 s49, s49, 0
	s_mov_b32 m0, s52
	v_lshl_add_u64 v[244:245], s[48:49], 0, v[152:153]
	ds_read_b128 v[184:187], v171 offset:32768
	ds_read_b128 v[188:191], v171 offset:33792
	ds_read_b128 v[204:207], v171 offset:34816
	ds_read_b128 v[208:211], v171 offset:35840
	ds_read_b128 v[212:215], v171 offset:36864
	ds_read_b128 v[216:219], v171 offset:37888
	ds_read_b128 v[220:223], v171 offset:38912
	ds_read_b128 v[224:227], v171 offset:39936
	global_load_lds_dwordx4 v[244:245], off
	v_lshl_add_u64 v[244:245], s[48:49], 0, v[150:151]
	s_mov_b32 m0, s53
	s_nop 0
	global_load_lds_dwordx4 v[244:245], off
	s_waitcnt vmcnt(8)
	s_waitcnt lgkmcnt(0)
	s_barrier
	s_setprio 1
	s_waitcnt lgkmcnt(0)
	v_mfma_i32_16x16x64_i8 v[136:139], v[60:63], v[184:187], v[136:139]
	v_mfma_i32_16x16x64_i8 v[136:139], v[68:71], v[188:191], v[136:139]
	v_mfma_i32_16x16x64_i8 v[120:123], v[60:63], v[204:207], v[120:123]
	v_mfma_i32_16x16x64_i8 v[120:123], v[68:71], v[208:211], v[120:123]
	v_mfma_i32_16x16x64_i8 v[104:107], v[60:63], v[212:215], v[104:107]
	v_mfma_i32_16x16x64_i8 v[104:107], v[68:71], v[216:219], v[104:107]
	v_mfma_i32_16x16x64_i8 v[88:91], v[60:63], v[220:223], v[88:91]
	v_mfma_i32_16x16x64_i8 v[88:91], v[68:71], v[224:227], v[88:91]
	v_mfma_i32_16x16x64_i8 v[128:131], v[140:143], v[184:187], v[128:131]
	v_mfma_i32_16x16x64_i8 v[128:131], v[144:147], v[188:191], v[128:131]
	v_mfma_i32_16x16x64_i8 v[112:115], v[140:143], v[204:207], v[112:115]
	v_mfma_i32_16x16x64_i8 v[112:115], v[144:147], v[208:211], v[112:115]
	v_mfma_i32_16x16x64_i8 v[96:99], v[140:143], v[212:215], v[96:99]
	v_mfma_i32_16x16x64_i8 v[96:99], v[144:147], v[216:219], v[96:99]
	v_mfma_i32_16x16x64_i8 v[80:83], v[140:143], v[220:223], v[80:83]
	v_mfma_i32_16x16x64_i8 v[80:83], v[144:147], v[224:227], v[80:83]
	s_setprio 0
	s_setprio 1
	v_mfma_i32_16x16x64_i8 v[132:135], v[160:163], v[184:187], v[132:135]
	v_mfma_i32_16x16x64_i8 v[132:135], v[172:175], v[188:191], v[132:135]
	v_mfma_i32_16x16x64_i8 v[116:119], v[160:163], v[204:207], v[116:119]
	v_mfma_i32_16x16x64_i8 v[116:119], v[172:175], v[208:211], v[116:119]
	v_mfma_i32_16x16x64_i8 v[100:103], v[160:163], v[212:215], v[100:103]
	v_mfma_i32_16x16x64_i8 v[100:103], v[172:175], v[216:219], v[100:103]
	v_mfma_i32_16x16x64_i8 v[84:87], v[160:163], v[220:223], v[84:87]
	v_mfma_i32_16x16x64_i8 v[84:87], v[172:175], v[224:227], v[84:87]
	v_mfma_i32_16x16x64_i8 v[124:127], v[176:179], v[184:187], v[124:127]
	v_mfma_i32_16x16x64_i8 v[124:127], v[180:183], v[188:191], v[124:127]
	v_mfma_i32_16x16x64_i8 v[108:111], v[176:179], v[204:207], v[108:111]
	v_mfma_i32_16x16x64_i8 v[108:111], v[180:183], v[208:211], v[108:111]
	v_mfma_i32_16x16x64_i8 v[92:95], v[176:179], v[212:215], v[92:95]
	v_mfma_i32_16x16x64_i8 v[92:95], v[180:183], v[216:219], v[92:95]
	v_mfma_i32_16x16x64_i8 v[76:79], v[176:179], v[220:223], v[76:79]
	v_mfma_i32_16x16x64_i8 v[76:79], v[180:183], v[224:227], v[76:79]
	s_setprio 0
	s_barrier
	s_add_i32 s48, s64, s47
	v_lshl_add_u64 v[164:165], v[164:165], 0, s[84:85]
	s_mov_b32 m0, s48
	ds_read_b128 v[184:187], v171 offset:49152
	ds_read_b128 v[188:191], v171 offset:50176
	ds_read_b128 v[204:207], v171 offset:51200
	ds_read_b128 v[208:211], v171 offset:52224
	ds_read_b128 v[212:215], v171 offset:53248
	ds_read_b128 v[216:219], v171 offset:54272
	ds_read_b128 v[220:223], v171 offset:55296
	ds_read_b128 v[224:227], v171 offset:56320
	global_load_lds_dwordx4 v[164:165], off
	s_add_i32 m0, s48, 0x2000
	s_add_u32 s44, s44, 0x80080
	v_lshl_add_u64 v[164:165], v[228:229], 0, s[84:85]
	s_addc_u32 s45, s45, 0
	s_add_i32 s48, s65, s47
	global_load_lds_dwordx4 v[164:165], off
	v_lshl_add_u64 v[164:165], s[44:45], 0, v[2:3]
	s_mov_b32 m0, s48
	s_nop 0
	global_load_lds_dwordx4 v[164:165], off
	v_lshl_add_u64 v[164:165], s[44:45], 0, v[148:149]
	s_add_i32 m0, s48, 0x2000
	s_nop 0
	global_load_lds_dwordx4 v[164:165], off
	v_lshl_add_u64 v[164:165], v[240:241], 0, s[84:85]
	s_mov_b32 m0, s54
	s_nop 0
	global_load_lds_dwordx4 v[164:165], off
	v_lshl_add_u64 v[164:165], v[242:243], 0, s[84:85]
	s_mov_b32 m0, s55
	s_nop 0
	global_load_lds_dwordx4 v[164:165], off
	s_waitcnt vmcnt(8)
	s_waitcnt lgkmcnt(0)
	s_barrier
	s_setprio 1
	s_waitcnt lgkmcnt(0)
	v_mfma_i32_16x16x64_i8 v[72:75], v[60:63], v[184:187], v[72:75]
	v_mfma_i32_16x16x64_i8 v[72:75], v[68:71], v[188:191], v[72:75]
	v_mfma_i32_16x16x64_i8 v[56:59], v[60:63], v[204:207], v[56:59]
	v_mfma_i32_16x16x64_i8 v[56:59], v[68:71], v[208:211], v[56:59]
	v_mfma_i32_16x16x64_i8 v[32:35], v[60:63], v[212:215], v[32:35]
	v_mfma_i32_16x16x64_i8 v[32:35], v[68:71], v[216:219], v[32:35]
	v_mfma_i32_16x16x64_i8 v[16:19], v[60:63], v[220:223], v[16:19]
	v_mfma_i32_16x16x64_i8 v[16:19], v[68:71], v[224:227], v[16:19]
	v_mfma_i32_16x16x64_i8 v[64:67], v[140:143], v[184:187], v[64:67]
	v_mfma_i32_16x16x64_i8 v[64:67], v[144:147], v[188:191], v[64:67]
	v_mfma_i32_16x16x64_i8 v[48:51], v[140:143], v[204:207], v[48:51]
	v_mfma_i32_16x16x64_i8 v[48:51], v[144:147], v[208:211], v[48:51]
	v_mfma_i32_16x16x64_i8 v[24:27], v[140:143], v[212:215], v[24:27]
	v_mfma_i32_16x16x64_i8 v[24:27], v[144:147], v[216:219], v[24:27]
	v_mfma_i32_16x16x64_i8 v[8:11], v[140:143], v[220:223], v[8:11]
	v_mfma_i32_16x16x64_i8 v[8:11], v[144:147], v[224:227], v[8:11]
	s_setprio 0
	s_setprio 1
	v_mfma_i32_16x16x64_i8 v[36:39], v[160:163], v[184:187], v[36:39]
	v_mfma_i32_16x16x64_i8 v[68:71], v[172:175], v[188:191], v[36:39]
	v_mfma_i32_16x16x64_i8 v[36:39], v[160:163], v[204:207], v[52:55]
	v_mfma_i32_16x16x64_i8 v[52:55], v[172:175], v[208:211], v[36:39]
	v_mfma_i32_16x16x64_i8 v[28:31], v[160:163], v[212:215], v[28:31]
	v_mfma_i32_16x16x64_i8 v[28:31], v[172:175], v[216:219], v[28:31]
	v_mfma_i32_16x16x64_i8 v[12:15], v[160:163], v[220:223], v[12:15]
	v_mfma_i32_16x16x64_i8 v[12:15], v[172:175], v[224:227], v[12:15]
	v_mfma_i32_16x16x64_i8 v[36:39], v[176:179], v[184:187], v[44:47]
	v_mfma_i32_16x16x64_i8 v[60:63], v[180:183], v[188:191], v[36:39]
	v_mfma_i32_16x16x64_i8 v[36:39], v[176:179], v[204:207], v[40:43]
	v_mfma_i32_16x16x64_i8 v[40:43], v[180:183], v[208:211], v[36:39]
	v_mfma_i32_16x16x64_i8 v[20:23], v[176:179], v[212:215], v[20:23]
	v_mfma_i32_16x16x64_i8 v[20:23], v[180:183], v[216:219], v[20:23]
	v_mfma_i32_16x16x64_i8 v[4:7], v[176:179], v[220:223], v[4:7]
	v_mfma_i32_16x16x64_i8 v[4:7], v[180:183], v[224:227], v[4:7]
	s_setprio 0
	s_barrier
	s_add_i32 s61, s61, 2
	s_add_u32 s40, s40, 0x100
	s_addc_u32 s41, s41, 0
	s_add_u32 s59, s59, 0x100
	s_addc_u32 s60, s60, 0
	s_cmp_gt_u32 s61, 29
	s_cbranch_scc0 .LBB0_1591

; #define PG8_STAGE(bufoff, gbase, voff) do { _Pragma("unroll") for (int _i = 0; _i < 2; ++_i) \
;         __builtin_amdgcn_global_load_lds((const unsigned*)((const char*)(gbase) + (voff)[_i]), (PG8_LAS unsigned*)(lds + (bufoff) + ldsw + _i * 8192), 16, 0, 0); } while (0)
; #define PG8_LDA(dst, b, h) do { _Pragma("unroll") for (int m = 0; m < 4; ++m) _Pragma("unroll") for (int k = 0; k < 2; ++k) dst[m][k] = *(const PG8_LAS bf16x8*)(lds + PG8_SA(b, h) + aoff + m * 2048 + k * 1024); } while (0)
; #define PG8_LDB(dst, b, h) do { _Pragma("unroll") for (int n = 0; n < 2; ++n) _Pragma("unroll") for (int k = 0; k < 2; ++k) dst[n][k] = *(const PG8_LAS bf16x8*)(lds + PG8_SB(b, h) + boff + n * 2048 + k * 1024); } while (0)
; #define PG8_WAIT_V(n) asm volatile("s_waitcnt vmcnt(" #n ")" ::: "memory")
; #define PG8_WAIT_L(n) asm volatile("s_waitcnt lgkmcnt(" #n ")" ::: "memory")
; #define PG8_BAR __builtin_amdgcn_s_barrier()
; #define PG8_SCHED __builtin_amdgcn_sched_barrier(0)
; template <class Epi, class Sched, bool ALIGN_EPI = false, bool SP2 = false, bool I8 = false>
; __device__ __forceinline__ void gemm_phase(PG8_LAS unsigned char* lds, const Gemm g, const Sched& S, const Epi& E) {
;     ...
; #pragma unroll
;     for (int a = 0; a < 2; ++a)
; #pragma unroll
;         for (int b = 0; b < 2; ++b)
; #pragma unroll
;             for (int m = 0; m < 4; ++m)
; #pragma unroll
;                 for (int n = 0; n < 2; ++n) acc[a][b][m][n] = (acc_t){0, 0, 0, 0};
;     ...
;         for (int t = 0; t < nt; t += 2) {
;             const bool last = (t == nt - 2);
;             const char* a1 = cA + (size_t)(t + 1) * kstep;
;             const char* a2 = last ? nA : cA + (size_t)(t + 2) * kstep; const char* b2 = last ? nB : cB + (size_t)(t + 2) * kstep;
;             const char* a3 = a2 + kstep; const char* b3 = b2 + kstep;
;             if (last && has_next) S.a_ready(nxt);
;             if constexpr (SP2) {
;             PG8_LDB(B0, 0, 0); PG8_LDB(B1, 0, 1); PG8_SCHED; PG8_LDA(At, 0, 0); PG8_STAGE(PG8_SA(1, 1), a1 + hstep, voffA);
;             PG8_WAIT_V(8); PG8_WAIT_L(0); PG8_BAR; PG8_MMA(0, 0, At, B0); PG8_MMA(0, 1, At, B1); PG8_BAR; PG8_SCHED;
.LBB0_1621:
	v_mov_b32_e32 v127, 0
	s_andn2_b64 vcc, exec, s[26:27]
	v_mov_b32_e32 v126, v127
	v_mov_b32_e32 v125, v127
	v_mov_b32_e32 v124, v127
	v_mov_b32_e32 v131, v127
	v_mov_b32_e32 v130, v127
	v_mov_b32_e32 v129, v127
	v_mov_b32_e32 v128, v127
	v_mov_b32_e32 v115, v127
	v_mov_b32_e32 v114, v127
	v_mov_b32_e32 v113, v127
	v_mov_b32_e32 v112, v127
	v_mov_b32_e32 v111, v127
	v_mov_b32_e32 v110, v127
	v_mov_b32_e32 v109, v127
	v_mov_b32_e32 v108, v127
	v_mov_b32_e32 v99, v127
	v_mov_b32_e32 v98, v127
	v_mov_b32_e32 v97, v127
	v_mov_b32_e32 v96, v127
	v_mov_b32_e32 v95, v127
	v_mov_b32_e32 v94, v127
	v_mov_b32_e32 v93, v127
	v_mov_b32_e32 v92, v127
	v_mov_b32_e32 v83, v127
	v_mov_b32_e32 v82, v127
	v_mov_b32_e32 v81, v127
	v_mov_b32_e32 v80, v127
	v_mov_b32_e32 v79, v127
	v_mov_b32_e32 v78, v127
	v_mov_b32_e32 v77, v127
	v_mov_b32_e32 v76, v127
	v_mov_b32_e32 v123, v127
	v_mov_b32_e32 v122, v127
	v_mov_b32_e32 v121, v127
	v_mov_b32_e32 v120, v127
	v_mov_b32_e32 v119, v127
	v_mov_b32_e32 v118, v127
	v_mov_b32_e32 v117, v127
	v_mov_b32_e32 v116, v127
	v_mov_b32_e32 v107, v127
	v_mov_b32_e32 v106, v127
	v_mov_b32_e32 v105, v127
	v_mov_b32_e32 v104, v127
	v_mov_b32_e32 v103, v127
	v_mov_b32_e32 v102, v127
	v_mov_b32_e32 v101, v127
	v_mov_b32_e32 v100, v127
	v_mov_b32_e32 v91, v127
	v_mov_b32_e32 v90, v127
	v_mov_b32_e32 v89, v127
	v_mov_b32_e32 v88, v127
	v_mov_b32_e32 v87, v127
	v_mov_b32_e32 v86, v127
	v_mov_b32_e32 v85, v127
	v_mov_b32_e32 v84, v127
	v_mov_b32_e32 v75, v127
	v_mov_b32_e32 v74, v127
	v_mov_b32_e32 v73, v127
	v_mov_b32_e32 v72, v127
	v_mov_b32_e32 v71, v127
	v_mov_b32_e32 v70, v127
	v_mov_b32_e32 v69, v127
	v_mov_b32_e32 v68, v127
	v_mov_b32_e32 v67, v127
	v_mov_b32_e32 v66, v127
	v_mov_b32_e32 v65, v127
	v_mov_b32_e32 v64, v127
	v_mov_b32_e32 v63, v127
	v_mov_b32_e32 v62, v127
	v_mov_b32_e32 v61, v127
	v_mov_b32_e32 v60, v127
	v_mov_b32_e32 v51, v127
	v_mov_b32_e32 v50, v127
	v_mov_b32_e32 v49, v127
	v_mov_b32_e32 v48, v127
	v_mov_b32_e32 v47, v127
	v_mov_b32_e32 v46, v127
	v_mov_b32_e32 v45, v127
	v_mov_b32_e32 v44, v127
	v_mov_b32_e32 v35, v127
	v_mov_b32_e32 v34, v127
	v_mov_b32_e32 v33, v127
	v_mov_b32_e32 v32, v127
	v_mov_b32_e32 v31, v127
	v_mov_b32_e32 v30, v127
	v_mov_b32_e32 v29, v127
	v_mov_b32_e32 v28, v127
	v_mov_b32_e32 v19, v127
	v_mov_b32_e32 v18, v127
	v_mov_b32_e32 v17, v127
	v_mov_b32_e32 v16, v127
	v_mov_b32_e32 v15, v127
	v_mov_b32_e32 v14, v127
	v_mov_b32_e32 v13, v127
	v_mov_b32_e32 v12, v127
	v_mov_b32_e32 v59, v127
	v_mov_b32_e32 v58, v127
	v_mov_b32_e32 v57, v127
	v_mov_b32_e32 v56, v127
	v_mov_b32_e32 v55, v127
	v_mov_b32_e32 v54, v127
	v_mov_b32_e32 v53, v127
	v_mov_b32_e32 v52, v127
	v_mov_b32_e32 v43, v127
	v_mov_b32_e32 v42, v127
	v_mov_b32_e32 v41, v127
	v_mov_b32_e32 v40, v127
	v_mov_b32_e32 v39, v127
	v_mov_b32_e32 v38, v127
	v_mov_b32_e32 v37, v127
	v_mov_b32_e32 v36, v127
	v_mov_b32_e32 v27, v127
	v_mov_b32_e32 v26, v127
	v_mov_b32_e32 v25, v127
	v_mov_b32_e32 v24, v127
	v_mov_b32_e32 v23, v127
	v_mov_b32_e32 v22, v127
	v_mov_b32_e32 v21, v127
	v_mov_b32_e32 v20, v127
	v_mov_b32_e32 v11, v127
	v_mov_b32_e32 v10, v127
	v_mov_b32_e32 v9, v127
	v_mov_b32_e32 v8, v127
	v_mov_b32_e32 v7, v127
	v_mov_b32_e32 v6, v127
	v_mov_b32_e32 v5, v127
	v_mov_b32_e32 v4, v127
	s_cbranch_vccnz .LBB0_1625
	s_add_u32 s44, s44, 0x80
	s_addc_u32 s45, s45, 0
	s_add_u32 s65, s48, 0x100
	s_addc_u32 s67, s49, 0
	s_mov_b32 s48, 0
	s_add_i32 s72, s48, 2
	s_add_u32 s73, s44, 0x80
	s_addc_u32 s49, s45, 0
	s_add_i32 s86, 0, 0x10000
	s_cmp_eq_u32 s57, s48
	s_cselect_b32 s49, s13, s49
	s_cselect_b32 s48, s12, s73
	s_cselect_b32 s77, s41, s67
	s_cselect_b32 s76, s40, s65
	s_add_i32 s73, 0, 0x14000
	v_add_u32_e32 v158, s86, v143
	v_add_u32_e32 v174, s73, v143
	ds_read_b128 v[146:149], v158
	ds_read_b128 v[150:153], v158 offset:1024
	ds_read_b128 v[154:157], v158 offset:2048
	ds_read_b128 v[158:161], v158 offset:3072
	ds_read_b128 v[162:165], v174
	ds_read_b128 v[166:169], v174 offset:1024
	ds_read_b128 v[170:173], v174 offset:2048
	ds_read_b128 v[174:177], v174 offset:3072
	v_lshl_add_u64 v[190:191], s[44:45], 0, v[138:139]
	s_add_i32 m0, s47, 0xc000
	ds_read_b128 v[178:181], v145
	ds_read_b128 v[182:185], v145 offset:1024
	ds_read_b128 v[186:189], v145 offset:2048
	ds_read_b128 v[204:207], v145 offset:3072
	ds_read_b128 v[208:211], v145 offset:4096
	ds_read_b128 v[212:215], v145 offset:5120
	ds_read_b128 v[216:219], v145 offset:6144
	ds_read_b128 v[220:223], v145 offset:7168
	global_load_lds_dwordx4 v[190:191], off
	v_lshl_add_u64 v[190:191], s[44:45], 0, v[140:141]
	s_add_i32 m0, s47, 0xe000
	s_nop 0
	global_load_lds_dwordx4 v[190:191], off
	s_waitcnt vmcnt(8)
	s_waitcnt lgkmcnt(0)
	s_barrier
; #define PG8_STAGE(bufoff, gbase, voff) do { _Pragma("unroll") for (int _i = 0; _i < 2; ++_i) \
;         __builtin_amdgcn_global_load_lds((const unsigned*)((const char*)(gbase) + (voff)[_i]), (PG8_LAS unsigned*)(lds + (bufoff) + ldsw + _i * 8192), 16, 0, 0); } while (0)
; #define PG8_LDA(dst, b, h) do { _Pragma("unroll") for (int m = 0; m < 4; ++m) _Pragma("unroll") for (int k = 0; k < 2; ++k) dst[m][k] = *(const PG8_LAS bf16x8*)(lds + PG8_SA(b, h) + aoff + m * 2048 + k * 1024); } while (0)
; #define PG8_LDB(dst, b, h) do { _Pragma("unroll") for (int n = 0; n < 2; ++n) _Pragma("unroll") for (int k = 0; k < 2; ++k) dst[n][k] = *(const PG8_LAS bf16x8*)(lds + PG8_SB(b, h) + boff + n * 2048 + k * 1024); } while (0)
; #define PG8_WAIT_V(n) asm volatile("s_waitcnt vmcnt(" #n ")" ::: "memory")
; #define PG8_WAIT_L(n) asm volatile("s_waitcnt lgkmcnt(" #n ")" ::: "memory")
; #define PG8_BAR __builtin_amdgcn_s_barrier()
; #define PG8_SCHED __builtin_amdgcn_sched_barrier(0)
; template <class Epi, class Sched, bool ALIGN_EPI = false, bool SP2 = false, bool I8 = false>
; __device__ __forceinline__ void gemm_phase(PG8_LAS unsigned char* lds, const Gemm g, const Sched& S, const Epi& E) {
;     ...
;             if constexpr (SP2) {
;             PG8_LDB(B0, 0, 0); PG8_LDB(B1, 0, 1); PG8_SCHED; PG8_LDA(At, 0, 0); PG8_STAGE(PG8_SA(1, 1), a1 + hstep, voffA);
;             PG8_WAIT_V(8); PG8_WAIT_L(0); PG8_BAR; PG8_MMA(0, 0, At, B0); PG8_MMA(0, 1, At, B1); PG8_BAR; PG8_SCHED;
;             PG8_LDA(At, 0, 1); PG8_STAGE(PG8_SB(0, 0), b2, voffB); PG8_STAGE(PG8_SB(0, 1), b2 + hstep, voffB); PG8_STAGE(PG8_SA(0, 0), a2, voffA);
;             PG8_WAIT_V(8); PG8_WAIT_L(0); PG8_BAR; PG8_MMA(1, 0, At, B0); PG8_MMA(1, 1, At, B1); PG8_BAR; PG8_SCHED;
	s_setprio 1
	s_waitcnt lgkmcnt(0)
	v_mfma_f32_16x16x32_bf16 v[124:127], v[146:149], v[178:181], 0
	v_mfma_f32_16x16x32_bf16 v[124:127], v[150:153], v[182:185], v[124:127]
	v_mfma_f32_16x16x32_bf16 v[112:115], v[146:149], v[186:189], 0
	v_mfma_f32_16x16x32_bf16 v[112:115], v[150:153], v[204:207], v[112:115]
	v_mfma_f32_16x16x32_bf16 v[96:99], v[146:149], v[208:211], 0
	v_mfma_f32_16x16x32_bf16 v[96:99], v[150:153], v[212:215], v[96:99]
	v_mfma_f32_16x16x32_bf16 v[80:83], v[146:149], v[216:219], 0
	v_mfma_f32_16x16x32_bf16 v[80:83], v[150:153], v[220:223], v[80:83]
	v_mfma_f32_16x16x32_bf16 v[128:131], v[154:157], v[178:181], 0
	v_mfma_f32_16x16x32_bf16 v[128:131], v[158:161], v[182:185], v[128:131]
	v_mfma_f32_16x16x32_bf16 v[108:111], v[154:157], v[186:189], 0
	v_mfma_f32_16x16x32_bf16 v[108:111], v[158:161], v[204:207], v[108:111]
	v_mfma_f32_16x16x32_bf16 v[92:95], v[154:157], v[208:211], 0
	v_mfma_f32_16x16x32_bf16 v[92:95], v[158:161], v[212:215], v[92:95]
	v_mfma_f32_16x16x32_bf16 v[76:79], v[154:157], v[216:219], 0
	v_mfma_f32_16x16x32_bf16 v[76:79], v[158:161], v[220:223], v[76:79]
	s_setprio 0
	s_setprio 1
	v_mfma_f32_16x16x32_bf16 v[120:123], v[162:165], v[178:181], 0
	v_mfma_f32_16x16x32_bf16 v[120:123], v[166:169], v[182:185], v[120:123]
	v_mfma_f32_16x16x32_bf16 v[104:107], v[162:165], v[186:189], 0
	v_mfma_f32_16x16x32_bf16 v[104:107], v[166:169], v[204:207], v[104:107]
	v_mfma_f32_16x16x32_bf16 v[88:91], v[162:165], v[208:211], 0
	v_mfma_f32_16x16x32_bf16 v[88:91], v[166:169], v[212:215], v[88:91]
	v_mfma_f32_16x16x32_bf16 v[72:75], v[162:165], v[216:219], 0
	v_mfma_f32_16x16x32_bf16 v[72:75], v[166:169], v[220:223], v[72:75]
	v_mfma_f32_16x16x32_bf16 v[116:119], v[170:173], v[178:181], 0
	v_mfma_f32_16x16x32_bf16 v[116:119], v[174:177], v[182:185], v[116:119]
	v_mfma_f32_16x16x32_bf16 v[100:103], v[170:173], v[186:189], 0
	v_mfma_f32_16x16x32_bf16 v[100:103], v[174:177], v[204:207], v[100:103]
	v_mfma_f32_16x16x32_bf16 v[84:87], v[170:173], v[208:211], 0
	v_mfma_f32_16x16x32_bf16 v[84:87], v[174:177], v[212:215], v[84:87]
	v_mfma_f32_16x16x32_bf16 v[68:71], v[170:173], v[216:219], 0
	v_mfma_f32_16x16x32_bf16 v[68:71], v[174:177], v[220:223], v[68:71]
	s_setprio 0
	s_barrier
	s_add_i32 s86, s86, s28
	v_lshl_add_u64 v[190:191], s[76:77], 0, v[2:3]
	s_mov_b32 m0, s86
	ds_read_b128 v[178:181], v145 offset:16384
	ds_read_b128 v[182:185], v145 offset:17408
	ds_read_b128 v[186:189], v145 offset:18432
	ds_read_b128 v[204:207], v145 offset:19456
	ds_read_b128 v[208:211], v145 offset:20480
	ds_read_b128 v[212:215], v145 offset:21504
	ds_read_b128 v[216:219], v145 offset:22528
	ds_read_b128 v[220:223], v145 offset:23552
	global_load_lds_dwordx4 v[190:191], off
	s_add_i32 m0, s86, 0x2000
	v_lshl_add_u64 v[224:225], s[76:77], 0, v[136:137]
	s_add_u32 s76, s76, s18
	s_addc_u32 s77, s77, s19
	s_add_i32 s73, s73, s28
	global_load_lds_dwordx4 v[224:225], off
	v_lshl_add_u64 v[226:227], s[76:77], 0, v[2:3]
	s_mov_b32 m0, s73
	v_lshl_add_u64 v[228:229], s[76:77], 0, v[136:137]
	global_load_lds_dwordx4 v[226:227], off
	s_add_i32 m0, s73, 0x2000
	v_lshl_add_u64 v[240:241], s[48:49], 0, v[132:133]
	global_load_lds_dwordx4 v[228:229], off
	s_mov_b32 m0, s47
	v_lshl_add_u64 v[242:243], s[48:49], 0, v[134:135]
	global_load_lds_dwordx4 v[240:241], off
	s_mov_b32 m0, s50
	s_nop 0
	global_load_lds_dwordx4 v[242:243], off
	s_waitcnt vmcnt(8)
	s_waitcnt lgkmcnt(0)
	s_barrier
	s_setprio 1
	s_waitcnt lgkmcnt(0)
	v_mfma_f32_16x16x32_bf16 v[64:67], v[146:149], v[178:181], 0
	v_mfma_f32_16x16x32_bf16 v[64:67], v[150:153], v[182:185], v[64:67]
	v_mfma_f32_16x16x32_bf16 v[48:51], v[146:149], v[186:189], 0
	v_mfma_f32_16x16x32_bf16 v[48:51], v[150:153], v[204:207], v[48:51]
	v_mfma_f32_16x16x32_bf16 v[32:35], v[146:149], v[208:211], 0
	v_mfma_f32_16x16x32_bf16 v[32:35], v[150:153], v[212:215], v[32:35]
	v_mfma_f32_16x16x32_bf16 v[16:19], v[146:149], v[216:219], 0
	v_mfma_f32_16x16x32_bf16 v[16:19], v[150:153], v[220:223], v[16:19]
	v_mfma_f32_16x16x32_bf16 v[60:63], v[154:157], v[178:181], 0
	v_mfma_f32_16x16x32_bf16 v[60:63], v[158:161], v[182:185], v[60:63]
	v_mfma_f32_16x16x32_bf16 v[44:47], v[154:157], v[186:189], 0
	v_mfma_f32_16x16x32_bf16 v[44:47], v[158:161], v[204:207], v[44:47]
	v_mfma_f32_16x16x32_bf16 v[28:31], v[154:157], v[208:211], 0
	v_mfma_f32_16x16x32_bf16 v[28:31], v[158:161], v[212:215], v[28:31]
	v_mfma_f32_16x16x32_bf16 v[12:15], v[154:157], v[216:219], 0
	v_mfma_f32_16x16x32_bf16 v[12:15], v[158:161], v[220:223], v[12:15]
	s_setprio 0
	s_setprio 1
	v_mfma_f32_16x16x32_bf16 v[56:59], v[162:165], v[178:181], 0
	v_mfma_f32_16x16x32_bf16 v[56:59], v[166:169], v[182:185], v[56:59]
	v_mfma_f32_16x16x32_bf16 v[40:43], v[162:165], v[186:189], 0
	v_mfma_f32_16x16x32_bf16 v[40:43], v[166:169], v[204:207], v[40:43]
	v_mfma_f32_16x16x32_bf16 v[24:27], v[162:165], v[208:211], 0
	v_mfma_f32_16x16x32_bf16 v[24:27], v[166:169], v[212:215], v[24:27]
	v_mfma_f32_16x16x32_bf16 v[8:11], v[162:165], v[216:219], 0
	v_mfma_f32_16x16x32_bf16 v[8:11], v[166:169], v[220:223], v[8:11]
	v_mfma_f32_16x16x32_bf16 v[52:55], v[170:173], v[178:181], 0
	v_mfma_f32_16x16x32_bf16 v[52:55], v[174:177], v[182:185], v[52:55]
	v_mfma_f32_16x16x32_bf16 v[36:39], v[170:173], v[186:189], 0
	v_mfma_f32_16x16x32_bf16 v[36:39], v[174:177], v[204:207], v[36:39]
	v_mfma_f32_16x16x32_bf16 v[20:23], v[170:173], v[208:211], 0
	v_mfma_f32_16x16x32_bf16 v[20:23], v[174:177], v[212:215], v[20:23]
	v_mfma_f32_16x16x32_bf16 v[4:7], v[170:173], v[216:219], 0
	v_mfma_f32_16x16x32_bf16 v[4:7], v[174:177], v[220:223], v[4:7]
	s_setprio 0
	s_barrier
; #define PG8_STAGE(bufoff, gbase, voff) do { _Pragma("unroll") for (int _i = 0; _i < 2; ++_i) \
;         __builtin_amdgcn_global_load_lds((const unsigned*)((const char*)(gbase) + (voff)[_i]), (PG8_LAS unsigned*)(lds + (bufoff) + ldsw + _i * 8192), 16, 0, 0); } while (0)
; #define PG8_LDA(dst, b, h) do { _Pragma("unroll") for (int m = 0; m < 4; ++m) _Pragma("unroll") for (int k = 0; k < 2; ++k) dst[m][k] = *(const PG8_LAS bf16x8*)(lds + PG8_SA(b, h) + aoff + m * 2048 + k * 1024); } while (0)
; #define PG8_LDB(dst, b, h) do { _Pragma("unroll") for (int n = 0; n < 2; ++n) _Pragma("unroll") for (int k = 0; k < 2; ++k) dst[n][k] = *(const PG8_LAS bf16x8*)(lds + PG8_SB(b, h) + boff + n * 2048 + k * 1024); } while (0)
; #define PG8_WAIT_V(n) asm volatile("s_waitcnt vmcnt(" #n ")" ::: "memory")
; #define PG8_WAIT_L(n) asm volatile("s_waitcnt lgkmcnt(" #n ")" ::: "memory")
; #define PG8_BAR __builtin_amdgcn_s_barrier()
; #define PG8_SCHED __builtin_amdgcn_sched_barrier(0)
; template <class Epi, class Sched, bool ALIGN_EPI = false, bool SP2 = false, bool I8 = false>
; __device__ __forceinline__ void gemm_phase(PG8_LAS unsigned char* lds, const Gemm g, const Sched& S, const Epi& E) {
;     ...
;             if constexpr (SP2) {
;             PG8_LDB(B0, 0, 0); PG8_LDB(B1, 0, 1); PG8_SCHED; PG8_LDA(At, 0, 0); PG8_STAGE(PG8_SA(1, 1), a1 + hstep, voffA);
;             PG8_WAIT_V(8); PG8_WAIT_L(0); PG8_BAR; PG8_MMA(0, 0, At, B0); PG8_MMA(0, 1, At, B1); PG8_BAR; PG8_SCHED;
;             PG8_LDA(At, 0, 1); PG8_STAGE(PG8_SB(0, 0), b2, voffB); PG8_STAGE(PG8_SB(0, 1), b2 + hstep, voffB); PG8_STAGE(PG8_SA(0, 0), a2, voffA);
;             PG8_WAIT_V(8); PG8_WAIT_L(0); PG8_BAR; PG8_MMA(1, 0, At, B0); PG8_MMA(1, 1, At, B1); PG8_BAR; PG8_SCHED;
;             PG8_LDB(B0, 1, 0); PG8_LDB(B1, 1, 1); PG8_SCHED; PG8_LDA(At, 1, 0); PG8_STAGE(PG8_SA(0, 1), a2 + hstep, voffA);
;             PG8_WAIT_V(8); PG8_WAIT_L(0); PG8_BAR; PG8_MMA(0, 0, At, B0); PG8_MMA(0, 1, At, B1); PG8_BAR; PG8_SCHED;
;             PG8_LDA(At, 1, 1); PG8_STAGE(PG8_SB(1, 0), b3, voffB); PG8_STAGE(PG8_SB(1, 1), b3 + hstep, voffB); PG8_STAGE(PG8_SA(1, 0), a3, voffA);
;             PG8_WAIT_V(8); PG8_WAIT_L(0); PG8_BAR; PG8_MMA(1, 0, At, B0); PG8_MMA(1, 1, At, B1); PG8_BAR; PG8_SCHED;
	s_add_i32 s73, 0, 0x18000
	s_add_i32 s76, 0, 0x1c000
	v_add_u32_e32 v158, s73, v143
	v_add_u32_e32 v174, s76, v143
	ds_read_b128 v[146:149], v158
	ds_read_b128 v[150:153], v158 offset:1024
	ds_read_b128 v[154:157], v158 offset:2048
	ds_read_b128 v[158:161], v158 offset:3072
	ds_read_b128 v[162:165], v174
	ds_read_b128 v[166:169], v174 offset:1024
	ds_read_b128 v[170:173], v174 offset:2048
	ds_read_b128 v[174:177], v174 offset:3072
	s_add_u32 s48, s48, s18
	s_addc_u32 s49, s49, s19
	s_mov_b32 m0, s51
	v_lshl_add_u64 v[244:245], s[48:49], 0, v[132:133]
	ds_read_b128 v[178:181], v145 offset:32768
	ds_read_b128 v[182:185], v145 offset:33792
	ds_read_b128 v[186:189], v145 offset:34816
	ds_read_b128 v[204:207], v145 offset:35840
	ds_read_b128 v[208:211], v145 offset:36864
	ds_read_b128 v[212:215], v145 offset:37888
	ds_read_b128 v[216:219], v145 offset:38912
	ds_read_b128 v[220:223], v145 offset:39936
	global_load_lds_dwordx4 v[244:245], off
	v_lshl_add_u64 v[244:245], s[48:49], 0, v[134:135]
	s_mov_b32 m0, s52
	s_nop 0
	global_load_lds_dwordx4 v[244:245], off
	s_waitcnt vmcnt(8)
	s_waitcnt lgkmcnt(0)
	s_barrier
	s_setprio 1
	s_waitcnt lgkmcnt(0)
	v_mfma_f32_16x16x32_bf16 v[124:127], v[146:149], v[178:181], v[124:127]
	v_mfma_f32_16x16x32_bf16 v[124:127], v[150:153], v[182:185], v[124:127]
	v_mfma_f32_16x16x32_bf16 v[112:115], v[146:149], v[186:189], v[112:115]
	v_mfma_f32_16x16x32_bf16 v[112:115], v[150:153], v[204:207], v[112:115]
	v_mfma_f32_16x16x32_bf16 v[96:99], v[146:149], v[208:211], v[96:99]
	v_mfma_f32_16x16x32_bf16 v[96:99], v[150:153], v[212:215], v[96:99]
	v_mfma_f32_16x16x32_bf16 v[80:83], v[146:149], v[216:219], v[80:83]
	v_mfma_f32_16x16x32_bf16 v[80:83], v[150:153], v[220:223], v[80:83]
	v_mfma_f32_16x16x32_bf16 v[128:131], v[154:157], v[178:181], v[128:131]
	v_mfma_f32_16x16x32_bf16 v[128:131], v[158:161], v[182:185], v[128:131]
	v_mfma_f32_16x16x32_bf16 v[108:111], v[154:157], v[186:189], v[108:111]
	v_mfma_f32_16x16x32_bf16 v[108:111], v[158:161], v[204:207], v[108:111]
	v_mfma_f32_16x16x32_bf16 v[92:95], v[154:157], v[208:211], v[92:95]
	v_mfma_f32_16x16x32_bf16 v[92:95], v[158:161], v[212:215], v[92:95]
	v_mfma_f32_16x16x32_bf16 v[76:79], v[154:157], v[216:219], v[76:79]
	v_mfma_f32_16x16x32_bf16 v[76:79], v[158:161], v[220:223], v[76:79]
	s_setprio 0
	s_setprio 1
	v_mfma_f32_16x16x32_bf16 v[120:123], v[162:165], v[178:181], v[120:123]
	v_mfma_f32_16x16x32_bf16 v[120:123], v[166:169], v[182:185], v[120:123]
	v_mfma_f32_16x16x32_bf16 v[104:107], v[162:165], v[186:189], v[104:107]
	v_mfma_f32_16x16x32_bf16 v[104:107], v[166:169], v[204:207], v[104:107]
	v_mfma_f32_16x16x32_bf16 v[88:91], v[162:165], v[208:211], v[88:91]
	v_mfma_f32_16x16x32_bf16 v[88:91], v[166:169], v[212:215], v[88:91]
	v_mfma_f32_16x16x32_bf16 v[72:75], v[162:165], v[216:219], v[72:75]
	v_mfma_f32_16x16x32_bf16 v[72:75], v[166:169], v[220:223], v[72:75]
	v_mfma_f32_16x16x32_bf16 v[116:119], v[170:173], v[178:181], v[116:119]
	v_mfma_f32_16x16x32_bf16 v[116:119], v[174:177], v[182:185], v[116:119]
	v_mfma_f32_16x16x32_bf16 v[100:103], v[170:173], v[186:189], v[100:103]
	v_mfma_f32_16x16x32_bf16 v[100:103], v[174:177], v[204:207], v[100:103]
	v_mfma_f32_16x16x32_bf16 v[84:87], v[170:173], v[208:211], v[84:87]
	v_mfma_f32_16x16x32_bf16 v[84:87], v[174:177], v[212:215], v[84:87]
	v_mfma_f32_16x16x32_bf16 v[68:71], v[170:173], v[216:219], v[68:71]
	v_mfma_f32_16x16x32_bf16 v[68:71], v[174:177], v[220:223], v[68:71]
	s_setprio 0
	s_barrier
	s_add_i32 s48, s73, s28
	v_lshl_add_u64 v[190:191], v[190:191], 0, s[84:85]
	s_mov_b32 m0, s48
	ds_read_b128 v[178:181], v145 offset:49152
	ds_read_b128 v[182:185], v145 offset:50176
	ds_read_b128 v[186:189], v145 offset:51200
	ds_read_b128 v[204:207], v145 offset:52224
	ds_read_b128 v[208:211], v145 offset:53248
	ds_read_b128 v[212:215], v145 offset:54272
	ds_read_b128 v[216:219], v145 offset:55296
	ds_read_b128 v[220:223], v145 offset:56320
	global_load_lds_dwordx4 v[190:191], off
	v_lshl_add_u64 v[190:191], v[224:225], 0, s[84:85]
	s_add_i32 m0, s48, 0x2000
	s_add_i32 s48, s76, s28
	global_load_lds_dwordx4 v[190:191], off
	v_lshl_add_u64 v[190:191], v[226:227], 0, s[84:85]
	s_mov_b32 m0, s48
	s_nop 0
	global_load_lds_dwordx4 v[190:191], off
	v_lshl_add_u64 v[190:191], v[228:229], 0, s[84:85]
	s_add_i32 m0, s48, 0x2000
	s_nop 0
	global_load_lds_dwordx4 v[190:191], off
	v_lshl_add_u64 v[190:191], v[240:241], 0, s[84:85]
	s_mov_b32 m0, s55
	s_nop 0
	global_load_lds_dwordx4 v[190:191], off
	v_lshl_add_u64 v[190:191], v[242:243], 0, s[84:85]
	s_mov_b32 m0, s56
	s_nop 0
	global_load_lds_dwordx4 v[190:191], off
	s_waitcnt vmcnt(8)
	s_waitcnt lgkmcnt(0)
	s_barrier
; #define PG8_STAGE(bufoff, gbase, voff) do { _Pragma("unroll") for (int _i = 0; _i < 2; ++_i) \
;         __builtin_amdgcn_global_load_lds((const unsigned*)((const char*)(gbase) + (voff)[_i]), (PG8_LAS unsigned*)(lds + (bufoff) + ldsw + _i * 8192), 16, 0, 0); } while (0)
; #define PG8_LDA(dst, b, h) do { _Pragma("unroll") for (int m = 0; m < 4; ++m) _Pragma("unroll") for (int k = 0; k < 2; ++k) dst[m][k] = *(const PG8_LAS bf16x8*)(lds + PG8_SA(b, h) + aoff + m * 2048 + k * 1024); } while (0)
; #define PG8_LDB(dst, b, h) do { _Pragma("unroll") for (int n = 0; n < 2; ++n) _Pragma("unroll") for (int k = 0; k < 2; ++k) dst[n][k] = *(const PG8_LAS bf16x8*)(lds + PG8_SB(b, h) + boff + n * 2048 + k * 1024); } while (0)
; #define PG8_WAIT_V(n) asm volatile("s_waitcnt vmcnt(" #n ")" ::: "memory")
; #define PG8_WAIT_L(n) asm volatile("s_waitcnt lgkmcnt(" #n ")" ::: "memory")
; #define PG8_BAR __builtin_amdgcn_s_barrier()
; #define PG8_SCHED __builtin_amdgcn_sched_barrier(0)
; template <class Epi, class Sched, bool ALIGN_EPI = false, bool SP2 = false, bool I8 = false>
; __device__ __forceinline__ void gemm_phase(PG8_LAS unsigned char* lds, const Gemm g, const Sched& S, const Epi& E) {
;     ...
;             if constexpr (SP2) {
;             PG8_LDB(B0, 0, 0); PG8_LDB(B1, 0, 1); PG8_SCHED; PG8_LDA(At, 0, 0); PG8_STAGE(PG8_SA(1, 1), a1 + hstep, voffA);
;             PG8_WAIT_V(8); PG8_WAIT_L(0); PG8_BAR; PG8_MMA(0, 0, At, B0); PG8_MMA(0, 1, At, B1); PG8_BAR; PG8_SCHED;
;             PG8_LDA(At, 0, 1); PG8_STAGE(PG8_SB(0, 0), b2, voffB); PG8_STAGE(PG8_SB(0, 1), b2 + hstep, voffB); PG8_STAGE(PG8_SA(0, 0), a2, voffA);
;             PG8_WAIT_V(8); PG8_WAIT_L(0); PG8_BAR; PG8_MMA(1, 0, At, B0); PG8_MMA(1, 1, At, B1); PG8_BAR; PG8_SCHED;
;             PG8_LDB(B0, 1, 0); PG8_LDB(B1, 1, 1); PG8_SCHED; PG8_LDA(At, 1, 0); PG8_STAGE(PG8_SA(0, 1), a2 + hstep, voffA);
;             PG8_WAIT_V(8); PG8_WAIT_L(0); PG8_BAR; PG8_MMA(0, 0, At, B0); PG8_MMA(0, 1, At, B1); PG8_BAR; PG8_SCHED;
;             PG8_LDA(At, 1, 1); PG8_STAGE(PG8_SB(1, 0), b3, voffB); PG8_STAGE(PG8_SB(1, 1), b3 + hstep, voffB); PG8_STAGE(PG8_SA(1, 0), a3, voffA);
;             PG8_WAIT_V(8); PG8_WAIT_L(0); PG8_BAR; PG8_MMA(1, 0, At, B0); PG8_MMA(1, 1, At, B1); PG8_BAR; PG8_SCHED;
	s_setprio 1
	s_waitcnt lgkmcnt(0)
	v_mfma_f32_16x16x32_bf16 v[64:67], v[146:149], v[178:181], v[64:67]
	v_mfma_f32_16x16x32_bf16 v[64:67], v[150:153], v[182:185], v[64:67]
	v_mfma_f32_16x16x32_bf16 v[48:51], v[146:149], v[186:189], v[48:51]
	v_mfma_f32_16x16x32_bf16 v[48:51], v[150:153], v[204:207], v[48:51]
	v_mfma_f32_16x16x32_bf16 v[32:35], v[146:149], v[208:211], v[32:35]
	v_mfma_f32_16x16x32_bf16 v[32:35], v[150:153], v[212:215], v[32:35]
	v_mfma_f32_16x16x32_bf16 v[16:19], v[146:149], v[216:219], v[16:19]
	v_mfma_f32_16x16x32_bf16 v[16:19], v[150:153], v[220:223], v[16:19]
	v_mfma_f32_16x16x32_bf16 v[60:63], v[154:157], v[178:181], v[60:63]
	v_mfma_f32_16x16x32_bf16 v[60:63], v[158:161], v[182:185], v[60:63]
	v_mfma_f32_16x16x32_bf16 v[44:47], v[154:157], v[186:189], v[44:47]
	v_mfma_f32_16x16x32_bf16 v[44:47], v[158:161], v[204:207], v[44:47]
	v_mfma_f32_16x16x32_bf16 v[28:31], v[154:157], v[208:211], v[28:31]
	v_mfma_f32_16x16x32_bf16 v[28:31], v[158:161], v[212:215], v[28:31]
	v_mfma_f32_16x16x32_bf16 v[12:15], v[154:157], v[216:219], v[12:15]
	v_mfma_f32_16x16x32_bf16 v[12:15], v[158:161], v[220:223], v[12:15]
	s_setprio 0
	s_setprio 1
	v_mfma_f32_16x16x32_bf16 v[56:59], v[162:165], v[178:181], v[56:59]
	v_mfma_f32_16x16x32_bf16 v[56:59], v[166:169], v[182:185], v[56:59]
	v_mfma_f32_16x16x32_bf16 v[40:43], v[162:165], v[186:189], v[40:43]
	v_mfma_f32_16x16x32_bf16 v[40:43], v[166:169], v[204:207], v[40:43]
	v_mfma_f32_16x16x32_bf16 v[24:27], v[162:165], v[208:211], v[24:27]
	v_mfma_f32_16x16x32_bf16 v[24:27], v[166:169], v[212:215], v[24:27]
	v_mfma_f32_16x16x32_bf16 v[8:11], v[162:165], v[216:219], v[8:11]
	v_mfma_f32_16x16x32_bf16 v[8:11], v[166:169], v[220:223], v[8:11]
	v_mfma_f32_16x16x32_bf16 v[52:55], v[170:173], v[178:181], v[52:55]
	v_mfma_f32_16x16x32_bf16 v[52:55], v[174:177], v[182:185], v[52:55]
	v_mfma_f32_16x16x32_bf16 v[36:39], v[170:173], v[186:189], v[36:39]
	v_mfma_f32_16x16x32_bf16 v[36:39], v[174:177], v[204:207], v[36:39]
	v_mfma_f32_16x16x32_bf16 v[20:23], v[170:173], v[208:211], v[20:23]
	v_mfma_f32_16x16x32_bf16 v[20:23], v[174:177], v[212:215], v[20:23]
	v_mfma_f32_16x16x32_bf16 v[4:7], v[170:173], v[216:219], v[4:7]
	v_mfma_f32_16x16x32_bf16 v[4:7], v[174:177], v[220:223], v[4:7]
	s_setprio 0
	s_barrier
	s_add_u32 s44, s44, 0x100
	s_addc_u32 s45, s45, 0
	s_add_u32 s65, s65, 0x100
	s_addc_u32 s67, s67, 0
	s_cmp_ge_i32 s72, s53
	s_mov_b32 s48, s72
	s_cbranch_scc1 .Lkloop_exit_4
.LBB0_1623:
	s_add_i32 s72, s48, 2
	s_add_u32 s73, s44, 0x80
	s_addc_u32 s49, s45, 0
	s_add_i32 s86, 0, 0x10000
	s_cmp_eq_u32 s57, s48
	s_cselect_b32 s49, s13, s49
	s_cselect_b32 s48, s12, s73
	s_cselect_b32 s77, s41, s67
	s_cselect_b32 s76, s40, s65
	s_add_i32 s73, 0, 0x14000
	v_add_u32_e32 v158, s86, v143
	v_add_u32_e32 v174, s73, v143
	ds_read_b128 v[146:149], v158
	ds_read_b128 v[150:153], v158 offset:1024
	ds_read_b128 v[154:157], v158 offset:2048
	ds_read_b128 v[158:161], v158 offset:3072
	ds_read_b128 v[162:165], v174
	ds_read_b128 v[166:169], v174 offset:1024
	ds_read_b128 v[170:173], v174 offset:2048
	ds_read_b128 v[174:177], v174 offset:3072
	v_lshl_add_u64 v[190:191], s[44:45], 0, v[138:139]
	s_add_i32 m0, s47, 0xc000
	ds_read_b128 v[178:181], v145
	ds_read_b128 v[182:185], v145 offset:1024
	ds_read_b128 v[186:189], v145 offset:2048
	ds_read_b128 v[204:207], v145 offset:3072
	ds_read_b128 v[208:211], v145 offset:4096
	ds_read_b128 v[212:215], v145 offset:5120
	ds_read_b128 v[216:219], v145 offset:6144
	ds_read_b128 v[220:223], v145 offset:7168
	global_load_lds_dwordx4 v[190:191], off
	v_lshl_add_u64 v[190:191], s[44:45], 0, v[140:141]
	s_add_i32 m0, s47, 0xe000
	s_nop 0
	global_load_lds_dwordx4 v[190:191], off
	s_waitcnt vmcnt(8)
	s_waitcnt lgkmcnt(0)
	s_barrier
	s_setprio 1
	s_waitcnt lgkmcnt(0)
	v_mfma_f32_16x16x32_bf16 v[124:127], v[146:149], v[178:181], v[124:127]
	v_mfma_f32_16x16x32_bf16 v[124:127], v[150:153], v[182:185], v[124:127]
	v_mfma_f32_16x16x32_bf16 v[112:115], v[146:149], v[186:189], v[112:115]
	v_mfma_f32_16x16x32_bf16 v[112:115], v[150:153], v[204:207], v[112:115]
	v_mfma_f32_16x16x32_bf16 v[96:99], v[146:149], v[208:211], v[96:99]
	v_mfma_f32_16x16x32_bf16 v[96:99], v[150:153], v[212:215], v[96:99]
	v_mfma_f32_16x16x32_bf16 v[80:83], v[146:149], v[216:219], v[80:83]
	v_mfma_f32_16x16x32_bf16 v[80:83], v[150:153], v[220:223], v[80:83]
	v_mfma_f32_16x16x32_bf16 v[128:131], v[154:157], v[178:181], v[128:131]
	v_mfma_f32_16x16x32_bf16 v[128:131], v[158:161], v[182:185], v[128:131]
	v_mfma_f32_16x16x32_bf16 v[108:111], v[154:157], v[186:189], v[108:111]
	v_mfma_f32_16x16x32_bf16 v[108:111], v[158:161], v[204:207], v[108:111]
	v_mfma_f32_16x16x32_bf16 v[92:95], v[154:157], v[208:211], v[92:95]
	v_mfma_f32_16x16x32_bf16 v[92:95], v[158:161], v[212:215], v[92:95]
	v_mfma_f32_16x16x32_bf16 v[76:79], v[154:157], v[216:219], v[76:79]
	v_mfma_f32_16x16x32_bf16 v[76:79], v[158:161], v[220:223], v[76:79]
	s_setprio 0
	s_setprio 1
	v_mfma_f32_16x16x32_bf16 v[120:123], v[162:165], v[178:181], v[120:123]
	v_mfma_f32_16x16x32_bf16 v[120:123], v[166:169], v[182:185], v[120:123]
	v_mfma_f32_16x16x32_bf16 v[104:107], v[162:165], v[186:189], v[104:107]
	v_mfma_f32_16x16x32_bf16 v[104:107], v[166:169], v[204:207], v[104:107]
	v_mfma_f32_16x16x32_bf16 v[88:91], v[162:165], v[208:211], v[88:91]
	v_mfma_f32_16x16x32_bf16 v[88:91], v[166:169], v[212:215], v[88:91]
	v_mfma_f32_16x16x32_bf16 v[72:75], v[162:165], v[216:219], v[72:75]
	v_mfma_f32_16x16x32_bf16 v[72:75], v[166:169], v[220:223], v[72:75]
	v_mfma_f32_16x16x32_bf16 v[116:119], v[170:173], v[178:181], v[116:119]
	v_mfma_f32_16x16x32_bf16 v[116:119], v[174:177], v[182:185], v[116:119]
	v_mfma_f32_16x16x32_bf16 v[100:103], v[170:173], v[186:189], v[100:103]
	v_mfma_f32_16x16x32_bf16 v[100:103], v[174:177], v[204:207], v[100:103]
	v_mfma_f32_16x16x32_bf16 v[84:87], v[170:173], v[208:211], v[84:87]
	v_mfma_f32_16x16x32_bf16 v[84:87], v[174:177], v[212:215], v[84:87]
	v_mfma_f32_16x16x32_bf16 v[68:71], v[170:173], v[216:219], v[68:71]
	v_mfma_f32_16x16x32_bf16 v[68:71], v[174:177], v[220:223], v[68:71]
	s_setprio 0
	s_barrier
; #define PG8_STAGE(bufoff, gbase, voff) do { _Pragma("unroll") for (int _i = 0; _i < 2; ++_i) \
;         __builtin_amdgcn_global_load_lds((const unsigned*)((const char*)(gbase) + (voff)[_i]), (PG8_LAS unsigned*)(lds + (bufoff) + ldsw + _i * 8192), 16, 0, 0); } while (0)
; #define PG8_LDA(dst, b, h) do { _Pragma("unroll") for (int m = 0; m < 4; ++m) _Pragma("unroll") for (int k = 0; k < 2; ++k) dst[m][k] = *(const PG8_LAS bf16x8*)(lds + PG8_SA(b, h) + aoff + m * 2048 + k * 1024); } while (0)
; #define PG8_LDB(dst, b, h) do { _Pragma("unroll") for (int n = 0; n < 2; ++n) _Pragma("unroll") for (int k = 0; k < 2; ++k) dst[n][k] = *(const PG8_LAS bf16x8*)(lds + PG8_SB(b, h) + boff + n * 2048 + k * 1024); } while (0)
; #define PG8_WAIT_V(n) asm volatile("s_waitcnt vmcnt(" #n ")" ::: "memory")
; #define PG8_WAIT_L(n) asm volatile("s_waitcnt lgkmcnt(" #n ")" ::: "memory")
; #define PG8_BAR __builtin_amdgcn_s_barrier()
; #define PG8_SCHED __builtin_amdgcn_sched_barrier(0)
; template <class Epi, class Sched, bool ALIGN_EPI = false, bool SP2 = false, bool I8 = false>
; __device__ __forceinline__ void gemm_phase(PG8_LAS unsigned char* lds, const Gemm g, const Sched& S, const Epi& E) {
;     ...
;             if constexpr (SP2) {
;             PG8_LDB(B0, 0, 0); PG8_LDB(B1, 0, 1); PG8_SCHED; PG8_LDA(At, 0, 0); PG8_STAGE(PG8_SA(1, 1), a1 + hstep, voffA);
;             PG8_WAIT_V(8); PG8_WAIT_L(0); PG8_BAR; PG8_MMA(0, 0, At, B0); PG8_MMA(0, 1, At, B1); PG8_BAR; PG8_SCHED;
;             PG8_LDA(At, 0, 1); PG8_STAGE(PG8_SB(0, 0), b2, voffB); PG8_STAGE(PG8_SB(0, 1), b2 + hstep, voffB); PG8_STAGE(PG8_SA(0, 0), a2, voffA);
;             PG8_WAIT_V(8); PG8_WAIT_L(0); PG8_BAR; PG8_MMA(1, 0, At, B0); PG8_MMA(1, 1, At, B1); PG8_BAR; PG8_SCHED;
;             PG8_LDB(B0, 1, 0); PG8_LDB(B1, 1, 1); PG8_SCHED; PG8_LDA(At, 1, 0); PG8_STAGE(PG8_SA(0, 1), a2 + hstep, voffA);
;             PG8_WAIT_V(8); PG8_WAIT_L(0); PG8_BAR; PG8_MMA(0, 0, At, B0); PG8_MMA(0, 1, At, B1); PG8_BAR; PG8_SCHED;
;             PG8_LDA(At, 1, 1); PG8_STAGE(PG8_SB(1, 0), b3, voffB); PG8_STAGE(PG8_SB(1, 1), b3 + hstep, voffB); PG8_STAGE(PG8_SA(1, 0), a3, voffA);
;             PG8_WAIT_V(8); PG8_WAIT_L(0); PG8_BAR; PG8_MMA(1, 0, At, B0); PG8_MMA(1, 1, At, B1); PG8_BAR; PG8_SCHED;
	s_add_i32 s86, s86, s28
	v_lshl_add_u64 v[190:191], s[76:77], 0, v[2:3]
	s_mov_b32 m0, s86
	ds_read_b128 v[178:181], v145 offset:16384
	ds_read_b128 v[182:185], v145 offset:17408
	ds_read_b128 v[186:189], v145 offset:18432
	ds_read_b128 v[204:207], v145 offset:19456
	ds_read_b128 v[208:211], v145 offset:20480
	ds_read_b128 v[212:215], v145 offset:21504
	ds_read_b128 v[216:219], v145 offset:22528
	ds_read_b128 v[220:223], v145 offset:23552
	global_load_lds_dwordx4 v[190:191], off
	s_add_i32 m0, s86, 0x2000
	v_lshl_add_u64 v[224:225], s[76:77], 0, v[136:137]
	s_add_u32 s76, s76, s18
	s_addc_u32 s77, s77, s19
	s_add_i32 s73, s73, s28
	global_load_lds_dwordx4 v[224:225], off
	v_lshl_add_u64 v[226:227], s[76:77], 0, v[2:3]
	s_mov_b32 m0, s73
	v_lshl_add_u64 v[228:229], s[76:77], 0, v[136:137]
	global_load_lds_dwordx4 v[226:227], off
	s_add_i32 m0, s73, 0x2000
	v_lshl_add_u64 v[240:241], s[48:49], 0, v[132:133]
	global_load_lds_dwordx4 v[228:229], off
	s_mov_b32 m0, s47
	v_lshl_add_u64 v[242:243], s[48:49], 0, v[134:135]
	global_load_lds_dwordx4 v[240:241], off
	s_mov_b32 m0, s50
	s_nop 0
	global_load_lds_dwordx4 v[242:243], off
	s_waitcnt vmcnt(8)
	s_waitcnt lgkmcnt(0)
	s_barrier
	s_setprio 1
	s_waitcnt lgkmcnt(0)
	v_mfma_f32_16x16x32_bf16 v[64:67], v[146:149], v[178:181], v[64:67]
	v_mfma_f32_16x16x32_bf16 v[64:67], v[150:153], v[182:185], v[64:67]
	v_mfma_f32_16x16x32_bf16 v[48:51], v[146:149], v[186:189], v[48:51]
	v_mfma_f32_16x16x32_bf16 v[48:51], v[150:153], v[204:207], v[48:51]
	v_mfma_f32_16x16x32_bf16 v[32:35], v[146:149], v[208:211], v[32:35]
	v_mfma_f32_16x16x32_bf16 v[32:35], v[150:153], v[212:215], v[32:35]
	v_mfma_f32_16x16x32_bf16 v[16:19], v[146:149], v[216:219], v[16:19]
	v_mfma_f32_16x16x32_bf16 v[16:19], v[150:153], v[220:223], v[16:19]
	v_mfma_f32_16x16x32_bf16 v[60:63], v[154:157], v[178:181], v[60:63]
	v_mfma_f32_16x16x32_bf16 v[60:63], v[158:161], v[182:185], v[60:63]
	v_mfma_f32_16x16x32_bf16 v[44:47], v[154:157], v[186:189], v[44:47]
	v_mfma_f32_16x16x32_bf16 v[44:47], v[158:161], v[204:207], v[44:47]
	v_mfma_f32_16x16x32_bf16 v[28:31], v[154:157], v[208:211], v[28:31]
	v_mfma_f32_16x16x32_bf16 v[28:31], v[158:161], v[212:215], v[28:31]
	v_mfma_f32_16x16x32_bf16 v[12:15], v[154:157], v[216:219], v[12:15]
	v_mfma_f32_16x16x32_bf16 v[12:15], v[158:161], v[220:223], v[12:15]
	s_setprio 0
	s_setprio 1
	v_mfma_f32_16x16x32_bf16 v[56:59], v[162:165], v[178:181], v[56:59]
	v_mfma_f32_16x16x32_bf16 v[56:59], v[166:169], v[182:185], v[56:59]
	v_mfma_f32_16x16x32_bf16 v[40:43], v[162:165], v[186:189], v[40:43]
	v_mfma_f32_16x16x32_bf16 v[40:43], v[166:169], v[204:207], v[40:43]
	v_mfma_f32_16x16x32_bf16 v[24:27], v[162:165], v[208:211], v[24:27]
	v_mfma_f32_16x16x32_bf16 v[24:27], v[166:169], v[212:215], v[24:27]
	v_mfma_f32_16x16x32_bf16 v[8:11], v[162:165], v[216:219], v[8:11]
	v_mfma_f32_16x16x32_bf16 v[8:11], v[166:169], v[220:223], v[8:11]
	v_mfma_f32_16x16x32_bf16 v[52:55], v[170:173], v[178:181], v[52:55]
	v_mfma_f32_16x16x32_bf16 v[52:55], v[174:177], v[182:185], v[52:55]
	v_mfma_f32_16x16x32_bf16 v[36:39], v[170:173], v[186:189], v[36:39]
	v_mfma_f32_16x16x32_bf16 v[36:39], v[174:177], v[204:207], v[36:39]
	v_mfma_f32_16x16x32_bf16 v[20:23], v[170:173], v[208:211], v[20:23]
	v_mfma_f32_16x16x32_bf16 v[20:23], v[174:177], v[212:215], v[20:23]
	v_mfma_f32_16x16x32_bf16 v[4:7], v[170:173], v[216:219], v[4:7]
	v_mfma_f32_16x16x32_bf16 v[4:7], v[174:177], v[220:223], v[4:7]
	s_setprio 0
	s_barrier
	s_add_i32 s73, 0, 0x18000
	s_add_i32 s76, 0, 0x1c000
	v_add_u32_e32 v158, s73, v143
	v_add_u32_e32 v174, s76, v143
	ds_read_b128 v[146:149], v158
	ds_read_b128 v[150:153], v158 offset:1024
	ds_read_b128 v[154:157], v158 offset:2048
	ds_read_b128 v[158:161], v158 offset:3072
	ds_read_b128 v[162:165], v174
	ds_read_b128 v[166:169], v174 offset:1024
	ds_read_b128 v[170:173], v174 offset:2048
	ds_read_b128 v[174:177], v174 offset:3072
	s_add_u32 s48, s48, s18
	s_addc_u32 s49, s49, s19
	s_mov_b32 m0, s51
	v_lshl_add_u64 v[244:245], s[48:49], 0, v[132:133]
	ds_read_b128 v[178:181], v145 offset:32768
	ds_read_b128 v[182:185], v145 offset:33792
	ds_read_b128 v[186:189], v145 offset:34816
	ds_read_b128 v[204:207], v145 offset:35840
	ds_read_b128 v[208:211], v145 offset:36864
	ds_read_b128 v[212:215], v145 offset:37888
	ds_read_b128 v[216:219], v145 offset:38912
	ds_read_b128 v[220:223], v145 offset:39936
	global_load_lds_dwordx4 v[244:245], off
	v_lshl_add_u64 v[244:245], s[48:49], 0, v[134:135]
	s_mov_b32 m0, s52
	s_nop 0
	global_load_lds_dwordx4 v[244:245], off
	s_waitcnt vmcnt(8)
	s_waitcnt lgkmcnt(0)
	s_barrier
; #define PG8_STAGE(bufoff, gbase, voff) do { _Pragma("unroll") for (int _i = 0; _i < 2; ++_i) \
;         __builtin_amdgcn_global_load_lds((const unsigned*)((const char*)(gbase) + (voff)[_i]), (PG8_LAS unsigned*)(lds + (bufoff) + ldsw + _i * 8192), 16, 0, 0); } while (0)
; #define PG8_LDA(dst, b, h) do { _Pragma("unroll") for (int m = 0; m < 4; ++m) _Pragma("unroll") for (int k = 0; k < 2; ++k) dst[m][k] = *(const PG8_LAS bf16x8*)(lds + PG8_SA(b, h) + aoff + m * 2048 + k * 1024); } while (0)
; #define PG8_LDB(dst, b, h) do { _Pragma("unroll") for (int n = 0; n < 2; ++n) _Pragma("unroll") for (int k = 0; k < 2; ++k) dst[n][k] = *(const PG8_LAS bf16x8*)(lds + PG8_SB(b, h) + boff + n * 2048 + k * 1024); } while (0)
; #define PG8_WAIT_V(n) asm volatile("s_waitcnt vmcnt(" #n ")" ::: "memory")
; #define PG8_WAIT_L(n) asm volatile("s_waitcnt lgkmcnt(" #n ")" ::: "memory")
; #define PG8_BAR __builtin_amdgcn_s_barrier()
; #define PG8_SCHED __builtin_amdgcn_sched_barrier(0)
; template <class Epi, class Sched, bool ALIGN_EPI = false, bool SP2 = false, bool I8 = false>
; __device__ __forceinline__ void gemm_phase(PG8_LAS unsigned char* lds, const Gemm g, const Sched& S, const Epi& E) {
;     ...
;             if constexpr (SP2) {
;             PG8_LDB(B0, 0, 0); PG8_LDB(B1, 0, 1); PG8_SCHED; PG8_LDA(At, 0, 0); PG8_STAGE(PG8_SA(1, 1), a1 + hstep, voffA);
;             PG8_WAIT_V(8); PG8_WAIT_L(0); PG8_BAR; PG8_MMA(0, 0, At, B0); PG8_MMA(0, 1, At, B1); PG8_BAR; PG8_SCHED;
;             PG8_LDA(At, 0, 1); PG8_STAGE(PG8_SB(0, 0), b2, voffB); PG8_STAGE(PG8_SB(0, 1), b2 + hstep, voffB); PG8_STAGE(PG8_SA(0, 0), a2, voffA);
;             PG8_WAIT_V(8); PG8_WAIT_L(0); PG8_BAR; PG8_MMA(1, 0, At, B0); PG8_MMA(1, 1, At, B1); PG8_BAR; PG8_SCHED;
;             PG8_LDB(B0, 1, 0); PG8_LDB(B1, 1, 1); PG8_SCHED; PG8_LDA(At, 1, 0); PG8_STAGE(PG8_SA(0, 1), a2 + hstep, voffA);
;             PG8_WAIT_V(8); PG8_WAIT_L(0); PG8_BAR; PG8_MMA(0, 0, At, B0); PG8_MMA(0, 1, At, B1); PG8_BAR; PG8_SCHED;
;             PG8_LDA(At, 1, 1); PG8_STAGE(PG8_SB(1, 0), b3, voffB); PG8_STAGE(PG8_SB(1, 1), b3 + hstep, voffB); PG8_STAGE(PG8_SA(1, 0), a3, voffA);
;             PG8_WAIT_V(8); PG8_WAIT_L(0); PG8_BAR; PG8_MMA(1, 0, At, B0); PG8_MMA(1, 1, At, B1); PG8_BAR; PG8_SCHED;
	s_setprio 1
	s_waitcnt lgkmcnt(0)
	v_mfma_f32_16x16x32_bf16 v[124:127], v[146:149], v[178:181], v[124:127]
	v_mfma_f32_16x16x32_bf16 v[124:127], v[150:153], v[182:185], v[124:127]
	v_mfma_f32_16x16x32_bf16 v[112:115], v[146:149], v[186:189], v[112:115]
	v_mfma_f32_16x16x32_bf16 v[112:115], v[150:153], v[204:207], v[112:115]
	v_mfma_f32_16x16x32_bf16 v[96:99], v[146:149], v[208:211], v[96:99]
	v_mfma_f32_16x16x32_bf16 v[96:99], v[150:153], v[212:215], v[96:99]
	v_mfma_f32_16x16x32_bf16 v[80:83], v[146:149], v[216:219], v[80:83]
	v_mfma_f32_16x16x32_bf16 v[80:83], v[150:153], v[220:223], v[80:83]
	v_mfma_f32_16x16x32_bf16 v[128:131], v[154:157], v[178:181], v[128:131]
	v_mfma_f32_16x16x32_bf16 v[128:131], v[158:161], v[182:185], v[128:131]
	v_mfma_f32_16x16x32_bf16 v[108:111], v[154:157], v[186:189], v[108:111]
	v_mfma_f32_16x16x32_bf16 v[108:111], v[158:161], v[204:207], v[108:111]
	v_mfma_f32_16x16x32_bf16 v[92:95], v[154:157], v[208:211], v[92:95]
	v_mfma_f32_16x16x32_bf16 v[92:95], v[158:161], v[212:215], v[92:95]
	v_mfma_f32_16x16x32_bf16 v[76:79], v[154:157], v[216:219], v[76:79]
	v_mfma_f32_16x16x32_bf16 v[76:79], v[158:161], v[220:223], v[76:79]
	s_setprio 0
	s_setprio 1
	v_mfma_f32_16x16x32_bf16 v[120:123], v[162:165], v[178:181], v[120:123]
	v_mfma_f32_16x16x32_bf16 v[120:123], v[166:169], v[182:185], v[120:123]
	v_mfma_f32_16x16x32_bf16 v[104:107], v[162:165], v[186:189], v[104:107]
	v_mfma_f32_16x16x32_bf16 v[104:107], v[166:169], v[204:207], v[104:107]
	v_mfma_f32_16x16x32_bf16 v[88:91], v[162:165], v[208:211], v[88:91]
	v_mfma_f32_16x16x32_bf16 v[88:91], v[166:169], v[212:215], v[88:91]
	v_mfma_f32_16x16x32_bf16 v[72:75], v[162:165], v[216:219], v[72:75]
	v_mfma_f32_16x16x32_bf16 v[72:75], v[166:169], v[220:223], v[72:75]
	v_mfma_f32_16x16x32_bf16 v[116:119], v[170:173], v[178:181], v[116:119]
	v_mfma_f32_16x16x32_bf16 v[116:119], v[174:177], v[182:185], v[116:119]
	v_mfma_f32_16x16x32_bf16 v[100:103], v[170:173], v[186:189], v[100:103]
	v_mfma_f32_16x16x32_bf16 v[100:103], v[174:177], v[204:207], v[100:103]
	v_mfma_f32_16x16x32_bf16 v[84:87], v[170:173], v[208:211], v[84:87]
	v_mfma_f32_16x16x32_bf16 v[84:87], v[174:177], v[212:215], v[84:87]
	v_mfma_f32_16x16x32_bf16 v[68:71], v[170:173], v[216:219], v[68:71]
	v_mfma_f32_16x16x32_bf16 v[68:71], v[174:177], v[220:223], v[68:71]
	s_setprio 0
	s_barrier
	s_add_i32 s48, s73, s28
	v_lshl_add_u64 v[190:191], v[190:191], 0, s[84:85]
	s_mov_b32 m0, s48
	ds_read_b128 v[178:181], v145 offset:49152
	ds_read_b128 v[182:185], v145 offset:50176
	ds_read_b128 v[186:189], v145 offset:51200
	ds_read_b128 v[204:207], v145 offset:52224
	ds_read_b128 v[208:211], v145 offset:53248
	ds_read_b128 v[212:215], v145 offset:54272
	ds_read_b128 v[216:219], v145 offset:55296
	ds_read_b128 v[220:223], v145 offset:56320
	global_load_lds_dwordx4 v[190:191], off
	v_lshl_add_u64 v[190:191], v[224:225], 0, s[84:85]
	s_add_i32 m0, s48, 0x2000
	s_add_i32 s48, s76, s28
	global_load_lds_dwordx4 v[190:191], off
	v_lshl_add_u64 v[190:191], v[226:227], 0, s[84:85]
	s_mov_b32 m0, s48
	s_nop 0
	global_load_lds_dwordx4 v[190:191], off
	v_lshl_add_u64 v[190:191], v[228:229], 0, s[84:85]
	s_add_i32 m0, s48, 0x2000
	s_nop 0
	global_load_lds_dwordx4 v[190:191], off
	v_lshl_add_u64 v[190:191], v[240:241], 0, s[84:85]
	s_mov_b32 m0, s55
	s_nop 0
	global_load_lds_dwordx4 v[190:191], off
	v_lshl_add_u64 v[190:191], v[242:243], 0, s[84:85]
	s_mov_b32 m0, s56
	s_nop 0
	global_load_lds_dwordx4 v[190:191], off
	s_waitcnt vmcnt(8)
	s_waitcnt lgkmcnt(0)
	s_barrier
	s_setprio 1
	s_waitcnt lgkmcnt(0)
	v_mfma_f32_16x16x32_bf16 v[64:67], v[146:149], v[178:181], v[64:67]
	v_mfma_f32_16x16x32_bf16 v[64:67], v[150:153], v[182:185], v[64:67]
	v_mfma_f32_16x16x32_bf16 v[48:51], v[146:149], v[186:189], v[48:51]
	v_mfma_f32_16x16x32_bf16 v[48:51], v[150:153], v[204:207], v[48:51]
	v_mfma_f32_16x16x32_bf16 v[32:35], v[146:149], v[208:211], v[32:35]
	v_mfma_f32_16x16x32_bf16 v[32:35], v[150:153], v[212:215], v[32:35]
	v_mfma_f32_16x16x32_bf16 v[16:19], v[146:149], v[216:219], v[16:19]
	v_mfma_f32_16x16x32_bf16 v[16:19], v[150:153], v[220:223], v[16:19]
	v_mfma_f32_16x16x32_bf16 v[60:63], v[154:157], v[178:181], v[60:63]
	v_mfma_f32_16x16x32_bf16 v[60:63], v[158:161], v[182:185], v[60:63]
	v_mfma_f32_16x16x32_bf16 v[44:47], v[154:157], v[186:189], v[44:47]
	v_mfma_f32_16x16x32_bf16 v[44:47], v[158:161], v[204:207], v[44:47]
	v_mfma_f32_16x16x32_bf16 v[28:31], v[154:157], v[208:211], v[28:31]
	v_mfma_f32_16x16x32_bf16 v[28:31], v[158:161], v[212:215], v[28:31]
	v_mfma_f32_16x16x32_bf16 v[12:15], v[154:157], v[216:219], v[12:15]
	v_mfma_f32_16x16x32_bf16 v[12:15], v[158:161], v[220:223], v[12:15]
	s_setprio 0
	s_setprio 1
	v_mfma_f32_16x16x32_bf16 v[56:59], v[162:165], v[178:181], v[56:59]
	v_mfma_f32_16x16x32_bf16 v[56:59], v[166:169], v[182:185], v[56:59]
	v_mfma_f32_16x16x32_bf16 v[40:43], v[162:165], v[186:189], v[40:43]
	v_mfma_f32_16x16x32_bf16 v[40:43], v[166:169], v[204:207], v[40:43]
	v_mfma_f32_16x16x32_bf16 v[24:27], v[162:165], v[208:211], v[24:27]
	v_mfma_f32_16x16x32_bf16 v[24:27], v[166:169], v[212:215], v[24:27]
	v_mfma_f32_16x16x32_bf16 v[8:11], v[162:165], v[216:219], v[8:11]
	v_mfma_f32_16x16x32_bf16 v[8:11], v[166:169], v[220:223], v[8:11]
	v_mfma_f32_16x16x32_bf16 v[52:55], v[170:173], v[178:181], v[52:55]
	v_mfma_f32_16x16x32_bf16 v[52:55], v[174:177], v[182:185], v[52:55]
	v_mfma_f32_16x16x32_bf16 v[36:39], v[170:173], v[186:189], v[36:39]
	v_mfma_f32_16x16x32_bf16 v[36:39], v[174:177], v[204:207], v[36:39]
	v_mfma_f32_16x16x32_bf16 v[20:23], v[170:173], v[208:211], v[20:23]
	v_mfma_f32_16x16x32_bf16 v[20:23], v[174:177], v[212:215], v[20:23]
	v_mfma_f32_16x16x32_bf16 v[4:7], v[170:173], v[216:219], v[4:7]
	v_mfma_f32_16x16x32_bf16 v[4:7], v[174:177], v[220:223], v[4:7]
	s_setprio 0
	s_barrier
	s_add_u32 s44, s44, 0x100
	s_addc_u32 s45, s45, 0
	s_add_u32 s65, s65, 0x100
	s_addc_u32 s67, s67, 0
	s_cmp_ge_i32 s72, s53
	s_mov_b32 s48, s72
	s_cbranch_scc0 .LBB0_1623

; #define PG8_STAGE(bufoff, gbase, voff) do { _Pragma("unroll") for (int _i = 0; _i < 2; ++_i) \
;         __builtin_amdgcn_global_load_lds((const unsigned*)((const char*)(gbase) + (voff)[_i]), (PG8_LAS unsigned*)(lds + (bufoff) + ldsw + _i * 8192), 16, 0, 0); } while (0)
; #define PG8_LDA(dst, b, h) do { _Pragma("unroll") for (int m = 0; m < 4; ++m) _Pragma("unroll") for (int k = 0; k < 2; ++k) dst[m][k] = *(const PG8_LAS bf16x8*)(lds + PG8_SA(b, h) + aoff + m * 2048 + k * 1024); } while (0)
; #define PG8_LDB(dst, b, h) do { _Pragma("unroll") for (int n = 0; n < 2; ++n) _Pragma("unroll") for (int k = 0; k < 2; ++k) dst[n][k] = *(const PG8_LAS bf16x8*)(lds + PG8_SB(b, h) + boff + n * 2048 + k * 1024); } while (0)
; #define PG8_WAIT_V(n) asm volatile("s_waitcnt vmcnt(" #n ")" ::: "memory")
; #define PG8_WAIT_L(n) asm volatile("s_waitcnt lgkmcnt(" #n ")" ::: "memory")
; #define PG8_BAR __builtin_amdgcn_s_barrier()
; #define PG8_SCHED __builtin_amdgcn_sched_barrier(0)
; template <class Epi, class Sched, bool ALIGN_EPI = false, bool SP2 = false, bool I8 = false>
; __device__ __forceinline__ void gemm_phase(PG8_LAS unsigned char* lds, const Gemm g, const Sched& S, const Epi& E) {
;     ...
;         const bool has_next = S.next(ui + 1, nxt);
;         const char* nA = has_next ? (const char*)g.A + (size_t)nxt.pm * tstep : cA; const char* nB = has_next ? (const char*)g.Bt + (size_t)nxt.pn * tstep : cB;
;         for (int t = 0; t < nt; t += 2) {
;             const bool last = (t == nt - 2);
;             const char* a1 = cA + (size_t)(t + 1) * kstep;
;             const char* a2 = last ? nA : cA + (size_t)(t + 2) * kstep; const char* b2 = last ? nB : cB + (size_t)(t + 2) * kstep;
;             const char* a3 = a2 + kstep; const char* b3 = b2 + kstep;
;             if (last && has_next) S.a_ready(nxt);
;             if constexpr (SP2) {
;             PG8_LDB(B0, 0, 0); PG8_LDB(B1, 0, 1); PG8_SCHED; PG8_LDA(At, 0, 0); PG8_STAGE(PG8_SA(1, 1), a1 + hstep, voffA);
;             PG8_WAIT_V(8); PG8_WAIT_L(0); PG8_BAR; PG8_MMA(0, 0, At, B0); PG8_MMA(0, 1, At, B1); PG8_BAR; PG8_SCHED;
;             PG8_LDA(At, 0, 1); PG8_STAGE(PG8_SB(0, 0), b2, voffB); PG8_STAGE(PG8_SB(0, 1), b2 + hstep, voffB); PG8_STAGE(PG8_SA(0, 0), a2, voffA);
;             PG8_WAIT_V(8); PG8_WAIT_L(0); PG8_BAR; PG8_MMA(1, 0, At, B0); PG8_MMA(1, 1, At, B1); PG8_BAR; PG8_SCHED;
.LBB0_1699:
	s_add_u32 s53, s24, 0x100
	s_addc_u32 s54, s25, 0
	s_mov_b32 s55, -2
	s_add_u32 s24, s22, 0x100
	s_addc_u32 s25, s23, 0
	s_add_i32 s56, 0, 0x10000
	s_cmpk_eq_i32 s55, 0xa8
	s_cselect_b32 s37, s13, s25
	s_cselect_b32 s36, s12, s24
	s_cselect_b32 s27, s21, s54
	s_cselect_b32 s26, s20, s53
	s_add_i32 s57, 0, 0x14000
	v_add_u32_e32 v144, s56, v240
	v_add_u32_e32 v160, s57, v240
	ds_read_b128 v[124:127], v144
	ds_read_b128 v[128:131], v144 offset:1024
	ds_read_b128 v[132:135], v144 offset:2048
	ds_read_b128 v[144:147], v144 offset:3072
	ds_read_b128 v[148:151], v160
	ds_read_b128 v[152:155], v160 offset:1024
	ds_read_b128 v[156:159], v160 offset:2048
	ds_read_b128 v[160:163], v160 offset:3072
	v_lshl_add_u64 v[218:219], s[22:23], 0, v[210:211]
	s_add_i32 m0, s42, 0xc000
	ds_read_b128 v[164:167], v242
	ds_read_b128 v[168:171], v242 offset:1024
	ds_read_b128 v[172:175], v242 offset:2048
	ds_read_b128 v[176:179], v242 offset:3072
	ds_read_b128 v[180:183], v242 offset:4096
	ds_read_b128 v[184:187], v242 offset:5120
	ds_read_b128 v[188:191], v242 offset:6144
	ds_read_b128 v[214:217], v242 offset:7168
	global_load_lds_dwordx4 v[218:219], off
	v_lshl_add_u64 v[218:219], s[22:23], 0, v[212:213]
	s_add_i32 m0, s42, 0xe000
	s_nop 0
	global_load_lds_dwordx4 v[218:219], off
	s_waitcnt vmcnt(8)
	s_waitcnt lgkmcnt(0)
	s_barrier
	s_setprio 1
	s_waitcnt lgkmcnt(0)
	v_mfma_f32_16x16x32_bf16 v[140:143], v[124:127], v[164:167], 0
	v_mfma_f32_16x16x32_bf16 v[140:143], v[128:131], v[168:171], v[140:143]
	v_mfma_f32_16x16x32_bf16 v[112:115], v[124:127], v[172:175], 0
	v_mfma_f32_16x16x32_bf16 v[112:115], v[128:131], v[176:179], v[112:115]
	v_mfma_f32_16x16x32_bf16 v[96:99], v[124:127], v[180:183], 0
	v_mfma_f32_16x16x32_bf16 v[96:99], v[128:131], v[184:187], v[96:99]
	v_mfma_f32_16x16x32_bf16 v[80:83], v[124:127], v[188:191], 0
	v_mfma_f32_16x16x32_bf16 v[80:83], v[128:131], v[214:217], v[80:83]
	v_mfma_f32_16x16x32_bf16 v[136:139], v[132:135], v[164:167], 0
	v_mfma_f32_16x16x32_bf16 v[136:139], v[144:147], v[168:171], v[136:139]
	v_mfma_f32_16x16x32_bf16 v[108:111], v[132:135], v[172:175], 0
	v_mfma_f32_16x16x32_bf16 v[108:111], v[144:147], v[176:179], v[108:111]
	v_mfma_f32_16x16x32_bf16 v[92:95], v[132:135], v[180:183], 0
	v_mfma_f32_16x16x32_bf16 v[92:95], v[144:147], v[184:187], v[92:95]
	v_mfma_f32_16x16x32_bf16 v[76:79], v[132:135], v[188:191], 0
	v_mfma_f32_16x16x32_bf16 v[76:79], v[144:147], v[214:217], v[76:79]
	s_setprio 0
	s_setprio 1
	v_mfma_f32_16x16x32_bf16 v[120:123], v[148:151], v[164:167], 0
	v_mfma_f32_16x16x32_bf16 v[120:123], v[152:155], v[168:171], v[120:123]
	v_mfma_f32_16x16x32_bf16 v[104:107], v[148:151], v[172:175], 0
	v_mfma_f32_16x16x32_bf16 v[104:107], v[152:155], v[176:179], v[104:107]
	v_mfma_f32_16x16x32_bf16 v[88:91], v[148:151], v[180:183], 0
	v_mfma_f32_16x16x32_bf16 v[88:91], v[152:155], v[184:187], v[88:91]
	v_mfma_f32_16x16x32_bf16 v[72:75], v[148:151], v[188:191], 0
	v_mfma_f32_16x16x32_bf16 v[72:75], v[152:155], v[214:217], v[72:75]
	v_mfma_f32_16x16x32_bf16 v[116:119], v[156:159], v[164:167], 0
	v_mfma_f32_16x16x32_bf16 v[116:119], v[160:163], v[168:171], v[116:119]
	v_mfma_f32_16x16x32_bf16 v[100:103], v[156:159], v[172:175], 0
	v_mfma_f32_16x16x32_bf16 v[100:103], v[160:163], v[176:179], v[100:103]
	v_mfma_f32_16x16x32_bf16 v[84:87], v[156:159], v[180:183], 0
	v_mfma_f32_16x16x32_bf16 v[84:87], v[160:163], v[184:187], v[84:87]
	v_mfma_f32_16x16x32_bf16 v[68:71], v[156:159], v[188:191], 0
	v_mfma_f32_16x16x32_bf16 v[68:71], v[160:163], v[214:217], v[68:71]
	s_setprio 0
	s_barrier
	s_add_i32 s22, s56, s41
	v_lshl_add_u64 v[218:219], s[26:27], 0, v[2:3]
	s_mov_b32 m0, s22
	ds_read_b128 v[164:167], v242 offset:16384
	ds_read_b128 v[168:171], v242 offset:17408
	ds_read_b128 v[172:175], v242 offset:18432
	ds_read_b128 v[176:179], v242 offset:19456
	ds_read_b128 v[180:183], v242 offset:20480
	ds_read_b128 v[184:187], v242 offset:21504
	ds_read_b128 v[188:191], v242 offset:22528
	ds_read_b128 v[214:217], v242 offset:23552
	global_load_lds_dwordx4 v[218:219], off
	s_add_i32 m0, s22, 0x2000
	s_add_u32 s22, s26, 0x2b0000
	v_lshl_add_u64 v[220:221], s[26:27], 0, v[204:205]
	s_addc_u32 s23, s27, 0
	s_add_i32 s56, s57, s41
	global_load_lds_dwordx4 v[220:221], off
	v_lshl_add_u64 v[222:223], s[22:23], 0, v[2:3]
	s_mov_b32 m0, s56
	v_lshl_add_u64 v[224:225], s[36:37], 0, v[206:207]
	global_load_lds_dwordx4 v[222:223], off
	v_lshl_add_u64 v[222:223], s[22:23], 0, v[204:205]
	s_add_i32 m0, s56, 0x2000
	s_nop 0
	global_load_lds_dwordx4 v[222:223], off
	v_lshl_add_u64 v[222:223], s[36:37], 0, v[208:209]
	s_mov_b32 m0, s42
	s_nop 0
	global_load_lds_dwordx4 v[222:223], off
	s_mov_b32 m0, s43
	s_nop 0
	global_load_lds_dwordx4 v[224:225], off
	s_waitcnt vmcnt(8)
	s_waitcnt lgkmcnt(0)
	s_barrier
; #define PG8_STAGE(bufoff, gbase, voff) do { _Pragma("unroll") for (int _i = 0; _i < 2; ++_i) \
;         __builtin_amdgcn_global_load_lds((const unsigned*)((const char*)(gbase) + (voff)[_i]), (PG8_LAS unsigned*)(lds + (bufoff) + ldsw + _i * 8192), 16, 0, 0); } while (0)
; #define PG8_LDA(dst, b, h) do { _Pragma("unroll") for (int m = 0; m < 4; ++m) _Pragma("unroll") for (int k = 0; k < 2; ++k) dst[m][k] = *(const PG8_LAS bf16x8*)(lds + PG8_SA(b, h) + aoff + m * 2048 + k * 1024); } while (0)
; #define PG8_LDB(dst, b, h) do { _Pragma("unroll") for (int n = 0; n < 2; ++n) _Pragma("unroll") for (int k = 0; k < 2; ++k) dst[n][k] = *(const PG8_LAS bf16x8*)(lds + PG8_SB(b, h) + boff + n * 2048 + k * 1024); } while (0)
; #define PG8_WAIT_V(n) asm volatile("s_waitcnt vmcnt(" #n ")" ::: "memory")
; #define PG8_WAIT_L(n) asm volatile("s_waitcnt lgkmcnt(" #n ")" ::: "memory")
; #define PG8_BAR __builtin_amdgcn_s_barrier()
; #define PG8_SCHED __builtin_amdgcn_sched_barrier(0)
; template <class Epi, class Sched, bool ALIGN_EPI = false, bool SP2 = false, bool I8 = false>
; __device__ __forceinline__ void gemm_phase(PG8_LAS unsigned char* lds, const Gemm g, const Sched& S, const Epi& E) {
;     ...
;             if constexpr (SP2) {
;             PG8_LDB(B0, 0, 0); PG8_LDB(B1, 0, 1); PG8_SCHED; PG8_LDA(At, 0, 0); PG8_STAGE(PG8_SA(1, 1), a1 + hstep, voffA);
;             PG8_WAIT_V(8); PG8_WAIT_L(0); PG8_BAR; PG8_MMA(0, 0, At, B0); PG8_MMA(0, 1, At, B1); PG8_BAR; PG8_SCHED;
;             PG8_LDA(At, 0, 1); PG8_STAGE(PG8_SB(0, 0), b2, voffB); PG8_STAGE(PG8_SB(0, 1), b2 + hstep, voffB); PG8_STAGE(PG8_SA(0, 0), a2, voffA);
;             PG8_WAIT_V(8); PG8_WAIT_L(0); PG8_BAR; PG8_MMA(1, 0, At, B0); PG8_MMA(1, 1, At, B1); PG8_BAR; PG8_SCHED;
;             PG8_LDB(B0, 1, 0); PG8_LDB(B1, 1, 1); PG8_SCHED; PG8_LDA(At, 1, 0); PG8_STAGE(PG8_SA(0, 1), a2 + hstep, voffA);
;             PG8_WAIT_V(8); PG8_WAIT_L(0); PG8_BAR; PG8_MMA(0, 0, At, B0); PG8_MMA(0, 1, At, B1); PG8_BAR; PG8_SCHED;
;             PG8_LDA(At, 1, 1); PG8_STAGE(PG8_SB(1, 0), b3, voffB); PG8_STAGE(PG8_SB(1, 1), b3 + hstep, voffB); PG8_STAGE(PG8_SA(1, 0), a3, voffA);
;             PG8_WAIT_V(8); PG8_WAIT_L(0); PG8_BAR; PG8_MMA(1, 0, At, B0); PG8_MMA(1, 1, At, B1); PG8_BAR; PG8_SCHED;
	s_setprio 1
	s_waitcnt lgkmcnt(0)
	v_mfma_f32_16x16x32_bf16 v[64:67], v[124:127], v[164:167], 0
	v_mfma_f32_16x16x32_bf16 v[64:67], v[128:131], v[168:171], v[64:67]
	v_mfma_f32_16x16x32_bf16 v[48:51], v[124:127], v[172:175], 0
	v_mfma_f32_16x16x32_bf16 v[48:51], v[128:131], v[176:179], v[48:51]
	v_mfma_f32_16x16x32_bf16 v[32:35], v[124:127], v[180:183], 0
	v_mfma_f32_16x16x32_bf16 v[32:35], v[128:131], v[184:187], v[32:35]
	v_mfma_f32_16x16x32_bf16 v[16:19], v[124:127], v[188:191], 0
	v_mfma_f32_16x16x32_bf16 v[16:19], v[128:131], v[214:217], v[16:19]
	v_mfma_f32_16x16x32_bf16 v[60:63], v[132:135], v[164:167], 0
	v_mfma_f32_16x16x32_bf16 v[60:63], v[144:147], v[168:171], v[60:63]
	v_mfma_f32_16x16x32_bf16 v[44:47], v[132:135], v[172:175], 0
	v_mfma_f32_16x16x32_bf16 v[44:47], v[144:147], v[176:179], v[44:47]
	v_mfma_f32_16x16x32_bf16 v[28:31], v[132:135], v[180:183], 0
	v_mfma_f32_16x16x32_bf16 v[28:31], v[144:147], v[184:187], v[28:31]
	v_mfma_f32_16x16x32_bf16 v[12:15], v[132:135], v[188:191], 0
	v_mfma_f32_16x16x32_bf16 v[12:15], v[144:147], v[214:217], v[12:15]
	s_setprio 0
	s_setprio 1
	v_mfma_f32_16x16x32_bf16 v[56:59], v[148:151], v[164:167], 0
	v_mfma_f32_16x16x32_bf16 v[56:59], v[152:155], v[168:171], v[56:59]
	v_mfma_f32_16x16x32_bf16 v[40:43], v[148:151], v[172:175], 0
	v_mfma_f32_16x16x32_bf16 v[40:43], v[152:155], v[176:179], v[40:43]
	v_mfma_f32_16x16x32_bf16 v[24:27], v[148:151], v[180:183], 0
	v_mfma_f32_16x16x32_bf16 v[24:27], v[152:155], v[184:187], v[24:27]
	v_mfma_f32_16x16x32_bf16 v[8:11], v[148:151], v[188:191], 0
	v_mfma_f32_16x16x32_bf16 v[8:11], v[152:155], v[214:217], v[8:11]
	v_mfma_f32_16x16x32_bf16 v[52:55], v[156:159], v[164:167], 0
	v_mfma_f32_16x16x32_bf16 v[52:55], v[160:163], v[168:171], v[52:55]
	v_mfma_f32_16x16x32_bf16 v[36:39], v[156:159], v[172:175], 0
	v_mfma_f32_16x16x32_bf16 v[36:39], v[160:163], v[176:179], v[36:39]
	v_mfma_f32_16x16x32_bf16 v[20:23], v[156:159], v[180:183], 0
	v_mfma_f32_16x16x32_bf16 v[20:23], v[160:163], v[184:187], v[20:23]
	v_mfma_f32_16x16x32_bf16 v[4:7], v[156:159], v[188:191], 0
	v_mfma_f32_16x16x32_bf16 v[4:7], v[160:163], v[214:217], v[4:7]
	s_setprio 0
	s_barrier
	s_add_i32 s56, 0, 0x18000
	s_add_i32 s57, 0, 0x1c000
	v_add_u32_e32 v144, s56, v240
	v_add_u32_e32 v160, s57, v240
	ds_read_b128 v[124:127], v144
	ds_read_b128 v[128:131], v144 offset:1024
	ds_read_b128 v[132:135], v144 offset:2048
	ds_read_b128 v[144:147], v144 offset:3072
	ds_read_b128 v[148:151], v160
	ds_read_b128 v[152:155], v160 offset:1024
	ds_read_b128 v[156:159], v160 offset:2048
	ds_read_b128 v[160:163], v160 offset:3072
	s_add_u32 s22, s36, 0x2b0000
	s_addc_u32 s23, s37, 0
	s_mov_b32 m0, s44
	v_lshl_add_u64 v[226:227], s[22:23], 0, v[208:209]
	ds_read_b128 v[164:167], v242 offset:32768
	ds_read_b128 v[168:171], v242 offset:33792
	ds_read_b128 v[172:175], v242 offset:34816
	ds_read_b128 v[176:179], v242 offset:35840
	ds_read_b128 v[180:183], v242 offset:36864
	ds_read_b128 v[184:187], v242 offset:37888
	ds_read_b128 v[188:191], v242 offset:38912
	ds_read_b128 v[214:217], v242 offset:39936
	global_load_lds_dwordx4 v[226:227], off
	v_lshl_add_u64 v[226:227], s[22:23], 0, v[206:207]
	s_mov_b32 m0, s45
	s_nop 0
	global_load_lds_dwordx4 v[226:227], off
	s_waitcnt vmcnt(8)
	s_waitcnt lgkmcnt(0)
	s_barrier
	s_setprio 1
	s_waitcnt lgkmcnt(0)
	v_mfma_f32_16x16x32_bf16 v[140:143], v[124:127], v[164:167], v[140:143]
	v_mfma_f32_16x16x32_bf16 v[140:143], v[128:131], v[168:171], v[140:143]
	v_mfma_f32_16x16x32_bf16 v[112:115], v[124:127], v[172:175], v[112:115]
	v_mfma_f32_16x16x32_bf16 v[112:115], v[128:131], v[176:179], v[112:115]
	v_mfma_f32_16x16x32_bf16 v[96:99], v[124:127], v[180:183], v[96:99]
	v_mfma_f32_16x16x32_bf16 v[96:99], v[128:131], v[184:187], v[96:99]
	v_mfma_f32_16x16x32_bf16 v[80:83], v[124:127], v[188:191], v[80:83]
	v_mfma_f32_16x16x32_bf16 v[80:83], v[128:131], v[214:217], v[80:83]
	v_mfma_f32_16x16x32_bf16 v[136:139], v[132:135], v[164:167], v[136:139]
	v_mfma_f32_16x16x32_bf16 v[136:139], v[144:147], v[168:171], v[136:139]
	v_mfma_f32_16x16x32_bf16 v[108:111], v[132:135], v[172:175], v[108:111]
	v_mfma_f32_16x16x32_bf16 v[108:111], v[144:147], v[176:179], v[108:111]
	v_mfma_f32_16x16x32_bf16 v[92:95], v[132:135], v[180:183], v[92:95]
	v_mfma_f32_16x16x32_bf16 v[92:95], v[144:147], v[184:187], v[92:95]
	v_mfma_f32_16x16x32_bf16 v[76:79], v[132:135], v[188:191], v[76:79]
	v_mfma_f32_16x16x32_bf16 v[76:79], v[144:147], v[214:217], v[76:79]
	s_setprio 0
	s_setprio 1
	v_mfma_f32_16x16x32_bf16 v[120:123], v[148:151], v[164:167], v[120:123]
	v_mfma_f32_16x16x32_bf16 v[120:123], v[152:155], v[168:171], v[120:123]
	v_mfma_f32_16x16x32_bf16 v[104:107], v[148:151], v[172:175], v[104:107]
	v_mfma_f32_16x16x32_bf16 v[104:107], v[152:155], v[176:179], v[104:107]
	v_mfma_f32_16x16x32_bf16 v[88:91], v[148:151], v[180:183], v[88:91]
	v_mfma_f32_16x16x32_bf16 v[88:91], v[152:155], v[184:187], v[88:91]
	v_mfma_f32_16x16x32_bf16 v[72:75], v[148:151], v[188:191], v[72:75]
	v_mfma_f32_16x16x32_bf16 v[72:75], v[152:155], v[214:217], v[72:75]
	v_mfma_f32_16x16x32_bf16 v[116:119], v[156:159], v[164:167], v[116:119]
	v_mfma_f32_16x16x32_bf16 v[116:119], v[160:163], v[168:171], v[116:119]
	v_mfma_f32_16x16x32_bf16 v[100:103], v[156:159], v[172:175], v[100:103]
	v_mfma_f32_16x16x32_bf16 v[100:103], v[160:163], v[176:179], v[100:103]
	v_mfma_f32_16x16x32_bf16 v[84:87], v[156:159], v[180:183], v[84:87]
	v_mfma_f32_16x16x32_bf16 v[84:87], v[160:163], v[184:187], v[84:87]
	v_mfma_f32_16x16x32_bf16 v[68:71], v[156:159], v[188:191], v[68:71]
	v_mfma_f32_16x16x32_bf16 v[68:71], v[160:163], v[214:217], v[68:71]
	s_setprio 0
	s_barrier
; #define PG8_STAGE(bufoff, gbase, voff) do { _Pragma("unroll") for (int _i = 0; _i < 2; ++_i) \
;         __builtin_amdgcn_global_load_lds((const unsigned*)((const char*)(gbase) + (voff)[_i]), (PG8_LAS unsigned*)(lds + (bufoff) + ldsw + _i * 8192), 16, 0, 0); } while (0)
; #define PG8_LDA(dst, b, h) do { _Pragma("unroll") for (int m = 0; m < 4; ++m) _Pragma("unroll") for (int k = 0; k < 2; ++k) dst[m][k] = *(const PG8_LAS bf16x8*)(lds + PG8_SA(b, h) + aoff + m * 2048 + k * 1024); } while (0)
; #define PG8_LDB(dst, b, h) do { _Pragma("unroll") for (int n = 0; n < 2; ++n) _Pragma("unroll") for (int k = 0; k < 2; ++k) dst[n][k] = *(const PG8_LAS bf16x8*)(lds + PG8_SB(b, h) + boff + n * 2048 + k * 1024); } while (0)
; #define PG8_WAIT_V(n) asm volatile("s_waitcnt vmcnt(" #n ")" ::: "memory")
; #define PG8_WAIT_L(n) asm volatile("s_waitcnt lgkmcnt(" #n ")" ::: "memory")
; #define PG8_BAR __builtin_amdgcn_s_barrier()
; #define PG8_SCHED __builtin_amdgcn_sched_barrier(0)
; template <class Epi, class Sched, bool ALIGN_EPI = false, bool SP2 = false, bool I8 = false>
; __device__ __forceinline__ void gemm_phase(PG8_LAS unsigned char* lds, const Gemm g, const Sched& S, const Epi& E) {
;     ...
;             if constexpr (SP2) {
;             PG8_LDB(B0, 0, 0); PG8_LDB(B1, 0, 1); PG8_SCHED; PG8_LDA(At, 0, 0); PG8_STAGE(PG8_SA(1, 1), a1 + hstep, voffA);
;             PG8_WAIT_V(8); PG8_WAIT_L(0); PG8_BAR; PG8_MMA(0, 0, At, B0); PG8_MMA(0, 1, At, B1); PG8_BAR; PG8_SCHED;
;             PG8_LDA(At, 0, 1); PG8_STAGE(PG8_SB(0, 0), b2, voffB); PG8_STAGE(PG8_SB(0, 1), b2 + hstep, voffB); PG8_STAGE(PG8_SA(0, 0), a2, voffA);
;             PG8_WAIT_V(8); PG8_WAIT_L(0); PG8_BAR; PG8_MMA(1, 0, At, B0); PG8_MMA(1, 1, At, B1); PG8_BAR; PG8_SCHED;
;             PG8_LDB(B0, 1, 0); PG8_LDB(B1, 1, 1); PG8_SCHED; PG8_LDA(At, 1, 0); PG8_STAGE(PG8_SA(0, 1), a2 + hstep, voffA);
;             PG8_WAIT_V(8); PG8_WAIT_L(0); PG8_BAR; PG8_MMA(0, 0, At, B0); PG8_MMA(0, 1, At, B1); PG8_BAR; PG8_SCHED;
;             PG8_LDA(At, 1, 1); PG8_STAGE(PG8_SB(1, 0), b3, voffB); PG8_STAGE(PG8_SB(1, 1), b3 + hstep, voffB); PG8_STAGE(PG8_SA(1, 0), a3, voffA);
;             PG8_WAIT_V(8); PG8_WAIT_L(0); PG8_BAR; PG8_MMA(1, 0, At, B0); PG8_MMA(1, 1, At, B1); PG8_BAR; PG8_SCHED;
	s_add_i32 s22, s56, s41
	v_lshl_add_u64 v[218:219], v[218:219], 0, s[84:85]
	s_mov_b32 m0, s22
	ds_read_b128 v[164:167], v242 offset:49152
	ds_read_b128 v[168:171], v242 offset:50176
	ds_read_b128 v[172:175], v242 offset:51200
	ds_read_b128 v[176:179], v242 offset:52224
	ds_read_b128 v[180:183], v242 offset:53248
	ds_read_b128 v[184:187], v242 offset:54272
	ds_read_b128 v[188:191], v242 offset:55296
	ds_read_b128 v[214:217], v242 offset:56320
	global_load_lds_dwordx4 v[218:219], off
	s_add_i32 m0, s22, 0x2000
	s_add_u32 s22, s26, 0x2b0080
	v_lshl_add_u64 v[218:219], v[220:221], 0, s[84:85]
	s_addc_u32 s23, s27, 0
	s_add_i32 s26, s57, s41
	global_load_lds_dwordx4 v[218:219], off
	v_lshl_add_u64 v[218:219], s[22:23], 0, v[2:3]
	s_mov_b32 m0, s26
	s_nop 0
	global_load_lds_dwordx4 v[218:219], off
	v_lshl_add_u64 v[218:219], s[22:23], 0, v[204:205]
	s_add_i32 m0, s26, 0x2000
	s_nop 0
	global_load_lds_dwordx4 v[218:219], off
	v_lshl_add_u64 v[218:219], v[222:223], 0, s[84:85]
	s_mov_b32 m0, s46
	s_nop 0
	global_load_lds_dwordx4 v[218:219], off
	v_lshl_add_u64 v[218:219], v[224:225], 0, s[84:85]
	s_mov_b32 m0, s47
	s_nop 0
	global_load_lds_dwordx4 v[218:219], off
	s_waitcnt vmcnt(8)
	s_waitcnt lgkmcnt(0)
	s_barrier
	s_setprio 1
	s_waitcnt lgkmcnt(0)
	v_mfma_f32_16x16x32_bf16 v[64:67], v[124:127], v[164:167], v[64:67]
	v_mfma_f32_16x16x32_bf16 v[64:67], v[128:131], v[168:171], v[64:67]
	v_mfma_f32_16x16x32_bf16 v[48:51], v[124:127], v[172:175], v[48:51]
	v_mfma_f32_16x16x32_bf16 v[48:51], v[128:131], v[176:179], v[48:51]
	v_mfma_f32_16x16x32_bf16 v[32:35], v[124:127], v[180:183], v[32:35]
	v_mfma_f32_16x16x32_bf16 v[32:35], v[128:131], v[184:187], v[32:35]
	v_mfma_f32_16x16x32_bf16 v[16:19], v[124:127], v[188:191], v[16:19]
	v_mfma_f32_16x16x32_bf16 v[16:19], v[128:131], v[214:217], v[16:19]
	v_mfma_f32_16x16x32_bf16 v[60:63], v[132:135], v[164:167], v[60:63]
	v_mfma_f32_16x16x32_bf16 v[60:63], v[144:147], v[168:171], v[60:63]
	v_mfma_f32_16x16x32_bf16 v[44:47], v[132:135], v[172:175], v[44:47]
	v_mfma_f32_16x16x32_bf16 v[44:47], v[144:147], v[176:179], v[44:47]
	v_mfma_f32_16x16x32_bf16 v[28:31], v[132:135], v[180:183], v[28:31]
	v_mfma_f32_16x16x32_bf16 v[28:31], v[144:147], v[184:187], v[28:31]
	v_mfma_f32_16x16x32_bf16 v[12:15], v[132:135], v[188:191], v[12:15]
	v_mfma_f32_16x16x32_bf16 v[12:15], v[144:147], v[214:217], v[12:15]
	s_setprio 0
	s_setprio 1
	v_mfma_f32_16x16x32_bf16 v[56:59], v[148:151], v[164:167], v[56:59]
	v_mfma_f32_16x16x32_bf16 v[56:59], v[152:155], v[168:171], v[56:59]
	v_mfma_f32_16x16x32_bf16 v[40:43], v[148:151], v[172:175], v[40:43]
	v_mfma_f32_16x16x32_bf16 v[40:43], v[152:155], v[176:179], v[40:43]
	v_mfma_f32_16x16x32_bf16 v[24:27], v[148:151], v[180:183], v[24:27]
	v_mfma_f32_16x16x32_bf16 v[24:27], v[152:155], v[184:187], v[24:27]
	v_mfma_f32_16x16x32_bf16 v[8:11], v[148:151], v[188:191], v[8:11]
	v_mfma_f32_16x16x32_bf16 v[8:11], v[152:155], v[214:217], v[8:11]
	v_mfma_f32_16x16x32_bf16 v[52:55], v[156:159], v[164:167], v[52:55]
	v_mfma_f32_16x16x32_bf16 v[52:55], v[160:163], v[168:171], v[52:55]
	v_mfma_f32_16x16x32_bf16 v[36:39], v[156:159], v[172:175], v[36:39]
	v_mfma_f32_16x16x32_bf16 v[36:39], v[160:163], v[176:179], v[36:39]
	v_mfma_f32_16x16x32_bf16 v[20:23], v[156:159], v[180:183], v[20:23]
	v_mfma_f32_16x16x32_bf16 v[20:23], v[160:163], v[184:187], v[20:23]
	v_mfma_f32_16x16x32_bf16 v[4:7], v[156:159], v[188:191], v[4:7]
	v_mfma_f32_16x16x32_bf16 v[4:7], v[160:163], v[214:217], v[4:7]
	s_setprio 0
	s_barrier
	s_add_i32 s55, s55, 2
	s_add_u32 s53, s53, 0x100
	s_addc_u32 s54, s54, 0
	s_cmpk_gt_u32 s55, 0xa9
	s_mov_b64 s[22:23], s[24:25]
	s_cbranch_scc1 .Lkloop_exit_5
.LBB0_1700:
	s_add_u32 s24, s22, 0x100
	s_addc_u32 s25, s23, 0
	s_add_i32 s56, 0, 0x10000
	s_cmpk_eq_i32 s55, 0xa8
	s_cselect_b32 s37, s13, s25
	s_cselect_b32 s36, s12, s24
	s_cselect_b32 s27, s21, s54
	s_cselect_b32 s26, s20, s53
	s_add_i32 s57, 0, 0x14000
	v_add_u32_e32 v144, s56, v240
	v_add_u32_e32 v160, s57, v240
	ds_read_b128 v[124:127], v144
	ds_read_b128 v[128:131], v144 offset:1024
	ds_read_b128 v[132:135], v144 offset:2048
	ds_read_b128 v[144:147], v144 offset:3072
	ds_read_b128 v[148:151], v160
	ds_read_b128 v[152:155], v160 offset:1024
	ds_read_b128 v[156:159], v160 offset:2048
	ds_read_b128 v[160:163], v160 offset:3072
	v_lshl_add_u64 v[218:219], s[22:23], 0, v[210:211]
	s_add_i32 m0, s42, 0xc000
	ds_read_b128 v[164:167], v242
	ds_read_b128 v[168:171], v242 offset:1024
	ds_read_b128 v[172:175], v242 offset:2048
	ds_read_b128 v[176:179], v242 offset:3072
	ds_read_b128 v[180:183], v242 offset:4096
	ds_read_b128 v[184:187], v242 offset:5120
	ds_read_b128 v[188:191], v242 offset:6144
	ds_read_b128 v[214:217], v242 offset:7168
	global_load_lds_dwordx4 v[218:219], off
	v_lshl_add_u64 v[218:219], s[22:23], 0, v[212:213]
	s_add_i32 m0, s42, 0xe000
	s_nop 0
	global_load_lds_dwordx4 v[218:219], off
	s_waitcnt vmcnt(8)
	s_waitcnt lgkmcnt(0)
	s_barrier
; #define PG8_STAGE(bufoff, gbase, voff) do { _Pragma("unroll") for (int _i = 0; _i < 2; ++_i) \
;         __builtin_amdgcn_global_load_lds((const unsigned*)((const char*)(gbase) + (voff)[_i]), (PG8_LAS unsigned*)(lds + (bufoff) + ldsw + _i * 8192), 16, 0, 0); } while (0)
; #define PG8_LDA(dst, b, h) do { _Pragma("unroll") for (int m = 0; m < 4; ++m) _Pragma("unroll") for (int k = 0; k < 2; ++k) dst[m][k] = *(const PG8_LAS bf16x8*)(lds + PG8_SA(b, h) + aoff + m * 2048 + k * 1024); } while (0)
; #define PG8_LDB(dst, b, h) do { _Pragma("unroll") for (int n = 0; n < 2; ++n) _Pragma("unroll") for (int k = 0; k < 2; ++k) dst[n][k] = *(const PG8_LAS bf16x8*)(lds + PG8_SB(b, h) + boff + n * 2048 + k * 1024); } while (0)
; #define PG8_WAIT_V(n) asm volatile("s_waitcnt vmcnt(" #n ")" ::: "memory")
; #define PG8_WAIT_L(n) asm volatile("s_waitcnt lgkmcnt(" #n ")" ::: "memory")
; #define PG8_BAR __builtin_amdgcn_s_barrier()
; #define PG8_SCHED __builtin_amdgcn_sched_barrier(0)
; template <class Epi, class Sched, bool ALIGN_EPI = false, bool SP2 = false, bool I8 = false>
; __device__ __forceinline__ void gemm_phase(PG8_LAS unsigned char* lds, const Gemm g, const Sched& S, const Epi& E) {
;     ...
;             if constexpr (SP2) {
;             PG8_LDB(B0, 0, 0); PG8_LDB(B1, 0, 1); PG8_SCHED; PG8_LDA(At, 0, 0); PG8_STAGE(PG8_SA(1, 1), a1 + hstep, voffA);
;             PG8_WAIT_V(8); PG8_WAIT_L(0); PG8_BAR; PG8_MMA(0, 0, At, B0); PG8_MMA(0, 1, At, B1); PG8_BAR; PG8_SCHED;
;             PG8_LDA(At, 0, 1); PG8_STAGE(PG8_SB(0, 0), b2, voffB); PG8_STAGE(PG8_SB(0, 1), b2 + hstep, voffB); PG8_STAGE(PG8_SA(0, 0), a2, voffA);
;             PG8_WAIT_V(8); PG8_WAIT_L(0); PG8_BAR; PG8_MMA(1, 0, At, B0); PG8_MMA(1, 1, At, B1); PG8_BAR; PG8_SCHED;
;             PG8_LDB(B0, 1, 0); PG8_LDB(B1, 1, 1); PG8_SCHED; PG8_LDA(At, 1, 0); PG8_STAGE(PG8_SA(0, 1), a2 + hstep, voffA);
;             PG8_WAIT_V(8); PG8_WAIT_L(0); PG8_BAR; PG8_MMA(0, 0, At, B0); PG8_MMA(0, 1, At, B1); PG8_BAR; PG8_SCHED;
;             PG8_LDA(At, 1, 1); PG8_STAGE(PG8_SB(1, 0), b3, voffB); PG8_STAGE(PG8_SB(1, 1), b3 + hstep, voffB); PG8_STAGE(PG8_SA(1, 0), a3, voffA);
;             PG8_WAIT_V(8); PG8_WAIT_L(0); PG8_BAR; PG8_MMA(1, 0, At, B0); PG8_MMA(1, 1, At, B1); PG8_BAR; PG8_SCHED;
	s_setprio 1
	s_waitcnt lgkmcnt(0)
	v_mfma_f32_16x16x32_bf16 v[140:143], v[124:127], v[164:167], v[140:143]
	v_mfma_f32_16x16x32_bf16 v[140:143], v[128:131], v[168:171], v[140:143]
	v_mfma_f32_16x16x32_bf16 v[112:115], v[124:127], v[172:175], v[112:115]
	v_mfma_f32_16x16x32_bf16 v[112:115], v[128:131], v[176:179], v[112:115]
	v_mfma_f32_16x16x32_bf16 v[96:99], v[124:127], v[180:183], v[96:99]
	v_mfma_f32_16x16x32_bf16 v[96:99], v[128:131], v[184:187], v[96:99]
	v_mfma_f32_16x16x32_bf16 v[80:83], v[124:127], v[188:191], v[80:83]
	v_mfma_f32_16x16x32_bf16 v[80:83], v[128:131], v[214:217], v[80:83]
	v_mfma_f32_16x16x32_bf16 v[136:139], v[132:135], v[164:167], v[136:139]
	v_mfma_f32_16x16x32_bf16 v[136:139], v[144:147], v[168:171], v[136:139]
	v_mfma_f32_16x16x32_bf16 v[108:111], v[132:135], v[172:175], v[108:111]
	v_mfma_f32_16x16x32_bf16 v[108:111], v[144:147], v[176:179], v[108:111]
	v_mfma_f32_16x16x32_bf16 v[92:95], v[132:135], v[180:183], v[92:95]
	v_mfma_f32_16x16x32_bf16 v[92:95], v[144:147], v[184:187], v[92:95]
	v_mfma_f32_16x16x32_bf16 v[76:79], v[132:135], v[188:191], v[76:79]
	v_mfma_f32_16x16x32_bf16 v[76:79], v[144:147], v[214:217], v[76:79]
	s_setprio 0
	s_setprio 1
	v_mfma_f32_16x16x32_bf16 v[120:123], v[148:151], v[164:167], v[120:123]
	v_mfma_f32_16x16x32_bf16 v[120:123], v[152:155], v[168:171], v[120:123]
	v_mfma_f32_16x16x32_bf16 v[104:107], v[148:151], v[172:175], v[104:107]
	v_mfma_f32_16x16x32_bf16 v[104:107], v[152:155], v[176:179], v[104:107]
	v_mfma_f32_16x16x32_bf16 v[88:91], v[148:151], v[180:183], v[88:91]
	v_mfma_f32_16x16x32_bf16 v[88:91], v[152:155], v[184:187], v[88:91]
	v_mfma_f32_16x16x32_bf16 v[72:75], v[148:151], v[188:191], v[72:75]
	v_mfma_f32_16x16x32_bf16 v[72:75], v[152:155], v[214:217], v[72:75]
	v_mfma_f32_16x16x32_bf16 v[116:119], v[156:159], v[164:167], v[116:119]
	v_mfma_f32_16x16x32_bf16 v[116:119], v[160:163], v[168:171], v[116:119]
	v_mfma_f32_16x16x32_bf16 v[100:103], v[156:159], v[172:175], v[100:103]
	v_mfma_f32_16x16x32_bf16 v[100:103], v[160:163], v[176:179], v[100:103]
	v_mfma_f32_16x16x32_bf16 v[84:87], v[156:159], v[180:183], v[84:87]
	v_mfma_f32_16x16x32_bf16 v[84:87], v[160:163], v[184:187], v[84:87]
	v_mfma_f32_16x16x32_bf16 v[68:71], v[156:159], v[188:191], v[68:71]
	v_mfma_f32_16x16x32_bf16 v[68:71], v[160:163], v[214:217], v[68:71]
	s_setprio 0
	s_barrier
	s_add_i32 s22, s56, s41
	v_lshl_add_u64 v[218:219], s[26:27], 0, v[2:3]
	s_mov_b32 m0, s22
	ds_read_b128 v[164:167], v242 offset:16384
	ds_read_b128 v[168:171], v242 offset:17408
	ds_read_b128 v[172:175], v242 offset:18432
	ds_read_b128 v[176:179], v242 offset:19456
	ds_read_b128 v[180:183], v242 offset:20480
	ds_read_b128 v[184:187], v242 offset:21504
	ds_read_b128 v[188:191], v242 offset:22528
	ds_read_b128 v[214:217], v242 offset:23552
	global_load_lds_dwordx4 v[218:219], off
	s_add_i32 m0, s22, 0x2000
	s_add_u32 s22, s26, 0x2b0000
	v_lshl_add_u64 v[220:221], s[26:27], 0, v[204:205]
	s_addc_u32 s23, s27, 0
	s_add_i32 s56, s57, s41
	global_load_lds_dwordx4 v[220:221], off
	v_lshl_add_u64 v[222:223], s[22:23], 0, v[2:3]
	s_mov_b32 m0, s56
	v_lshl_add_u64 v[224:225], s[36:37], 0, v[206:207]
	global_load_lds_dwordx4 v[222:223], off
	v_lshl_add_u64 v[222:223], s[22:23], 0, v[204:205]
	s_add_i32 m0, s56, 0x2000
	s_nop 0
	global_load_lds_dwordx4 v[222:223], off
	v_lshl_add_u64 v[222:223], s[36:37], 0, v[208:209]
	s_mov_b32 m0, s42
	s_nop 0
	global_load_lds_dwordx4 v[222:223], off
	s_mov_b32 m0, s43
	s_nop 0
	global_load_lds_dwordx4 v[224:225], off
	s_waitcnt vmcnt(8)
	s_waitcnt lgkmcnt(0)
	s_barrier
	s_setprio 1
	s_waitcnt lgkmcnt(0)
	v_mfma_f32_16x16x32_bf16 v[64:67], v[124:127], v[164:167], v[64:67]
	v_mfma_f32_16x16x32_bf16 v[64:67], v[128:131], v[168:171], v[64:67]
	v_mfma_f32_16x16x32_bf16 v[48:51], v[124:127], v[172:175], v[48:51]
	v_mfma_f32_16x16x32_bf16 v[48:51], v[128:131], v[176:179], v[48:51]
	v_mfma_f32_16x16x32_bf16 v[32:35], v[124:127], v[180:183], v[32:35]
	v_mfma_f32_16x16x32_bf16 v[32:35], v[128:131], v[184:187], v[32:35]
	v_mfma_f32_16x16x32_bf16 v[16:19], v[124:127], v[188:191], v[16:19]
	v_mfma_f32_16x16x32_bf16 v[16:19], v[128:131], v[214:217], v[16:19]
	v_mfma_f32_16x16x32_bf16 v[60:63], v[132:135], v[164:167], v[60:63]
	v_mfma_f32_16x16x32_bf16 v[60:63], v[144:147], v[168:171], v[60:63]
	v_mfma_f32_16x16x32_bf16 v[44:47], v[132:135], v[172:175], v[44:47]
	v_mfma_f32_16x16x32_bf16 v[44:47], v[144:147], v[176:179], v[44:47]
	v_mfma_f32_16x16x32_bf16 v[28:31], v[132:135], v[180:183], v[28:31]
	v_mfma_f32_16x16x32_bf16 v[28:31], v[144:147], v[184:187], v[28:31]
	v_mfma_f32_16x16x32_bf16 v[12:15], v[132:135], v[188:191], v[12:15]
	v_mfma_f32_16x16x32_bf16 v[12:15], v[144:147], v[214:217], v[12:15]
	s_setprio 0
	s_setprio 1
	v_mfma_f32_16x16x32_bf16 v[56:59], v[148:151], v[164:167], v[56:59]
	v_mfma_f32_16x16x32_bf16 v[56:59], v[152:155], v[168:171], v[56:59]
	v_mfma_f32_16x16x32_bf16 v[40:43], v[148:151], v[172:175], v[40:43]
	v_mfma_f32_16x16x32_bf16 v[40:43], v[152:155], v[176:179], v[40:43]
	v_mfma_f32_16x16x32_bf16 v[24:27], v[148:151], v[180:183], v[24:27]
	v_mfma_f32_16x16x32_bf16 v[24:27], v[152:155], v[184:187], v[24:27]
	v_mfma_f32_16x16x32_bf16 v[8:11], v[148:151], v[188:191], v[8:11]
	v_mfma_f32_16x16x32_bf16 v[8:11], v[152:155], v[214:217], v[8:11]
	v_mfma_f32_16x16x32_bf16 v[52:55], v[156:159], v[164:167], v[52:55]
	v_mfma_f32_16x16x32_bf16 v[52:55], v[160:163], v[168:171], v[52:55]
	v_mfma_f32_16x16x32_bf16 v[36:39], v[156:159], v[172:175], v[36:39]
	v_mfma_f32_16x16x32_bf16 v[36:39], v[160:163], v[176:179], v[36:39]
	v_mfma_f32_16x16x32_bf16 v[20:23], v[156:159], v[180:183], v[20:23]
	v_mfma_f32_16x16x32_bf16 v[20:23], v[160:163], v[184:187], v[20:23]
	v_mfma_f32_16x16x32_bf16 v[4:7], v[156:159], v[188:191], v[4:7]
	v_mfma_f32_16x16x32_bf16 v[4:7], v[160:163], v[214:217], v[4:7]
	s_setprio 0
	s_barrier
; #define PG8_STAGE(bufoff, gbase, voff) do { _Pragma("unroll") for (int _i = 0; _i < 2; ++_i) \
;         __builtin_amdgcn_global_load_lds((const unsigned*)((const char*)(gbase) + (voff)[_i]), (PG8_LAS unsigned*)(lds + (bufoff) + ldsw + _i * 8192), 16, 0, 0); } while (0)
; #define PG8_LDA(dst, b, h) do { _Pragma("unroll") for (int m = 0; m < 4; ++m) _Pragma("unroll") for (int k = 0; k < 2; ++k) dst[m][k] = *(const PG8_LAS bf16x8*)(lds + PG8_SA(b, h) + aoff + m * 2048 + k * 1024); } while (0)
; #define PG8_LDB(dst, b, h) do { _Pragma("unroll") for (int n = 0; n < 2; ++n) _Pragma("unroll") for (int k = 0; k < 2; ++k) dst[n][k] = *(const PG8_LAS bf16x8*)(lds + PG8_SB(b, h) + boff + n * 2048 + k * 1024); } while (0)
; #define PG8_WAIT_V(n) asm volatile("s_waitcnt vmcnt(" #n ")" ::: "memory")
; #define PG8_WAIT_L(n) asm volatile("s_waitcnt lgkmcnt(" #n ")" ::: "memory")
; #define PG8_BAR __builtin_amdgcn_s_barrier()
; #define PG8_SCHED __builtin_amdgcn_sched_barrier(0)
; template <class Epi, class Sched, bool ALIGN_EPI = false, bool SP2 = false, bool I8 = false>
; __device__ __forceinline__ void gemm_phase(PG8_LAS unsigned char* lds, const Gemm g, const Sched& S, const Epi& E) {
;     ...
;             if constexpr (SP2) {
;             PG8_LDB(B0, 0, 0); PG8_LDB(B1, 0, 1); PG8_SCHED; PG8_LDA(At, 0, 0); PG8_STAGE(PG8_SA(1, 1), a1 + hstep, voffA);
;             PG8_WAIT_V(8); PG8_WAIT_L(0); PG8_BAR; PG8_MMA(0, 0, At, B0); PG8_MMA(0, 1, At, B1); PG8_BAR; PG8_SCHED;
;             PG8_LDA(At, 0, 1); PG8_STAGE(PG8_SB(0, 0), b2, voffB); PG8_STAGE(PG8_SB(0, 1), b2 + hstep, voffB); PG8_STAGE(PG8_SA(0, 0), a2, voffA);
;             PG8_WAIT_V(8); PG8_WAIT_L(0); PG8_BAR; PG8_MMA(1, 0, At, B0); PG8_MMA(1, 1, At, B1); PG8_BAR; PG8_SCHED;
;             PG8_LDB(B0, 1, 0); PG8_LDB(B1, 1, 1); PG8_SCHED; PG8_LDA(At, 1, 0); PG8_STAGE(PG8_SA(0, 1), a2 + hstep, voffA);
;             PG8_WAIT_V(8); PG8_WAIT_L(0); PG8_BAR; PG8_MMA(0, 0, At, B0); PG8_MMA(0, 1, At, B1); PG8_BAR; PG8_SCHED;
	s_add_i32 s56, 0, 0x18000
	s_add_i32 s57, 0, 0x1c000
	v_add_u32_e32 v144, s56, v240
	v_add_u32_e32 v160, s57, v240
	ds_read_b128 v[124:127], v144
	ds_read_b128 v[128:131], v144 offset:1024
	ds_read_b128 v[132:135], v144 offset:2048
	ds_read_b128 v[144:147], v144 offset:3072
	ds_read_b128 v[148:151], v160
	ds_read_b128 v[152:155], v160 offset:1024
	ds_read_b128 v[156:159], v160 offset:2048
	ds_read_b128 v[160:163], v160 offset:3072
	s_add_u32 s22, s36, 0x2b0000
	s_addc_u32 s23, s37, 0
	s_mov_b32 m0, s44
	v_lshl_add_u64 v[226:227], s[22:23], 0, v[208:209]
	ds_read_b128 v[164:167], v242 offset:32768
	ds_read_b128 v[168:171], v242 offset:33792
	ds_read_b128 v[172:175], v242 offset:34816
	ds_read_b128 v[176:179], v242 offset:35840
	ds_read_b128 v[180:183], v242 offset:36864
	ds_read_b128 v[184:187], v242 offset:37888
	ds_read_b128 v[188:191], v242 offset:38912
	ds_read_b128 v[214:217], v242 offset:39936
	global_load_lds_dwordx4 v[226:227], off
	v_lshl_add_u64 v[226:227], s[22:23], 0, v[206:207]
	s_mov_b32 m0, s45
	s_nop 0
	global_load_lds_dwordx4 v[226:227], off
	s_waitcnt vmcnt(8)
	s_waitcnt lgkmcnt(0)
	s_barrier
	s_setprio 1
	s_waitcnt lgkmcnt(0)
	v_mfma_f32_16x16x32_bf16 v[140:143], v[124:127], v[164:167], v[140:143]
	v_mfma_f32_16x16x32_bf16 v[140:143], v[128:131], v[168:171], v[140:143]
	v_mfma_f32_16x16x32_bf16 v[112:115], v[124:127], v[172:175], v[112:115]
	v_mfma_f32_16x16x32_bf16 v[112:115], v[128:131], v[176:179], v[112:115]
	v_mfma_f32_16x16x32_bf16 v[96:99], v[124:127], v[180:183], v[96:99]
	v_mfma_f32_16x16x32_bf16 v[96:99], v[128:131], v[184:187], v[96:99]
	v_mfma_f32_16x16x32_bf16 v[80:83], v[124:127], v[188:191], v[80:83]
	v_mfma_f32_16x16x32_bf16 v[80:83], v[128:131], v[214:217], v[80:83]
	v_mfma_f32_16x16x32_bf16 v[136:139], v[132:135], v[164:167], v[136:139]
	v_mfma_f32_16x16x32_bf16 v[136:139], v[144:147], v[168:171], v[136:139]
	v_mfma_f32_16x16x32_bf16 v[108:111], v[132:135], v[172:175], v[108:111]
	v_mfma_f32_16x16x32_bf16 v[108:111], v[144:147], v[176:179], v[108:111]
	v_mfma_f32_16x16x32_bf16 v[92:95], v[132:135], v[180:183], v[92:95]
	v_mfma_f32_16x16x32_bf16 v[92:95], v[144:147], v[184:187], v[92:95]
	v_mfma_f32_16x16x32_bf16 v[76:79], v[132:135], v[188:191], v[76:79]
	v_mfma_f32_16x16x32_bf16 v[76:79], v[144:147], v[214:217], v[76:79]
	s_setprio 0
	s_setprio 1
	v_mfma_f32_16x16x32_bf16 v[120:123], v[148:151], v[164:167], v[120:123]
	v_mfma_f32_16x16x32_bf16 v[120:123], v[152:155], v[168:171], v[120:123]
	v_mfma_f32_16x16x32_bf16 v[104:107], v[148:151], v[172:175], v[104:107]
	v_mfma_f32_16x16x32_bf16 v[104:107], v[152:155], v[176:179], v[104:107]
	v_mfma_f32_16x16x32_bf16 v[88:91], v[148:151], v[180:183], v[88:91]
	v_mfma_f32_16x16x32_bf16 v[88:91], v[152:155], v[184:187], v[88:91]
	v_mfma_f32_16x16x32_bf16 v[72:75], v[148:151], v[188:191], v[72:75]
	v_mfma_f32_16x16x32_bf16 v[72:75], v[152:155], v[214:217], v[72:75]
	v_mfma_f32_16x16x32_bf16 v[116:119], v[156:159], v[164:167], v[116:119]
	v_mfma_f32_16x16x32_bf16 v[116:119], v[160:163], v[168:171], v[116:119]
	v_mfma_f32_16x16x32_bf16 v[100:103], v[156:159], v[172:175], v[100:103]
	v_mfma_f32_16x16x32_bf16 v[100:103], v[160:163], v[176:179], v[100:103]
	v_mfma_f32_16x16x32_bf16 v[84:87], v[156:159], v[180:183], v[84:87]
	v_mfma_f32_16x16x32_bf16 v[84:87], v[160:163], v[184:187], v[84:87]
	v_mfma_f32_16x16x32_bf16 v[68:71], v[156:159], v[188:191], v[68:71]
	v_mfma_f32_16x16x32_bf16 v[68:71], v[160:163], v[214:217], v[68:71]
	s_setprio 0
	s_barrier
; #define PG8_STAGE(bufoff, gbase, voff) do { _Pragma("unroll") for (int _i = 0; _i < 2; ++_i) \
;         __builtin_amdgcn_global_load_lds((const unsigned*)((const char*)(gbase) + (voff)[_i]), (PG8_LAS unsigned*)(lds + (bufoff) + ldsw + _i * 8192), 16, 0, 0); } while (0)
; #define PG8_LDA(dst, b, h) do { _Pragma("unroll") for (int m = 0; m < 4; ++m) _Pragma("unroll") for (int k = 0; k < 2; ++k) dst[m][k] = *(const PG8_LAS bf16x8*)(lds + PG8_SA(b, h) + aoff + m * 2048 + k * 1024); } while (0)
; #define PG8_WAIT_V(n) asm volatile("s_waitcnt vmcnt(" #n ")" ::: "memory")
; #define PG8_WAIT_L(n) asm volatile("s_waitcnt lgkmcnt(" #n ")" ::: "memory")
; #define PG8_BAR __builtin_amdgcn_s_barrier()
; #define PG8_SCHED __builtin_amdgcn_sched_barrier(0)
; template <class Epi, class Sched, bool ALIGN_EPI = false, bool SP2 = false, bool I8 = false>
; __device__ __forceinline__ void gemm_phase(PG8_LAS unsigned char* lds, const Gemm g, const Sched& S, const Epi& E) {
;     ...
;             PG8_LDA(At, 1, 1); PG8_STAGE(PG8_SB(1, 0), b3, voffB); PG8_STAGE(PG8_SB(1, 1), b3 + hstep, voffB); PG8_STAGE(PG8_SA(1, 0), a3, voffA);
;             PG8_WAIT_V(8); PG8_WAIT_L(0); PG8_BAR; PG8_MMA(1, 0, At, B0); PG8_MMA(1, 1, At, B1); PG8_BAR; PG8_SCHED;
	s_add_i32 s22, s56, s41
	v_lshl_add_u64 v[218:219], v[218:219], 0, s[84:85]
	s_mov_b32 m0, s22
	ds_read_b128 v[164:167], v242 offset:49152
	ds_read_b128 v[168:171], v242 offset:50176
	ds_read_b128 v[172:175], v242 offset:51200
	ds_read_b128 v[176:179], v242 offset:52224
	ds_read_b128 v[180:183], v242 offset:53248
	ds_read_b128 v[184:187], v242 offset:54272
	ds_read_b128 v[188:191], v242 offset:55296
	ds_read_b128 v[214:217], v242 offset:56320
	global_load_lds_dwordx4 v[218:219], off
	s_add_i32 m0, s22, 0x2000
	s_add_u32 s22, s26, 0x2b0080
	v_lshl_add_u64 v[218:219], v[220:221], 0, s[84:85]
	s_addc_u32 s23, s27, 0
	s_add_i32 s26, s57, s41
	global_load_lds_dwordx4 v[218:219], off
	v_lshl_add_u64 v[218:219], s[22:23], 0, v[2:3]
	s_mov_b32 m0, s26
	s_nop 0
	global_load_lds_dwordx4 v[218:219], off
	v_lshl_add_u64 v[218:219], s[22:23], 0, v[204:205]
	s_add_i32 m0, s26, 0x2000
	s_nop 0
	global_load_lds_dwordx4 v[218:219], off
	v_lshl_add_u64 v[218:219], v[222:223], 0, s[84:85]
	s_mov_b32 m0, s46
	s_nop 0
	global_load_lds_dwordx4 v[218:219], off
	v_lshl_add_u64 v[218:219], v[224:225], 0, s[84:85]
	s_mov_b32 m0, s47
	s_nop 0
	global_load_lds_dwordx4 v[218:219], off
	s_waitcnt vmcnt(8)
	s_waitcnt lgkmcnt(0)
	s_barrier
	s_setprio 1
	s_waitcnt lgkmcnt(0)
	v_mfma_f32_16x16x32_bf16 v[64:67], v[124:127], v[164:167], v[64:67]
	v_mfma_f32_16x16x32_bf16 v[64:67], v[128:131], v[168:171], v[64:67]
	v_mfma_f32_16x16x32_bf16 v[48:51], v[124:127], v[172:175], v[48:51]
	v_mfma_f32_16x16x32_bf16 v[48:51], v[128:131], v[176:179], v[48:51]
	v_mfma_f32_16x16x32_bf16 v[32:35], v[124:127], v[180:183], v[32:35]
	v_mfma_f32_16x16x32_bf16 v[32:35], v[128:131], v[184:187], v[32:35]
	v_mfma_f32_16x16x32_bf16 v[16:19], v[124:127], v[188:191], v[16:19]
	v_mfma_f32_16x16x32_bf16 v[16:19], v[128:131], v[214:217], v[16:19]
	v_mfma_f32_16x16x32_bf16 v[60:63], v[132:135], v[164:167], v[60:63]
	v_mfma_f32_16x16x32_bf16 v[60:63], v[144:147], v[168:171], v[60:63]
	v_mfma_f32_16x16x32_bf16 v[44:47], v[132:135], v[172:175], v[44:47]
	v_mfma_f32_16x16x32_bf16 v[44:47], v[144:147], v[176:179], v[44:47]
	v_mfma_f32_16x16x32_bf16 v[28:31], v[132:135], v[180:183], v[28:31]
	v_mfma_f32_16x16x32_bf16 v[28:31], v[144:147], v[184:187], v[28:31]
	v_mfma_f32_16x16x32_bf16 v[12:15], v[132:135], v[188:191], v[12:15]
	v_mfma_f32_16x16x32_bf16 v[12:15], v[144:147], v[214:217], v[12:15]
	s_setprio 0
	s_setprio 1
	v_mfma_f32_16x16x32_bf16 v[56:59], v[148:151], v[164:167], v[56:59]
	v_mfma_f32_16x16x32_bf16 v[56:59], v[152:155], v[168:171], v[56:59]
	v_mfma_f32_16x16x32_bf16 v[40:43], v[148:151], v[172:175], v[40:43]
	v_mfma_f32_16x16x32_bf16 v[40:43], v[152:155], v[176:179], v[40:43]
	v_mfma_f32_16x16x32_bf16 v[24:27], v[148:151], v[180:183], v[24:27]
	v_mfma_f32_16x16x32_bf16 v[24:27], v[152:155], v[184:187], v[24:27]
	v_mfma_f32_16x16x32_bf16 v[8:11], v[148:151], v[188:191], v[8:11]
	v_mfma_f32_16x16x32_bf16 v[8:11], v[152:155], v[214:217], v[8:11]
	v_mfma_f32_16x16x32_bf16 v[52:55], v[156:159], v[164:167], v[52:55]
	v_mfma_f32_16x16x32_bf16 v[52:55], v[160:163], v[168:171], v[52:55]
	v_mfma_f32_16x16x32_bf16 v[36:39], v[156:159], v[172:175], v[36:39]
	v_mfma_f32_16x16x32_bf16 v[36:39], v[160:163], v[176:179], v[36:39]
	v_mfma_f32_16x16x32_bf16 v[20:23], v[156:159], v[180:183], v[20:23]
	v_mfma_f32_16x16x32_bf16 v[20:23], v[160:163], v[184:187], v[20:23]
	v_mfma_f32_16x16x32_bf16 v[4:7], v[156:159], v[188:191], v[4:7]
	v_mfma_f32_16x16x32_bf16 v[4:7], v[160:163], v[214:217], v[4:7]
	s_setprio 0
	s_barrier
	s_add_i32 s55, s55, 2
	s_add_u32 s53, s53, 0x100
	s_addc_u32 s54, s54, 0
	s_cmpk_gt_u32 s55, 0xa9
	s_mov_b64 s[22:23], s[24:25]
	s_cbranch_scc0 .LBB0_1700

; #define PG8_STAGE(bufoff, gbase, voff) do { _Pragma("unroll") for (int _i = 0; _i < 2; ++_i) \
;         __builtin_amdgcn_global_load_lds((const unsigned*)((const char*)(gbase) + (voff)[_i]), (PG8_LAS unsigned*)(lds + (bufoff) + ldsw + _i * 8192), 16, 0, 0); } while (0)
; #define PG8_LDA(dst, b, h) do { _Pragma("unroll") for (int m = 0; m < 4; ++m) _Pragma("unroll") for (int k = 0; k < 2; ++k) dst[m][k] = *(const PG8_LAS bf16x8*)(lds + PG8_SA(b, h) + aoff + m * 2048 + k * 1024); } while (0)
; #define PG8_LDB(dst, b, h) do { _Pragma("unroll") for (int n = 0; n < 2; ++n) _Pragma("unroll") for (int k = 0; k < 2; ++k) dst[n][k] = *(const PG8_LAS bf16x8*)(lds + PG8_SB(b, h) + boff + n * 2048 + k * 1024); } while (0)
; #define PG8_WAIT_V(n) asm volatile("s_waitcnt vmcnt(" #n ")" ::: "memory")
; #define PG8_WAIT_L(n) asm volatile("s_waitcnt lgkmcnt(" #n ")" ::: "memory")
; #define PG8_BAR __builtin_amdgcn_s_barrier()
; #define PG8_SCHED __builtin_amdgcn_sched_barrier(0)
; template <class Epi, class Sched, bool ALIGN_EPI = false, bool SP2 = false, bool I8 = false>
; __device__ __forceinline__ void gemm_phase(PG8_LAS unsigned char* lds, const Gemm g, const Sched& S, const Epi& E) {
;     ...
;         const bool has_next = S.next(ui + 1, nxt);
;         const char* nA = has_next ? (const char*)g.A + (size_t)nxt.pm * tstep : cA; const char* nB = has_next ? (const char*)g.Bt + (size_t)nxt.pn * tstep : cB;
;         for (int t = 0; t < nt; t += 2) {
;             const bool last = (t == nt - 2);
;             const char* a1 = cA + (size_t)(t + 1) * kstep;
;             const char* a2 = last ? nA : cA + (size_t)(t + 2) * kstep; const char* b2 = last ? nB : cB + (size_t)(t + 2) * kstep;
;             const char* a3 = a2 + kstep; const char* b3 = b2 + kstep;
;             if (last && has_next) S.a_ready(nxt);
;             if constexpr (SP2) {
;             PG8_LDB(B0, 0, 0); PG8_LDB(B1, 0, 1); PG8_SCHED; PG8_LDA(At, 0, 0); PG8_STAGE(PG8_SA(1, 1), a1 + hstep, voffA);
;             PG8_WAIT_V(8); PG8_WAIT_L(0); PG8_BAR; PG8_MMA(0, 0, At, B0); PG8_MMA(0, 1, At, B1); PG8_BAR; PG8_SCHED;
;             PG8_LDA(At, 0, 1); PG8_STAGE(PG8_SB(0, 0), b2, voffB); PG8_STAGE(PG8_SB(0, 1), b2 + hstep, voffB); PG8_STAGE(PG8_SA(0, 0), a2, voffA);
;             PG8_WAIT_V(8); PG8_WAIT_L(0); PG8_BAR; PG8_MMA(1, 0, At, B0); PG8_MMA(1, 1, At, B1); PG8_BAR; PG8_SCHED;
.LBB0_1842:
	s_ashr_i32 s45, s44, 31
	s_lshl_b64 s[34:35], s[44:45], 20
	s_add_u32 s50, s47, s34
	s_addc_u32 s51, s52, s35
	s_and_b64 s[34:35], s[8:9], exec
	s_cselect_b32 s11, s51, s55
	s_cselect_b32 s13, s50, s54
	s_ashr_i32 s49, s48, 31
	s_lshl_b64 s[34:35], s[48:49], 20
	s_add_u32 s56, s53, s34
	s_addc_u32 s57, s64, s35
	s_and_b64 s[34:35], s[8:9], exec
	s_cselect_b32 s34, s57, s59
	s_cselect_b32 s35, s56, s58
	s_add_u32 s54, s54, 0x80080
	s_addc_u32 s55, s55, 0
	s_add_u32 s45, s58, 0x100
	s_addc_u32 s49, s59, 0
	s_mov_b32 s86, -2
	s_waitcnt lgkmcnt(0)
	s_add_u32 s58, s54, 0xfff80080
	s_addc_u32 s59, s55, -1
	s_add_i32 s87, 0, 0x10000
	s_cmp_eq_u32 s86, 28
	s_cselect_b32 s61, s11, s59
	s_cselect_b32 s60, s13, s58
	s_cselect_b32 s59, s34, s49
	s_cselect_b32 s58, s35, s45
	s_add_i32 vcc_lo, 0, 0x14000
	v_add_u32_e32 v40, s87, v217
	v_add_u32_e32 v160, vcc_lo, v217
	ds_read_b128 v[28:31], v40
	ds_read_b128 v[32:35], v40 offset:1024
	ds_read_b128 v[36:39], v40 offset:2048
	ds_read_b128 v[40:43], v40 offset:3072
	ds_read_b128 v[140:143], v160
	ds_read_b128 v[144:147], v160 offset:1024
	ds_read_b128 v[156:159], v160 offset:2048
	ds_read_b128 v[160:163], v160 offset:3072
	v_lshl_add_u64 v[190:191], s[54:55], 0, v[186:187]
	s_add_i32 m0, s65, 0xc000
	ds_read_b128 v[164:167], v219
	ds_read_b128 v[168:171], v219 offset:1024
	ds_read_b128 v[172:175], v219 offset:2048
	ds_read_b128 v[176:179], v219 offset:3072
	ds_read_b128 v[204:207], v219 offset:4096
	ds_read_b128 v[208:211], v219 offset:5120
	ds_read_b128 v[212:215], v219 offset:6144
	ds_read_b128 v[220:223], v219 offset:7168
	global_load_lds_dwordx4 v[190:191], off
	v_lshl_add_u64 v[190:191], s[54:55], 0, v[188:189]
	s_add_i32 m0, s65, 0xe000
	s_nop 0
	global_load_lds_dwordx4 v[190:191], off
	s_waitcnt vmcnt(8)
	s_waitcnt lgkmcnt(0)
	s_barrier
	s_setprio 1
	s_waitcnt lgkmcnt(0)
	v_mfma_i32_16x16x64_i8 v[152:155], v[28:31], v[164:167], 0
	v_mfma_i32_16x16x64_i8 v[152:155], v[32:35], v[168:171], v[152:155]
	v_mfma_i32_16x16x64_i8 v[128:131], v[28:31], v[172:175], 0
	v_mfma_i32_16x16x64_i8 v[128:131], v[32:35], v[176:179], v[128:131]
	v_mfma_i32_16x16x64_i8 v[112:115], v[28:31], v[204:207], 0
	v_mfma_i32_16x16x64_i8 v[112:115], v[32:35], v[208:211], v[112:115]
	v_mfma_i32_16x16x64_i8 v[96:99], v[28:31], v[212:215], 0
	v_mfma_i32_16x16x64_i8 v[96:99], v[32:35], v[220:223], v[96:99]
	v_mfma_i32_16x16x64_i8 v[148:151], v[36:39], v[164:167], 0
	v_mfma_i32_16x16x64_i8 v[148:151], v[40:43], v[168:171], v[148:151]
	v_mfma_i32_16x16x64_i8 v[124:127], v[36:39], v[172:175], 0
	v_mfma_i32_16x16x64_i8 v[124:127], v[40:43], v[176:179], v[124:127]
	v_mfma_i32_16x16x64_i8 v[108:111], v[36:39], v[204:207], 0
	v_mfma_i32_16x16x64_i8 v[108:111], v[40:43], v[208:211], v[108:111]
	v_mfma_i32_16x16x64_i8 v[92:95], v[36:39], v[212:215], 0
	v_mfma_i32_16x16x64_i8 v[92:95], v[40:43], v[220:223], v[92:95]
	s_setprio 0
	s_setprio 1
	v_mfma_i32_16x16x64_i8 v[136:139], v[140:143], v[164:167], 0
	v_mfma_i32_16x16x64_i8 v[136:139], v[144:147], v[168:171], v[136:139]
	v_mfma_i32_16x16x64_i8 v[120:123], v[140:143], v[172:175], 0
	v_mfma_i32_16x16x64_i8 v[120:123], v[144:147], v[176:179], v[120:123]
	v_mfma_i32_16x16x64_i8 v[104:107], v[140:143], v[204:207], 0
	v_mfma_i32_16x16x64_i8 v[104:107], v[144:147], v[208:211], v[104:107]
	v_mfma_i32_16x16x64_i8 v[88:91], v[140:143], v[212:215], 0
	v_mfma_i32_16x16x64_i8 v[88:91], v[144:147], v[220:223], v[88:91]
	v_mfma_i32_16x16x64_i8 v[132:135], v[156:159], v[164:167], 0
	v_mfma_i32_16x16x64_i8 v[132:135], v[160:163], v[168:171], v[132:135]
	v_mfma_i32_16x16x64_i8 v[116:119], v[156:159], v[172:175], 0
	v_mfma_i32_16x16x64_i8 v[116:119], v[160:163], v[176:179], v[116:119]
	v_mfma_i32_16x16x64_i8 v[100:103], v[156:159], v[204:207], 0
	v_mfma_i32_16x16x64_i8 v[100:103], v[160:163], v[208:211], v[100:103]
	v_mfma_i32_16x16x64_i8 v[84:87], v[156:159], v[212:215], 0
	v_mfma_i32_16x16x64_i8 v[84:87], v[160:163], v[220:223], v[84:87]
	s_setprio 0
	s_barrier
	s_add_i32 s87, s87, s46
	v_lshl_add_u64 v[190:191], s[58:59], 0, v[2:3]
	s_mov_b32 m0, s87
	ds_read_b128 v[164:167], v219 offset:16384
	ds_read_b128 v[168:171], v219 offset:17408
	ds_read_b128 v[172:175], v219 offset:18432
	ds_read_b128 v[176:179], v219 offset:19456
	ds_read_b128 v[204:207], v219 offset:20480
	ds_read_b128 v[208:211], v219 offset:21504
	ds_read_b128 v[212:215], v219 offset:22528
	ds_read_b128 v[220:223], v219 offset:23552
	global_load_lds_dwordx4 v[190:191], off
	s_add_i32 m0, s87, 0x2000
	s_add_u32 s96, s58, 0x80000
	v_lshl_add_u64 v[224:225], s[58:59], 0, v[184:185]
	s_addc_u32 s97, s59, 0
	s_add_i32 s87, vcc_lo, s46
	global_load_lds_dwordx4 v[224:225], off
	v_lshl_add_u64 v[226:227], s[96:97], 0, v[2:3]
	s_mov_b32 m0, s87
	v_lshl_add_u64 v[228:229], s[60:61], 0, v[182:183]
	global_load_lds_dwordx4 v[226:227], off
	v_lshl_add_u64 v[226:227], s[96:97], 0, v[184:185]
	s_add_i32 m0, s87, 0x2000
	s_nop 0
	global_load_lds_dwordx4 v[226:227], off
	v_lshl_add_u64 v[226:227], s[60:61], 0, v[180:181]
	s_mov_b32 m0, s65
	s_nop 0
	global_load_lds_dwordx4 v[226:227], off
	s_mov_b32 m0, s67
	s_nop 0
	global_load_lds_dwordx4 v[228:229], off
	s_waitcnt vmcnt(8)
	s_waitcnt lgkmcnt(0)
	s_barrier
; #define PG8_STAGE(bufoff, gbase, voff) do { _Pragma("unroll") for (int _i = 0; _i < 2; ++_i) \
;         __builtin_amdgcn_global_load_lds((const unsigned*)((const char*)(gbase) + (voff)[_i]), (PG8_LAS unsigned*)(lds + (bufoff) + ldsw + _i * 8192), 16, 0, 0); } while (0)
; #define PG8_LDA(dst, b, h) do { _Pragma("unroll") for (int m = 0; m < 4; ++m) _Pragma("unroll") for (int k = 0; k < 2; ++k) dst[m][k] = *(const PG8_LAS bf16x8*)(lds + PG8_SA(b, h) + aoff + m * 2048 + k * 1024); } while (0)
; #define PG8_LDB(dst, b, h) do { _Pragma("unroll") for (int n = 0; n < 2; ++n) _Pragma("unroll") for (int k = 0; k < 2; ++k) dst[n][k] = *(const PG8_LAS bf16x8*)(lds + PG8_SB(b, h) + boff + n * 2048 + k * 1024); } while (0)
; #define PG8_WAIT_V(n) asm volatile("s_waitcnt vmcnt(" #n ")" ::: "memory")
; #define PG8_WAIT_L(n) asm volatile("s_waitcnt lgkmcnt(" #n ")" ::: "memory")
; #define PG8_BAR __builtin_amdgcn_s_barrier()
; #define PG8_SCHED __builtin_amdgcn_sched_barrier(0)
; template <class Epi, class Sched, bool ALIGN_EPI = false, bool SP2 = false, bool I8 = false>
; __device__ __forceinline__ void gemm_phase(PG8_LAS unsigned char* lds, const Gemm g, const Sched& S, const Epi& E) {
;     ...
;             if constexpr (SP2) {
;             PG8_LDB(B0, 0, 0); PG8_LDB(B1, 0, 1); PG8_SCHED; PG8_LDA(At, 0, 0); PG8_STAGE(PG8_SA(1, 1), a1 + hstep, voffA);
;             PG8_WAIT_V(8); PG8_WAIT_L(0); PG8_BAR; PG8_MMA(0, 0, At, B0); PG8_MMA(0, 1, At, B1); PG8_BAR; PG8_SCHED;
;             PG8_LDA(At, 0, 1); PG8_STAGE(PG8_SB(0, 0), b2, voffB); PG8_STAGE(PG8_SB(0, 1), b2 + hstep, voffB); PG8_STAGE(PG8_SA(0, 0), a2, voffA);
;             PG8_WAIT_V(8); PG8_WAIT_L(0); PG8_BAR; PG8_MMA(1, 0, At, B0); PG8_MMA(1, 1, At, B1); PG8_BAR; PG8_SCHED;
;             PG8_LDB(B0, 1, 0); PG8_LDB(B1, 1, 1); PG8_SCHED; PG8_LDA(At, 1, 0); PG8_STAGE(PG8_SA(0, 1), a2 + hstep, voffA);
;             PG8_WAIT_V(8); PG8_WAIT_L(0); PG8_BAR; PG8_MMA(0, 0, At, B0); PG8_MMA(0, 1, At, B1); PG8_BAR; PG8_SCHED;
	s_setprio 1
	s_waitcnt lgkmcnt(0)
	v_mfma_i32_16x16x64_i8 v[80:83], v[28:31], v[164:167], 0
	v_mfma_i32_16x16x64_i8 v[80:83], v[32:35], v[168:171], v[80:83]
	v_mfma_i32_16x16x64_i8 v[64:67], v[28:31], v[172:175], 0
	v_mfma_i32_16x16x64_i8 v[64:67], v[32:35], v[176:179], v[64:67]
	v_mfma_i32_16x16x64_i8 v[48:51], v[28:31], v[204:207], 0
	v_mfma_i32_16x16x64_i8 v[48:51], v[32:35], v[208:211], v[48:51]
	v_mfma_i32_16x16x64_i8 v[16:19], v[28:31], v[212:215], 0
	v_mfma_i32_16x16x64_i8 v[16:19], v[32:35], v[220:223], v[16:19]
	v_mfma_i32_16x16x64_i8 v[76:79], v[36:39], v[164:167], 0
	v_mfma_i32_16x16x64_i8 v[76:79], v[40:43], v[168:171], v[76:79]
	v_mfma_i32_16x16x64_i8 v[60:63], v[36:39], v[172:175], 0
	v_mfma_i32_16x16x64_i8 v[60:63], v[40:43], v[176:179], v[60:63]
	v_mfma_i32_16x16x64_i8 v[44:47], v[36:39], v[204:207], 0
	v_mfma_i32_16x16x64_i8 v[44:47], v[40:43], v[208:211], v[44:47]
	v_mfma_i32_16x16x64_i8 v[12:15], v[36:39], v[212:215], 0
	v_mfma_i32_16x16x64_i8 v[12:15], v[40:43], v[220:223], v[12:15]
	s_setprio 0
	s_setprio 1
	v_mfma_i32_16x16x64_i8 v[24:27], v[140:143], v[204:207], 0
	v_mfma_i32_16x16x64_i8 v[24:27], v[144:147], v[208:211], v[24:27]
	v_mfma_i32_16x16x64_i8 v[8:11], v[140:143], v[212:215], 0
	v_mfma_i32_16x16x64_i8 v[8:11], v[144:147], v[220:223], v[8:11]
	v_mfma_i32_16x16x64_i8 v[28:31], v[140:143], v[164:167], 0
	v_mfma_i32_16x16x64_i8 v[28:31], v[144:147], v[168:171], v[28:31]
	v_mfma_i32_16x16x64_i8 v[36:39], v[140:143], v[172:175], 0
	v_mfma_i32_16x16x64_i8 v[36:39], v[144:147], v[176:179], v[36:39]
	v_mfma_i32_16x16x64_i8 v[20:23], v[156:159], v[204:207], 0
	v_mfma_i32_16x16x64_i8 v[20:23], v[160:163], v[208:211], v[20:23]
	v_mfma_i32_16x16x64_i8 v[4:7], v[156:159], v[212:215], 0
	v_mfma_i32_16x16x64_i8 v[4:7], v[160:163], v[220:223], v[4:7]
	v_mfma_i32_16x16x64_i8 v[32:35], v[156:159], v[164:167], 0
	v_mfma_i32_16x16x64_i8 v[32:35], v[160:163], v[168:171], v[32:35]
	v_mfma_i32_16x16x64_i8 v[40:43], v[156:159], v[172:175], 0
	v_mfma_i32_16x16x64_i8 v[40:43], v[160:163], v[176:179], v[40:43]
	s_setprio 0
	s_barrier
	s_add_i32 s87, 0, 0x18000
	s_add_i32 s96, 0, 0x1c000
	v_add_u32_e32 v72, s87, v217
	v_add_u32_e32 v160, s96, v217
	ds_read_b128 v[52:55], v72
	ds_read_b128 v[56:59], v72 offset:1024
	ds_read_b128 v[68:71], v72 offset:2048
	ds_read_b128 v[72:75], v72 offset:3072
	ds_read_b128 v[140:143], v160
	ds_read_b128 v[144:147], v160 offset:1024
	ds_read_b128 v[156:159], v160 offset:2048
	ds_read_b128 v[160:163], v160 offset:3072
	s_add_u32 s60, s60, 0x80000
	s_addc_u32 s61, s61, 0
	s_mov_b32 m0, s72
	v_lshl_add_u64 v[240:241], s[60:61], 0, v[180:181]
	ds_read_b128 v[164:167], v219 offset:32768
	ds_read_b128 v[168:171], v219 offset:33792
	ds_read_b128 v[172:175], v219 offset:34816
	ds_read_b128 v[176:179], v219 offset:35840
	ds_read_b128 v[204:207], v219 offset:36864
	ds_read_b128 v[208:211], v219 offset:37888
	ds_read_b128 v[212:215], v219 offset:38912
	ds_read_b128 v[220:223], v219 offset:39936
	global_load_lds_dwordx4 v[240:241], off
	v_lshl_add_u64 v[240:241], s[60:61], 0, v[182:183]
	s_mov_b32 m0, s73
	s_nop 0
	global_load_lds_dwordx4 v[240:241], off
	s_waitcnt vmcnt(8)
	s_waitcnt lgkmcnt(0)
	s_barrier
	s_setprio 1
	s_waitcnt lgkmcnt(0)
	v_mfma_i32_16x16x64_i8 v[152:155], v[52:55], v[164:167], v[152:155]
	v_mfma_i32_16x16x64_i8 v[152:155], v[56:59], v[168:171], v[152:155]
	v_mfma_i32_16x16x64_i8 v[128:131], v[52:55], v[172:175], v[128:131]
	v_mfma_i32_16x16x64_i8 v[128:131], v[56:59], v[176:179], v[128:131]
	v_mfma_i32_16x16x64_i8 v[112:115], v[52:55], v[204:207], v[112:115]
	v_mfma_i32_16x16x64_i8 v[112:115], v[56:59], v[208:211], v[112:115]
	v_mfma_i32_16x16x64_i8 v[96:99], v[52:55], v[212:215], v[96:99]
	v_mfma_i32_16x16x64_i8 v[96:99], v[56:59], v[220:223], v[96:99]
	v_mfma_i32_16x16x64_i8 v[148:151], v[68:71], v[164:167], v[148:151]
	v_mfma_i32_16x16x64_i8 v[148:151], v[72:75], v[168:171], v[148:151]
	v_mfma_i32_16x16x64_i8 v[124:127], v[68:71], v[172:175], v[124:127]
	v_mfma_i32_16x16x64_i8 v[124:127], v[72:75], v[176:179], v[124:127]
	v_mfma_i32_16x16x64_i8 v[108:111], v[68:71], v[204:207], v[108:111]
	v_mfma_i32_16x16x64_i8 v[108:111], v[72:75], v[208:211], v[108:111]
	v_mfma_i32_16x16x64_i8 v[92:95], v[68:71], v[212:215], v[92:95]
	v_mfma_i32_16x16x64_i8 v[92:95], v[72:75], v[220:223], v[92:95]
	s_setprio 0
	s_setprio 1
	v_mfma_i32_16x16x64_i8 v[136:139], v[140:143], v[164:167], v[136:139]
	v_mfma_i32_16x16x64_i8 v[136:139], v[144:147], v[168:171], v[136:139]
	v_mfma_i32_16x16x64_i8 v[120:123], v[140:143], v[172:175], v[120:123]
	v_mfma_i32_16x16x64_i8 v[120:123], v[144:147], v[176:179], v[120:123]
	v_mfma_i32_16x16x64_i8 v[104:107], v[140:143], v[204:207], v[104:107]
	v_mfma_i32_16x16x64_i8 v[104:107], v[144:147], v[208:211], v[104:107]
	v_mfma_i32_16x16x64_i8 v[88:91], v[140:143], v[212:215], v[88:91]
	v_mfma_i32_16x16x64_i8 v[88:91], v[144:147], v[220:223], v[88:91]
	v_mfma_i32_16x16x64_i8 v[132:135], v[156:159], v[164:167], v[132:135]
	v_mfma_i32_16x16x64_i8 v[132:135], v[160:163], v[168:171], v[132:135]
	v_mfma_i32_16x16x64_i8 v[116:119], v[156:159], v[172:175], v[116:119]
	v_mfma_i32_16x16x64_i8 v[116:119], v[160:163], v[176:179], v[116:119]
	v_mfma_i32_16x16x64_i8 v[100:103], v[156:159], v[204:207], v[100:103]
	v_mfma_i32_16x16x64_i8 v[100:103], v[160:163], v[208:211], v[100:103]
	v_mfma_i32_16x16x64_i8 v[84:87], v[156:159], v[212:215], v[84:87]
	v_mfma_i32_16x16x64_i8 v[84:87], v[160:163], v[220:223], v[84:87]
	s_setprio 0
	s_barrier
; #define PG8_STAGE(bufoff, gbase, voff) do { _Pragma("unroll") for (int _i = 0; _i < 2; ++_i) \
;         __builtin_amdgcn_global_load_lds((const unsigned*)((const char*)(gbase) + (voff)[_i]), (PG8_LAS unsigned*)(lds + (bufoff) + ldsw + _i * 8192), 16, 0, 0); } while (0)
; #define PG8_LDA(dst, b, h) do { _Pragma("unroll") for (int m = 0; m < 4; ++m) _Pragma("unroll") for (int k = 0; k < 2; ++k) dst[m][k] = *(const PG8_LAS bf16x8*)(lds + PG8_SA(b, h) + aoff + m * 2048 + k * 1024); } while (0)
; #define PG8_WAIT_V(n) asm volatile("s_waitcnt vmcnt(" #n ")" ::: "memory")
; #define PG8_WAIT_L(n) asm volatile("s_waitcnt lgkmcnt(" #n ")" ::: "memory")
; #define PG8_BAR __builtin_amdgcn_s_barrier()
; template <class Epi, class Sched, bool ALIGN_EPI = false, bool SP2 = false, bool I8 = false>
; __device__ __forceinline__ void gemm_phase(PG8_LAS unsigned char* lds, const Gemm g, const Sched& S, const Epi& E) {
;     ...
;         for (int t = 0; t < nt; t += 2) {
;             const bool last = (t == nt - 2);
;             const char* a1 = cA + (size_t)(t + 1) * kstep;
;             const char* a2 = last ? nA : cA + (size_t)(t + 2) * kstep; const char* b2 = last ? nB : cB + (size_t)(t + 2) * kstep;
;             const char* a3 = a2 + kstep; const char* b3 = b2 + kstep;
;             if (last && has_next) S.a_ready(nxt);
;             if constexpr (SP2) {
;             PG8_LDB(B0, 0, 0); PG8_LDB(B1, 0, 1); PG8_SCHED; PG8_LDA(At, 0, 0); PG8_STAGE(PG8_SA(1, 1), a1 + hstep, voffA);
;             PG8_WAIT_V(8); PG8_WAIT_L(0); PG8_BAR; PG8_MMA(0, 0, At, B0); PG8_MMA(0, 1, At, B1); PG8_BAR; PG8_SCHED;
;             PG8_LDA(At, 0, 1); PG8_STAGE(PG8_SB(0, 0), b2, voffB); PG8_STAGE(PG8_SB(0, 1), b2 + hstep, voffB); PG8_STAGE(PG8_SA(0, 0), a2, voffA);
;             PG8_WAIT_V(8); PG8_WAIT_L(0); PG8_BAR; PG8_MMA(1, 0, At, B0); PG8_MMA(1, 1, At, B1); PG8_BAR; PG8_SCHED;
;             PG8_LDB(B0, 1, 0); PG8_LDB(B1, 1, 1); PG8_SCHED; PG8_LDA(At, 1, 0); PG8_STAGE(PG8_SA(0, 1), a2 + hstep, voffA);
;             PG8_WAIT_V(8); PG8_WAIT_L(0); PG8_BAR; PG8_MMA(0, 0, At, B0); PG8_MMA(0, 1, At, B1); PG8_BAR; PG8_SCHED;
;             PG8_LDA(At, 1, 1); PG8_STAGE(PG8_SB(1, 0), b3, voffB); PG8_STAGE(PG8_SB(1, 1), b3 + hstep, voffB); PG8_STAGE(PG8_SA(1, 0), a3, voffA);
;             PG8_WAIT_V(8); PG8_WAIT_L(0); PG8_BAR; PG8_MMA(1, 0, At, B0); PG8_MMA(1, 1, At, B1); PG8_BAR; PG8_SCHED;
	s_add_i32 s60, s87, s46
	v_lshl_add_u64 v[190:191], v[190:191], 0, s[84:85]
	s_mov_b32 m0, s60
	ds_read_b128 v[164:167], v219 offset:49152
	ds_read_b128 v[168:171], v219 offset:50176
	ds_read_b128 v[172:175], v219 offset:51200
	ds_read_b128 v[176:179], v219 offset:52224
	ds_read_b128 v[204:207], v219 offset:53248
	ds_read_b128 v[208:211], v219 offset:54272
	ds_read_b128 v[212:215], v219 offset:55296
	ds_read_b128 v[220:223], v219 offset:56320
	global_load_lds_dwordx4 v[190:191], off
	s_add_i32 m0, s60, 0x2000
	s_add_u32 s58, s58, 0x80080
	v_lshl_add_u64 v[190:191], v[224:225], 0, s[84:85]
	s_addc_u32 s59, s59, 0
	s_add_i32 s60, s96, s46
	global_load_lds_dwordx4 v[190:191], off
	v_lshl_add_u64 v[190:191], s[58:59], 0, v[2:3]
	s_mov_b32 m0, s60
	s_nop 0
	global_load_lds_dwordx4 v[190:191], off
	v_lshl_add_u64 v[190:191], s[58:59], 0, v[184:185]
	s_add_i32 m0, s60, 0x2000
	s_nop 0
	global_load_lds_dwordx4 v[190:191], off
	v_lshl_add_u64 v[190:191], v[226:227], 0, s[84:85]
	s_mov_b32 m0, s28
	s_nop 0
	global_load_lds_dwordx4 v[190:191], off
	v_lshl_add_u64 v[190:191], v[228:229], 0, s[84:85]
	s_mov_b32 m0, s77
	s_nop 0
	global_load_lds_dwordx4 v[190:191], off
	s_waitcnt vmcnt(8)
	s_waitcnt lgkmcnt(0)
	s_barrier
	s_setprio 1
	s_waitcnt lgkmcnt(0)
	v_mfma_i32_16x16x64_i8 v[80:83], v[52:55], v[164:167], v[80:83]
	v_mfma_i32_16x16x64_i8 v[80:83], v[56:59], v[168:171], v[80:83]
	v_mfma_i32_16x16x64_i8 v[64:67], v[52:55], v[172:175], v[64:67]
	v_mfma_i32_16x16x64_i8 v[64:67], v[56:59], v[176:179], v[64:67]
	v_mfma_i32_16x16x64_i8 v[48:51], v[52:55], v[204:207], v[48:51]
	v_mfma_i32_16x16x64_i8 v[48:51], v[56:59], v[208:211], v[48:51]
	v_mfma_i32_16x16x64_i8 v[16:19], v[52:55], v[212:215], v[16:19]
	v_mfma_i32_16x16x64_i8 v[16:19], v[56:59], v[220:223], v[16:19]
	v_mfma_i32_16x16x64_i8 v[76:79], v[68:71], v[164:167], v[76:79]
	v_mfma_i32_16x16x64_i8 v[76:79], v[72:75], v[168:171], v[76:79]
	v_mfma_i32_16x16x64_i8 v[60:63], v[68:71], v[172:175], v[60:63]
	v_mfma_i32_16x16x64_i8 v[60:63], v[72:75], v[176:179], v[60:63]
	v_mfma_i32_16x16x64_i8 v[44:47], v[68:71], v[204:207], v[44:47]
	v_mfma_i32_16x16x64_i8 v[44:47], v[72:75], v[208:211], v[44:47]
	v_mfma_i32_16x16x64_i8 v[12:15], v[68:71], v[212:215], v[12:15]
	v_mfma_i32_16x16x64_i8 v[12:15], v[72:75], v[220:223], v[12:15]
	s_setprio 0
	s_setprio 1
	v_mfma_i32_16x16x64_i8 v[28:31], v[140:143], v[164:167], v[28:31]
	v_mfma_i32_16x16x64_i8 v[72:75], v[144:147], v[168:171], v[28:31]
	v_mfma_i32_16x16x64_i8 v[28:31], v[140:143], v[172:175], v[36:39]
	v_mfma_i32_16x16x64_i8 v[56:59], v[144:147], v[176:179], v[28:31]
	v_mfma_i32_16x16x64_i8 v[24:27], v[140:143], v[204:207], v[24:27]
	v_mfma_i32_16x16x64_i8 v[24:27], v[144:147], v[208:211], v[24:27]
	v_mfma_i32_16x16x64_i8 v[8:11], v[140:143], v[212:215], v[8:11]
	v_mfma_i32_16x16x64_i8 v[8:11], v[144:147], v[220:223], v[8:11]
	v_mfma_i32_16x16x64_i8 v[28:31], v[156:159], v[164:167], v[32:35]
	v_mfma_i32_16x16x64_i8 v[68:71], v[160:163], v[168:171], v[28:31]
	v_mfma_i32_16x16x64_i8 v[28:31], v[156:159], v[172:175], v[40:43]
	v_mfma_i32_16x16x64_i8 v[52:55], v[160:163], v[176:179], v[28:31]
	v_mfma_i32_16x16x64_i8 v[20:23], v[156:159], v[204:207], v[20:23]
	v_mfma_i32_16x16x64_i8 v[20:23], v[160:163], v[208:211], v[20:23]
	v_mfma_i32_16x16x64_i8 v[4:7], v[156:159], v[212:215], v[4:7]
	v_mfma_i32_16x16x64_i8 v[4:7], v[160:163], v[220:223], v[4:7]
	s_setprio 0
	s_barrier
	s_add_i32 s86, s86, 2
	s_add_u32 s54, s54, 0x100
	s_addc_u32 s55, s55, 0
	s_add_u32 s45, s45, 0x100
	s_addc_u32 s49, s49, 0
	s_cmp_gt_u32 s86, 29
	s_cbranch_scc1 .Lkloop_exit_6
.LBB0_1843:
	s_add_u32 s58, s54, 0xfff80080
	s_addc_u32 s59, s55, -1
	s_add_i32 s87, 0, 0x10000
	s_cmp_eq_u32 s86, 28
	s_cselect_b32 s61, s11, s59
	s_cselect_b32 s60, s13, s58
	s_cselect_b32 s59, s34, s49
	s_cselect_b32 s58, s35, s45
	s_add_i32 vcc_lo, 0, 0x14000
	v_add_u32_e32 v40, s87, v217
	v_add_u32_e32 v160, vcc_lo, v217
	ds_read_b128 v[28:31], v40
	ds_read_b128 v[32:35], v40 offset:1024
	ds_read_b128 v[36:39], v40 offset:2048
	ds_read_b128 v[40:43], v40 offset:3072
	ds_read_b128 v[140:143], v160
	ds_read_b128 v[144:147], v160 offset:1024
	ds_read_b128 v[156:159], v160 offset:2048
	ds_read_b128 v[160:163], v160 offset:3072
	v_lshl_add_u64 v[190:191], s[54:55], 0, v[186:187]
	s_add_i32 m0, s65, 0xc000
	ds_read_b128 v[164:167], v219
	ds_read_b128 v[168:171], v219 offset:1024
	ds_read_b128 v[172:175], v219 offset:2048
	ds_read_b128 v[176:179], v219 offset:3072
	ds_read_b128 v[204:207], v219 offset:4096
	ds_read_b128 v[208:211], v219 offset:5120
	ds_read_b128 v[212:215], v219 offset:6144
	ds_read_b128 v[220:223], v219 offset:7168
	global_load_lds_dwordx4 v[190:191], off
	v_lshl_add_u64 v[190:191], s[54:55], 0, v[188:189]
	s_add_i32 m0, s65, 0xe000
	s_nop 0
	global_load_lds_dwordx4 v[190:191], off
	s_waitcnt vmcnt(8)
	s_waitcnt lgkmcnt(0)
	s_barrier
; #define PG8_STAGE(bufoff, gbase, voff) do { _Pragma("unroll") for (int _i = 0; _i < 2; ++_i) \
;         __builtin_amdgcn_global_load_lds((const unsigned*)((const char*)(gbase) + (voff)[_i]), (PG8_LAS unsigned*)(lds + (bufoff) + ldsw + _i * 8192), 16, 0, 0); } while (0)
; #define PG8_LDA(dst, b, h) do { _Pragma("unroll") for (int m = 0; m < 4; ++m) _Pragma("unroll") for (int k = 0; k < 2; ++k) dst[m][k] = *(const PG8_LAS bf16x8*)(lds + PG8_SA(b, h) + aoff + m * 2048 + k * 1024); } while (0)
; #define PG8_WAIT_V(n) asm volatile("s_waitcnt vmcnt(" #n ")" ::: "memory")
; #define PG8_WAIT_L(n) asm volatile("s_waitcnt lgkmcnt(" #n ")" ::: "memory")
; #define PG8_BAR __builtin_amdgcn_s_barrier()
; #define PG8_SCHED __builtin_amdgcn_sched_barrier(0)
; template <class Epi, class Sched, bool ALIGN_EPI = false, bool SP2 = false, bool I8 = false>
; __device__ __forceinline__ void gemm_phase(PG8_LAS unsigned char* lds, const Gemm g, const Sched& S, const Epi& E) {
;     ...
;             PG8_WAIT_V(8); PG8_WAIT_L(0); PG8_BAR; PG8_MMA(0, 0, At, B0); PG8_MMA(0, 1, At, B1); PG8_BAR; PG8_SCHED;
;             PG8_LDA(At, 0, 1); PG8_STAGE(PG8_SB(0, 0), b2, voffB); PG8_STAGE(PG8_SB(0, 1), b2 + hstep, voffB); PG8_STAGE(PG8_SA(0, 0), a2, voffA);
;             PG8_WAIT_V(8); PG8_WAIT_L(0); PG8_BAR; PG8_MMA(1, 0, At, B0); PG8_MMA(1, 1, At, B1); PG8_BAR; PG8_SCHED;
	s_setprio 1
	s_waitcnt lgkmcnt(0)
	v_mfma_i32_16x16x64_i8 v[152:155], v[28:31], v[164:167], v[152:155]
	v_mfma_i32_16x16x64_i8 v[152:155], v[32:35], v[168:171], v[152:155]
	v_mfma_i32_16x16x64_i8 v[128:131], v[28:31], v[172:175], v[128:131]
	v_mfma_i32_16x16x64_i8 v[128:131], v[32:35], v[176:179], v[128:131]
	v_mfma_i32_16x16x64_i8 v[112:115], v[28:31], v[204:207], v[112:115]
	v_mfma_i32_16x16x64_i8 v[112:115], v[32:35], v[208:211], v[112:115]
	v_mfma_i32_16x16x64_i8 v[96:99], v[28:31], v[212:215], v[96:99]
	v_mfma_i32_16x16x64_i8 v[96:99], v[32:35], v[220:223], v[96:99]
	v_mfma_i32_16x16x64_i8 v[148:151], v[36:39], v[164:167], v[148:151]
	v_mfma_i32_16x16x64_i8 v[148:151], v[40:43], v[168:171], v[148:151]
	v_mfma_i32_16x16x64_i8 v[124:127], v[36:39], v[172:175], v[124:127]
	v_mfma_i32_16x16x64_i8 v[124:127], v[40:43], v[176:179], v[124:127]
	v_mfma_i32_16x16x64_i8 v[108:111], v[36:39], v[204:207], v[108:111]
	v_mfma_i32_16x16x64_i8 v[108:111], v[40:43], v[208:211], v[108:111]
	v_mfma_i32_16x16x64_i8 v[92:95], v[36:39], v[212:215], v[92:95]
	v_mfma_i32_16x16x64_i8 v[92:95], v[40:43], v[220:223], v[92:95]
	s_setprio 0
	s_setprio 1
	v_mfma_i32_16x16x64_i8 v[136:139], v[140:143], v[164:167], v[136:139]
	v_mfma_i32_16x16x64_i8 v[136:139], v[144:147], v[168:171], v[136:139]
	v_mfma_i32_16x16x64_i8 v[120:123], v[140:143], v[172:175], v[120:123]
	v_mfma_i32_16x16x64_i8 v[120:123], v[144:147], v[176:179], v[120:123]
	v_mfma_i32_16x16x64_i8 v[104:107], v[140:143], v[204:207], v[104:107]
	v_mfma_i32_16x16x64_i8 v[104:107], v[144:147], v[208:211], v[104:107]
	v_mfma_i32_16x16x64_i8 v[88:91], v[140:143], v[212:215], v[88:91]
	v_mfma_i32_16x16x64_i8 v[88:91], v[144:147], v[220:223], v[88:91]
	v_mfma_i32_16x16x64_i8 v[132:135], v[156:159], v[164:167], v[132:135]
	v_mfma_i32_16x16x64_i8 v[132:135], v[160:163], v[168:171], v[132:135]
	v_mfma_i32_16x16x64_i8 v[116:119], v[156:159], v[172:175], v[116:119]
	v_mfma_i32_16x16x64_i8 v[116:119], v[160:163], v[176:179], v[116:119]
	v_mfma_i32_16x16x64_i8 v[100:103], v[156:159], v[204:207], v[100:103]
	v_mfma_i32_16x16x64_i8 v[100:103], v[160:163], v[208:211], v[100:103]
	v_mfma_i32_16x16x64_i8 v[84:87], v[156:159], v[212:215], v[84:87]
	v_mfma_i32_16x16x64_i8 v[84:87], v[160:163], v[220:223], v[84:87]
	s_setprio 0
	s_barrier
	s_add_i32 s87, s87, s46
	v_lshl_add_u64 v[190:191], s[58:59], 0, v[2:3]
	s_mov_b32 m0, s87
	ds_read_b128 v[164:167], v219 offset:16384
	ds_read_b128 v[168:171], v219 offset:17408
	ds_read_b128 v[172:175], v219 offset:18432
	ds_read_b128 v[176:179], v219 offset:19456
	ds_read_b128 v[204:207], v219 offset:20480
	ds_read_b128 v[208:211], v219 offset:21504
	ds_read_b128 v[212:215], v219 offset:22528
	ds_read_b128 v[220:223], v219 offset:23552
	global_load_lds_dwordx4 v[190:191], off
	s_add_i32 m0, s87, 0x2000
	s_add_u32 s96, s58, 0x80000
	v_lshl_add_u64 v[224:225], s[58:59], 0, v[184:185]
	s_addc_u32 s97, s59, 0
	s_add_i32 s87, vcc_lo, s46
	global_load_lds_dwordx4 v[224:225], off
	v_lshl_add_u64 v[226:227], s[96:97], 0, v[2:3]
	s_mov_b32 m0, s87
	v_lshl_add_u64 v[228:229], s[60:61], 0, v[182:183]
	global_load_lds_dwordx4 v[226:227], off
	v_lshl_add_u64 v[226:227], s[96:97], 0, v[184:185]
	s_add_i32 m0, s87, 0x2000
	s_nop 0
	global_load_lds_dwordx4 v[226:227], off
	v_lshl_add_u64 v[226:227], s[60:61], 0, v[180:181]
	s_mov_b32 m0, s65
	s_nop 0
	global_load_lds_dwordx4 v[226:227], off
	s_mov_b32 m0, s67
	s_nop 0
	global_load_lds_dwordx4 v[228:229], off
	s_waitcnt vmcnt(8)
	s_waitcnt lgkmcnt(0)
	s_barrier
	s_setprio 1
	s_waitcnt lgkmcnt(0)
	v_mfma_i32_16x16x64_i8 v[80:83], v[28:31], v[164:167], v[80:83]
	v_mfma_i32_16x16x64_i8 v[80:83], v[32:35], v[168:171], v[80:83]
	v_mfma_i32_16x16x64_i8 v[64:67], v[28:31], v[172:175], v[64:67]
	v_mfma_i32_16x16x64_i8 v[64:67], v[32:35], v[176:179], v[64:67]
	v_mfma_i32_16x16x64_i8 v[48:51], v[28:31], v[204:207], v[48:51]
	v_mfma_i32_16x16x64_i8 v[48:51], v[32:35], v[208:211], v[48:51]
	v_mfma_i32_16x16x64_i8 v[16:19], v[28:31], v[212:215], v[16:19]
	v_mfma_i32_16x16x64_i8 v[16:19], v[32:35], v[220:223], v[16:19]
	v_mfma_i32_16x16x64_i8 v[76:79], v[36:39], v[164:167], v[76:79]
	v_mfma_i32_16x16x64_i8 v[76:79], v[40:43], v[168:171], v[76:79]
	v_mfma_i32_16x16x64_i8 v[60:63], v[36:39], v[172:175], v[60:63]
	v_mfma_i32_16x16x64_i8 v[60:63], v[40:43], v[176:179], v[60:63]
	v_mfma_i32_16x16x64_i8 v[44:47], v[36:39], v[204:207], v[44:47]
	v_mfma_i32_16x16x64_i8 v[44:47], v[40:43], v[208:211], v[44:47]
	v_mfma_i32_16x16x64_i8 v[12:15], v[36:39], v[212:215], v[12:15]
	v_mfma_i32_16x16x64_i8 v[12:15], v[40:43], v[220:223], v[12:15]
	s_setprio 0
	s_setprio 1
	v_mfma_i32_16x16x64_i8 v[24:27], v[140:143], v[204:207], v[24:27]
	v_mfma_i32_16x16x64_i8 v[24:27], v[144:147], v[208:211], v[24:27]
	v_mfma_i32_16x16x64_i8 v[8:11], v[140:143], v[212:215], v[8:11]
	v_mfma_i32_16x16x64_i8 v[8:11], v[144:147], v[220:223], v[8:11]
	v_mfma_i32_16x16x64_i8 v[28:31], v[140:143], v[164:167], v[72:75]
	v_mfma_i32_16x16x64_i8 v[28:31], v[144:147], v[168:171], v[28:31]
	v_mfma_i32_16x16x64_i8 v[36:39], v[140:143], v[172:175], v[56:59]
	v_mfma_i32_16x16x64_i8 v[36:39], v[144:147], v[176:179], v[36:39]
	v_mfma_i32_16x16x64_i8 v[20:23], v[156:159], v[204:207], v[20:23]
	v_mfma_i32_16x16x64_i8 v[20:23], v[160:163], v[208:211], v[20:23]
	v_mfma_i32_16x16x64_i8 v[4:7], v[156:159], v[212:215], v[4:7]
	v_mfma_i32_16x16x64_i8 v[4:7], v[160:163], v[220:223], v[4:7]
	v_mfma_i32_16x16x64_i8 v[32:35], v[156:159], v[164:167], v[68:71]
	v_mfma_i32_16x16x64_i8 v[32:35], v[160:163], v[168:171], v[32:35]
	v_mfma_i32_16x16x64_i8 v[40:43], v[156:159], v[172:175], v[52:55]
	v_mfma_i32_16x16x64_i8 v[40:43], v[160:163], v[176:179], v[40:43]
	s_setprio 0
	s_barrier
; #define PG8_STAGE(bufoff, gbase, voff) do { _Pragma("unroll") for (int _i = 0; _i < 2; ++_i) \
;         __builtin_amdgcn_global_load_lds((const unsigned*)((const char*)(gbase) + (voff)[_i]), (PG8_LAS unsigned*)(lds + (bufoff) + ldsw + _i * 8192), 16, 0, 0); } while (0)
; #define PG8_LDA(dst, b, h) do { _Pragma("unroll") for (int m = 0; m < 4; ++m) _Pragma("unroll") for (int k = 0; k < 2; ++k) dst[m][k] = *(const PG8_LAS bf16x8*)(lds + PG8_SA(b, h) + aoff + m * 2048 + k * 1024); } while (0)
; #define PG8_LDB(dst, b, h) do { _Pragma("unroll") for (int n = 0; n < 2; ++n) _Pragma("unroll") for (int k = 0; k < 2; ++k) dst[n][k] = *(const PG8_LAS bf16x8*)(lds + PG8_SB(b, h) + boff + n * 2048 + k * 1024); } while (0)
; #define PG8_WAIT_V(n) asm volatile("s_waitcnt vmcnt(" #n ")" ::: "memory")
; #define PG8_WAIT_L(n) asm volatile("s_waitcnt lgkmcnt(" #n ")" ::: "memory")
; #define PG8_BAR __builtin_amdgcn_s_barrier()
; #define PG8_SCHED __builtin_amdgcn_sched_barrier(0)
; template <class Epi, class Sched, bool ALIGN_EPI = false, bool SP2 = false, bool I8 = false>
; __device__ __forceinline__ void gemm_phase(PG8_LAS unsigned char* lds, const Gemm g, const Sched& S, const Epi& E) {
;     ...
;             PG8_LDB(B0, 1, 0); PG8_LDB(B1, 1, 1); PG8_SCHED; PG8_LDA(At, 1, 0); PG8_STAGE(PG8_SA(0, 1), a2 + hstep, voffA);
;             PG8_WAIT_V(8); PG8_WAIT_L(0); PG8_BAR; PG8_MMA(0, 0, At, B0); PG8_MMA(0, 1, At, B1); PG8_BAR; PG8_SCHED;
;             PG8_LDA(At, 1, 1); PG8_STAGE(PG8_SB(1, 0), b3, voffB); PG8_STAGE(PG8_SB(1, 1), b3 + hstep, voffB); PG8_STAGE(PG8_SA(1, 0), a3, voffA);
;             PG8_WAIT_V(8); PG8_WAIT_L(0); PG8_BAR; PG8_MMA(1, 0, At, B0); PG8_MMA(1, 1, At, B1); PG8_BAR; PG8_SCHED;
	s_add_i32 s87, 0, 0x18000
	s_add_i32 s96, 0, 0x1c000
	v_add_u32_e32 v72, s87, v217
	v_add_u32_e32 v160, s96, v217
	ds_read_b128 v[52:55], v72
	ds_read_b128 v[56:59], v72 offset:1024
	ds_read_b128 v[68:71], v72 offset:2048
	ds_read_b128 v[72:75], v72 offset:3072
	ds_read_b128 v[140:143], v160
	ds_read_b128 v[144:147], v160 offset:1024
	ds_read_b128 v[156:159], v160 offset:2048
	ds_read_b128 v[160:163], v160 offset:3072
	s_add_u32 s60, s60, 0x80000
	s_addc_u32 s61, s61, 0
	s_mov_b32 m0, s72
	v_lshl_add_u64 v[240:241], s[60:61], 0, v[180:181]
	ds_read_b128 v[164:167], v219 offset:32768
	ds_read_b128 v[168:171], v219 offset:33792
	ds_read_b128 v[172:175], v219 offset:34816
	ds_read_b128 v[176:179], v219 offset:35840
	ds_read_b128 v[204:207], v219 offset:36864
	ds_read_b128 v[208:211], v219 offset:37888
	ds_read_b128 v[212:215], v219 offset:38912
	ds_read_b128 v[220:223], v219 offset:39936
	global_load_lds_dwordx4 v[240:241], off
	v_lshl_add_u64 v[240:241], s[60:61], 0, v[182:183]
	s_mov_b32 m0, s73
	s_nop 0
	global_load_lds_dwordx4 v[240:241], off
	s_waitcnt vmcnt(8)
	s_waitcnt lgkmcnt(0)
	s_barrier
	s_setprio 1
	s_waitcnt lgkmcnt(0)
	v_mfma_i32_16x16x64_i8 v[152:155], v[52:55], v[164:167], v[152:155]
	v_mfma_i32_16x16x64_i8 v[152:155], v[56:59], v[168:171], v[152:155]
	v_mfma_i32_16x16x64_i8 v[128:131], v[52:55], v[172:175], v[128:131]
	v_mfma_i32_16x16x64_i8 v[128:131], v[56:59], v[176:179], v[128:131]
	v_mfma_i32_16x16x64_i8 v[112:115], v[52:55], v[204:207], v[112:115]
	v_mfma_i32_16x16x64_i8 v[112:115], v[56:59], v[208:211], v[112:115]
	v_mfma_i32_16x16x64_i8 v[96:99], v[52:55], v[212:215], v[96:99]
	v_mfma_i32_16x16x64_i8 v[96:99], v[56:59], v[220:223], v[96:99]
	v_mfma_i32_16x16x64_i8 v[148:151], v[68:71], v[164:167], v[148:151]
	v_mfma_i32_16x16x64_i8 v[148:151], v[72:75], v[168:171], v[148:151]
	v_mfma_i32_16x16x64_i8 v[124:127], v[68:71], v[172:175], v[124:127]
	v_mfma_i32_16x16x64_i8 v[124:127], v[72:75], v[176:179], v[124:127]
	v_mfma_i32_16x16x64_i8 v[108:111], v[68:71], v[204:207], v[108:111]
	v_mfma_i32_16x16x64_i8 v[108:111], v[72:75], v[208:211], v[108:111]
	v_mfma_i32_16x16x64_i8 v[92:95], v[68:71], v[212:215], v[92:95]
	v_mfma_i32_16x16x64_i8 v[92:95], v[72:75], v[220:223], v[92:95]
	s_setprio 0
	s_setprio 1
	v_mfma_i32_16x16x64_i8 v[136:139], v[140:143], v[164:167], v[136:139]
	v_mfma_i32_16x16x64_i8 v[136:139], v[144:147], v[168:171], v[136:139]
	v_mfma_i32_16x16x64_i8 v[120:123], v[140:143], v[172:175], v[120:123]
	v_mfma_i32_16x16x64_i8 v[120:123], v[144:147], v[176:179], v[120:123]
	v_mfma_i32_16x16x64_i8 v[104:107], v[140:143], v[204:207], v[104:107]
	v_mfma_i32_16x16x64_i8 v[104:107], v[144:147], v[208:211], v[104:107]
	v_mfma_i32_16x16x64_i8 v[88:91], v[140:143], v[212:215], v[88:91]
	v_mfma_i32_16x16x64_i8 v[88:91], v[144:147], v[220:223], v[88:91]
	v_mfma_i32_16x16x64_i8 v[132:135], v[156:159], v[164:167], v[132:135]
	v_mfma_i32_16x16x64_i8 v[132:135], v[160:163], v[168:171], v[132:135]
	v_mfma_i32_16x16x64_i8 v[116:119], v[156:159], v[172:175], v[116:119]
	v_mfma_i32_16x16x64_i8 v[116:119], v[160:163], v[176:179], v[116:119]
	v_mfma_i32_16x16x64_i8 v[100:103], v[156:159], v[204:207], v[100:103]
	v_mfma_i32_16x16x64_i8 v[100:103], v[160:163], v[208:211], v[100:103]
	v_mfma_i32_16x16x64_i8 v[84:87], v[156:159], v[212:215], v[84:87]
	v_mfma_i32_16x16x64_i8 v[84:87], v[160:163], v[220:223], v[84:87]
	s_setprio 0
	s_barrier
	s_add_i32 s60, s87, s46
	v_lshl_add_u64 v[190:191], v[190:191], 0, s[84:85]
	s_mov_b32 m0, s60
	ds_read_b128 v[164:167], v219 offset:49152
	ds_read_b128 v[168:171], v219 offset:50176
	ds_read_b128 v[172:175], v219 offset:51200
	ds_read_b128 v[176:179], v219 offset:52224
	ds_read_b128 v[204:207], v219 offset:53248
	ds_read_b128 v[208:211], v219 offset:54272
	ds_read_b128 v[212:215], v219 offset:55296
	ds_read_b128 v[220:223], v219 offset:56320
	global_load_lds_dwordx4 v[190:191], off
	s_add_i32 m0, s60, 0x2000
	s_add_u32 s58, s58, 0x80080
	v_lshl_add_u64 v[190:191], v[224:225], 0, s[84:85]
	s_addc_u32 s59, s59, 0
	s_add_i32 s60, s96, s46
	global_load_lds_dwordx4 v[190:191], off
	v_lshl_add_u64 v[190:191], s[58:59], 0, v[2:3]
	s_mov_b32 m0, s60
	s_nop 0
	global_load_lds_dwordx4 v[190:191], off
	v_lshl_add_u64 v[190:191], s[58:59], 0, v[184:185]
	s_add_i32 m0, s60, 0x2000
	s_nop 0
	global_load_lds_dwordx4 v[190:191], off
	v_lshl_add_u64 v[190:191], v[226:227], 0, s[84:85]
	s_mov_b32 m0, s28
	s_nop 0
	global_load_lds_dwordx4 v[190:191], off
	v_lshl_add_u64 v[190:191], v[228:229], 0, s[84:85]
	s_mov_b32 m0, s77
	s_nop 0
	global_load_lds_dwordx4 v[190:191], off
	s_waitcnt vmcnt(8)
	s_waitcnt lgkmcnt(0)
	s_barrier
	s_setprio 1
	s_waitcnt lgkmcnt(0)
	v_mfma_i32_16x16x64_i8 v[80:83], v[52:55], v[164:167], v[80:83]
	v_mfma_i32_16x16x64_i8 v[80:83], v[56:59], v[168:171], v[80:83]
	v_mfma_i32_16x16x64_i8 v[64:67], v[52:55], v[172:175], v[64:67]
	v_mfma_i32_16x16x64_i8 v[64:67], v[56:59], v[176:179], v[64:67]
	v_mfma_i32_16x16x64_i8 v[48:51], v[52:55], v[204:207], v[48:51]
	v_mfma_i32_16x16x64_i8 v[48:51], v[56:59], v[208:211], v[48:51]
	v_mfma_i32_16x16x64_i8 v[16:19], v[52:55], v[212:215], v[16:19]
	v_mfma_i32_16x16x64_i8 v[16:19], v[56:59], v[220:223], v[16:19]
	v_mfma_i32_16x16x64_i8 v[76:79], v[68:71], v[164:167], v[76:79]
	v_mfma_i32_16x16x64_i8 v[76:79], v[72:75], v[168:171], v[76:79]
	v_mfma_i32_16x16x64_i8 v[60:63], v[68:71], v[172:175], v[60:63]
	v_mfma_i32_16x16x64_i8 v[60:63], v[72:75], v[176:179], v[60:63]
	v_mfma_i32_16x16x64_i8 v[44:47], v[68:71], v[204:207], v[44:47]
	v_mfma_i32_16x16x64_i8 v[44:47], v[72:75], v[208:211], v[44:47]
	v_mfma_i32_16x16x64_i8 v[12:15], v[68:71], v[212:215], v[12:15]
	v_mfma_i32_16x16x64_i8 v[12:15], v[72:75], v[220:223], v[12:15]
	s_setprio 0
	s_setprio 1
	v_mfma_i32_16x16x64_i8 v[28:31], v[140:143], v[164:167], v[28:31]
	v_mfma_i32_16x16x64_i8 v[72:75], v[144:147], v[168:171], v[28:31]
	v_mfma_i32_16x16x64_i8 v[28:31], v[140:143], v[172:175], v[36:39]
	v_mfma_i32_16x16x64_i8 v[56:59], v[144:147], v[176:179], v[28:31]
	v_mfma_i32_16x16x64_i8 v[24:27], v[140:143], v[204:207], v[24:27]
	v_mfma_i32_16x16x64_i8 v[24:27], v[144:147], v[208:211], v[24:27]
	v_mfma_i32_16x16x64_i8 v[8:11], v[140:143], v[212:215], v[8:11]
	v_mfma_i32_16x16x64_i8 v[8:11], v[144:147], v[220:223], v[8:11]
	v_mfma_i32_16x16x64_i8 v[28:31], v[156:159], v[164:167], v[32:35]
	v_mfma_i32_16x16x64_i8 v[68:71], v[160:163], v[168:171], v[28:31]
	v_mfma_i32_16x16x64_i8 v[28:31], v[156:159], v[172:175], v[40:43]
	v_mfma_i32_16x16x64_i8 v[52:55], v[160:163], v[176:179], v[28:31]
	v_mfma_i32_16x16x64_i8 v[20:23], v[156:159], v[204:207], v[20:23]
	v_mfma_i32_16x16x64_i8 v[20:23], v[160:163], v[208:211], v[20:23]
	v_mfma_i32_16x16x64_i8 v[4:7], v[156:159], v[212:215], v[4:7]
	v_mfma_i32_16x16x64_i8 v[4:7], v[160:163], v[220:223], v[4:7]
	s_setprio 0
	s_barrier
	s_add_i32 s86, s86, 2
	s_add_u32 s54, s54, 0x100
	s_addc_u32 s55, s55, 0
	s_add_u32 s45, s45, 0x100
	s_addc_u32 s49, s49, 0
	s_cmp_gt_u32 s86, 29
	s_cbranch_scc0 .LBB0_1843
